# HNAQP2S + nt hint on the 192 residual-stream (x) loads of the residual GEMM epilogues
# baseline (speedup 1.0000x reference)
; #define LAS __attribute__((address_space(3)))
;     __device__ __forceinline__ void operator()(const f32x4 (&acc)[2][2][4][2], const Unit& u, int wr, int wc, int fr, int fq) const {
;         const int s = u.pm >> 5, lane = fq * 16 + fr, rr = lane >> 3, pc = lane & 7;
;         const float* __restrict__ xi = xin + (size_t)u.pm * BM * DM; float* __restrict__ xo = xout + (size_t)u.pm * BM * DM; bf16_t* __restrict__ ho = Hn + (size_t)u.pm * BM * DM;
;         LAS unsigned char* st = lds_epi + (wr * 4 + wc) * 2304;
;         LAS float* sst = (LAS float*)(lds_epi + 18432 + (wr * 4 + wc) * 512);
;         const int colr = u.pn * BM + wc * 64 + 4 * pc;
;         const unsigned eb = (unsigned)((wr * 64 + rr) * DM + colr);
;         f32x4 gv[2], gsn[2];
; #pragma unroll
;         for (int bj = 0; bj < 2; ++bj) { gv[bj] = *(const f32x4*)(gate + (size_t)s * MODW + colr + bj * 32) * (0.5f * GS2);
;             if (!PLAIN) gsn[bj] = *(const f32x4*)(gnext + colr + bj * 32) * (*(const f32x4*)(scnext + (size_t)s * MODW + colr + bj * 32) + 1.0f); else gsn[bj] = gv[bj]; }
;         const unsigned wr_off = (unsigned)(fr * 144 + 16 * fq), rd_off = (unsigned)(rr * 144 + pc * 16);
;         const bool odd = (rr & 1) != 0;
;         f32x4 xb[2][2][2];
;     ...
;         ERN_LOADX(0);
; #pragma unroll
;         for (int g = 0; g < 8; ++g) { const int ai = g >> 2, m = g & 3;
;             if (g + 1 < 8) ERN_LOADX(g + 1);
;             float sq0 = 0.f, sq1 = 0.f; u32x2 hw[2][2];
; #pragma unroll
;             for (int bj = 0; bj < 2; ++bj) {
;                 *(LAS f32x4*)(st + wr_off) = acc[ai][bj][m][0]; *(LAS f32x4*)(st + wr_off + 64) = acc[ai][bj][m][1];
;                 const f32x4 a0 = *(const LAS f32x4*)(st + rd_off), a1 = *(const LAS f32x4*)(st + rd_off + 8 * 144);
;                 { const f32x4 xv = xb[g & 1][bj][0] + gv[bj] * a0; __builtin_nontemporal_store(xv, (f32x4*)((char*)xo + 4u * ERN_EOFF(g, bj, 0)));
;                   sq0 += (xv.x * xv.x + xv.y * xv.y) + (xv.z * xv.z + xv.w * xv.w);
;                   const f32x4 hv = xv * gsn[bj]; hw[bj][0].x = cvt_pk_bf16(hv.x, hv.y); hw[bj][0].y = cvt_pk_bf16(hv.z, hv.w); }
;                 { const f32x4 xv = xb[g & 1][bj][1] + gv[bj] * a1; __builtin_nontemporal_store(xv, (f32x4*)((char*)xo + 4u * ERN_EOFF(g, bj, 1)));
;                   sq1 += (xv.x * xv.x + xv.y * xv.y) + (xv.z * xv.z + xv.w * xv.w);
.LBB0_320:
	s_ashr_i32 s12, s4, 5
	s_ashr_i32 s5, s4, 31
	v_lshl_or_b32 v130, s0, 8, v192
	s_mul_i32 s14, s12, 0x12000
	s_mul_hi_i32 s0, s12, 0x12000
	s_add_u32 s12, s35, s14
	v_ashrrev_i32_e32 v131, 31, v130
	s_addc_u32 s13, s36, s0
	v_lshlrev_b64 v[132:133], 2, v[130:131]
	v_lshl_add_u64 v[134:135], s[12:13], 0, v[132:133]
	s_add_u32 s12, s37, s14
	s_addc_u32 s13, s60, s0
	v_lshl_add_u64 v[136:137], s[46:47], 0, v[132:133]
	v_lshl_add_u64 v[132:133], s[12:13], 0, v[132:133]
	s_lshl_b64 s[54:55], s[4:5], 21
	v_readlane_b32 s12, v253, 2
	v_readlane_b32 s13, v253, 3
	s_add_u32 s58, s12, s54
	v_add_u32_e32 v202, v130, v193
	s_addc_u32 s59, s13, s55
	v_lshlrev_b32_e32 v207, 2, v202
	global_load_dwordx4 v[170:173], v[136:137], off
	global_load_dwordx4 v[166:169], v[134:135], off
	global_load_dwordx4 v[174:177], v[134:135], off offset:128
	global_load_dwordx4 v[186:189], v[132:133], off
	global_load_dwordx4 v[208:211], v[132:133], off offset:128
	global_load_dwordx4 v[212:215], v207, s[58:59] nt
	v_add_u32_e32 v130, 0x10000, v207
	global_load_dwordx4 v[216:219], v130, s[58:59] nt
	global_load_dwordx4 v[220:223], v[136:137], off offset:128
	global_load_dwordx4 v[224:227], v207, s[58:59] offset:128 nt
	v_add_u32_e32 v206, 0x10080, v207
	v_add_u32_e32 v130, 0x20000, v207
	global_load_dwordx4 v[228:231], v206, s[58:59] nt
	v_add_u32_e32 v154, 0x30000, v207
	v_add_u32_e32 v184, 0x20080, v207
	v_add_u32_e32 v182, 0x30080, v207
	global_load_dwordx4 v[142:145], v130, s[58:59] nt
	global_load_dwordx4 v[138:141], v154, s[58:59] nt
	global_load_dwordx4 v[134:137], v184, s[58:59] nt
	s_nop 0
	global_load_dwordx4 v[130:133], v182, s[58:59] nt
	ds_write_b128 v200, v[126:129]
	ds_write_b128 v200, v[122:125] offset:64
	v_and_b32_e32 v127, 64, v199
	ds_read_b128 v[122:125], v201
	ds_read_b128 v[232:235], v201 offset:1152
	v_xor_b32_e32 v126, 8, v199
	v_add_u32_e32 v183, 64, v127
	v_cmp_lt_i32_e32 vcc, v126, v183
	v_add_u32_e32 v185, 0x4000, v202
	s_add_u32 s56, s90, s54
	v_cndmask_b32_e32 v126, v199, v126, vcc
	v_lshlrev_b32_e32 v203, 2, v126
	v_lshlrev_b32_e32 v236, 2, v185
	s_addc_u32 s57, s91, s55
	s_lshl_b64 s[12:13], s[4:5], 20
	s_add_u32 s54, s93, s12
	v_readlane_b32 s16, v253, 6
	v_readlane_b32 s17, v253, 7
	s_addc_u32 s55, s92, s13
	v_readlane_b32 s14, v253, 4
	v_readlane_b32 s15, v253, 5
	v_readlane_b32 s18, v253, 8
	v_readlane_b32 s19, v253, 9
	v_readlane_b32 s20, v253, 10
	v_readlane_b32 s21, v253, 11
	v_readlane_b32 s22, v253, 12
	v_readlane_b32 s23, v253, 13
	v_readlane_b32 s24, v253, 14
	v_readlane_b32 s25, v253, 15
	v_readlane_b32 s26, v253, 16
	v_readlane_b32 s27, v253, 17
	s_waitcnt vmcnt(0)
	v_pk_mul_f32 v[180:181], v[166:167], 0.5 op_sel_hi:[1,0]
	v_pk_mul_f32 v[178:179], v[168:169], 0.5 op_sel_hi:[1,0]
	v_pk_add_f32 v[126:127], v[188:189], 1.0 op_sel_hi:[1,0]
	v_pk_add_f32 v[128:129], v[186:187], 1.0 op_sel_hi:[1,0]
	v_pk_mul_f32 v[166:167], v[176:177], 0.5 op_sel_hi:[1,0]
	v_pk_mul_f32 v[168:169], v[174:175], 0.5 op_sel_hi:[1,0]
	v_pk_mul_f32 v[174:175], v[172:173], v[126:127]
	v_pk_mul_f32 v[176:177], v[170:171], v[128:129]
	s_waitcnt lgkmcnt(1)
	v_pk_fma_f32 v[126:127], v[180:181], v[122:123], v[212:213]
	s_waitcnt lgkmcnt(0)
	v_pk_fma_f32 v[122:123], v[180:181], v[232:233], v[216:217]
	v_pk_fma_f32 v[128:129], v[178:179], v[124:125], v[214:215]
	v_pk_fma_f32 v[124:125], v[178:179], v[234:235], v[218:219]
	v_pk_mul_f32 v[186:187], v[176:177], v[122:123]
	global_store_dwordx4 v207, v[126:129], s[56:57] nt
	v_pk_mul_f32 v[170:171], v[174:175], v[128:129]
	v_pk_mul_f32 v[172:173], v[176:177], v[126:127]
	v_pk_mul_f32 v[204:205], v[174:175], v[124:125]
	v_cvt_pk_bf16_f32 v188, v172, v173
	v_cvt_pk_bf16_f32 v189, v170, v171
	global_store_dwordx4 v236, v[122:125], s[56:57] nt
	v_cvt_pk_bf16_f32 v186, v186, v187
	v_cvt_pk_bf16_f32 v187, v204, v205
	ds_write_b128 v200, v[118:121]
	ds_write_b128 v200, v[114:117] offset:64
	ds_read_b128 v[114:117], v201
	v_pk_add_f32 v[190:191], v[210:211], 1.0 op_sel_hi:[1,0]
	v_pk_add_f32 v[118:119], v[208:209], 1.0 op_sel_hi:[1,0]
	ds_read_b128 v[208:211], v201 offset:1152
	v_pk_mul_f32 v[170:171], v[222:223], v[190:191]
	v_pk_mul_f32 v[172:173], v[220:221], v[118:119]
	s_waitcnt lgkmcnt(1)
	v_pk_fma_f32 v[120:121], v[166:167], v[116:117], v[226:227]
	v_pk_fma_f32 v[118:119], v[168:169], v[114:115], v[224:225]
	v_pk_mul_f32 v[190:191], v[170:171], v[120:121]
	v_pk_mul_f32 v[204:205], v[172:173], v[118:119]
	global_store_dwordx4 v207, v[118:121], s[56:57] offset:128 nt
	v_cvt_pk_bf16_f32 v204, v204, v205
	v_cvt_pk_bf16_f32 v191, v190, v191
	ds_bpermute_b32 v190, v203, v204
	ds_bpermute_b32 v191, v203, v191
	s_waitcnt lgkmcnt(2)
	v_pk_fma_f32 v[116:117], v[166:167], v[210:211], v[230:231]
	v_pk_fma_f32 v[114:115], v[168:169], v[208:209], v[228:229]
	global_store_dwordx4 v206, v[114:117], s[56:57] nt
	v_pk_mul_f32 v[204:205], v[172:173], v[114:115]
	v_lshlrev_b32_e32 v206, 1, v202
	v_pk_mul_f32 v[208:209], v[170:171], v[116:117]
	v_cvt_pk_bf16_f32 v204, v204, v205
	s_nop 0
	v_cvt_pk_bf16_f32 v205, v208, v209
	s_waitcnt lgkmcnt(0)
	v_add_u32_e32 v250, 0xfffff040, v206
	v_cndmask_b32_e64 v250, v206, v250, s[40:41]
	v_cndmask_b32_e64 v248, v188, v190, s[40:41]
	v_cndmask_b32_e64 v249, v189, v191, s[40:41]
	global_store_dwordx2 v250, v[248:249], s[54:55]
	v_cndmask_b32_e64 v246, v190, v188, s[40:41]
	v_cndmask_b32_e64 v247, v191, v189, s[40:41]
	s_waitcnt lgkmcnt(1)
	v_add_u32_e32 v190, 0x1040, v206
	v_cndmask_b32_e64 v190, v206, v190, s[38:39]
	global_store_dwordx2 v190, v[246:247], s[54:55]
	ds_bpermute_b32 v188, v203, v204
	ds_bpermute_b32 v189, v203, v205
	v_lshlrev_b32_e32 v190, 1, v185
	s_waitcnt lgkmcnt(0)
; #define LAS __attribute__((address_space(3)))
; #define ERN_EOFF(q, m) (eb + (unsigned)((((q) & 1) * HALF + (m) * 16) * DM + ERN_COL((q) >> 1)))
;     __device__ __forceinline__ void operator()(const f32x4 (&acc)[2][2][4][2], const Unit& u, int wr, int wc, int fr, int fq) const {
;     ...
;         ERN_LOADX(0);
; #pragma unroll
;         for (int g = 0; g < 8; ++g) { const int ai = g >> 2, m = g & 3;
;             if (g + 1 < 8) ERN_LOADX(g + 1);
;             float sq0 = 0.f, sq1 = 0.f; u32x2 hw[2][2];
; #pragma unroll
;             for (int bj = 0; bj < 2; ++bj) {
;                 *(LAS f32x4*)(st + wr_off) = acc[ai][bj][m][0]; *(LAS f32x4*)(st + wr_off + 64) = acc[ai][bj][m][1];
;                 const f32x4 a0 = *(const LAS f32x4*)(st + rd_off), a1 = *(const LAS f32x4*)(st + rd_off + 8 * 144);
;                 { const f32x4 xv = xb[g & 1][bj][0] + gv[bj] * a0; __builtin_nontemporal_store(xv, (f32x4*)((char*)xo + 4u * ERN_EOFF(g, bj, 0)));
;                   sq0 += (xv.x * xv.x + xv.y * xv.y) + (xv.z * xv.z + xv.w * xv.w);
;                   const f32x4 hv = xv * gsn[bj]; hw[bj][0].x = cvt_pk_bf16(hv.x, hv.y); hw[bj][0].y = cvt_pk_bf16(hv.z, hv.w); }
;                 { const f32x4 xv = xb[g & 1][bj][1] + gv[bj] * a1; __builtin_nontemporal_store(xv, (f32x4*)((char*)xo + 4u * ERN_EOFF(g, bj, 1)));
;                   sq1 += (xv.x * xv.x + xv.y * xv.y) + (xv.z * xv.z + xv.w * xv.w);
;                   const f32x4 hv = xv * gsn[bj]; hw[bj][1].x = cvt_pk_bf16(hv.x, hv.y); hw[bj][1].y = cvt_pk_bf16(hv.z, hv.w); }
;             }
;             if (!NOH && !PLAIN) {
; #pragma unroll
;                 for (int rh = 0; rh < 2; ++rh) { u32x2 rv; rv.x = __shfl_xor(hw[1][rh].x, 8); rv.y = __shfl_xor(hw[1][rh].y, 8);
;                     const unsigned e0 = ERN_EOFF(g, 0, rh);
;                     const unsigned ee = odd ? (e0 - DM + 32) : e0, eo2 = odd ? e0 : (e0 + DM + 32);
;                     *(u32x2*)((char*)ho + 2u * ee) = odd ? rv : hw[0][rh];
;                     *(u32x2*)((char*)ho + 2u * eo2) = odd ? hw[0][rh] : rv; }
;             }
;             if (!PLAIN) { sq0 += __shfl_xor(sq0, 1); sq0 += __shfl_xor(sq0, 2); sq0 += __shfl_xor(sq0, 4);
;             sq1 += __shfl_xor(sq1, 1); sq1 += __shfl_xor(sq1, 2); sq1 += __shfl_xor(sq1, 4); }
;             if (!PLAIN && pc == 0) { sst[g * 16 + rr] = sq0; sst[g * 16 + 8 + rr] = sq1; }
	v_add_u32_e32 v250, 0xfffff040, v190
	v_cndmask_b32_e64 v250, v190, v250, s[40:41]
	v_cndmask_b32_e64 v248, v186, v188, s[40:41]
	v_cndmask_b32_e64 v249, v187, v189, s[40:41]
	global_store_dwordx2 v250, v[248:249], s[54:55]
	v_cndmask_b32_e64 v246, v188, v186, s[40:41]
	v_cndmask_b32_e64 v247, v189, v187, s[40:41]
	v_mul_f32_e32 v119, v119, v119
	v_mul_f32_e32 v127, v127, v127
	v_mul_f32_e32 v129, v129, v129
	v_fmac_f32_e32 v119, v118, v118
	v_mul_f32_e32 v118, v121, v121
	v_fmac_f32_e32 v129, v128, v128
	v_fmac_f32_e32 v118, v120, v120
	v_mul_f32_e32 v115, v115, v115
	v_fmac_f32_e32 v127, v126, v126
	v_add_f32_e32 v118, v119, v118
	v_fmac_f32_e32 v115, v114, v114
	v_mul_f32_e32 v114, v117, v117
	v_add_f32_e32 v117, v127, v129
	v_add_f32_e32 v117, v117, v118
	v_xor_b32_e32 v118, 1, v199
	v_cmp_lt_i32_e32 vcc, v118, v183
	v_mul_f32_e32 v123, v123, v123
	v_mul_f32_e32 v125, v125, v125
	v_cndmask_b32_e32 v118, v199, v118, vcc
	v_lshlrev_b32_e32 v204, 2, v118
	ds_bpermute_b32 v118, v204, v117
	v_fmac_f32_e32 v114, v116, v116
	v_fmac_f32_e32 v125, v124, v124
	v_fmac_f32_e32 v123, v122, v122
	v_add_f32_e32 v114, v115, v114
	s_waitcnt lgkmcnt(0)
	v_add_f32_e32 v116, v117, v118
	v_xor_b32_e32 v117, 2, v199
	v_cmp_lt_i32_e32 vcc, v117, v183
	v_add_f32_e32 v115, v123, v125
	v_add_f32_e32 v115, v115, v114
	v_cndmask_b32_e32 v117, v199, v117, vcc
	v_lshlrev_b32_e32 v205, 2, v117
	ds_bpermute_b32 v117, v205, v116
	ds_bpermute_b32 v118, v204, v115
	s_waitcnt lgkmcnt(1)
	v_add_f32_e32 v114, v116, v117
	s_waitcnt lgkmcnt(0)
	v_add_f32_e32 v117, v115, v118
	ds_bpermute_b32 v118, v205, v117
	v_xor_b32_e32 v116, 4, v199
	v_cmp_lt_i32_e32 vcc, v116, v183
	s_nop 1
	v_cndmask_b32_e32 v115, v199, v116, vcc
	v_lshlrev_b32_e32 v206, 2, v115
	s_waitcnt lgkmcnt(0)
	v_add_f32_e32 v116, v117, v118
	ds_bpermute_b32 v115, v206, v114
	ds_bpermute_b32 v117, v206, v116
	v_add_u32_e32 v118, 0x1040, v190
	v_cndmask_b32_e64 v118, v190, v118, s[38:39]
	global_store_dwordx2 v118, v[246:247], s[54:55]
	s_and_saveexec_b64 s[16:17], s[42:43]
	s_cbranch_execz .LBB0_330
	s_waitcnt lgkmcnt(1)
	v_add_f32_e32 v114, v114, v115
	s_waitcnt lgkmcnt(0)
	v_add_f32_e32 v115, v116, v117
	ds_write2_b32 v194, v114, v115 offset1:8
.LBB0_330:
	s_or_b64 exec, exec, s[16:17]
	v_add_u32_e32 v114, 0x40000, v207
	v_add_u32_e32 v190, 0x50000, v207
	v_add_u32_e32 v188, 0x40080, v207
	global_load_dwordx4 v[122:125], v190, s[58:59] nt
	global_load_dwordx4 v[118:121], v188, s[58:59] nt
	v_add_u32_e32 v186, 0x50080, v207
	global_load_dwordx4 v[126:129], v114, s[58:59] nt
	s_waitcnt lgkmcnt(0)
	global_load_dwordx4 v[114:117], v186, s[58:59] nt
	ds_write_b128 v200, v[110:113]
	ds_write_b128 v200, v[106:109] offset:64
	ds_read_b128 v[106:109], v201
	ds_read_b128 v[110:113], v201 offset:1152
	v_mov_b32_e32 v185, v155
	v_mov_b32_e32 v183, v155
	s_waitcnt lgkmcnt(1)
	v_pk_fma_f32 v[108:109], v[178:179], v[108:109], v[144:145]
	v_add_u32_e32 v144, 0x8000, v202
	v_pk_fma_f32 v[106:107], v[180:181], v[106:107], v[142:143]
	v_lshlrev_b32_e32 v142, 2, v144
	global_store_dwordx4 v142, v[106:109], s[56:57] nt
	v_pk_mul_f32 v[142:143], v[176:177], v[106:107]
	s_waitcnt lgkmcnt(0)
	v_pk_fma_f32 v[112:113], v[178:179], v[112:113], v[140:141]
	v_pk_fma_f32 v[110:111], v[180:181], v[110:111], v[138:139]
	v_lshl_add_u64 v[138:139], s[56:57], 0, v[154:155]
	v_pk_mul_f32 v[208:209], v[174:175], v[108:109]
	v_cvt_pk_bf16_f32 v142, v142, v143
	v_pk_mul_f32 v[140:141], v[174:175], v[112:113]
	v_cvt_pk_bf16_f32 v143, v208, v209
	global_store_dwordx4 v[138:139], v[110:113], off nt
	v_pk_mul_f32 v[138:139], v[176:177], v[110:111]
	s_nop 0
	v_cvt_pk_bf16_f32 v138, v138, v139
	v_cvt_pk_bf16_f32 v139, v140, v141
	ds_write_b128 v200, v[102:105]
	ds_write_b128 v200, v[98:101] offset:64
	ds_read_b128 v[98:101], v201
	ds_read_b128 v[102:105], v201 offset:1152
	s_waitcnt lgkmcnt(1)
	v_pk_fma_f32 v[98:99], v[168:169], v[98:99], v[134:135]
	v_pk_fma_f32 v[100:101], v[166:167], v[100:101], v[136:137]
	v_lshl_add_u64 v[134:135], s[56:57], 0, v[184:185]
	v_pk_mul_f32 v[136:137], v[172:173], v[98:99]
	s_waitcnt lgkmcnt(0)
	v_pk_fma_f32 v[104:105], v[166:167], v[104:105], v[132:133]
	v_pk_fma_f32 v[102:103], v[168:169], v[102:103], v[130:131]
	v_lshl_add_u64 v[130:131], s[56:57], 0, v[182:183]
	global_store_dwordx4 v[134:135], v[98:101], off nt
	v_pk_mul_f32 v[134:135], v[170:171], v[100:101]
	v_cvt_pk_bf16_f32 v136, v136, v137
	v_pk_mul_f32 v[132:133], v[172:173], v[102:103]
	v_cvt_pk_bf16_f32 v137, v134, v135
	global_store_dwordx4 v[130:131], v[102:105], off nt
	ds_bpermute_b32 v130, v203, v136
	ds_bpermute_b32 v131, v203, v137
	v_pk_mul_f32 v[134:135], v[170:171], v[104:105]
	v_cvt_pk_bf16_f32 v132, v132, v133
	s_nop 0
	v_cvt_pk_bf16_f32 v133, v134, v135
	v_lshlrev_b32_e32 v134, 1, v144
	s_waitcnt lgkmcnt(0)
	v_add_u32_e32 v250, 0xfffff040, v134
	v_cndmask_b32_e64 v250, v134, v250, s[40:41]
	v_cndmask_b32_e64 v248, v142, v130, s[40:41]
	v_cndmask_b32_e64 v249, v143, v131, s[40:41]
	global_store_dwordx2 v250, v[248:249], s[54:55]
	v_cndmask_b32_e64 v246, v130, v142, s[40:41]
	v_cndmask_b32_e64 v247, v131, v143, s[40:41]
	s_waitcnt lgkmcnt(1)
	v_add_u32_e32 v130, 0x1040, v134
	v_cndmask_b32_e64 v130, v134, v130, s[38:39]
	global_store_dwordx2 v130, v[246:247], s[54:55]
	ds_bpermute_b32 v130, v203, v132
	s_waitcnt lgkmcnt(1)
	ds_bpermute_b32 v131, v203, v133
	v_add_u32_e32 v133, 0xc000, v202
	v_lshlrev_b32_e32 v132, 1, v133
	s_waitcnt lgkmcnt(0)
; #define LAS __attribute__((address_space(3)))
; #define ERN_EOFF(q, m) (eb + (unsigned)((((q) & 1) * HALF + (m) * 16) * DM + ERN_COL((q) >> 1)))
;     __device__ __forceinline__ void operator()(const f32x4 (&acc)[2][2][4][2], const Unit& u, int wr, int wc, int fr, int fq) const {
;     ...
;         for (int g = 0; g < 8; ++g) { const int ai = g >> 2, m = g & 3;
;             if (g + 1 < 8) ERN_LOADX(g + 1);
;             float sq0 = 0.f, sq1 = 0.f; u32x2 hw[2][2];
; #pragma unroll
;             for (int bj = 0; bj < 2; ++bj) {
;                 *(LAS f32x4*)(st + wr_off) = acc[ai][bj][m][0]; *(LAS f32x4*)(st + wr_off + 64) = acc[ai][bj][m][1];
;                 const f32x4 a0 = *(const LAS f32x4*)(st + rd_off), a1 = *(const LAS f32x4*)(st + rd_off + 8 * 144);
;                 { const f32x4 xv = xb[g & 1][bj][0] + gv[bj] * a0; __builtin_nontemporal_store(xv, (f32x4*)((char*)xo + 4u * ERN_EOFF(g, bj, 0)));
;                   sq0 += (xv.x * xv.x + xv.y * xv.y) + (xv.z * xv.z + xv.w * xv.w);
;                   const f32x4 hv = xv * gsn[bj]; hw[bj][0].x = cvt_pk_bf16(hv.x, hv.y); hw[bj][0].y = cvt_pk_bf16(hv.z, hv.w); }
;                 { const f32x4 xv = xb[g & 1][bj][1] + gv[bj] * a1; __builtin_nontemporal_store(xv, (f32x4*)((char*)xo + 4u * ERN_EOFF(g, bj, 1)));
;                   sq1 += (xv.x * xv.x + xv.y * xv.y) + (xv.z * xv.z + xv.w * xv.w);
;                   const f32x4 hv = xv * gsn[bj]; hw[bj][1].x = cvt_pk_bf16(hv.x, hv.y); hw[bj][1].y = cvt_pk_bf16(hv.z, hv.w); }
;             }
;             if (!NOH && !PLAIN) {
; #pragma unroll
;                 for (int rh = 0; rh < 2; ++rh) { u32x2 rv; rv.x = __shfl_xor(hw[1][rh].x, 8); rv.y = __shfl_xor(hw[1][rh].y, 8);
;                     const unsigned e0 = ERN_EOFF(g, 0, rh);
;                     const unsigned ee = odd ? (e0 - DM + 32) : e0, eo2 = odd ? e0 : (e0 + DM + 32);
;                     *(u32x2*)((char*)ho + 2u * ee) = odd ? rv : hw[0][rh];
;                     *(u32x2*)((char*)ho + 2u * eo2) = odd ? hw[0][rh] : rv; }
;             }
;             if (!PLAIN) { sq0 += __shfl_xor(sq0, 1); sq0 += __shfl_xor(sq0, 2); sq0 += __shfl_xor(sq0, 4);
;             sq1 += __shfl_xor(sq1, 1); sq1 += __shfl_xor(sq1, 2); sq1 += __shfl_xor(sq1, 4); }
;             if (!PLAIN && pc == 0) { sst[g * 16 + rr] = sq0; sst[g * 16 + 8 + rr] = sq1; }
	v_add_u32_e32 v250, 0xfffff040, v132
	v_cndmask_b32_e64 v250, v132, v250, s[40:41]
	v_cndmask_b32_e64 v248, v138, v130, s[40:41]
	v_cndmask_b32_e64 v249, v139, v131, s[40:41]
	global_store_dwordx2 v250, v[248:249], s[54:55]
	v_cndmask_b32_e64 v246, v130, v138, s[40:41]
	v_cndmask_b32_e64 v247, v131, v139, s[40:41]
	v_mul_f32_e32 v99, v99, v99
	v_fmac_f32_e32 v99, v98, v98
	v_mul_f32_e32 v98, v101, v101
	v_mul_f32_e32 v109, v109, v109
	v_fmac_f32_e32 v98, v100, v100
	v_mul_f32_e32 v107, v107, v107
	v_fmac_f32_e32 v109, v108, v108
	v_mul_f32_e32 v108, v111, v111
	v_mul_f32_e32 v111, v113, v113
	v_add_f32_e32 v98, v99, v98
	v_mul_f32_e32 v99, v103, v103
	v_mul_f32_e32 v100, v105, v105
	v_fmac_f32_e32 v111, v112, v112
	v_fmac_f32_e32 v99, v102, v102
	v_fmac_f32_e32 v100, v104, v104
	v_fmac_f32_e32 v107, v106, v106
	v_fmac_f32_e32 v108, v110, v110
	v_add_f32_e32 v99, v99, v100
	v_add_f32_e32 v100, v107, v109
	v_add_f32_e32 v101, v108, v111
	v_add_f32_e32 v98, v100, v98
	v_add_f32_e32 v99, v101, v99
	ds_bpermute_b32 v100, v204, v98
	ds_bpermute_b32 v101, v204, v99
	s_waitcnt lgkmcnt(1)
	v_add_f32_e32 v98, v98, v100
	s_waitcnt lgkmcnt(0)
	v_add_f32_e32 v101, v99, v101
	ds_bpermute_b32 v100, v205, v98
	ds_bpermute_b32 v102, v205, v101
	s_waitcnt lgkmcnt(1)
	v_add_f32_e32 v98, v98, v100
	s_waitcnt lgkmcnt(0)
	v_add_f32_e32 v100, v101, v102
	ds_bpermute_b32 v99, v206, v98
	ds_bpermute_b32 v101, v206, v100
	v_add_u32_e32 v102, 0x1040, v132
	v_cndmask_b32_e64 v102, v132, v102, s[38:39]
	global_store_dwordx2 v102, v[246:247], s[54:55]
	s_and_saveexec_b64 s[16:17], s[42:43]
	s_cbranch_execz .LBB0_340
	s_waitcnt lgkmcnt(1)
	v_add_f32_e32 v98, v98, v99
	s_waitcnt lgkmcnt(0)
	v_add_f32_e32 v99, v100, v101
	ds_write2_b32 v194, v98, v99 offset0:16 offset1:24
.LBB0_340:
	s_or_b64 exec, exec, s[16:17]
	v_add_u32_e32 v98, 0x60000, v207
	v_add_u32_e32 v154, 0x70000, v207
	v_add_u32_e32 v132, 0x60080, v207
	global_load_dwordx4 v[106:109], v154, s[58:59] nt
	global_load_dwordx4 v[102:105], v132, s[58:59] nt
	v_add_u32_e32 v130, 0x70080, v207
	global_load_dwordx4 v[110:113], v98, s[58:59] nt
	s_waitcnt lgkmcnt(0)
	global_load_dwordx4 v[98:101], v130, s[58:59] nt
	ds_write_b128 v200, v[94:97]
	ds_write_b128 v200, v[90:93] offset:64
	ds_read_b128 v[90:93], v201
	ds_read_b128 v[94:97], v201 offset:1152
	v_mov_b32_e32 v191, v155
	v_mov_b32_e32 v189, v155
	v_mov_b32_e32 v187, v155
	s_waitcnt vmcnt(11) lgkmcnt(1)
	v_pk_fma_f32 v[92:93], v[178:179], v[92:93], v[128:129]
	v_add_u32_e32 v128, 0x10000, v202
	v_pk_fma_f32 v[90:91], v[180:181], v[90:91], v[126:127]
	v_lshlrev_b32_e32 v126, 2, v128
	global_store_dwordx4 v126, v[90:93], s[56:57] nt
	v_pk_mul_f32 v[126:127], v[176:177], v[90:91]
	s_waitcnt lgkmcnt(0)
	v_pk_fma_f32 v[96:97], v[178:179], v[96:97], v[124:125]
	v_pk_fma_f32 v[94:95], v[180:181], v[94:95], v[122:123]
	v_lshl_add_u64 v[122:123], s[56:57], 0, v[190:191]
	v_pk_mul_f32 v[134:135], v[174:175], v[92:93]
	v_cvt_pk_bf16_f32 v126, v126, v127
	v_pk_mul_f32 v[124:125], v[174:175], v[96:97]
	v_cvt_pk_bf16_f32 v127, v134, v135
	global_store_dwordx4 v[122:123], v[94:97], off nt
	v_pk_mul_f32 v[122:123], v[176:177], v[94:95]
	s_nop 0
	v_cvt_pk_bf16_f32 v122, v122, v123
	v_cvt_pk_bf16_f32 v123, v124, v125
	ds_write_b128 v200, v[86:89]
	ds_write_b128 v200, v[82:85] offset:64
	ds_read_b128 v[82:85], v201
	ds_read_b128 v[86:89], v201 offset:1152
	s_waitcnt lgkmcnt(1)
	v_pk_fma_f32 v[82:83], v[168:169], v[82:83], v[118:119]
	v_pk_fma_f32 v[84:85], v[166:167], v[84:85], v[120:121]
	v_lshl_add_u64 v[118:119], s[56:57], 0, v[188:189]
	v_pk_mul_f32 v[120:121], v[172:173], v[82:83]
	s_waitcnt vmcnt(12) lgkmcnt(0)
	v_pk_fma_f32 v[88:89], v[166:167], v[88:89], v[116:117]
	v_pk_fma_f32 v[86:87], v[168:169], v[86:87], v[114:115]
	v_lshl_add_u64 v[114:115], s[56:57], 0, v[186:187]
	global_store_dwordx4 v[118:119], v[82:85], off nt
	v_pk_mul_f32 v[118:119], v[170:171], v[84:85]
	v_cvt_pk_bf16_f32 v120, v120, v121
	v_pk_mul_f32 v[116:117], v[172:173], v[86:87]
	v_cvt_pk_bf16_f32 v121, v118, v119
	global_store_dwordx4 v[114:115], v[86:89], off nt
	ds_bpermute_b32 v114, v203, v120
	ds_bpermute_b32 v115, v203, v121
	v_pk_mul_f32 v[118:119], v[170:171], v[88:89]
	v_cvt_pk_bf16_f32 v116, v116, v117
	s_nop 0
	v_cvt_pk_bf16_f32 v117, v118, v119
	v_lshlrev_b32_e32 v118, 1, v128
	s_waitcnt lgkmcnt(0)
	v_add_u32_e32 v250, 0xfffff040, v118
	v_cndmask_b32_e64 v250, v118, v250, s[40:41]
	v_cndmask_b32_e64 v248, v126, v114, s[40:41]
	v_cndmask_b32_e64 v249, v127, v115, s[40:41]
	global_store_dwordx2 v250, v[248:249], s[54:55]
	v_cndmask_b32_e64 v246, v114, v126, s[40:41]
	v_cndmask_b32_e64 v247, v115, v127, s[40:41]
	s_waitcnt lgkmcnt(1)
	v_add_u32_e32 v114, 0x1040, v118
	v_cndmask_b32_e64 v114, v118, v114, s[38:39]
	global_store_dwordx2 v114, v[246:247], s[54:55]
	ds_bpermute_b32 v114, v203, v116
	s_waitcnt lgkmcnt(1)
	ds_bpermute_b32 v115, v203, v117
	v_add_u32_e32 v117, 0x14000, v202
	v_lshlrev_b32_e32 v116, 1, v117
	s_waitcnt lgkmcnt(0)
	v_add_u32_e32 v250, 0xfffff040, v116
	v_cndmask_b32_e64 v250, v116, v250, s[40:41]
	v_cndmask_b32_e64 v248, v122, v114, s[40:41]
	v_cndmask_b32_e64 v249, v123, v115, s[40:41]
	global_store_dwordx2 v250, v[248:249], s[54:55]
	v_cndmask_b32_e64 v246, v114, v122, s[40:41]
	v_cndmask_b32_e64 v247, v115, v123, s[40:41]
	v_mul_f32_e32 v83, v83, v83
	v_fmac_f32_e32 v83, v82, v82
	v_mul_f32_e32 v82, v85, v85
	v_mul_f32_e32 v93, v93, v93
	v_fmac_f32_e32 v82, v84, v84
	v_mul_f32_e32 v91, v91, v91
	v_fmac_f32_e32 v93, v92, v92
	v_mul_f32_e32 v92, v95, v95
	v_mul_f32_e32 v95, v97, v97
	v_add_f32_e32 v82, v83, v82
	v_mul_f32_e32 v83, v87, v87
	v_mul_f32_e32 v84, v89, v89
	v_fmac_f32_e32 v95, v96, v96
	v_fmac_f32_e32 v83, v86, v86
	v_fmac_f32_e32 v84, v88, v88
	v_fmac_f32_e32 v91, v90, v90
	v_fmac_f32_e32 v92, v94, v94
	v_add_f32_e32 v83, v83, v84
	v_add_f32_e32 v84, v91, v93
	v_add_f32_e32 v85, v92, v95
	v_add_f32_e32 v82, v84, v82
	v_add_f32_e32 v83, v85, v83
	ds_bpermute_b32 v84, v204, v82
	ds_bpermute_b32 v85, v204, v83
	s_waitcnt lgkmcnt(1)
	v_add_f32_e32 v82, v82, v84
	s_waitcnt lgkmcnt(0)
	v_add_f32_e32 v85, v83, v85
	ds_bpermute_b32 v84, v205, v82
	ds_bpermute_b32 v86, v205, v85
	s_waitcnt lgkmcnt(1)
	v_add_f32_e32 v82, v82, v84
	s_waitcnt lgkmcnt(0)
	v_add_f32_e32 v84, v85, v86
	ds_bpermute_b32 v83, v206, v82
	ds_bpermute_b32 v85, v206, v84
	v_add_u32_e32 v86, 0x1040, v116
	v_cndmask_b32_e64 v86, v116, v86, s[38:39]
	global_store_dwordx2 v86, v[246:247], s[54:55]
	s_and_saveexec_b64 s[16:17], s[42:43]
	s_cbranch_execz .LBB0_350
	s_waitcnt lgkmcnt(1)
	v_add_f32_e32 v82, v82, v83
	s_waitcnt lgkmcnt(0)
	v_add_f32_e32 v83, v84, v85
	ds_write2_b32 v194, v82, v83 offset0:32 offset1:40
; #define LAS __attribute__((address_space(3)))
; #define ERN_EOFF(q, m) (eb + (unsigned)((((q) & 1) * HALF + (m) * 16) * DM + ERN_COL((q) >> 1)))
;     __device__ __forceinline__ void operator()(const f32x4 (&acc)[2][2][4][2], const Unit& u, int wr, int wc, int fr, int fq) const {
;     ...
;         for (int g = 0; g < 8; ++g) { const int ai = g >> 2, m = g & 3;
;             if (g + 1 < 8) ERN_LOADX(g + 1);
;             float sq0 = 0.f, sq1 = 0.f; u32x2 hw[2][2];
; #pragma unroll
;             for (int bj = 0; bj < 2; ++bj) {
;                 *(LAS f32x4*)(st + wr_off) = acc[ai][bj][m][0]; *(LAS f32x4*)(st + wr_off + 64) = acc[ai][bj][m][1];
;                 const f32x4 a0 = *(const LAS f32x4*)(st + rd_off), a1 = *(const LAS f32x4*)(st + rd_off + 8 * 144);
;                 { const f32x4 xv = xb[g & 1][bj][0] + gv[bj] * a0; __builtin_nontemporal_store(xv, (f32x4*)((char*)xo + 4u * ERN_EOFF(g, bj, 0)));
;                   sq0 += (xv.x * xv.x + xv.y * xv.y) + (xv.z * xv.z + xv.w * xv.w);
;                   const f32x4 hv = xv * gsn[bj]; hw[bj][0].x = cvt_pk_bf16(hv.x, hv.y); hw[bj][0].y = cvt_pk_bf16(hv.z, hv.w); }
;                 { const f32x4 xv = xb[g & 1][bj][1] + gv[bj] * a1; __builtin_nontemporal_store(xv, (f32x4*)((char*)xo + 4u * ERN_EOFF(g, bj, 1)));
;                   sq1 += (xv.x * xv.x + xv.y * xv.y) + (xv.z * xv.z + xv.w * xv.w);
;                   const f32x4 hv = xv * gsn[bj]; hw[bj][1].x = cvt_pk_bf16(hv.x, hv.y); hw[bj][1].y = cvt_pk_bf16(hv.z, hv.w); }
;             }
;             if (!NOH && !PLAIN) {
; #pragma unroll
;                 for (int rh = 0; rh < 2; ++rh) { u32x2 rv; rv.x = __shfl_xor(hw[1][rh].x, 8); rv.y = __shfl_xor(hw[1][rh].y, 8);
;                     const unsigned e0 = ERN_EOFF(g, 0, rh);
;                     const unsigned ee = odd ? (e0 - DM + 32) : e0, eo2 = odd ? e0 : (e0 + DM + 32);
;                     *(u32x2*)((char*)ho + 2u * ee) = odd ? rv : hw[0][rh];
;                     *(u32x2*)((char*)ho + 2u * eo2) = odd ? hw[0][rh] : rv; }
;             }
;             if (!PLAIN) { sq0 += __shfl_xor(sq0, 1); sq0 += __shfl_xor(sq0, 2); sq0 += __shfl_xor(sq0, 4);
;             sq1 += __shfl_xor(sq1, 1); sq1 += __shfl_xor(sq1, 2); sq1 += __shfl_xor(sq1, 4); }
;             if (!PLAIN && pc == 0) { sst[g * 16 + rr] = sq0; sst[g * 16 + 8 + rr] = sq1; }
.LBB0_350:
	s_or_b64 exec, exec, s[16:17]
	v_add_u32_e32 v82, 0x100000, v207
	s_waitcnt lgkmcnt(1)
	v_add_u32_e32 v83, 0x110000, v207
	v_add_u32_e32 v116, 0x100080, v207
	global_load_dwordx4 v[94:97], v82, s[58:59] nt
	global_load_dwordx4 v[90:93], v83, s[58:59] nt
	v_add_u32_e32 v114, 0x110080, v207
	global_load_dwordx4 v[86:89], v116, s[58:59] nt
	s_waitcnt lgkmcnt(0)
	global_load_dwordx4 v[82:85], v114, s[58:59] nt
	ds_write_b128 v200, v[78:81]
	ds_write_b128 v200, v[74:77] offset:64
	ds_read_b128 v[74:77], v201
	ds_read_b128 v[78:81], v201 offset:1152
	v_mov_b32_e32 v133, v155
	v_mov_b32_e32 v131, v155
	s_waitcnt vmcnt(11) lgkmcnt(1)
	v_pk_fma_f32 v[76:77], v[178:179], v[76:77], v[112:113]
	v_add_u32_e32 v112, 0x18000, v202
	v_pk_fma_f32 v[74:75], v[180:181], v[74:75], v[110:111]
	v_lshlrev_b32_e32 v110, 2, v112
	global_store_dwordx4 v110, v[74:77], s[56:57] nt
	v_pk_mul_f32 v[110:111], v[176:177], v[74:75]
	s_waitcnt lgkmcnt(0)
	v_pk_fma_f32 v[80:81], v[178:179], v[80:81], v[108:109]
	v_pk_fma_f32 v[78:79], v[180:181], v[78:79], v[106:107]
	v_lshl_add_u64 v[106:107], s[56:57], 0, v[154:155]
	v_pk_mul_f32 v[118:119], v[174:175], v[76:77]
	v_cvt_pk_bf16_f32 v110, v110, v111
	v_pk_mul_f32 v[108:109], v[174:175], v[80:81]
	v_cvt_pk_bf16_f32 v111, v118, v119
	global_store_dwordx4 v[106:107], v[78:81], off nt
	v_pk_mul_f32 v[106:107], v[176:177], v[78:79]
	s_nop 0
	v_cvt_pk_bf16_f32 v106, v106, v107
	v_cvt_pk_bf16_f32 v107, v108, v109
	ds_write_b128 v200, v[70:73]
	ds_write_b128 v200, v[66:69] offset:64
	ds_read_b128 v[66:69], v201
	ds_read_b128 v[70:73], v201 offset:1152
	s_waitcnt lgkmcnt(1)
	v_pk_fma_f32 v[66:67], v[168:169], v[66:67], v[102:103]
	v_pk_fma_f32 v[68:69], v[166:167], v[68:69], v[104:105]
	v_lshl_add_u64 v[102:103], s[56:57], 0, v[132:133]
	v_pk_mul_f32 v[104:105], v[172:173], v[66:67]
	s_waitcnt vmcnt(12) lgkmcnt(0)
	v_pk_fma_f32 v[72:73], v[166:167], v[72:73], v[100:101]
	v_pk_fma_f32 v[70:71], v[168:169], v[70:71], v[98:99]
	v_lshl_add_u64 v[98:99], s[56:57], 0, v[130:131]
	global_store_dwordx4 v[102:103], v[66:69], off nt
	v_pk_mul_f32 v[102:103], v[170:171], v[68:69]
	v_cvt_pk_bf16_f32 v104, v104, v105
	v_pk_mul_f32 v[100:101], v[172:173], v[70:71]
	v_cvt_pk_bf16_f32 v105, v102, v103
	global_store_dwordx4 v[98:99], v[70:73], off nt
	ds_bpermute_b32 v98, v203, v104
	ds_bpermute_b32 v99, v203, v105
	v_pk_mul_f32 v[102:103], v[170:171], v[72:73]
	v_cvt_pk_bf16_f32 v100, v100, v101
	s_nop 0
	v_cvt_pk_bf16_f32 v101, v102, v103
	v_lshlrev_b32_e32 v102, 1, v112
	s_waitcnt lgkmcnt(0)
	v_add_u32_e32 v250, 0xfffff040, v102
	v_cndmask_b32_e64 v250, v102, v250, s[40:41]
	v_cndmask_b32_e64 v248, v110, v98, s[40:41]
	v_cndmask_b32_e64 v249, v111, v99, s[40:41]
	global_store_dwordx2 v250, v[248:249], s[54:55]
	v_cndmask_b32_e64 v246, v98, v110, s[40:41]
	v_cndmask_b32_e64 v247, v99, v111, s[40:41]
	s_waitcnt lgkmcnt(1)
	v_add_u32_e32 v98, 0x1040, v102
	v_cndmask_b32_e64 v98, v102, v98, s[38:39]
	global_store_dwordx2 v98, v[246:247], s[54:55]
	ds_bpermute_b32 v98, v203, v100
	s_waitcnt lgkmcnt(1)
	ds_bpermute_b32 v99, v203, v101
	v_add_u32_e32 v101, 0x1c000, v202
	v_lshlrev_b32_e32 v100, 1, v101
	s_waitcnt lgkmcnt(0)
	v_add_u32_e32 v250, 0xfffff040, v100
	v_cndmask_b32_e64 v250, v100, v250, s[40:41]
	v_cndmask_b32_e64 v248, v106, v98, s[40:41]
	v_cndmask_b32_e64 v249, v107, v99, s[40:41]
	global_store_dwordx2 v250, v[248:249], s[54:55]
	v_cndmask_b32_e64 v246, v98, v106, s[40:41]
	v_cndmask_b32_e64 v247, v99, v107, s[40:41]
	v_mul_f32_e32 v67, v67, v67
	v_fmac_f32_e32 v67, v66, v66
	v_mul_f32_e32 v66, v69, v69
	v_mul_f32_e32 v77, v77, v77
	v_fmac_f32_e32 v66, v68, v68
	v_mul_f32_e32 v75, v75, v75
	v_fmac_f32_e32 v77, v76, v76
	v_mul_f32_e32 v76, v79, v79
	v_mul_f32_e32 v79, v81, v81
	v_add_f32_e32 v66, v67, v66
	v_mul_f32_e32 v67, v71, v71
	v_mul_f32_e32 v68, v73, v73
	v_fmac_f32_e32 v79, v80, v80
	v_fmac_f32_e32 v67, v70, v70
	v_fmac_f32_e32 v68, v72, v72
	v_fmac_f32_e32 v75, v74, v74
	v_fmac_f32_e32 v76, v78, v78
	v_add_f32_e32 v67, v67, v68
	v_add_f32_e32 v68, v75, v77
	v_add_f32_e32 v69, v76, v79
	v_add_f32_e32 v66, v68, v66
	v_add_f32_e32 v67, v69, v67
	ds_bpermute_b32 v68, v204, v66
	ds_bpermute_b32 v69, v204, v67
	s_waitcnt lgkmcnt(1)
	v_add_f32_e32 v66, v66, v68
	s_waitcnt lgkmcnt(0)
	v_add_f32_e32 v69, v67, v69
	ds_bpermute_b32 v68, v205, v66
	ds_bpermute_b32 v70, v205, v69
	s_waitcnt lgkmcnt(1)
	v_add_f32_e32 v66, v66, v68
	s_waitcnt lgkmcnt(0)
	v_add_f32_e32 v68, v69, v70
	ds_bpermute_b32 v67, v206, v66
	ds_bpermute_b32 v69, v206, v68
	v_add_u32_e32 v70, 0x1040, v100
	v_cndmask_b32_e64 v70, v100, v70, s[38:39]
	global_store_dwordx2 v70, v[246:247], s[54:55]
	s_and_saveexec_b64 s[16:17], s[42:43]
	s_cbranch_execz .LBB0_360
	s_waitcnt lgkmcnt(1)
	v_add_f32_e32 v66, v66, v67
	s_waitcnt lgkmcnt(0)
	v_add_f32_e32 v67, v68, v69
	ds_write2_b32 v194, v66, v67 offset0:48 offset1:56
; #define LAS __attribute__((address_space(3)))
; #define ERN_EOFF(q, m) (eb + (unsigned)((((q) & 1) * HALF + (m) * 16) * DM + ERN_COL((q) >> 1)))
;     __device__ __forceinline__ void operator()(const f32x4 (&acc)[2][2][4][2], const Unit& u, int wr, int wc, int fr, int fq) const {
;     ...
;         for (int g = 0; g < 8; ++g) { const int ai = g >> 2, m = g & 3;
;             if (g + 1 < 8) ERN_LOADX(g + 1);
;             float sq0 = 0.f, sq1 = 0.f; u32x2 hw[2][2];
; #pragma unroll
;             for (int bj = 0; bj < 2; ++bj) {
;                 *(LAS f32x4*)(st + wr_off) = acc[ai][bj][m][0]; *(LAS f32x4*)(st + wr_off + 64) = acc[ai][bj][m][1];
;                 const f32x4 a0 = *(const LAS f32x4*)(st + rd_off), a1 = *(const LAS f32x4*)(st + rd_off + 8 * 144);
;                 { const f32x4 xv = xb[g & 1][bj][0] + gv[bj] * a0; __builtin_nontemporal_store(xv, (f32x4*)((char*)xo + 4u * ERN_EOFF(g, bj, 0)));
;                   sq0 += (xv.x * xv.x + xv.y * xv.y) + (xv.z * xv.z + xv.w * xv.w);
;                   const f32x4 hv = xv * gsn[bj]; hw[bj][0].x = cvt_pk_bf16(hv.x, hv.y); hw[bj][0].y = cvt_pk_bf16(hv.z, hv.w); }
;                 { const f32x4 xv = xb[g & 1][bj][1] + gv[bj] * a1; __builtin_nontemporal_store(xv, (f32x4*)((char*)xo + 4u * ERN_EOFF(g, bj, 1)));
;                   sq1 += (xv.x * xv.x + xv.y * xv.y) + (xv.z * xv.z + xv.w * xv.w);
;                   const f32x4 hv = xv * gsn[bj]; hw[bj][1].x = cvt_pk_bf16(hv.x, hv.y); hw[bj][1].y = cvt_pk_bf16(hv.z, hv.w); }
;             }
;             if (!NOH && !PLAIN) {
; #pragma unroll
;                 for (int rh = 0; rh < 2; ++rh) { u32x2 rv; rv.x = __shfl_xor(hw[1][rh].x, 8); rv.y = __shfl_xor(hw[1][rh].y, 8);
;                     const unsigned e0 = ERN_EOFF(g, 0, rh);
;                     const unsigned ee = odd ? (e0 - DM + 32) : e0, eo2 = odd ? e0 : (e0 + DM + 32);
;                     *(u32x2*)((char*)ho + 2u * ee) = odd ? rv : hw[0][rh];
;                     *(u32x2*)((char*)ho + 2u * eo2) = odd ? hw[0][rh] : rv; }
;             }
;             if (!PLAIN) { sq0 += __shfl_xor(sq0, 1); sq0 += __shfl_xor(sq0, 2); sq0 += __shfl_xor(sq0, 4);
;             sq1 += __shfl_xor(sq1, 1); sq1 += __shfl_xor(sq1, 2); sq1 += __shfl_xor(sq1, 4); }
;             if (!PLAIN && pc == 0) { sst[g * 16 + rr] = sq0; sst[g * 16 + 8 + rr] = sq1; }
.LBB0_360:
	s_or_b64 exec, exec, s[16:17]
	v_add_u32_e32 v154, 0x120000, v207
	v_add_u32_e32 v100, 0x120080, v207
	v_add_u32_e32 v102, 0x130000, v207
	global_load_dwordx4 v[78:81], v154, s[58:59] nt
	global_load_dwordx4 v[74:77], v102, s[58:59] nt
	v_add_u32_e32 v98, 0x130080, v207
	global_load_dwordx4 v[70:73], v100, s[58:59] nt
	s_waitcnt lgkmcnt(0)
	global_load_dwordx4 v[66:69], v98, s[58:59] nt
	ds_write_b128 v200, v[62:65]
	ds_write_b128 v200, v[58:61] offset:64
	ds_read_b128 v[58:61], v201
	ds_read_b128 v[62:65], v201 offset:1152
	v_mov_b32_e32 v117, v155
	v_mov_b32_e32 v115, v155
	s_waitcnt vmcnt(13) lgkmcnt(1)
	v_pk_fma_f32 v[60:61], v[178:179], v[60:61], v[96:97]
	v_add_u32_e32 v96, 0x40000, v202
	v_pk_fma_f32 v[58:59], v[180:181], v[58:59], v[94:95]
	v_lshlrev_b32_e32 v94, 2, v96
	s_waitcnt vmcnt(12) lgkmcnt(0)
	v_pk_fma_f32 v[64:65], v[178:179], v[64:65], v[92:93]
	v_add_u32_e32 v92, 0x44000, v202
	global_store_dwordx4 v94, v[58:61], s[56:57] nt
	v_pk_mul_f32 v[94:95], v[176:177], v[58:59]
	v_pk_fma_f32 v[62:63], v[180:181], v[62:63], v[90:91]
	v_lshlrev_b32_e32 v90, 2, v92
	v_pk_mul_f32 v[104:105], v[174:175], v[60:61]
	v_cvt_pk_bf16_f32 v94, v94, v95
	s_nop 0
	v_cvt_pk_bf16_f32 v95, v104, v105
	global_store_dwordx4 v90, v[62:65], s[56:57] nt
	v_pk_mul_f32 v[90:91], v[176:177], v[62:63]
	v_pk_mul_f32 v[104:105], v[174:175], v[64:65]
	v_cvt_pk_bf16_f32 v90, v90, v91
	s_nop 0
	v_cvt_pk_bf16_f32 v91, v104, v105
	ds_write_b128 v200, v[54:57]
	ds_write_b128 v200, v[50:53] offset:64
	ds_read_b128 v[50:53], v201
	ds_read_b128 v[54:57], v201 offset:1152
	s_waitcnt vmcnt(13) lgkmcnt(1)
	v_pk_fma_f32 v[50:51], v[168:169], v[50:51], v[86:87]
	v_pk_fma_f32 v[52:53], v[166:167], v[52:53], v[88:89]
	v_lshl_add_u64 v[86:87], s[56:57], 0, v[116:117]
	v_pk_mul_f32 v[88:89], v[172:173], v[50:51]
	s_waitcnt vmcnt(12) lgkmcnt(0)
	v_pk_fma_f32 v[56:57], v[166:167], v[56:57], v[84:85]
	v_pk_fma_f32 v[54:55], v[168:169], v[54:55], v[82:83]
	v_lshl_add_u64 v[82:83], s[56:57], 0, v[114:115]
	global_store_dwordx4 v[86:87], v[50:53], off nt
	v_pk_mul_f32 v[86:87], v[170:171], v[52:53]
	v_cvt_pk_bf16_f32 v88, v88, v89
	v_pk_mul_f32 v[84:85], v[172:173], v[54:55]
	v_cvt_pk_bf16_f32 v89, v86, v87
	global_store_dwordx4 v[82:83], v[54:57], off nt
	ds_bpermute_b32 v82, v203, v88
	ds_bpermute_b32 v83, v203, v89
	v_pk_mul_f32 v[86:87], v[170:171], v[56:57]
	v_cvt_pk_bf16_f32 v84, v84, v85
	s_nop 0
	v_cvt_pk_bf16_f32 v85, v86, v87
	v_lshlrev_b32_e32 v86, 1, v96
	s_waitcnt lgkmcnt(0)
	v_add_u32_e32 v250, 0xfffff040, v86
	v_cndmask_b32_e64 v250, v86, v250, s[40:41]
	v_cndmask_b32_e64 v248, v94, v82, s[40:41]
	v_cndmask_b32_e64 v249, v95, v83, s[40:41]
	global_store_dwordx2 v250, v[248:249], s[54:55]
	v_cndmask_b32_e64 v246, v82, v94, s[40:41]
	v_cndmask_b32_e64 v247, v83, v95, s[40:41]
	s_waitcnt lgkmcnt(1)
	v_add_u32_e32 v82, 0x1040, v86
	v_cndmask_b32_e64 v82, v86, v82, s[38:39]
	global_store_dwordx2 v82, v[246:247], s[54:55]
	ds_bpermute_b32 v82, v203, v84
	s_waitcnt lgkmcnt(1)
	ds_bpermute_b32 v83, v203, v85
	v_lshlrev_b32_e32 v84, 1, v92
	s_waitcnt lgkmcnt(0)
	v_add_u32_e32 v250, 0xfffff040, v84
	v_cndmask_b32_e64 v250, v84, v250, s[40:41]
	v_cndmask_b32_e64 v248, v90, v82, s[40:41]
	v_cndmask_b32_e64 v249, v91, v83, s[40:41]
	global_store_dwordx2 v250, v[248:249], s[54:55]
	v_cndmask_b32_e64 v246, v82, v90, s[40:41]
	v_cndmask_b32_e64 v247, v83, v91, s[40:41]
	v_mul_f32_e32 v51, v51, v51
	v_fmac_f32_e32 v51, v50, v50
	v_mul_f32_e32 v50, v53, v53
	v_mul_f32_e32 v61, v61, v61
	v_fmac_f32_e32 v50, v52, v52
	v_mul_f32_e32 v59, v59, v59
	v_fmac_f32_e32 v61, v60, v60
	v_mul_f32_e32 v60, v63, v63
	v_mul_f32_e32 v63, v65, v65
	v_add_f32_e32 v50, v51, v50
	v_mul_f32_e32 v51, v55, v55
	v_mul_f32_e32 v52, v57, v57
	v_fmac_f32_e32 v63, v64, v64
	v_fmac_f32_e32 v51, v54, v54
	v_fmac_f32_e32 v52, v56, v56
	v_fmac_f32_e32 v59, v58, v58
	v_fmac_f32_e32 v60, v62, v62
	v_add_f32_e32 v51, v51, v52
	v_add_f32_e32 v52, v59, v61
	v_add_f32_e32 v53, v60, v63
	v_add_f32_e32 v50, v52, v50
	v_add_f32_e32 v51, v53, v51
	ds_bpermute_b32 v52, v204, v50
	ds_bpermute_b32 v53, v204, v51
	s_waitcnt lgkmcnt(1)
	v_add_f32_e32 v50, v50, v52
	s_waitcnt lgkmcnt(0)
	v_add_f32_e32 v53, v51, v53
	ds_bpermute_b32 v52, v205, v50
	ds_bpermute_b32 v54, v205, v53
	s_waitcnt lgkmcnt(1)
	v_add_f32_e32 v50, v50, v52
	s_waitcnt lgkmcnt(0)
	v_add_f32_e32 v52, v53, v54
	ds_bpermute_b32 v51, v206, v50
	ds_bpermute_b32 v53, v206, v52
	v_add_u32_e32 v54, 0x1040, v84
	v_cndmask_b32_e64 v54, v84, v54, s[38:39]
	global_store_dwordx2 v54, v[246:247], s[54:55]
	s_and_saveexec_b64 s[16:17], s[42:43]
	s_cbranch_execz .LBB0_370
	s_waitcnt lgkmcnt(1)
	v_add_f32_e32 v50, v50, v51
	s_waitcnt lgkmcnt(0)
	v_add_f32_e32 v51, v52, v53
	ds_write2_b32 v194, v50, v51 offset0:64 offset1:72
; #define LAS __attribute__((address_space(3)))
; #define ERN_EOFF(q, m) (eb + (unsigned)((((q) & 1) * HALF + (m) * 16) * DM + ERN_COL((q) >> 1)))
;     __device__ __forceinline__ void operator()(const f32x4 (&acc)[2][2][4][2], const Unit& u, int wr, int wc, int fr, int fq) const {
;     ...
;         for (int g = 0; g < 8; ++g) { const int ai = g >> 2, m = g & 3;
;             if (g + 1 < 8) ERN_LOADX(g + 1);
;             float sq0 = 0.f, sq1 = 0.f; u32x2 hw[2][2];
; #pragma unroll
;             for (int bj = 0; bj < 2; ++bj) {
;                 *(LAS f32x4*)(st + wr_off) = acc[ai][bj][m][0]; *(LAS f32x4*)(st + wr_off + 64) = acc[ai][bj][m][1];
;                 const f32x4 a0 = *(const LAS f32x4*)(st + rd_off), a1 = *(const LAS f32x4*)(st + rd_off + 8 * 144);
;                 { const f32x4 xv = xb[g & 1][bj][0] + gv[bj] * a0; __builtin_nontemporal_store(xv, (f32x4*)((char*)xo + 4u * ERN_EOFF(g, bj, 0)));
;                   sq0 += (xv.x * xv.x + xv.y * xv.y) + (xv.z * xv.z + xv.w * xv.w);
;                   const f32x4 hv = xv * gsn[bj]; hw[bj][0].x = cvt_pk_bf16(hv.x, hv.y); hw[bj][0].y = cvt_pk_bf16(hv.z, hv.w); }
;                 { const f32x4 xv = xb[g & 1][bj][1] + gv[bj] * a1; __builtin_nontemporal_store(xv, (f32x4*)((char*)xo + 4u * ERN_EOFF(g, bj, 1)));
;                   sq1 += (xv.x * xv.x + xv.y * xv.y) + (xv.z * xv.z + xv.w * xv.w);
;                   const f32x4 hv = xv * gsn[bj]; hw[bj][1].x = cvt_pk_bf16(hv.x, hv.y); hw[bj][1].y = cvt_pk_bf16(hv.z, hv.w); }
;             }
;             if (!NOH && !PLAIN) {
; #pragma unroll
;                 for (int rh = 0; rh < 2; ++rh) { u32x2 rv; rv.x = __shfl_xor(hw[1][rh].x, 8); rv.y = __shfl_xor(hw[1][rh].y, 8);
;                     const unsigned e0 = ERN_EOFF(g, 0, rh);
;                     const unsigned ee = odd ? (e0 - DM + 32) : e0, eo2 = odd ? e0 : (e0 + DM + 32);
;                     *(u32x2*)((char*)ho + 2u * ee) = odd ? rv : hw[0][rh];
;                     *(u32x2*)((char*)ho + 2u * eo2) = odd ? hw[0][rh] : rv; }
;             }
;             if (!PLAIN) { sq0 += __shfl_xor(sq0, 1); sq0 += __shfl_xor(sq0, 2); sq0 += __shfl_xor(sq0, 4);
;             sq1 += __shfl_xor(sq1, 1); sq1 += __shfl_xor(sq1, 2); sq1 += __shfl_xor(sq1, 4); }
;             if (!PLAIN && pc == 0) { sst[g * 16 + rr] = sq0; sst[g * 16 + 8 + rr] = sq1; }
.LBB0_370:
	s_or_b64 exec, exec, s[16:17]
	v_add_u32_e32 v88, 0x140000, v207
	v_add_u32_e32 v84, 0x140080, v207
	v_add_u32_e32 v86, 0x150000, v207
	global_load_dwordx4 v[62:65], v88, s[58:59] nt
	global_load_dwordx4 v[58:61], v86, s[58:59] nt
	v_add_u32_e32 v82, 0x150080, v207
	global_load_dwordx4 v[54:57], v84, s[58:59] nt
	s_waitcnt lgkmcnt(0)
	global_load_dwordx4 v[50:53], v82, s[58:59] nt
	ds_write_b128 v200, v[46:49]
	ds_write_b128 v200, v[42:45] offset:64
	ds_read_b128 v[42:45], v201
	ds_read_b128 v[46:49], v201 offset:1152
	v_mov_b32_e32 v103, v155
	v_mov_b32_e32 v101, v155
	v_mov_b32_e32 v99, v155
	s_waitcnt vmcnt(13) lgkmcnt(1)
	v_pk_fma_f32 v[44:45], v[178:179], v[44:45], v[80:81]
	v_pk_fma_f32 v[42:43], v[180:181], v[42:43], v[78:79]
	v_lshl_add_u64 v[78:79], s[56:57], 0, v[154:155]
	global_store_dwordx4 v[78:79], v[42:45], off nt
	v_pk_mul_f32 v[78:79], v[176:177], v[42:43]
	s_waitcnt vmcnt(13) lgkmcnt(0)
	v_pk_fma_f32 v[48:49], v[178:179], v[48:49], v[76:77]
	v_pk_fma_f32 v[46:47], v[180:181], v[46:47], v[74:75]
	v_lshl_add_u64 v[74:75], s[56:57], 0, v[102:103]
	v_pk_mul_f32 v[80:81], v[174:175], v[44:45]
	v_cvt_pk_bf16_f32 v78, v78, v79
	v_pk_mul_f32 v[76:77], v[174:175], v[48:49]
	v_cvt_pk_bf16_f32 v79, v80, v81
	global_store_dwordx4 v[74:75], v[46:49], off nt
	v_pk_mul_f32 v[74:75], v[176:177], v[46:47]
	s_nop 0
	v_cvt_pk_bf16_f32 v74, v74, v75
	v_cvt_pk_bf16_f32 v75, v76, v77
	ds_write_b128 v200, v[38:41]
	ds_write_b128 v200, v[34:37] offset:64
	ds_read_b128 v[34:37], v201
	ds_read_b128 v[38:41], v201 offset:1152
	s_waitcnt vmcnt(13) lgkmcnt(1)
	v_pk_fma_f32 v[34:35], v[168:169], v[34:35], v[70:71]
	v_pk_fma_f32 v[36:37], v[166:167], v[36:37], v[72:73]
	v_lshl_add_u64 v[70:71], s[56:57], 0, v[100:101]
	v_pk_mul_f32 v[72:73], v[172:173], v[34:35]
	s_waitcnt vmcnt(12) lgkmcnt(0)
	v_pk_fma_f32 v[40:41], v[166:167], v[40:41], v[68:69]
	v_pk_fma_f32 v[38:39], v[168:169], v[38:39], v[66:67]
	v_lshl_add_u64 v[66:67], s[56:57], 0, v[98:99]
	global_store_dwordx4 v[70:71], v[34:37], off nt
	v_pk_mul_f32 v[70:71], v[170:171], v[36:37]
	v_cvt_pk_bf16_f32 v72, v72, v73
	v_pk_mul_f32 v[68:69], v[172:173], v[38:39]
	v_cvt_pk_bf16_f32 v73, v70, v71
	global_store_dwordx4 v[66:67], v[38:41], off nt
	ds_bpermute_b32 v66, v203, v72
	ds_bpermute_b32 v67, v203, v73
	v_pk_mul_f32 v[70:71], v[170:171], v[40:41]
	v_cvt_pk_bf16_f32 v68, v68, v69
	s_nop 0
	v_cvt_pk_bf16_f32 v69, v70, v71
	v_add_u32_e32 v71, 0x48000, v202
	v_lshlrev_b32_e32 v70, 1, v71
	s_waitcnt lgkmcnt(0)
	v_add_u32_e32 v250, 0xfffff040, v70
	v_cndmask_b32_e64 v250, v70, v250, s[40:41]
	v_cndmask_b32_e64 v248, v78, v66, s[40:41]
	v_cndmask_b32_e64 v249, v79, v67, s[40:41]
	global_store_dwordx2 v250, v[248:249], s[54:55]
	v_cndmask_b32_e64 v246, v66, v78, s[40:41]
	v_cndmask_b32_e64 v247, v67, v79, s[40:41]
	s_waitcnt lgkmcnt(1)
	v_add_u32_e32 v66, 0x1040, v70
	v_cndmask_b32_e64 v66, v70, v66, s[38:39]
	global_store_dwordx2 v66, v[246:247], s[54:55]
	ds_bpermute_b32 v66, v203, v68
	s_waitcnt lgkmcnt(1)
	ds_bpermute_b32 v67, v203, v69
	v_add_u32_e32 v69, 0x4c000, v202
	v_lshlrev_b32_e32 v68, 1, v69
	s_waitcnt lgkmcnt(0)
	v_add_u32_e32 v250, 0xfffff040, v68
	v_cndmask_b32_e64 v250, v68, v250, s[40:41]
	v_cndmask_b32_e64 v248, v74, v66, s[40:41]
	v_cndmask_b32_e64 v249, v75, v67, s[40:41]
	global_store_dwordx2 v250, v[248:249], s[54:55]
	v_cndmask_b32_e64 v246, v66, v74, s[40:41]
	v_cndmask_b32_e64 v247, v67, v75, s[40:41]
	v_mul_f32_e32 v35, v35, v35
	v_fmac_f32_e32 v35, v34, v34
	v_mul_f32_e32 v34, v37, v37
	v_mul_f32_e32 v45, v45, v45
	v_fmac_f32_e32 v34, v36, v36
	v_mul_f32_e32 v43, v43, v43
	v_fmac_f32_e32 v45, v44, v44
	v_mul_f32_e32 v44, v47, v47
	v_mul_f32_e32 v47, v49, v49
	v_add_f32_e32 v34, v35, v34
	v_mul_f32_e32 v35, v39, v39
	v_mul_f32_e32 v36, v41, v41
	v_fmac_f32_e32 v47, v48, v48
	v_fmac_f32_e32 v35, v38, v38
	v_fmac_f32_e32 v36, v40, v40
	v_fmac_f32_e32 v43, v42, v42
	v_fmac_f32_e32 v44, v46, v46
	v_add_f32_e32 v35, v35, v36
	v_add_f32_e32 v36, v43, v45
	v_add_f32_e32 v37, v44, v47
	v_add_f32_e32 v34, v36, v34
	v_add_f32_e32 v35, v37, v35
	ds_bpermute_b32 v36, v204, v34
	ds_bpermute_b32 v37, v204, v35
	s_waitcnt lgkmcnt(1)
	v_add_f32_e32 v34, v34, v36
	s_waitcnt lgkmcnt(0)
	v_add_f32_e32 v37, v35, v37
	ds_bpermute_b32 v36, v205, v34
	ds_bpermute_b32 v38, v205, v37
	s_waitcnt lgkmcnt(1)
	v_add_f32_e32 v34, v34, v36
	s_waitcnt lgkmcnt(0)
	v_add_f32_e32 v36, v37, v38
	ds_bpermute_b32 v35, v206, v34
	ds_bpermute_b32 v37, v206, v36
	v_add_u32_e32 v38, 0x1040, v68
	v_cndmask_b32_e64 v38, v68, v38, s[38:39]
	global_store_dwordx2 v38, v[246:247], s[54:55]
	s_and_saveexec_b64 s[16:17], s[42:43]
	s_cbranch_execz .LBB0_380
	s_waitcnt lgkmcnt(1)
	v_add_f32_e32 v34, v34, v35
	s_waitcnt lgkmcnt(0)
	v_add_f32_e32 v35, v36, v37
	ds_write2_b32 v194, v34, v35 offset0:80 offset1:88
; #define LAS __attribute__((address_space(3)))
; #define ERN_EOFF(q, m) (eb + (unsigned)((((q) & 1) * HALF + (m) * 16) * DM + ERN_COL((q) >> 1)))
;     __device__ __forceinline__ void operator()(const f32x4 (&acc)[2][2][4][2], const Unit& u, int wr, int wc, int fr, int fq) const {
;     ...
;         for (int g = 0; g < 8; ++g) { const int ai = g >> 2, m = g & 3;
;             if (g + 1 < 8) ERN_LOADX(g + 1);
;             float sq0 = 0.f, sq1 = 0.f; u32x2 hw[2][2];
; #pragma unroll
;             for (int bj = 0; bj < 2; ++bj) {
;                 *(LAS f32x4*)(st + wr_off) = acc[ai][bj][m][0]; *(LAS f32x4*)(st + wr_off + 64) = acc[ai][bj][m][1];
;                 const f32x4 a0 = *(const LAS f32x4*)(st + rd_off), a1 = *(const LAS f32x4*)(st + rd_off + 8 * 144);
;                 { const f32x4 xv = xb[g & 1][bj][0] + gv[bj] * a0; __builtin_nontemporal_store(xv, (f32x4*)((char*)xo + 4u * ERN_EOFF(g, bj, 0)));
;                   sq0 += (xv.x * xv.x + xv.y * xv.y) + (xv.z * xv.z + xv.w * xv.w);
;                   const f32x4 hv = xv * gsn[bj]; hw[bj][0].x = cvt_pk_bf16(hv.x, hv.y); hw[bj][0].y = cvt_pk_bf16(hv.z, hv.w); }
;                 { const f32x4 xv = xb[g & 1][bj][1] + gv[bj] * a1; __builtin_nontemporal_store(xv, (f32x4*)((char*)xo + 4u * ERN_EOFF(g, bj, 1)));
;                   sq1 += (xv.x * xv.x + xv.y * xv.y) + (xv.z * xv.z + xv.w * xv.w);
;                   const f32x4 hv = xv * gsn[bj]; hw[bj][1].x = cvt_pk_bf16(hv.x, hv.y); hw[bj][1].y = cvt_pk_bf16(hv.z, hv.w); }
;             }
;             if (!NOH && !PLAIN) {
; #pragma unroll
;                 for (int rh = 0; rh < 2; ++rh) { u32x2 rv; rv.x = __shfl_xor(hw[1][rh].x, 8); rv.y = __shfl_xor(hw[1][rh].y, 8);
;                     const unsigned e0 = ERN_EOFF(g, 0, rh);
;                     const unsigned ee = odd ? (e0 - DM + 32) : e0, eo2 = odd ? e0 : (e0 + DM + 32);
;                     *(u32x2*)((char*)ho + 2u * ee) = odd ? rv : hw[0][rh];
;                     *(u32x2*)((char*)ho + 2u * eo2) = odd ? hw[0][rh] : rv; }
;             }
;             if (!PLAIN) { sq0 += __shfl_xor(sq0, 1); sq0 += __shfl_xor(sq0, 2); sq0 += __shfl_xor(sq0, 4);
;             sq1 += __shfl_xor(sq1, 1); sq1 += __shfl_xor(sq1, 2); sq1 += __shfl_xor(sq1, 4); }
;             if (!PLAIN && pc == 0) { sst[g * 16 + rr] = sq0; sst[g * 16 + 8 + rr] = sq1; }
.LBB0_380:
	s_or_b64 exec, exec, s[16:17]
	v_add_u32_e32 v154, 0x160000, v207
	v_add_u32_e32 v68, 0x160080, v207
	v_add_u32_e32 v70, 0x170000, v207
	global_load_dwordx4 v[46:49], v154, s[58:59] nt
	global_load_dwordx4 v[42:45], v70, s[58:59] nt
	v_add_u32_e32 v66, 0x170080, v207
	global_load_dwordx4 v[38:41], v68, s[58:59] nt
	s_waitcnt lgkmcnt(0)
	global_load_dwordx4 v[34:37], v66, s[58:59] nt
	ds_write_b128 v200, v[30:33]
	ds_write_b128 v200, v[26:29] offset:64
	ds_read_b128 v[26:29], v201
	ds_read_b128 v[30:33], v201 offset:1152
	v_mov_b32_e32 v89, v155
	v_mov_b32_e32 v87, v155
	v_mov_b32_e32 v85, v155
	s_waitcnt vmcnt(13) lgkmcnt(1)
	v_pk_fma_f32 v[28:29], v[178:179], v[28:29], v[64:65]
	v_pk_fma_f32 v[26:27], v[180:181], v[26:27], v[62:63]
	v_lshl_add_u64 v[62:63], s[56:57], 0, v[88:89]
	global_store_dwordx4 v[62:63], v[26:29], off nt
	v_pk_mul_f32 v[62:63], v[176:177], v[26:27]
	s_waitcnt vmcnt(13) lgkmcnt(0)
	v_pk_fma_f32 v[32:33], v[178:179], v[32:33], v[60:61]
	v_pk_fma_f32 v[30:31], v[180:181], v[30:31], v[58:59]
	v_lshl_add_u64 v[58:59], s[56:57], 0, v[86:87]
	v_pk_mul_f32 v[64:65], v[174:175], v[28:29]
	v_cvt_pk_bf16_f32 v62, v62, v63
	v_pk_mul_f32 v[60:61], v[174:175], v[32:33]
	v_cvt_pk_bf16_f32 v63, v64, v65
	global_store_dwordx4 v[58:59], v[30:33], off nt
	v_pk_mul_f32 v[58:59], v[176:177], v[30:31]
	v_mov_b32_e32 v83, v155
	v_cvt_pk_bf16_f32 v58, v58, v59
	v_cvt_pk_bf16_f32 v59, v60, v61
	ds_write_b128 v200, v[22:25]
	ds_write_b128 v200, v[18:21] offset:64
	ds_read_b128 v[18:21], v201
	ds_read_b128 v[22:25], v201 offset:1152
	s_waitcnt vmcnt(13) lgkmcnt(1)
	v_pk_fma_f32 v[18:19], v[168:169], v[18:19], v[54:55]
	v_pk_fma_f32 v[20:21], v[166:167], v[20:21], v[56:57]
	v_lshl_add_u64 v[54:55], s[56:57], 0, v[84:85]
	v_pk_mul_f32 v[56:57], v[172:173], v[18:19]
	s_waitcnt vmcnt(12) lgkmcnt(0)
	v_pk_fma_f32 v[24:25], v[166:167], v[24:25], v[52:53]
	v_pk_fma_f32 v[22:23], v[168:169], v[22:23], v[50:51]
	v_lshl_add_u64 v[50:51], s[56:57], 0, v[82:83]
	global_store_dwordx4 v[54:55], v[18:21], off nt
	v_pk_mul_f32 v[54:55], v[170:171], v[20:21]
	v_cvt_pk_bf16_f32 v56, v56, v57
	v_pk_mul_f32 v[52:53], v[172:173], v[22:23]
	v_cvt_pk_bf16_f32 v57, v54, v55
	global_store_dwordx4 v[50:51], v[22:25], off nt
	ds_bpermute_b32 v50, v203, v56
	ds_bpermute_b32 v51, v203, v57
	v_pk_mul_f32 v[54:55], v[170:171], v[24:25]
	v_cvt_pk_bf16_f32 v52, v52, v53
	s_nop 0
	v_cvt_pk_bf16_f32 v53, v54, v55
	v_add_u32_e32 v55, 0x50000, v202
	v_lshlrev_b32_e32 v54, 1, v55
	s_waitcnt lgkmcnt(0)
	v_add_u32_e32 v250, 0xfffff040, v54
	v_cndmask_b32_e64 v250, v54, v250, s[40:41]
	v_cndmask_b32_e64 v248, v62, v50, s[40:41]
	v_cndmask_b32_e64 v249, v63, v51, s[40:41]
	global_store_dwordx2 v250, v[248:249], s[54:55]
	v_cndmask_b32_e64 v246, v50, v62, s[40:41]
	v_cndmask_b32_e64 v247, v51, v63, s[40:41]
	s_waitcnt lgkmcnt(1)
	v_add_u32_e32 v50, 0x1040, v54
	v_cndmask_b32_e64 v50, v54, v50, s[38:39]
	global_store_dwordx2 v50, v[246:247], s[54:55]
	ds_bpermute_b32 v50, v203, v52
	s_waitcnt lgkmcnt(1)
	ds_bpermute_b32 v51, v203, v53
	v_add_u32_e32 v53, 0x54000, v202
	v_lshlrev_b32_e32 v52, 1, v53
	s_waitcnt lgkmcnt(0)
	v_add_u32_e32 v250, 0xfffff040, v52
	v_cndmask_b32_e64 v250, v52, v250, s[40:41]
	v_cndmask_b32_e64 v248, v58, v50, s[40:41]
	v_cndmask_b32_e64 v249, v59, v51, s[40:41]
	global_store_dwordx2 v250, v[248:249], s[54:55]
	v_cndmask_b32_e64 v246, v50, v58, s[40:41]
	v_cndmask_b32_e64 v247, v51, v59, s[40:41]
	v_mul_f32_e32 v19, v19, v19
	v_fmac_f32_e32 v19, v18, v18
	v_mul_f32_e32 v18, v21, v21
	v_mul_f32_e32 v29, v29, v29
	v_fmac_f32_e32 v18, v20, v20
	v_mul_f32_e32 v27, v27, v27
	v_fmac_f32_e32 v29, v28, v28
	v_mul_f32_e32 v28, v31, v31
	v_mul_f32_e32 v31, v33, v33
	v_add_f32_e32 v18, v19, v18
	v_mul_f32_e32 v19, v23, v23
	v_mul_f32_e32 v20, v25, v25
	v_fmac_f32_e32 v31, v32, v32
	v_fmac_f32_e32 v19, v22, v22
	v_fmac_f32_e32 v20, v24, v24
	v_fmac_f32_e32 v27, v26, v26
	v_fmac_f32_e32 v28, v30, v30
	v_add_f32_e32 v19, v19, v20
	v_add_f32_e32 v20, v27, v29
	v_add_f32_e32 v21, v28, v31
	v_add_f32_e32 v18, v20, v18
	v_add_f32_e32 v19, v21, v19
	ds_bpermute_b32 v20, v204, v18
	ds_bpermute_b32 v21, v204, v19
	s_waitcnt lgkmcnt(1)
	v_add_f32_e32 v18, v18, v20
	s_waitcnt lgkmcnt(0)
	v_add_f32_e32 v21, v19, v21
	ds_bpermute_b32 v20, v205, v18
	ds_bpermute_b32 v22, v205, v21
	s_waitcnt lgkmcnt(1)
	v_add_f32_e32 v18, v18, v20
	s_waitcnt lgkmcnt(0)
	v_add_f32_e32 v20, v21, v22
	ds_bpermute_b32 v19, v206, v18
	ds_bpermute_b32 v21, v206, v20
	v_add_u32_e32 v22, 0x1040, v52
	v_cndmask_b32_e64 v22, v52, v22, s[38:39]
	global_store_dwordx2 v22, v[246:247], s[54:55]
	s_and_saveexec_b64 s[16:17], s[42:43]
	s_cbranch_execz .LBB0_390
	s_waitcnt lgkmcnt(1)
	v_add_f32_e32 v18, v18, v19
	s_waitcnt lgkmcnt(0)
	v_add_f32_e32 v19, v20, v21
	ds_write2_b32 v194, v18, v19 offset0:96 offset1:104

; #define LAS __attribute__((address_space(3)))
;     __device__ __forceinline__ void operator()(const f32x4 (&acc)[2][2][4][2], const Unit& u, int wr, int wc, int fr, int fq) const {
;         const int s = u.pm >> 5, lane = fq * 16 + fr, rr = lane >> 3, pc = lane & 7;
;         const float* __restrict__ xi = xin + (size_t)u.pm * BM * DM; float* __restrict__ xo = xout + (size_t)u.pm * BM * DM; bf16_t* __restrict__ ho = Hn + (size_t)u.pm * BM * DM;
;         LAS unsigned char* st = lds_epi + (wr * 4 + wc) * 2304;
;         LAS float* sst = (LAS float*)(lds_epi + 18432 + (wr * 4 + wc) * 512);
;         const int colr = u.pn * BM + wc * 64 + 4 * pc;
;         const unsigned eb = (unsigned)((wr * 64 + rr) * DM + colr);
;         f32x4 gv[2], gsn[2];
; #pragma unroll
;         for (int bj = 0; bj < 2; ++bj) { gv[bj] = *(const f32x4*)(gate + (size_t)s * MODW + colr + bj * 32) * (0.5f * GS2);
;             if (!PLAIN) gsn[bj] = *(const f32x4*)(gnext + colr + bj * 32) * (*(const f32x4*)(scnext + (size_t)s * MODW + colr + bj * 32) + 1.0f); else gsn[bj] = gv[bj]; }
;         const unsigned wr_off = (unsigned)(fr * 144 + 16 * fq), rd_off = (unsigned)(rr * 144 + pc * 16);
;         const bool odd = (rr & 1) != 0;
;         f32x4 xb[2][2][2];
;     ...
;         ERN_LOADX(0);
; #pragma unroll
;         for (int g = 0; g < 8; ++g) { const int ai = g >> 2, m = g & 3;
;             if (g + 1 < 8) ERN_LOADX(g + 1);
;             float sq0 = 0.f, sq1 = 0.f; u32x2 hw[2][2];
; #pragma unroll
;             for (int bj = 0; bj < 2; ++bj) {
;                 *(LAS f32x4*)(st + wr_off) = acc[ai][bj][m][0]; *(LAS f32x4*)(st + wr_off + 64) = acc[ai][bj][m][1];
;                 const f32x4 a0 = *(const LAS f32x4*)(st + rd_off), a1 = *(const LAS f32x4*)(st + rd_off + 8 * 144);
;                 { const f32x4 xv = xb[g & 1][bj][0] + gv[bj] * a0; __builtin_nontemporal_store(xv, (f32x4*)((char*)xo + 4u * ERN_EOFF(g, bj, 0)));
;                   sq0 += (xv.x * xv.x + xv.y * xv.y) + (xv.z * xv.z + xv.w * xv.w);
;                   const f32x4 hv = xv * gsn[bj]; hw[bj][0].x = cvt_pk_bf16(hv.x, hv.y); hw[bj][0].y = cvt_pk_bf16(hv.z, hv.w); }
;                 { const f32x4 xv = xb[g & 1][bj][1] + gv[bj] * a1; __builtin_nontemporal_store(xv, (f32x4*)((char*)xo + 4u * ERN_EOFF(g, bj, 1)));
;                   sq1 += (xv.x * xv.x + xv.y * xv.y) + (xv.z * xv.z + xv.w * xv.w);
.LBB0_1253:
	s_ashr_i32 s0, s92, 5
	s_ashr_i32 s93, s92, 31
	v_lshl_or_b32 v50, s46, 8, v192
	s_mul_hi_i32 s15, s0, 0x12000
	s_mul_i32 s0, s0, 0x12000
	s_add_u32 s16, s35, s0
	v_ashrrev_i32_e32 v51, 31, v50
	s_addc_u32 s17, s36, s15
	v_lshlrev_b64 v[52:53], 2, v[50:51]
	v_lshl_add_u64 v[138:139], s[16:17], 0, v[52:53]
	s_add_u32 s16, s37, s0
	s_addc_u32 s17, s52, s15
	v_lshl_add_u64 v[140:141], s[8:9], 0, v[52:53]
	v_lshl_add_u64 v[52:53], s[16:17], 0, v[52:53]
	s_lshl_b64 s[16:17], s[92:93], 21
	s_add_u32 s48, s90, s16
	v_add_u32_e32 v202, v50, v193
	s_addc_u32 s49, s91, s17
	v_lshlrev_b32_e32 v205, 2, v202
	global_load_dwordx4 v[54:57], v[138:139], off
	global_load_dwordx4 v[174:177], v[140:141], off
	global_load_dwordx4 v[178:181], v[52:53], off
	global_load_dwordx4 v[206:209], v[52:53], off offset:128
	global_load_dwordx4 v[186:189], v205, s[48:49] nt
	v_add_u32_e32 v50, 0x10000, v205
	global_load_dwordx4 v[210:213], v50, s[48:49] nt
	global_load_dwordx4 v[214:217], v[140:141], off offset:128
	s_nop 0
	global_load_dwordx4 v[50:53], v[138:139], off offset:128
	global_load_dwordx4 v[218:221], v205, s[48:49] offset:128 nt
	v_add_u32_e32 v204, 0x10080, v205
	global_load_dwordx4 v[222:225], v204, s[48:49] nt
	v_add_u32_e32 v138, 0x20000, v205
	v_add_u32_e32 v162, 0x30000, v205
	v_add_u32_e32 v184, 0x20080, v205
	v_add_u32_e32 v182, 0x30080, v205
	global_load_dwordx4 v[150:153], v138, s[48:49] nt
	global_load_dwordx4 v[146:149], v162, s[48:49] nt
	global_load_dwordx4 v[142:145], v184, s[48:49] nt
	s_nop 0
	global_load_dwordx4 v[138:141], v182, s[48:49] nt
	ds_write_b128 v200, v[134:137]
	ds_write_b128 v200, v[130:133] offset:64
	v_and_b32_e32 v135, 64, v199
	ds_read_b128 v[130:133], v201
	ds_read_b128 v[226:229], v201 offset:1152
	v_xor_b32_e32 v134, 8, v199
	v_add_u32_e32 v183, 64, v135
	v_cmp_lt_i32_e32 vcc, v134, v183
	v_add_u32_e32 v185, 0x4000, v202
	v_lshlrev_b32_e32 v230, 2, v185
	v_cndmask_b32_e32 v134, v199, v134, vcc
	v_lshlrev_b32_e32 v203, 2, v134
	s_lshl_b64 s[16:17], s[92:93], 20
	v_readlane_b32 s0, v252, 41
	s_add_u32 s46, s0, s16
	v_readlane_b32 s0, v252, 42
	s_addc_u32 s47, s0, s17
	s_waitcnt vmcnt(0)
	v_pk_add_f32 v[134:135], v[180:181], 1.0 op_sel_hi:[1,0]
	v_pk_add_f32 v[136:137], v[178:179], 1.0 op_sel_hi:[1,0]
	v_pk_mul_f32 v[178:179], v[176:177], v[134:135]
	v_pk_mul_f32 v[180:181], v[174:175], v[136:137]
	s_waitcnt lgkmcnt(1)
	v_pk_fma_f32 v[134:135], v[54:55], v[130:131], v[186:187]
	s_waitcnt lgkmcnt(0)
	v_pk_fma_f32 v[130:131], v[54:55], v[226:227], v[210:211]
	v_pk_fma_f32 v[136:137], v[56:57], v[132:133], v[188:189]
	v_pk_fma_f32 v[132:133], v[56:57], v[228:229], v[212:213]
	v_pk_mul_f32 v[186:187], v[180:181], v[130:131]
	v_pk_add_f32 v[190:191], v[208:209], 1.0 op_sel_hi:[1,0]
	global_store_dwordx4 v205, v[134:137], s[48:49] nt
	v_pk_mul_f32 v[174:175], v[178:179], v[136:137]
	v_pk_mul_f32 v[176:177], v[180:181], v[134:135]
	v_pk_mul_f32 v[208:209], v[178:179], v[132:133]
	v_cvt_pk_bf16_f32 v188, v176, v177
	v_cvt_pk_bf16_f32 v189, v174, v175
	global_store_dwordx4 v230, v[130:133], s[48:49] nt
	v_cvt_pk_bf16_f32 v186, v186, v187
	v_cvt_pk_bf16_f32 v187, v208, v209
	ds_write_b128 v200, v[126:129]
	ds_write_b128 v200, v[122:125] offset:64
	ds_read_b128 v[122:125], v201
	v_pk_add_f32 v[126:127], v[206:207], 1.0 op_sel_hi:[1,0]
	ds_read_b128 v[206:209], v201 offset:1152
	v_pk_mul_f32 v[174:175], v[216:217], v[190:191]
	v_pk_mul_f32 v[176:177], v[214:215], v[126:127]
	s_waitcnt lgkmcnt(1)
	v_pk_fma_f32 v[128:129], v[52:53], v[124:125], v[220:221]
	v_pk_fma_f32 v[126:127], v[50:51], v[122:123], v[218:219]
	s_waitcnt lgkmcnt(0)
	v_pk_fma_f32 v[122:123], v[50:51], v[206:207], v[222:223]
	v_pk_mul_f32 v[190:191], v[174:175], v[128:129]
	v_pk_mul_f32 v[206:207], v[176:177], v[126:127]
	global_store_dwordx4 v205, v[126:129], s[48:49] offset:128 nt
	v_cvt_pk_bf16_f32 v206, v206, v207
	v_cvt_pk_bf16_f32 v191, v190, v191
	ds_bpermute_b32 v190, v203, v206
	ds_bpermute_b32 v191, v203, v191
	v_pk_fma_f32 v[124:125], v[52:53], v[208:209], v[224:225]
	v_pk_mul_f32 v[206:207], v[176:177], v[122:123]
	global_store_dwordx4 v204, v[122:125], s[48:49] nt
	v_cvt_pk_bf16_f32 v204, v206, v207
	v_lshlrev_b32_e32 v207, 1, v202
	v_pk_mul_f32 v[208:209], v[174:175], v[124:125]
	s_nop 0
	v_cvt_pk_bf16_f32 v206, v208, v209
	s_waitcnt lgkmcnt(0)
	v_add_u32_e32 v250, 0xfffff040, v207
	v_cndmask_b32_e64 v250, v207, v250, s[40:41]
	v_cndmask_b32_e64 v248, v188, v190, s[40:41]
	v_cndmask_b32_e64 v249, v189, v191, s[40:41]
	global_store_dwordx2 v250, v[248:249], s[46:47]
	v_cndmask_b32_e64 v246, v190, v188, s[40:41]
	v_cndmask_b32_e64 v247, v191, v189, s[40:41]
	s_waitcnt lgkmcnt(1)
	v_add_u32_e32 v190, 0x1040, v207
	v_cndmask_b32_e64 v190, v207, v190, s[38:39]
	global_store_dwordx2 v190, v[246:247], s[46:47]
	ds_bpermute_b32 v188, v203, v204
	ds_bpermute_b32 v189, v203, v206
	v_lshlrev_b32_e32 v206, 1, v185
	s_and_saveexec_b64 s[16:17], s[40:41]
	v_readlane_b32 s60, v252, 4
	v_readlane_b32 s58, v252, 10
	s_xor_b64 s[16:17], exec, s[16:17]
	v_readlane_b32 s61, v252, 5
	v_readlane_b32 s59, v252, 11
	s_cbranch_execz .LBB0_1259
	v_lshlrev_b32_e32 v206, 1, v185
	v_add_u32_e32 v185, 0xfffff040, v206
	s_waitcnt lgkmcnt(0)
	global_store_dwordx2 v185, v[188:189], s[46:47]

; #define LAS __attribute__((address_space(3)))
; #define ERN_EOFF(q, m) (eb + (unsigned)((((q) & 1) * HALF + (m) * 16) * DM + ERN_COL((q) >> 1)))
;     __device__ __forceinline__ void operator()(const f32x4 (&acc)[2][2][4][2], const Unit& u, int wr, int wc, int fr, int fq) const {
;     ...
;         for (int g = 0; g < 8; ++g) { const int ai = g >> 2, m = g & 3;
;             if (g + 1 < 8) ERN_LOADX(g + 1);
;             float sq0 = 0.f, sq1 = 0.f; u32x2 hw[2][2];
; #pragma unroll
;             for (int bj = 0; bj < 2; ++bj) {
;                 *(LAS f32x4*)(st + wr_off) = acc[ai][bj][m][0]; *(LAS f32x4*)(st + wr_off + 64) = acc[ai][bj][m][1];
;                 const f32x4 a0 = *(const LAS f32x4*)(st + rd_off), a1 = *(const LAS f32x4*)(st + rd_off + 8 * 144);
;                 { const f32x4 xv = xb[g & 1][bj][0] + gv[bj] * a0; __builtin_nontemporal_store(xv, (f32x4*)((char*)xo + 4u * ERN_EOFF(g, bj, 0)));
;                   sq0 += (xv.x * xv.x + xv.y * xv.y) + (xv.z * xv.z + xv.w * xv.w);
;                   const f32x4 hv = xv * gsn[bj]; hw[bj][0].x = cvt_pk_bf16(hv.x, hv.y); hw[bj][0].y = cvt_pk_bf16(hv.z, hv.w); }
;                 { const f32x4 xv = xb[g & 1][bj][1] + gv[bj] * a1; __builtin_nontemporal_store(xv, (f32x4*)((char*)xo + 4u * ERN_EOFF(g, bj, 1)));
;                   sq1 += (xv.x * xv.x + xv.y * xv.y) + (xv.z * xv.z + xv.w * xv.w);
;                   const f32x4 hv = xv * gsn[bj]; hw[bj][1].x = cvt_pk_bf16(hv.x, hv.y); hw[bj][1].y = cvt_pk_bf16(hv.z, hv.w); }
;             }
;             if (!NOH && !PLAIN) {
; #pragma unroll
;                 for (int rh = 0; rh < 2; ++rh) { u32x2 rv; rv.x = __shfl_xor(hw[1][rh].x, 8); rv.y = __shfl_xor(hw[1][rh].y, 8);
;                     const unsigned e0 = ERN_EOFF(g, 0, rh);
;                     const unsigned ee = odd ? (e0 - DM + 32) : e0, eo2 = odd ? e0 : (e0 + DM + 32);
;                     *(u32x2*)((char*)ho + 2u * ee) = odd ? rv : hw[0][rh];
;                     *(u32x2*)((char*)ho + 2u * eo2) = odd ? hw[0][rh] : rv; }
;             }
;             if (!PLAIN) { sq0 += __shfl_xor(sq0, 1); sq0 += __shfl_xor(sq0, 2); sq0 += __shfl_xor(sq0, 4);
;             sq1 += __shfl_xor(sq1, 1); sq1 += __shfl_xor(sq1, 2); sq1 += __shfl_xor(sq1, 4); }
;             if (!PLAIN && pc == 0) { sst[g * 16 + rr] = sq0; sst[g * 16 + 8 + rr] = sq1; }
.LBB0_1263:
	s_or_b64 exec, exec, s[16:17]
	v_lshl_add_u64 v[206:207], s[48:49], 0, v[162:163]
	v_add_u32_e32 v122, 0x40000, v205
	v_add_u32_e32 v162, 0x50000, v205
	v_add_u32_e32 v186, 0x40080, v205
	global_load_dwordx4 v[130:133], v162, s[48:49] nt
	global_load_dwordx4 v[126:129], v186, s[48:49] nt
	v_add_u32_e32 v188, 0x50080, v205
	global_load_dwordx4 v[134:137], v122, s[48:49] nt
	s_waitcnt lgkmcnt(0)
	global_load_dwordx4 v[122:125], v188, s[48:49] nt
	ds_write_b128 v200, v[118:121]
	ds_write_b128 v200, v[114:117] offset:64
	ds_read_b128 v[114:117], v201
	ds_read_b128 v[118:121], v201 offset:1152
	v_mov_b32_e32 v185, v163
	v_mov_b32_e32 v183, v163
	v_lshl_add_u64 v[182:183], s[48:49], 0, v[182:183]
	s_waitcnt lgkmcnt(1)
	v_pk_fma_f32 v[116:117], v[56:57], v[116:117], v[152:153]
	v_add_u32_e32 v152, 0x8000, v202
	v_pk_fma_f32 v[114:115], v[54:55], v[114:115], v[150:151]
	v_lshlrev_b32_e32 v150, 2, v152
	s_waitcnt lgkmcnt(0)
	v_pk_fma_f32 v[118:119], v[54:55], v[118:119], v[146:147]
	global_store_dwordx4 v150, v[114:117], s[48:49] nt
	v_pk_mul_f32 v[150:151], v[180:181], v[114:115]
	v_pk_fma_f32 v[120:121], v[56:57], v[120:121], v[148:149]
	v_pk_mul_f32 v[146:147], v[180:181], v[118:119]
	v_pk_mul_f32 v[208:209], v[178:179], v[116:117]
	v_cvt_pk_bf16_f32 v150, v150, v151
	v_pk_mul_f32 v[148:149], v[178:179], v[120:121]
	v_cvt_pk_bf16_f32 v151, v208, v209
	global_store_dwordx4 v[206:207], v[118:121], off nt
	v_cvt_pk_bf16_f32 v146, v146, v147
	v_cvt_pk_bf16_f32 v147, v148, v149
	ds_write_b128 v200, v[110:113]
	ds_write_b128 v200, v[106:109] offset:64
	ds_read_b128 v[106:109], v201
	ds_read_b128 v[110:113], v201 offset:1152
	v_lshl_add_u64 v[148:149], s[48:49], 0, v[184:185]
	s_waitcnt lgkmcnt(1)
	v_pk_fma_f32 v[106:107], v[50:51], v[106:107], v[142:143]
	v_pk_fma_f32 v[108:109], v[52:53], v[108:109], v[144:145]
	v_pk_mul_f32 v[144:145], v[176:177], v[106:107]
	global_store_dwordx4 v[148:149], v[106:109], off nt
	v_pk_mul_f32 v[142:143], v[174:175], v[108:109]
	v_cvt_pk_bf16_f32 v144, v144, v145
	s_waitcnt lgkmcnt(0)
	v_pk_fma_f32 v[110:111], v[50:51], v[110:111], v[138:139]
	v_cvt_pk_bf16_f32 v145, v142, v143
	ds_bpermute_b32 v138, v203, v144
	ds_bpermute_b32 v139, v203, v145
	v_pk_fma_f32 v[112:113], v[52:53], v[112:113], v[140:141]
	v_pk_mul_f32 v[140:141], v[176:177], v[110:111]
	v_pk_mul_f32 v[142:143], v[174:175], v[112:113]
	global_store_dwordx4 v[182:183], v[110:113], off nt
	v_cvt_pk_bf16_f32 v140, v140, v141
	v_cvt_pk_bf16_f32 v141, v142, v143
	v_lshlrev_b32_e32 v142, 1, v152
	s_waitcnt lgkmcnt(0)
	v_add_u32_e32 v250, 0xfffff040, v142
	v_cndmask_b32_e64 v250, v142, v250, s[40:41]
	v_cndmask_b32_e64 v248, v150, v138, s[40:41]
	v_cndmask_b32_e64 v249, v151, v139, s[40:41]
	global_store_dwordx2 v250, v[248:249], s[46:47]
	v_cndmask_b32_e64 v246, v138, v150, s[40:41]
	v_cndmask_b32_e64 v247, v139, v151, s[40:41]
	s_waitcnt lgkmcnt(1)
	v_add_u32_e32 v138, 0x1040, v142
	v_cndmask_b32_e64 v138, v142, v138, s[38:39]
	global_store_dwordx2 v138, v[246:247], s[46:47]
	ds_bpermute_b32 v138, v203, v140
	s_waitcnt lgkmcnt(1)
	ds_bpermute_b32 v139, v203, v141
	v_add_u32_e32 v141, 0xc000, v202
	v_lshlrev_b32_e32 v140, 1, v141
	s_waitcnt lgkmcnt(0)
	v_add_u32_e32 v250, 0xfffff040, v140
	v_cndmask_b32_e64 v250, v140, v250, s[40:41]
	v_cndmask_b32_e64 v248, v146, v138, s[40:41]
	v_cndmask_b32_e64 v249, v147, v139, s[40:41]
	global_store_dwordx2 v250, v[248:249], s[46:47]
	v_cndmask_b32_e64 v246, v138, v146, s[40:41]
	v_cndmask_b32_e64 v247, v139, v147, s[40:41]
	v_mul_f32_e32 v107, v107, v107
	v_fmac_f32_e32 v107, v106, v106
	v_mul_f32_e32 v106, v109, v109
	v_mul_f32_e32 v117, v117, v117
	v_fmac_f32_e32 v106, v108, v108
	v_mul_f32_e32 v115, v115, v115
	v_fmac_f32_e32 v117, v116, v116
	v_mul_f32_e32 v116, v119, v119
	v_mul_f32_e32 v119, v121, v121
	v_add_f32_e32 v106, v107, v106
	v_mul_f32_e32 v107, v111, v111
	v_mul_f32_e32 v108, v113, v113
	v_fmac_f32_e32 v119, v120, v120
	v_fmac_f32_e32 v107, v110, v110
	v_fmac_f32_e32 v108, v112, v112
	v_fmac_f32_e32 v115, v114, v114
	v_fmac_f32_e32 v116, v118, v118
	v_add_f32_e32 v107, v107, v108
	v_add_f32_e32 v108, v115, v117
	v_add_f32_e32 v109, v116, v119
	v_add_f32_e32 v106, v108, v106
	v_add_f32_e32 v107, v109, v107
	ds_bpermute_b32 v108, v190, v106
	ds_bpermute_b32 v109, v190, v107
	s_waitcnt lgkmcnt(1)
	v_add_f32_e32 v106, v106, v108
	s_waitcnt lgkmcnt(0)
	v_add_f32_e32 v109, v107, v109
	ds_bpermute_b32 v108, v191, v106
	ds_bpermute_b32 v110, v191, v109
	s_waitcnt lgkmcnt(1)
	v_add_f32_e32 v106, v106, v108
	s_waitcnt lgkmcnt(0)
	v_add_f32_e32 v108, v109, v110
	ds_bpermute_b32 v107, v204, v106
	ds_bpermute_b32 v109, v204, v108
	v_add_u32_e32 v110, 0x1040, v140
	v_cndmask_b32_e64 v110, v140, v110, s[38:39]
	global_store_dwordx2 v110, v[246:247], s[46:47]
	s_and_saveexec_b64 s[16:17], s[42:43]
	s_cbranch_execz .LBB0_1273
	s_waitcnt lgkmcnt(1)
	v_add_f32_e32 v106, v106, v107
	s_waitcnt lgkmcnt(0)
	v_add_f32_e32 v107, v108, v109
	ds_write2_b32 v194, v106, v107 offset0:16 offset1:24
; #define LAS __attribute__((address_space(3)))
; #define ERN_EOFF(q, m) (eb + (unsigned)((((q) & 1) * HALF + (m) * 16) * DM + ERN_COL((q) >> 1)))
;     __device__ __forceinline__ void operator()(const f32x4 (&acc)[2][2][4][2], const Unit& u, int wr, int wc, int fr, int fq) const {
;     ...
;         for (int g = 0; g < 8; ++g) { const int ai = g >> 2, m = g & 3;
;             if (g + 1 < 8) ERN_LOADX(g + 1);
;             float sq0 = 0.f, sq1 = 0.f; u32x2 hw[2][2];
; #pragma unroll
;             for (int bj = 0; bj < 2; ++bj) {
;                 *(LAS f32x4*)(st + wr_off) = acc[ai][bj][m][0]; *(LAS f32x4*)(st + wr_off + 64) = acc[ai][bj][m][1];
;                 const f32x4 a0 = *(const LAS f32x4*)(st + rd_off), a1 = *(const LAS f32x4*)(st + rd_off + 8 * 144);
;                 { const f32x4 xv = xb[g & 1][bj][0] + gv[bj] * a0; __builtin_nontemporal_store(xv, (f32x4*)((char*)xo + 4u * ERN_EOFF(g, bj, 0)));
;                   sq0 += (xv.x * xv.x + xv.y * xv.y) + (xv.z * xv.z + xv.w * xv.w);
;                   const f32x4 hv = xv * gsn[bj]; hw[bj][0].x = cvt_pk_bf16(hv.x, hv.y); hw[bj][0].y = cvt_pk_bf16(hv.z, hv.w); }
;                 { const f32x4 xv = xb[g & 1][bj][1] + gv[bj] * a1; __builtin_nontemporal_store(xv, (f32x4*)((char*)xo + 4u * ERN_EOFF(g, bj, 1)));
;                   sq1 += (xv.x * xv.x + xv.y * xv.y) + (xv.z * xv.z + xv.w * xv.w);
;                   const f32x4 hv = xv * gsn[bj]; hw[bj][1].x = cvt_pk_bf16(hv.x, hv.y); hw[bj][1].y = cvt_pk_bf16(hv.z, hv.w); }
;             }
;             if (!NOH && !PLAIN) {
; #pragma unroll
;                 for (int rh = 0; rh < 2; ++rh) { u32x2 rv; rv.x = __shfl_xor(hw[1][rh].x, 8); rv.y = __shfl_xor(hw[1][rh].y, 8);
;                     const unsigned e0 = ERN_EOFF(g, 0, rh);
;                     const unsigned ee = odd ? (e0 - DM + 32) : e0, eo2 = odd ? e0 : (e0 + DM + 32);
;                     *(u32x2*)((char*)ho + 2u * ee) = odd ? rv : hw[0][rh];
;                     *(u32x2*)((char*)ho + 2u * eo2) = odd ? hw[0][rh] : rv; }
;             }
;             if (!PLAIN) { sq0 += __shfl_xor(sq0, 1); sq0 += __shfl_xor(sq0, 2); sq0 += __shfl_xor(sq0, 4);
;             sq1 += __shfl_xor(sq1, 1); sq1 += __shfl_xor(sq1, 2); sq1 += __shfl_xor(sq1, 4); }
;             if (!PLAIN && pc == 0) { sst[g * 16 + rr] = sq0; sst[g * 16 + 8 + rr] = sq1; }
.LBB0_1273:
	s_or_b64 exec, exec, s[16:17]
	v_lshl_add_u64 v[142:143], s[48:49], 0, v[162:163]
	v_add_u32_e32 v106, 0x60000, v205
	v_add_u32_e32 v162, 0x70000, v205
	v_add_u32_e32 v138, 0x60080, v205
	global_load_dwordx4 v[114:117], v162, s[48:49] nt
	global_load_dwordx4 v[110:113], v138, s[48:49] nt
	v_add_u32_e32 v140, 0x70080, v205
	global_load_dwordx4 v[118:121], v106, s[48:49] nt
	s_waitcnt lgkmcnt(0)
	global_load_dwordx4 v[106:109], v140, s[48:49] nt
	ds_write_b128 v200, v[102:105]
	ds_write_b128 v200, v[98:101] offset:64
	ds_read_b128 v[98:101], v201
	ds_read_b128 v[102:105], v201 offset:1152
	v_mov_b32_e32 v187, v163
	v_mov_b32_e32 v189, v163
	s_waitcnt vmcnt(11) lgkmcnt(1)
	v_pk_fma_f32 v[100:101], v[56:57], v[100:101], v[136:137]
	v_add_u32_e32 v136, 0x10000, v202
	v_pk_fma_f32 v[98:99], v[54:55], v[98:99], v[134:135]
	v_lshlrev_b32_e32 v134, 2, v136
	s_waitcnt lgkmcnt(0)
	v_pk_fma_f32 v[102:103], v[54:55], v[102:103], v[130:131]
	global_store_dwordx4 v134, v[98:101], s[48:49] nt
	v_pk_mul_f32 v[134:135], v[180:181], v[98:99]
	v_pk_fma_f32 v[104:105], v[56:57], v[104:105], v[132:133]
	v_pk_mul_f32 v[130:131], v[180:181], v[102:103]
	v_pk_mul_f32 v[144:145], v[178:179], v[100:101]
	v_cvt_pk_bf16_f32 v134, v134, v135
	v_pk_mul_f32 v[132:133], v[178:179], v[104:105]
	v_cvt_pk_bf16_f32 v135, v144, v145
	global_store_dwordx4 v[142:143], v[102:105], off nt
	v_cvt_pk_bf16_f32 v130, v130, v131
	v_cvt_pk_bf16_f32 v131, v132, v133
	ds_write_b128 v200, v[94:97]
	ds_write_b128 v200, v[90:93] offset:64
	ds_read_b128 v[90:93], v201
	ds_read_b128 v[94:97], v201 offset:1152
	v_lshl_add_u64 v[132:133], s[48:49], 0, v[186:187]
	v_lshl_add_u64 v[142:143], s[48:49], 0, v[188:189]
	s_waitcnt lgkmcnt(1)
	v_pk_fma_f32 v[90:91], v[50:51], v[90:91], v[126:127]
	v_pk_fma_f32 v[92:93], v[52:53], v[92:93], v[128:129]
	v_pk_mul_f32 v[128:129], v[176:177], v[90:91]
	global_store_dwordx4 v[132:133], v[90:93], off nt
	v_pk_mul_f32 v[126:127], v[174:175], v[92:93]
	v_cvt_pk_bf16_f32 v128, v128, v129
	s_waitcnt vmcnt(13) lgkmcnt(0)
	v_pk_fma_f32 v[94:95], v[50:51], v[94:95], v[122:123]
	v_cvt_pk_bf16_f32 v129, v126, v127
	ds_bpermute_b32 v122, v203, v128
	ds_bpermute_b32 v123, v203, v129
	v_pk_fma_f32 v[96:97], v[52:53], v[96:97], v[124:125]
	v_pk_mul_f32 v[124:125], v[176:177], v[94:95]
	v_pk_mul_f32 v[126:127], v[174:175], v[96:97]
	global_store_dwordx4 v[142:143], v[94:97], off nt
	v_cvt_pk_bf16_f32 v124, v124, v125
	v_cvt_pk_bf16_f32 v125, v126, v127
	v_lshlrev_b32_e32 v126, 1, v136
	s_waitcnt lgkmcnt(0)
	v_add_u32_e32 v250, 0xfffff040, v126
	v_cndmask_b32_e64 v250, v126, v250, s[40:41]
	v_cndmask_b32_e64 v248, v134, v122, s[40:41]
	v_cndmask_b32_e64 v249, v135, v123, s[40:41]
	global_store_dwordx2 v250, v[248:249], s[46:47]
	v_cndmask_b32_e64 v246, v122, v134, s[40:41]
	v_cndmask_b32_e64 v247, v123, v135, s[40:41]
	s_waitcnt lgkmcnt(1)
	v_add_u32_e32 v122, 0x1040, v126
	v_cndmask_b32_e64 v122, v126, v122, s[38:39]
	global_store_dwordx2 v122, v[246:247], s[46:47]
	ds_bpermute_b32 v122, v203, v124
	s_waitcnt lgkmcnt(1)
	ds_bpermute_b32 v123, v203, v125
	v_add_u32_e32 v125, 0x14000, v202
	v_lshlrev_b32_e32 v124, 1, v125
	s_waitcnt lgkmcnt(0)
	v_add_u32_e32 v250, 0xfffff040, v124
	v_cndmask_b32_e64 v250, v124, v250, s[40:41]
	v_cndmask_b32_e64 v248, v130, v122, s[40:41]
	v_cndmask_b32_e64 v249, v131, v123, s[40:41]
	global_store_dwordx2 v250, v[248:249], s[46:47]
	v_cndmask_b32_e64 v246, v122, v130, s[40:41]
	v_cndmask_b32_e64 v247, v123, v131, s[40:41]
	v_mul_f32_e32 v91, v91, v91
	v_fmac_f32_e32 v91, v90, v90
	v_mul_f32_e32 v90, v93, v93
	v_mul_f32_e32 v101, v101, v101
	v_fmac_f32_e32 v90, v92, v92
	v_mul_f32_e32 v99, v99, v99
	v_fmac_f32_e32 v101, v100, v100
	v_mul_f32_e32 v100, v103, v103
	v_mul_f32_e32 v103, v105, v105
	v_add_f32_e32 v90, v91, v90
	v_mul_f32_e32 v91, v95, v95
	v_mul_f32_e32 v92, v97, v97
	v_fmac_f32_e32 v103, v104, v104
	v_fmac_f32_e32 v91, v94, v94
	v_fmac_f32_e32 v92, v96, v96
	v_fmac_f32_e32 v99, v98, v98
	v_fmac_f32_e32 v100, v102, v102
	v_add_f32_e32 v91, v91, v92
	v_add_f32_e32 v92, v99, v101
	v_add_f32_e32 v93, v100, v103
	v_add_f32_e32 v90, v92, v90
	v_add_f32_e32 v91, v93, v91
	ds_bpermute_b32 v92, v190, v90
	ds_bpermute_b32 v93, v190, v91
	s_waitcnt lgkmcnt(1)
	v_add_f32_e32 v90, v90, v92
	s_waitcnt lgkmcnt(0)
	v_add_f32_e32 v93, v91, v93
	ds_bpermute_b32 v92, v191, v90
	ds_bpermute_b32 v94, v191, v93
	s_waitcnt lgkmcnt(1)
	v_add_f32_e32 v90, v90, v92
	s_waitcnt lgkmcnt(0)
	v_add_f32_e32 v92, v93, v94
	ds_bpermute_b32 v91, v204, v90
	ds_bpermute_b32 v93, v204, v92
	v_add_u32_e32 v94, 0x1040, v124
	v_cndmask_b32_e64 v94, v124, v94, s[38:39]
	global_store_dwordx2 v94, v[246:247], s[46:47]
	s_and_saveexec_b64 s[16:17], s[42:43]
	s_cbranch_execz .LBB0_1283
	s_waitcnt lgkmcnt(1)
	v_add_f32_e32 v90, v90, v91
	s_waitcnt lgkmcnt(0)
	v_add_f32_e32 v91, v92, v93
	ds_write2_b32 v194, v90, v91 offset0:32 offset1:40
; #define LAS __attribute__((address_space(3)))
; #define ERN_EOFF(q, m) (eb + (unsigned)((((q) & 1) * HALF + (m) * 16) * DM + ERN_COL((q) >> 1)))
;     __device__ __forceinline__ void operator()(const f32x4 (&acc)[2][2][4][2], const Unit& u, int wr, int wc, int fr, int fq) const {
;     ...
;         for (int g = 0; g < 8; ++g) { const int ai = g >> 2, m = g & 3;
;             if (g + 1 < 8) ERN_LOADX(g + 1);
;             float sq0 = 0.f, sq1 = 0.f; u32x2 hw[2][2];
; #pragma unroll
;             for (int bj = 0; bj < 2; ++bj) {
;                 *(LAS f32x4*)(st + wr_off) = acc[ai][bj][m][0]; *(LAS f32x4*)(st + wr_off + 64) = acc[ai][bj][m][1];
;                 const f32x4 a0 = *(const LAS f32x4*)(st + rd_off), a1 = *(const LAS f32x4*)(st + rd_off + 8 * 144);
;                 { const f32x4 xv = xb[g & 1][bj][0] + gv[bj] * a0; __builtin_nontemporal_store(xv, (f32x4*)((char*)xo + 4u * ERN_EOFF(g, bj, 0)));
;                   sq0 += (xv.x * xv.x + xv.y * xv.y) + (xv.z * xv.z + xv.w * xv.w);
;                   const f32x4 hv = xv * gsn[bj]; hw[bj][0].x = cvt_pk_bf16(hv.x, hv.y); hw[bj][0].y = cvt_pk_bf16(hv.z, hv.w); }
;                 { const f32x4 xv = xb[g & 1][bj][1] + gv[bj] * a1; __builtin_nontemporal_store(xv, (f32x4*)((char*)xo + 4u * ERN_EOFF(g, bj, 1)));
;                   sq1 += (xv.x * xv.x + xv.y * xv.y) + (xv.z * xv.z + xv.w * xv.w);
;                   const f32x4 hv = xv * gsn[bj]; hw[bj][1].x = cvt_pk_bf16(hv.x, hv.y); hw[bj][1].y = cvt_pk_bf16(hv.z, hv.w); }
;             }
;             if (!NOH && !PLAIN) {
; #pragma unroll
;                 for (int rh = 0; rh < 2; ++rh) { u32x2 rv; rv.x = __shfl_xor(hw[1][rh].x, 8); rv.y = __shfl_xor(hw[1][rh].y, 8);
;                     const unsigned e0 = ERN_EOFF(g, 0, rh);
;                     const unsigned ee = odd ? (e0 - DM + 32) : e0, eo2 = odd ? e0 : (e0 + DM + 32);
;                     *(u32x2*)((char*)ho + 2u * ee) = odd ? rv : hw[0][rh];
;                     *(u32x2*)((char*)ho + 2u * eo2) = odd ? hw[0][rh] : rv; }
;             }
;             if (!PLAIN) { sq0 += __shfl_xor(sq0, 1); sq0 += __shfl_xor(sq0, 2); sq0 += __shfl_xor(sq0, 4);
;             sq1 += __shfl_xor(sq1, 1); sq1 += __shfl_xor(sq1, 2); sq1 += __shfl_xor(sq1, 4); }
;             if (!PLAIN && pc == 0) { sst[g * 16 + rr] = sq0; sst[g * 16 + 8 + rr] = sq1; }
.LBB0_1283:
	s_or_b64 exec, exec, s[16:17]
	v_lshl_add_u64 v[124:125], s[48:49], 0, v[162:163]
	v_add_u32_e32 v90, 0x100000, v205
	s_waitcnt lgkmcnt(1)
	v_add_u32_e32 v91, 0x110000, v205
	v_add_u32_e32 v162, 0x100080, v205
	global_load_dwordx4 v[102:105], v90, s[48:49] nt
	global_load_dwordx4 v[98:101], v91, s[48:49] nt
	v_add_u32_e32 v122, 0x110080, v205
	global_load_dwordx4 v[94:97], v162, s[48:49] nt
	s_waitcnt lgkmcnt(0)
	global_load_dwordx4 v[90:93], v122, s[48:49] nt
	ds_write_b128 v200, v[86:89]
	ds_write_b128 v200, v[82:85] offset:64
	ds_read_b128 v[82:85], v201
	ds_read_b128 v[86:89], v201 offset:1152
	v_mov_b32_e32 v139, v163
	v_mov_b32_e32 v141, v163
	s_waitcnt vmcnt(11) lgkmcnt(1)
	v_pk_fma_f32 v[84:85], v[56:57], v[84:85], v[120:121]
	v_add_u32_e32 v120, 0x18000, v202
	v_pk_fma_f32 v[82:83], v[54:55], v[82:83], v[118:119]
	v_lshlrev_b32_e32 v118, 2, v120
	s_waitcnt lgkmcnt(0)
	v_pk_fma_f32 v[86:87], v[54:55], v[86:87], v[114:115]
	global_store_dwordx4 v118, v[82:85], s[48:49] nt
	v_pk_mul_f32 v[118:119], v[180:181], v[82:83]
	v_pk_fma_f32 v[88:89], v[56:57], v[88:89], v[116:117]
	v_pk_mul_f32 v[114:115], v[180:181], v[86:87]
	v_pk_mul_f32 v[126:127], v[178:179], v[84:85]
	v_cvt_pk_bf16_f32 v118, v118, v119
	v_pk_mul_f32 v[116:117], v[178:179], v[88:89]
	v_cvt_pk_bf16_f32 v119, v126, v127
	global_store_dwordx4 v[124:125], v[86:89], off nt
	v_cvt_pk_bf16_f32 v114, v114, v115
	v_cvt_pk_bf16_f32 v115, v116, v117
	ds_write_b128 v200, v[78:81]
	ds_write_b128 v200, v[74:77] offset:64
	ds_read_b128 v[74:77], v201
	ds_read_b128 v[78:81], v201 offset:1152
	v_lshl_add_u64 v[116:117], s[48:49], 0, v[138:139]
	v_lshl_add_u64 v[124:125], s[48:49], 0, v[140:141]
	s_waitcnt lgkmcnt(1)
	v_pk_fma_f32 v[74:75], v[50:51], v[74:75], v[110:111]
	v_pk_fma_f32 v[76:77], v[52:53], v[76:77], v[112:113]
	v_pk_mul_f32 v[112:113], v[176:177], v[74:75]
	global_store_dwordx4 v[116:117], v[74:77], off nt
	v_pk_mul_f32 v[110:111], v[174:175], v[76:77]
	v_cvt_pk_bf16_f32 v112, v112, v113
	s_waitcnt vmcnt(13) lgkmcnt(0)
	v_pk_fma_f32 v[78:79], v[50:51], v[78:79], v[106:107]
	v_cvt_pk_bf16_f32 v113, v110, v111
	ds_bpermute_b32 v106, v203, v112
	ds_bpermute_b32 v107, v203, v113
	v_pk_fma_f32 v[80:81], v[52:53], v[80:81], v[108:109]
	v_pk_mul_f32 v[108:109], v[176:177], v[78:79]
	v_pk_mul_f32 v[110:111], v[174:175], v[80:81]
	global_store_dwordx4 v[124:125], v[78:81], off nt
	v_cvt_pk_bf16_f32 v108, v108, v109
	v_cvt_pk_bf16_f32 v109, v110, v111
	v_lshlrev_b32_e32 v110, 1, v120
	s_waitcnt lgkmcnt(0)
	v_add_u32_e32 v250, 0xfffff040, v110
	v_cndmask_b32_e64 v250, v110, v250, s[40:41]
	v_cndmask_b32_e64 v248, v118, v106, s[40:41]
	v_cndmask_b32_e64 v249, v119, v107, s[40:41]
	global_store_dwordx2 v250, v[248:249], s[46:47]
	v_cndmask_b32_e64 v246, v106, v118, s[40:41]
	v_cndmask_b32_e64 v247, v107, v119, s[40:41]
	s_waitcnt lgkmcnt(1)
	v_add_u32_e32 v106, 0x1040, v110
	v_cndmask_b32_e64 v106, v110, v106, s[38:39]
	global_store_dwordx2 v106, v[246:247], s[46:47]
	ds_bpermute_b32 v106, v203, v108
	s_waitcnt lgkmcnt(1)
	ds_bpermute_b32 v107, v203, v109
	v_add_u32_e32 v109, 0x1c000, v202
	v_lshlrev_b32_e32 v108, 1, v109
	s_waitcnt lgkmcnt(0)
	v_add_u32_e32 v250, 0xfffff040, v108
	v_cndmask_b32_e64 v250, v108, v250, s[40:41]
	v_cndmask_b32_e64 v248, v114, v106, s[40:41]
	v_cndmask_b32_e64 v249, v115, v107, s[40:41]
	global_store_dwordx2 v250, v[248:249], s[46:47]
	v_cndmask_b32_e64 v246, v106, v114, s[40:41]
	v_cndmask_b32_e64 v247, v107, v115, s[40:41]
	v_mul_f32_e32 v75, v75, v75
	v_fmac_f32_e32 v75, v74, v74
	v_mul_f32_e32 v74, v77, v77
	v_mul_f32_e32 v85, v85, v85
	v_fmac_f32_e32 v74, v76, v76
	v_mul_f32_e32 v83, v83, v83
	v_fmac_f32_e32 v85, v84, v84
	v_mul_f32_e32 v84, v87, v87
	v_mul_f32_e32 v87, v89, v89
	v_add_f32_e32 v74, v75, v74
	v_mul_f32_e32 v75, v79, v79
	v_mul_f32_e32 v76, v81, v81
	v_fmac_f32_e32 v87, v88, v88
	v_fmac_f32_e32 v75, v78, v78
	v_fmac_f32_e32 v76, v80, v80
	v_fmac_f32_e32 v83, v82, v82
	v_fmac_f32_e32 v84, v86, v86
	v_add_f32_e32 v75, v75, v76
	v_add_f32_e32 v76, v83, v85
	v_add_f32_e32 v77, v84, v87
	v_add_f32_e32 v74, v76, v74
	v_add_f32_e32 v75, v77, v75
	ds_bpermute_b32 v76, v190, v74
	ds_bpermute_b32 v77, v190, v75
	s_waitcnt lgkmcnt(1)
	v_add_f32_e32 v74, v74, v76
	s_waitcnt lgkmcnt(0)
	v_add_f32_e32 v77, v75, v77
	ds_bpermute_b32 v76, v191, v74
	ds_bpermute_b32 v78, v191, v77
	s_waitcnt lgkmcnt(1)
	v_add_f32_e32 v74, v74, v76
	s_waitcnt lgkmcnt(0)
	v_add_f32_e32 v76, v77, v78
	ds_bpermute_b32 v75, v204, v74
	ds_bpermute_b32 v77, v204, v76
	v_add_u32_e32 v78, 0x1040, v108
	v_cndmask_b32_e64 v78, v108, v78, s[38:39]
	global_store_dwordx2 v78, v[246:247], s[46:47]
	s_and_saveexec_b64 s[16:17], s[42:43]
	s_cbranch_execz .LBB0_1293
	s_waitcnt lgkmcnt(1)
	v_add_f32_e32 v74, v74, v75
	s_waitcnt lgkmcnt(0)
	v_add_f32_e32 v75, v76, v77
	ds_write2_b32 v194, v74, v75 offset0:48 offset1:56
; #define LAS __attribute__((address_space(3)))
; #define ERN_EOFF(q, m) (eb + (unsigned)((((q) & 1) * HALF + (m) * 16) * DM + ERN_COL((q) >> 1)))
;     __device__ __forceinline__ void operator()(const f32x4 (&acc)[2][2][4][2], const Unit& u, int wr, int wc, int fr, int fq) const {
;     ...
;         for (int g = 0; g < 8; ++g) { const int ai = g >> 2, m = g & 3;
;             if (g + 1 < 8) ERN_LOADX(g + 1);
;             float sq0 = 0.f, sq1 = 0.f; u32x2 hw[2][2];
; #pragma unroll
;             for (int bj = 0; bj < 2; ++bj) {
;                 *(LAS f32x4*)(st + wr_off) = acc[ai][bj][m][0]; *(LAS f32x4*)(st + wr_off + 64) = acc[ai][bj][m][1];
;                 const f32x4 a0 = *(const LAS f32x4*)(st + rd_off), a1 = *(const LAS f32x4*)(st + rd_off + 8 * 144);
;                 { const f32x4 xv = xb[g & 1][bj][0] + gv[bj] * a0; __builtin_nontemporal_store(xv, (f32x4*)((char*)xo + 4u * ERN_EOFF(g, bj, 0)));
;                   sq0 += (xv.x * xv.x + xv.y * xv.y) + (xv.z * xv.z + xv.w * xv.w);
;                   const f32x4 hv = xv * gsn[bj]; hw[bj][0].x = cvt_pk_bf16(hv.x, hv.y); hw[bj][0].y = cvt_pk_bf16(hv.z, hv.w); }
;                 { const f32x4 xv = xb[g & 1][bj][1] + gv[bj] * a1; __builtin_nontemporal_store(xv, (f32x4*)((char*)xo + 4u * ERN_EOFF(g, bj, 1)));
;                   sq1 += (xv.x * xv.x + xv.y * xv.y) + (xv.z * xv.z + xv.w * xv.w);
;                   const f32x4 hv = xv * gsn[bj]; hw[bj][1].x = cvt_pk_bf16(hv.x, hv.y); hw[bj][1].y = cvt_pk_bf16(hv.z, hv.w); }
;             }
;             if (!NOH && !PLAIN) {
; #pragma unroll
;                 for (int rh = 0; rh < 2; ++rh) { u32x2 rv; rv.x = __shfl_xor(hw[1][rh].x, 8); rv.y = __shfl_xor(hw[1][rh].y, 8);
;                     const unsigned e0 = ERN_EOFF(g, 0, rh);
;                     const unsigned ee = odd ? (e0 - DM + 32) : e0, eo2 = odd ? e0 : (e0 + DM + 32);
;                     *(u32x2*)((char*)ho + 2u * ee) = odd ? rv : hw[0][rh];
;                     *(u32x2*)((char*)ho + 2u * eo2) = odd ? hw[0][rh] : rv; }
;             }
;             if (!PLAIN) { sq0 += __shfl_xor(sq0, 1); sq0 += __shfl_xor(sq0, 2); sq0 += __shfl_xor(sq0, 4);
;             sq1 += __shfl_xor(sq1, 1); sq1 += __shfl_xor(sq1, 2); sq1 += __shfl_xor(sq1, 4); }
;             if (!PLAIN && pc == 0) { sst[g * 16 + rr] = sq0; sst[g * 16 + 8 + rr] = sq1; }
.LBB0_1293:
	s_or_b64 exec, exec, s[16:17]
	v_lshl_add_u64 v[112:113], s[48:49], 0, v[162:163]
	v_add_u32_e32 v162, 0x120000, v205
	v_add_u32_e32 v108, 0x120080, v205
	v_add_u32_e32 v110, 0x130000, v205
	global_load_dwordx4 v[86:89], v162, s[48:49] nt
	global_load_dwordx4 v[82:85], v110, s[48:49] nt
	v_add_u32_e32 v106, 0x130080, v205
	global_load_dwordx4 v[78:81], v108, s[48:49] nt
	s_waitcnt lgkmcnt(0)
	global_load_dwordx4 v[74:77], v106, s[48:49] nt
	ds_write_b128 v200, v[70:73]
	ds_write_b128 v200, v[66:69] offset:64
	ds_read_b128 v[66:69], v201
	ds_read_b128 v[70:73], v201 offset:1152
	v_mov_b32_e32 v123, v163
	s_waitcnt vmcnt(13) lgkmcnt(1)
	v_pk_fma_f32 v[68:69], v[56:57], v[68:69], v[104:105]
	v_add_u32_e32 v104, 0x40000, v202
	v_pk_fma_f32 v[66:67], v[54:55], v[66:67], v[102:103]
	v_lshlrev_b32_e32 v102, 2, v104
	s_waitcnt vmcnt(12) lgkmcnt(0)
	v_pk_fma_f32 v[72:73], v[56:57], v[72:73], v[100:101]
	v_add_u32_e32 v100, 0x44000, v202
	global_store_dwordx4 v102, v[66:69], s[48:49] nt
	v_pk_mul_f32 v[102:103], v[180:181], v[66:67]
	v_pk_fma_f32 v[70:71], v[54:55], v[70:71], v[98:99]
	v_lshlrev_b32_e32 v98, 2, v100
	v_pk_mul_f32 v[114:115], v[178:179], v[68:69]
	v_cvt_pk_bf16_f32 v102, v102, v103
	s_nop 0
	v_cvt_pk_bf16_f32 v103, v114, v115
	global_store_dwordx4 v98, v[70:73], s[48:49] nt
	v_pk_mul_f32 v[98:99], v[180:181], v[70:71]
	v_pk_mul_f32 v[114:115], v[178:179], v[72:73]
	v_cvt_pk_bf16_f32 v98, v98, v99
	s_nop 0
	v_cvt_pk_bf16_f32 v99, v114, v115
	ds_write_b128 v200, v[62:65]
	ds_write_b128 v200, v[58:61] offset:64
	ds_read_b128 v[58:61], v201
	ds_read_b128 v[62:65], v201 offset:1152
	v_lshl_add_u64 v[114:115], s[48:49], 0, v[122:123]
	s_waitcnt vmcnt(13) lgkmcnt(1)
	v_pk_fma_f32 v[58:59], v[50:51], v[58:59], v[94:95]
	v_pk_fma_f32 v[60:61], v[52:53], v[60:61], v[96:97]
	v_pk_mul_f32 v[96:97], v[176:177], v[58:59]
	global_store_dwordx4 v[112:113], v[58:61], off nt
	v_pk_mul_f32 v[94:95], v[174:175], v[60:61]
	v_cvt_pk_bf16_f32 v96, v96, v97
	s_waitcnt vmcnt(13) lgkmcnt(0)
	v_pk_fma_f32 v[62:63], v[50:51], v[62:63], v[90:91]
	v_cvt_pk_bf16_f32 v97, v94, v95
	ds_bpermute_b32 v90, v203, v96
	ds_bpermute_b32 v91, v203, v97
	v_pk_fma_f32 v[64:65], v[52:53], v[64:65], v[92:93]
	v_pk_mul_f32 v[92:93], v[176:177], v[62:63]
	v_pk_mul_f32 v[94:95], v[174:175], v[64:65]
	global_store_dwordx4 v[114:115], v[62:65], off nt
	v_cvt_pk_bf16_f32 v92, v92, v93
	v_cvt_pk_bf16_f32 v93, v94, v95
	v_lshlrev_b32_e32 v94, 1, v104
	s_waitcnt lgkmcnt(0)
	v_add_u32_e32 v250, 0xfffff040, v94
	v_cndmask_b32_e64 v250, v94, v250, s[40:41]
	v_cndmask_b32_e64 v248, v102, v90, s[40:41]
	v_cndmask_b32_e64 v249, v103, v91, s[40:41]
	global_store_dwordx2 v250, v[248:249], s[46:47]
	v_cndmask_b32_e64 v246, v90, v102, s[40:41]
	v_cndmask_b32_e64 v247, v91, v103, s[40:41]
	s_waitcnt lgkmcnt(1)
	v_add_u32_e32 v90, 0x1040, v94
	v_cndmask_b32_e64 v90, v94, v90, s[38:39]
	global_store_dwordx2 v90, v[246:247], s[46:47]
	ds_bpermute_b32 v90, v203, v92
	s_waitcnt lgkmcnt(1)
	ds_bpermute_b32 v91, v203, v93
	v_lshlrev_b32_e32 v92, 1, v100
	s_waitcnt lgkmcnt(0)
	v_add_u32_e32 v250, 0xfffff040, v92
	v_cndmask_b32_e64 v250, v92, v250, s[40:41]
	v_cndmask_b32_e64 v248, v98, v90, s[40:41]
	v_cndmask_b32_e64 v249, v99, v91, s[40:41]
	global_store_dwordx2 v250, v[248:249], s[46:47]
	v_cndmask_b32_e64 v246, v90, v98, s[40:41]
	v_cndmask_b32_e64 v247, v91, v99, s[40:41]
	v_mul_f32_e32 v59, v59, v59
	v_fmac_f32_e32 v59, v58, v58
	v_mul_f32_e32 v58, v61, v61
	v_mul_f32_e32 v69, v69, v69
	v_fmac_f32_e32 v58, v60, v60
	v_mul_f32_e32 v67, v67, v67
	v_fmac_f32_e32 v69, v68, v68
	v_mul_f32_e32 v68, v71, v71
	v_mul_f32_e32 v71, v73, v73
	v_add_f32_e32 v58, v59, v58
	v_mul_f32_e32 v59, v63, v63
	v_mul_f32_e32 v60, v65, v65
	v_fmac_f32_e32 v71, v72, v72
	v_fmac_f32_e32 v59, v62, v62
	v_fmac_f32_e32 v60, v64, v64
	v_fmac_f32_e32 v67, v66, v66
	v_fmac_f32_e32 v68, v70, v70
	v_add_f32_e32 v59, v59, v60
	v_add_f32_e32 v60, v67, v69
	v_add_f32_e32 v61, v68, v71
	v_add_f32_e32 v58, v60, v58
	v_add_f32_e32 v59, v61, v59
	ds_bpermute_b32 v60, v190, v58
	ds_bpermute_b32 v61, v190, v59
	s_waitcnt lgkmcnt(1)
	v_add_f32_e32 v58, v58, v60
	s_waitcnt lgkmcnt(0)
	v_add_f32_e32 v61, v59, v61
	ds_bpermute_b32 v60, v191, v58
	ds_bpermute_b32 v62, v191, v61
	s_waitcnt lgkmcnt(1)
	v_add_f32_e32 v58, v58, v60
	s_waitcnt lgkmcnt(0)
	v_add_f32_e32 v60, v61, v62
	ds_bpermute_b32 v59, v204, v58
	ds_bpermute_b32 v61, v204, v60
	v_add_u32_e32 v62, 0x1040, v92
	v_cndmask_b32_e64 v62, v92, v62, s[38:39]
	global_store_dwordx2 v62, v[246:247], s[46:47]
	s_and_saveexec_b64 s[16:17], s[42:43]
	s_cbranch_execz .LBB0_1303
	s_waitcnt lgkmcnt(1)
	v_add_f32_e32 v58, v58, v59
	s_waitcnt lgkmcnt(0)
	v_add_f32_e32 v59, v60, v61
	ds_write2_b32 v194, v58, v59 offset0:64 offset1:72
; #define LAS __attribute__((address_space(3)))
; #define ERN_EOFF(q, m) (eb + (unsigned)((((q) & 1) * HALF + (m) * 16) * DM + ERN_COL((q) >> 1)))
;     __device__ __forceinline__ void operator()(const f32x4 (&acc)[2][2][4][2], const Unit& u, int wr, int wc, int fr, int fq) const {
;     ...
;         for (int g = 0; g < 8; ++g) { const int ai = g >> 2, m = g & 3;
;             if (g + 1 < 8) ERN_LOADX(g + 1);
;             float sq0 = 0.f, sq1 = 0.f; u32x2 hw[2][2];
; #pragma unroll
;             for (int bj = 0; bj < 2; ++bj) {
;                 *(LAS f32x4*)(st + wr_off) = acc[ai][bj][m][0]; *(LAS f32x4*)(st + wr_off + 64) = acc[ai][bj][m][1];
;                 const f32x4 a0 = *(const LAS f32x4*)(st + rd_off), a1 = *(const LAS f32x4*)(st + rd_off + 8 * 144);
;                 { const f32x4 xv = xb[g & 1][bj][0] + gv[bj] * a0; __builtin_nontemporal_store(xv, (f32x4*)((char*)xo + 4u * ERN_EOFF(g, bj, 0)));
;                   sq0 += (xv.x * xv.x + xv.y * xv.y) + (xv.z * xv.z + xv.w * xv.w);
;                   const f32x4 hv = xv * gsn[bj]; hw[bj][0].x = cvt_pk_bf16(hv.x, hv.y); hw[bj][0].y = cvt_pk_bf16(hv.z, hv.w); }
;                 { const f32x4 xv = xb[g & 1][bj][1] + gv[bj] * a1; __builtin_nontemporal_store(xv, (f32x4*)((char*)xo + 4u * ERN_EOFF(g, bj, 1)));
;                   sq1 += (xv.x * xv.x + xv.y * xv.y) + (xv.z * xv.z + xv.w * xv.w);
;                   const f32x4 hv = xv * gsn[bj]; hw[bj][1].x = cvt_pk_bf16(hv.x, hv.y); hw[bj][1].y = cvt_pk_bf16(hv.z, hv.w); }
;             }
;             if (!NOH && !PLAIN) {
; #pragma unroll
;                 for (int rh = 0; rh < 2; ++rh) { u32x2 rv; rv.x = __shfl_xor(hw[1][rh].x, 8); rv.y = __shfl_xor(hw[1][rh].y, 8);
;                     const unsigned e0 = ERN_EOFF(g, 0, rh);
;                     const unsigned ee = odd ? (e0 - DM + 32) : e0, eo2 = odd ? e0 : (e0 + DM + 32);
;                     *(u32x2*)((char*)ho + 2u * ee) = odd ? rv : hw[0][rh];
;                     *(u32x2*)((char*)ho + 2u * eo2) = odd ? hw[0][rh] : rv; }
;             }
;             if (!PLAIN) { sq0 += __shfl_xor(sq0, 1); sq0 += __shfl_xor(sq0, 2); sq0 += __shfl_xor(sq0, 4);
;             sq1 += __shfl_xor(sq1, 1); sq1 += __shfl_xor(sq1, 2); sq1 += __shfl_xor(sq1, 4); }
;             if (!PLAIN && pc == 0) { sst[g * 16 + rr] = sq0; sst[g * 16 + 8 + rr] = sq1; }
.LBB0_1303:
	s_or_b64 exec, exec, s[16:17]
	v_lshl_add_u64 v[96:97], s[48:49], 0, v[162:163]
	v_add_u32_e32 v162, 0x140000, v205
	v_add_u32_e32 v92, 0x140080, v205
	v_add_u32_e32 v94, 0x150000, v205
	global_load_dwordx4 v[70:73], v162, s[48:49] nt
	global_load_dwordx4 v[66:69], v94, s[48:49] nt
	v_add_u32_e32 v90, 0x150080, v205
	global_load_dwordx4 v[62:65], v92, s[48:49] nt
	s_waitcnt lgkmcnt(0)
	global_load_dwordx4 v[58:61], v90, s[48:49] nt
	ds_write_b128 v200, v[46:49]
	ds_write_b128 v200, v[42:45] offset:64
	ds_read_b128 v[42:45], v201
	ds_read_b128 v[46:49], v201 offset:1152
	v_mov_b32_e32 v111, v163
	v_lshl_add_u64 v[98:99], s[48:49], 0, v[110:111]
	v_mov_b32_e32 v109, v163
	s_waitcnt vmcnt(13) lgkmcnt(1)
	v_pk_fma_f32 v[42:43], v[54:55], v[42:43], v[86:87]
	s_waitcnt vmcnt(12) lgkmcnt(0)
	v_pk_fma_f32 v[46:47], v[54:55], v[46:47], v[82:83]
	v_pk_fma_f32 v[44:45], v[56:57], v[44:45], v[88:89]
	v_pk_mul_f32 v[86:87], v[180:181], v[42:43]
	v_pk_fma_f32 v[48:49], v[56:57], v[48:49], v[84:85]
	v_pk_mul_f32 v[82:83], v[180:181], v[46:47]
	global_store_dwordx4 v[96:97], v[42:45], off nt
	v_pk_mul_f32 v[88:89], v[178:179], v[44:45]
	v_cvt_pk_bf16_f32 v86, v86, v87
	v_pk_mul_f32 v[84:85], v[178:179], v[48:49]
	v_cvt_pk_bf16_f32 v87, v88, v89
	global_store_dwordx4 v[98:99], v[46:49], off nt
	v_cvt_pk_bf16_f32 v82, v82, v83
	v_cvt_pk_bf16_f32 v83, v84, v85
	ds_write_b128 v200, v[38:41]
	ds_write_b128 v200, v[34:37] offset:64
	ds_read_b128 v[34:37], v201
	ds_read_b128 v[38:41], v201 offset:1152
	v_lshl_add_u64 v[84:85], s[48:49], 0, v[108:109]
	v_mov_b32_e32 v107, v163
	v_lshl_add_u64 v[88:89], s[48:49], 0, v[106:107]
	s_waitcnt vmcnt(13) lgkmcnt(1)
	v_pk_fma_f32 v[34:35], v[50:51], v[34:35], v[78:79]
	v_pk_fma_f32 v[36:37], v[52:53], v[36:37], v[80:81]
	v_pk_mul_f32 v[80:81], v[176:177], v[34:35]
	global_store_dwordx4 v[84:85], v[34:37], off nt
	v_pk_mul_f32 v[78:79], v[174:175], v[36:37]
	v_cvt_pk_bf16_f32 v80, v80, v81
	s_waitcnt vmcnt(13) lgkmcnt(0)
	v_pk_fma_f32 v[38:39], v[50:51], v[38:39], v[74:75]
	v_cvt_pk_bf16_f32 v81, v78, v79
	ds_bpermute_b32 v74, v203, v80
	ds_bpermute_b32 v75, v203, v81
	v_pk_fma_f32 v[40:41], v[52:53], v[40:41], v[76:77]
	v_pk_mul_f32 v[76:77], v[176:177], v[38:39]
	v_pk_mul_f32 v[78:79], v[174:175], v[40:41]
	global_store_dwordx4 v[88:89], v[38:41], off nt
	v_cvt_pk_bf16_f32 v76, v76, v77
	v_cvt_pk_bf16_f32 v77, v78, v79
	v_add_u32_e32 v79, 0x48000, v202
	v_lshlrev_b32_e32 v78, 1, v79
	s_waitcnt lgkmcnt(0)
	v_add_u32_e32 v250, 0xfffff040, v78
	v_cndmask_b32_e64 v250, v78, v250, s[40:41]
	v_cndmask_b32_e64 v248, v86, v74, s[40:41]
	v_cndmask_b32_e64 v249, v87, v75, s[40:41]
	global_store_dwordx2 v250, v[248:249], s[46:47]
	v_cndmask_b32_e64 v246, v74, v86, s[40:41]
	v_cndmask_b32_e64 v247, v75, v87, s[40:41]
	s_waitcnt lgkmcnt(1)
	v_add_u32_e32 v74, 0x1040, v78
	v_cndmask_b32_e64 v74, v78, v74, s[38:39]
	global_store_dwordx2 v74, v[246:247], s[46:47]
	ds_bpermute_b32 v74, v203, v76
	s_waitcnt lgkmcnt(1)
	ds_bpermute_b32 v75, v203, v77
	v_add_u32_e32 v77, 0x4c000, v202
	v_lshlrev_b32_e32 v76, 1, v77
	s_waitcnt lgkmcnt(0)
	v_add_u32_e32 v250, 0xfffff040, v76
	v_cndmask_b32_e64 v250, v76, v250, s[40:41]
	v_cndmask_b32_e64 v248, v82, v74, s[40:41]
	v_cndmask_b32_e64 v249, v83, v75, s[40:41]
	global_store_dwordx2 v250, v[248:249], s[46:47]
	v_cndmask_b32_e64 v246, v74, v82, s[40:41]
	v_cndmask_b32_e64 v247, v75, v83, s[40:41]
	v_mul_f32_e32 v35, v35, v35
	v_fmac_f32_e32 v35, v34, v34
	v_mul_f32_e32 v34, v37, v37
	v_mul_f32_e32 v45, v45, v45
	v_fmac_f32_e32 v34, v36, v36
	v_mul_f32_e32 v43, v43, v43
	v_fmac_f32_e32 v45, v44, v44
	v_mul_f32_e32 v44, v47, v47
	v_mul_f32_e32 v47, v49, v49
	v_add_f32_e32 v34, v35, v34
	v_mul_f32_e32 v35, v39, v39
	v_mul_f32_e32 v36, v41, v41
	v_fmac_f32_e32 v47, v48, v48
	v_fmac_f32_e32 v35, v38, v38
	v_fmac_f32_e32 v36, v40, v40
	v_fmac_f32_e32 v43, v42, v42
	v_fmac_f32_e32 v44, v46, v46
	v_add_f32_e32 v35, v35, v36
	v_add_f32_e32 v36, v43, v45
	v_add_f32_e32 v37, v44, v47
	v_add_f32_e32 v34, v36, v34
	v_add_f32_e32 v35, v37, v35
	ds_bpermute_b32 v36, v190, v34
	ds_bpermute_b32 v37, v190, v35
	s_waitcnt lgkmcnt(1)
	v_add_f32_e32 v34, v34, v36
	s_waitcnt lgkmcnt(0)
	v_add_f32_e32 v37, v35, v37
	ds_bpermute_b32 v36, v191, v34
	ds_bpermute_b32 v38, v191, v37
	s_waitcnt lgkmcnt(1)
	v_add_f32_e32 v34, v34, v36
	s_waitcnt lgkmcnt(0)
	v_add_f32_e32 v36, v37, v38
	ds_bpermute_b32 v35, v204, v34
	ds_bpermute_b32 v37, v204, v36
	v_add_u32_e32 v38, 0x1040, v76
	v_cndmask_b32_e64 v38, v76, v38, s[38:39]
	global_store_dwordx2 v38, v[246:247], s[46:47]
	s_and_saveexec_b64 s[16:17], s[42:43]
	s_cbranch_execz .LBB0_1313
	s_waitcnt lgkmcnt(1)
	v_add_f32_e32 v34, v34, v35
	s_waitcnt lgkmcnt(0)
	v_add_f32_e32 v35, v36, v37
	ds_write2_b32 v194, v34, v35 offset0:80 offset1:88
; #define LAS __attribute__((address_space(3)))
; #define ERN_EOFF(q, m) (eb + (unsigned)((((q) & 1) * HALF + (m) * 16) * DM + ERN_COL((q) >> 1)))
;     __device__ __forceinline__ void operator()(const f32x4 (&acc)[2][2][4][2], const Unit& u, int wr, int wc, int fr, int fq) const {
;     ...
;         for (int g = 0; g < 8; ++g) { const int ai = g >> 2, m = g & 3;
;             if (g + 1 < 8) ERN_LOADX(g + 1);
;             float sq0 = 0.f, sq1 = 0.f; u32x2 hw[2][2];
; #pragma unroll
;             for (int bj = 0; bj < 2; ++bj) {
;                 *(LAS f32x4*)(st + wr_off) = acc[ai][bj][m][0]; *(LAS f32x4*)(st + wr_off + 64) = acc[ai][bj][m][1];
;                 const f32x4 a0 = *(const LAS f32x4*)(st + rd_off), a1 = *(const LAS f32x4*)(st + rd_off + 8 * 144);
;                 { const f32x4 xv = xb[g & 1][bj][0] + gv[bj] * a0; __builtin_nontemporal_store(xv, (f32x4*)((char*)xo + 4u * ERN_EOFF(g, bj, 0)));
;                   sq0 += (xv.x * xv.x + xv.y * xv.y) + (xv.z * xv.z + xv.w * xv.w);
;                   const f32x4 hv = xv * gsn[bj]; hw[bj][0].x = cvt_pk_bf16(hv.x, hv.y); hw[bj][0].y = cvt_pk_bf16(hv.z, hv.w); }
;                 { const f32x4 xv = xb[g & 1][bj][1] + gv[bj] * a1; __builtin_nontemporal_store(xv, (f32x4*)((char*)xo + 4u * ERN_EOFF(g, bj, 1)));
;                   sq1 += (xv.x * xv.x + xv.y * xv.y) + (xv.z * xv.z + xv.w * xv.w);
;                   const f32x4 hv = xv * gsn[bj]; hw[bj][1].x = cvt_pk_bf16(hv.x, hv.y); hw[bj][1].y = cvt_pk_bf16(hv.z, hv.w); }
;             }
;             if (!NOH && !PLAIN) {
; #pragma unroll
;                 for (int rh = 0; rh < 2; ++rh) { u32x2 rv; rv.x = __shfl_xor(hw[1][rh].x, 8); rv.y = __shfl_xor(hw[1][rh].y, 8);
;                     const unsigned e0 = ERN_EOFF(g, 0, rh);
;                     const unsigned ee = odd ? (e0 - DM + 32) : e0, eo2 = odd ? e0 : (e0 + DM + 32);
;                     *(u32x2*)((char*)ho + 2u * ee) = odd ? rv : hw[0][rh];
;                     *(u32x2*)((char*)ho + 2u * eo2) = odd ? hw[0][rh] : rv; }
;             }
;             if (!PLAIN) { sq0 += __shfl_xor(sq0, 1); sq0 += __shfl_xor(sq0, 2); sq0 += __shfl_xor(sq0, 4);
;             sq1 += __shfl_xor(sq1, 1); sq1 += __shfl_xor(sq1, 2); sq1 += __shfl_xor(sq1, 4); }
;             if (!PLAIN && pc == 0) { sst[g * 16 + rr] = sq0; sst[g * 16 + 8 + rr] = sq1; }
.LBB0_1313:
	s_or_b64 exec, exec, s[16:17]
	v_lshl_add_u64 v[80:81], s[48:49], 0, v[162:163]
	v_add_u32_e32 v162, 0x160000, v205
	v_add_u32_e32 v76, 0x160080, v205
	v_add_u32_e32 v78, 0x170000, v205
	global_load_dwordx4 v[46:49], v162, s[48:49] nt
	global_load_dwordx4 v[42:45], v78, s[48:49] nt
	v_add_u32_e32 v74, 0x170080, v205
	global_load_dwordx4 v[38:41], v76, s[48:49] nt
	s_waitcnt lgkmcnt(0)
	global_load_dwordx4 v[34:37], v74, s[48:49] nt
	ds_write_b128 v200, v[30:33]
	ds_write_b128 v200, v[26:29] offset:64
	ds_read_b128 v[26:29], v201
	ds_read_b128 v[30:33], v201 offset:1152
	v_mov_b32_e32 v95, v163
	v_lshl_add_u64 v[82:83], s[48:49], 0, v[94:95]
	v_mov_b32_e32 v93, v163
	s_waitcnt vmcnt(13) lgkmcnt(1)
	v_pk_fma_f32 v[26:27], v[54:55], v[26:27], v[70:71]
	s_waitcnt vmcnt(12) lgkmcnt(0)
	v_pk_fma_f32 v[30:31], v[54:55], v[30:31], v[66:67]
	v_pk_fma_f32 v[28:29], v[56:57], v[28:29], v[72:73]
	v_pk_mul_f32 v[70:71], v[180:181], v[26:27]
	v_pk_fma_f32 v[32:33], v[56:57], v[32:33], v[68:69]
	v_pk_mul_f32 v[66:67], v[180:181], v[30:31]
	global_store_dwordx4 v[80:81], v[26:29], off nt
	v_pk_mul_f32 v[72:73], v[178:179], v[28:29]
	v_cvt_pk_bf16_f32 v70, v70, v71
	v_pk_mul_f32 v[68:69], v[178:179], v[32:33]
	v_cvt_pk_bf16_f32 v71, v72, v73
	global_store_dwordx4 v[82:83], v[30:33], off nt
	v_cvt_pk_bf16_f32 v66, v66, v67
	v_cvt_pk_bf16_f32 v67, v68, v69
	ds_write_b128 v200, v[22:25]
	ds_write_b128 v200, v[18:21] offset:64
	ds_read_b128 v[18:21], v201
	ds_read_b128 v[22:25], v201 offset:1152
	v_lshl_add_u64 v[68:69], s[48:49], 0, v[92:93]
	v_mov_b32_e32 v91, v163
	v_lshl_add_u64 v[72:73], s[48:49], 0, v[90:91]
	s_waitcnt vmcnt(13) lgkmcnt(1)
	v_pk_fma_f32 v[18:19], v[50:51], v[18:19], v[62:63]
	v_pk_fma_f32 v[20:21], v[52:53], v[20:21], v[64:65]
	v_pk_mul_f32 v[64:65], v[176:177], v[18:19]
	global_store_dwordx4 v[68:69], v[18:21], off nt
	v_pk_mul_f32 v[62:63], v[174:175], v[20:21]
	v_cvt_pk_bf16_f32 v64, v64, v65
	s_waitcnt vmcnt(13) lgkmcnt(0)
	v_pk_fma_f32 v[22:23], v[50:51], v[22:23], v[58:59]
	v_cvt_pk_bf16_f32 v65, v62, v63
	ds_bpermute_b32 v58, v203, v64
	ds_bpermute_b32 v59, v203, v65
	v_pk_fma_f32 v[24:25], v[52:53], v[24:25], v[60:61]
	v_pk_mul_f32 v[60:61], v[176:177], v[22:23]
	v_pk_mul_f32 v[62:63], v[174:175], v[24:25]
	global_store_dwordx4 v[72:73], v[22:25], off nt
	v_cvt_pk_bf16_f32 v60, v60, v61
	v_cvt_pk_bf16_f32 v61, v62, v63
	v_add_u32_e32 v63, 0x50000, v202
	v_lshlrev_b32_e32 v62, 1, v63
	s_waitcnt lgkmcnt(0)
	v_add_u32_e32 v250, 0xfffff040, v62
	v_cndmask_b32_e64 v250, v62, v250, s[40:41]
	v_cndmask_b32_e64 v248, v70, v58, s[40:41]
	v_cndmask_b32_e64 v249, v71, v59, s[40:41]
	global_store_dwordx2 v250, v[248:249], s[46:47]
	v_cndmask_b32_e64 v246, v58, v70, s[40:41]
	v_cndmask_b32_e64 v247, v59, v71, s[40:41]
	s_waitcnt lgkmcnt(1)
	v_add_u32_e32 v58, 0x1040, v62
	v_cndmask_b32_e64 v58, v62, v58, s[38:39]
	global_store_dwordx2 v58, v[246:247], s[46:47]
	ds_bpermute_b32 v58, v203, v60
	s_waitcnt lgkmcnt(1)
	ds_bpermute_b32 v59, v203, v61
	v_add_u32_e32 v61, 0x54000, v202
	v_lshlrev_b32_e32 v60, 1, v61
	s_waitcnt lgkmcnt(0)
	v_add_u32_e32 v250, 0xfffff040, v60
	v_cndmask_b32_e64 v250, v60, v250, s[40:41]
	v_cndmask_b32_e64 v248, v66, v58, s[40:41]
	v_cndmask_b32_e64 v249, v67, v59, s[40:41]
	global_store_dwordx2 v250, v[248:249], s[46:47]
	v_cndmask_b32_e64 v246, v58, v66, s[40:41]
	v_cndmask_b32_e64 v247, v59, v67, s[40:41]
	v_mul_f32_e32 v19, v19, v19
	v_fmac_f32_e32 v19, v18, v18
	v_mul_f32_e32 v18, v21, v21
	v_mul_f32_e32 v29, v29, v29
	v_fmac_f32_e32 v18, v20, v20
	v_mul_f32_e32 v27, v27, v27
	v_fmac_f32_e32 v29, v28, v28
	v_mul_f32_e32 v28, v31, v31
	v_mul_f32_e32 v31, v33, v33
	v_add_f32_e32 v18, v19, v18
	v_mul_f32_e32 v19, v23, v23
	v_mul_f32_e32 v20, v25, v25
	v_fmac_f32_e32 v31, v32, v32
	v_fmac_f32_e32 v19, v22, v22
	v_fmac_f32_e32 v20, v24, v24
	v_fmac_f32_e32 v27, v26, v26
	v_fmac_f32_e32 v28, v30, v30
	v_add_f32_e32 v19, v19, v20
	v_add_f32_e32 v20, v27, v29
	v_add_f32_e32 v21, v28, v31
	v_add_f32_e32 v18, v20, v18
	v_add_f32_e32 v19, v21, v19
	ds_bpermute_b32 v20, v190, v18
	ds_bpermute_b32 v21, v190, v19
	s_waitcnt lgkmcnt(1)
	v_add_f32_e32 v18, v18, v20
	s_waitcnt lgkmcnt(0)
	v_add_f32_e32 v21, v19, v21
	ds_bpermute_b32 v20, v191, v18
	ds_bpermute_b32 v22, v191, v21
	s_waitcnt lgkmcnt(1)
	v_add_f32_e32 v18, v18, v20
	s_waitcnt lgkmcnt(0)
	v_add_f32_e32 v20, v21, v22
	ds_bpermute_b32 v19, v204, v18
	ds_bpermute_b32 v21, v204, v20
	v_add_u32_e32 v22, 0x1040, v60
	v_cndmask_b32_e64 v22, v60, v22, s[38:39]
	global_store_dwordx2 v22, v[246:247], s[46:47]
	s_and_saveexec_b64 s[16:17], s[42:43]
	s_cbranch_execz .LBB0_1323
	s_waitcnt lgkmcnt(1)
	v_add_f32_e32 v18, v18, v19
	s_waitcnt lgkmcnt(0)
	v_add_f32_e32 v19, v20, v21
	ds_write2_b32 v194, v18, v19 offset0:96 offset1:104

; #define LAS __attribute__((address_space(3)))
;     __device__ __forceinline__ void operator()(const f32x4 (&acc)[2][2][4][2], const Unit& u, int wr, int wc, int fr, int fq) const {
;         const int s = u.pm >> 5, lane = fq * 16 + fr, rr = lane >> 3, pc = lane & 7;
;         const float* __restrict__ xi = xin + (size_t)u.pm * BM * DM; float* __restrict__ xo = xout + (size_t)u.pm * BM * DM; bf16_t* __restrict__ ho = Hn + (size_t)u.pm * BM * DM;
;         LAS unsigned char* st = lds_epi + (wr * 4 + wc) * 2304;
;         LAS float* sst = (LAS float*)(lds_epi + 18432 + (wr * 4 + wc) * 512);
;         const int colr = u.pn * BM + wc * 64 + 4 * pc;
;         const unsigned eb = (unsigned)((wr * 64 + rr) * DM + colr);
;         f32x4 gv[2], gsn[2];
; #pragma unroll
;         for (int bj = 0; bj < 2; ++bj) { gv[bj] = *(const f32x4*)(gate + (size_t)s * MODW + colr + bj * 32) * (0.5f * GS2);
;             if (!PLAIN) gsn[bj] = *(const f32x4*)(gnext + colr + bj * 32) * (*(const f32x4*)(scnext + (size_t)s * MODW + colr + bj * 32) + 1.0f); else gsn[bj] = gv[bj]; }
;         const unsigned wr_off = (unsigned)(fr * 144 + 16 * fq), rd_off = (unsigned)(rr * 144 + pc * 16);
;         const bool odd = (rr & 1) != 0;
;         f32x4 xb[2][2][2];
;     ...
;         ERN_LOADX(0);
; #pragma unroll
;         for (int g = 0; g < 8; ++g) { const int ai = g >> 2, m = g & 3;
;             if (g + 1 < 8) ERN_LOADX(g + 1);
;             float sq0 = 0.f, sq1 = 0.f; u32x2 hw[2][2];
; #pragma unroll
;             for (int bj = 0; bj < 2; ++bj) {
;                 *(LAS f32x4*)(st + wr_off) = acc[ai][bj][m][0]; *(LAS f32x4*)(st + wr_off + 64) = acc[ai][bj][m][1];
;                 const f32x4 a0 = *(const LAS f32x4*)(st + rd_off), a1 = *(const LAS f32x4*)(st + rd_off + 8 * 144);
;                 { const f32x4 xv = xb[g & 1][bj][0] + gv[bj] * a0; __builtin_nontemporal_store(xv, (f32x4*)((char*)xo + 4u * ERN_EOFF(g, bj, 0)));
;                   sq0 += (xv.x * xv.x + xv.y * xv.y) + (xv.z * xv.z + xv.w * xv.w);
;                   const f32x4 hv = xv * gsn[bj]; hw[bj][0].x = cvt_pk_bf16(hv.x, hv.y); hw[bj][0].y = cvt_pk_bf16(hv.z, hv.w); }
;                 { const f32x4 xv = xb[g & 1][bj][1] + gv[bj] * a1; __builtin_nontemporal_store(xv, (f32x4*)((char*)xo + 4u * ERN_EOFF(g, bj, 1)));
;                   sq1 += (xv.x * xv.x + xv.y * xv.y) + (xv.z * xv.z + xv.w * xv.w);
.LBB0_1598:
	s_ashr_i32 s16, s8, 5
	s_ashr_i32 s9, s8, 31
	v_lshl_or_b32 v130, s0, 8, v192
	s_mul_i32 s20, s16, 0x12000
	s_mul_hi_i32 s0, s16, 0x12000
	s_add_u32 s16, s37, s20
	v_ashrrev_i32_e32 v131, 31, v130
	s_addc_u32 s17, s48, s0
	v_lshlrev_b64 v[132:133], 2, v[130:131]
	v_lshl_add_u64 v[134:135], s[16:17], 0, v[132:133]
	s_add_u32 s16, s26, s20
	s_addc_u32 s17, s27, s0
	v_lshl_add_u64 v[136:137], s[4:5], 0, v[132:133]
	v_lshl_add_u64 v[132:133], s[16:17], 0, v[132:133]
	s_lshl_b64 s[16:17], s[8:9], 21
	s_add_u32 s22, s90, s16
	v_add_u32_e32 v202, v130, v193
	s_addc_u32 s23, s91, s17
	v_lshlrev_b32_e32 v205, 2, v202
	global_load_dwordx4 v[170:173], v[136:137], off
	global_load_dwordx4 v[166:169], v[134:135], off
	global_load_dwordx4 v[186:189], v[134:135], off offset:128
	global_load_dwordx4 v[206:209], v[132:133], off
	global_load_dwordx4 v[210:213], v[132:133], off offset:128
	global_load_dwordx4 v[214:217], v205, s[22:23] nt
	v_add_u32_e32 v130, 0x10000, v205
	global_load_dwordx4 v[218:221], v130, s[22:23] nt
	global_load_dwordx4 v[222:225], v[136:137], off offset:128
	global_load_dwordx4 v[226:229], v205, s[22:23] offset:128 nt
	v_add_u32_e32 v204, 0x10080, v205
	global_load_dwordx4 v[230:233], v204, s[22:23] nt
	v_add_u32_e32 v130, 0x20000, v205
	v_add_u32_e32 v154, 0x30000, v205
	v_add_u32_e32 v184, 0x20080, v205
	v_add_u32_e32 v182, 0x30080, v205
	global_load_dwordx4 v[142:145], v130, s[22:23] nt
	global_load_dwordx4 v[138:141], v154, s[22:23] nt
	global_load_dwordx4 v[134:137], v184, s[22:23] nt
	s_nop 0
	global_load_dwordx4 v[130:133], v182, s[22:23] nt
	ds_write_b128 v200, v[126:129]
	ds_write_b128 v200, v[122:125] offset:64
	v_and_b32_e32 v127, 64, v199
	ds_read_b128 v[122:125], v201
	ds_read_b128 v[234:237], v201 offset:1152
	v_xor_b32_e32 v126, 8, v199
	v_add_u32_e32 v183, 64, v127
	v_cmp_lt_i32_e32 vcc, v126, v183
	v_add_u32_e32 v185, 0x4000, v202
	v_lshlrev_b32_e32 v238, 2, v185
	v_cndmask_b32_e32 v126, v199, v126, vcc
	v_lshlrev_b32_e32 v203, 2, v126
	s_lshl_b64 s[16:17], s[8:9], 20
	s_add_u32 s20, s93, s16
	s_addc_u32 s21, s92, s17
	s_waitcnt vmcnt(0)
	v_pk_mul_f32 v[180:181], v[166:167], 0.5 op_sel_hi:[1,0]
	v_pk_mul_f32 v[176:177], v[168:169], 0.5 op_sel_hi:[1,0]
	v_pk_add_f32 v[126:127], v[208:209], 1.0 op_sel_hi:[1,0]
	v_pk_add_f32 v[128:129], v[206:207], 1.0 op_sel_hi:[1,0]
	v_pk_mul_f32 v[174:175], v[172:173], v[126:127]
	v_pk_mul_f32 v[178:179], v[170:171], v[128:129]
	s_waitcnt lgkmcnt(1)
	v_pk_fma_f32 v[126:127], v[180:181], v[122:123], v[214:215]
	s_waitcnt lgkmcnt(0)
	v_pk_fma_f32 v[122:123], v[180:181], v[234:235], v[218:219]
	v_pk_mul_f32 v[168:169], v[186:187], 0.5 op_sel_hi:[1,0]
	v_pk_fma_f32 v[128:129], v[176:177], v[124:125], v[216:217]
	v_pk_fma_f32 v[124:125], v[176:177], v[236:237], v[220:221]
	v_pk_mul_f32 v[186:187], v[178:179], v[122:123]
	v_pk_mul_f32 v[166:167], v[188:189], 0.5 op_sel_hi:[1,0]
	global_store_dwordx4 v205, v[126:129], s[22:23] nt
	v_pk_mul_f32 v[170:171], v[174:175], v[128:129]
	v_pk_mul_f32 v[172:173], v[178:179], v[126:127]
	v_pk_mul_f32 v[206:207], v[174:175], v[124:125]
	v_cvt_pk_bf16_f32 v188, v172, v173
	v_cvt_pk_bf16_f32 v189, v170, v171
	global_store_dwordx4 v238, v[122:125], s[22:23] nt
	v_cvt_pk_bf16_f32 v186, v186, v187
	v_cvt_pk_bf16_f32 v187, v206, v207
	ds_write_b128 v200, v[118:121]
	ds_write_b128 v200, v[114:117] offset:64
	ds_read_b128 v[114:117], v201
	ds_read_b128 v[206:209], v201 offset:1152
	v_pk_add_f32 v[190:191], v[212:213], 1.0 op_sel_hi:[1,0]
	v_pk_add_f32 v[118:119], v[210:211], 1.0 op_sel_hi:[1,0]
	v_pk_mul_f32 v[170:171], v[224:225], v[190:191]
	v_pk_mul_f32 v[172:173], v[222:223], v[118:119]
	s_waitcnt lgkmcnt(1)
	v_pk_fma_f32 v[120:121], v[166:167], v[116:117], v[228:229]
	v_pk_fma_f32 v[118:119], v[168:169], v[114:115], v[226:227]
	s_waitcnt lgkmcnt(0)
	v_pk_fma_f32 v[114:115], v[168:169], v[206:207], v[230:231]
	v_pk_mul_f32 v[190:191], v[170:171], v[120:121]
	v_pk_mul_f32 v[206:207], v[172:173], v[118:119]
	global_store_dwordx4 v205, v[118:121], s[22:23] offset:128 nt
	v_cvt_pk_bf16_f32 v206, v206, v207
	v_cvt_pk_bf16_f32 v191, v190, v191
	ds_bpermute_b32 v190, v203, v206
	ds_bpermute_b32 v191, v203, v191
	v_pk_fma_f32 v[116:117], v[166:167], v[208:209], v[232:233]
	v_pk_mul_f32 v[206:207], v[172:173], v[114:115]
	global_store_dwordx4 v204, v[114:117], s[22:23] nt
	v_cvt_pk_bf16_f32 v204, v206, v207
	v_lshlrev_b32_e32 v207, 1, v202
	v_pk_mul_f32 v[208:209], v[170:171], v[116:117]
	s_nop 0
	v_cvt_pk_bf16_f32 v206, v208, v209
	s_waitcnt lgkmcnt(0)
	v_add_u32_e32 v250, 0xfffff040, v207
	v_cndmask_b32_e64 v250, v207, v250, s[40:41]
	v_cndmask_b32_e64 v248, v188, v190, s[40:41]
	v_cndmask_b32_e64 v249, v189, v191, s[40:41]
	global_store_dwordx2 v250, v[248:249], s[20:21]
	v_cndmask_b32_e64 v246, v190, v188, s[40:41]
	v_cndmask_b32_e64 v247, v191, v189, s[40:41]
	s_waitcnt lgkmcnt(1)
	v_add_u32_e32 v190, 0x1040, v207
	v_cndmask_b32_e64 v190, v207, v190, s[38:39]
	global_store_dwordx2 v190, v[246:247], s[20:21]
	ds_bpermute_b32 v188, v203, v204
	ds_bpermute_b32 v189, v203, v206
	v_lshlrev_b32_e32 v206, 1, v185
	s_waitcnt lgkmcnt(0)
; #define LAS __attribute__((address_space(3)))
; #define ERN_EOFF(q, m) (eb + (unsigned)((((q) & 1) * HALF + (m) * 16) * DM + ERN_COL((q) >> 1)))
;     __device__ __forceinline__ void operator()(const f32x4 (&acc)[2][2][4][2], const Unit& u, int wr, int wc, int fr, int fq) const {
;     ...
;         for (int g = 0; g < 8; ++g) { const int ai = g >> 2, m = g & 3;
;             if (g + 1 < 8) ERN_LOADX(g + 1);
;             float sq0 = 0.f, sq1 = 0.f; u32x2 hw[2][2];
; #pragma unroll
;             for (int bj = 0; bj < 2; ++bj) {
;                 *(LAS f32x4*)(st + wr_off) = acc[ai][bj][m][0]; *(LAS f32x4*)(st + wr_off + 64) = acc[ai][bj][m][1];
;                 const f32x4 a0 = *(const LAS f32x4*)(st + rd_off), a1 = *(const LAS f32x4*)(st + rd_off + 8 * 144);
;                 { const f32x4 xv = xb[g & 1][bj][0] + gv[bj] * a0; __builtin_nontemporal_store(xv, (f32x4*)((char*)xo + 4u * ERN_EOFF(g, bj, 0)));
;                   sq0 += (xv.x * xv.x + xv.y * xv.y) + (xv.z * xv.z + xv.w * xv.w);
;                   const f32x4 hv = xv * gsn[bj]; hw[bj][0].x = cvt_pk_bf16(hv.x, hv.y); hw[bj][0].y = cvt_pk_bf16(hv.z, hv.w); }
;                 { const f32x4 xv = xb[g & 1][bj][1] + gv[bj] * a1; __builtin_nontemporal_store(xv, (f32x4*)((char*)xo + 4u * ERN_EOFF(g, bj, 1)));
;                   sq1 += (xv.x * xv.x + xv.y * xv.y) + (xv.z * xv.z + xv.w * xv.w);
;                   const f32x4 hv = xv * gsn[bj]; hw[bj][1].x = cvt_pk_bf16(hv.x, hv.y); hw[bj][1].y = cvt_pk_bf16(hv.z, hv.w); }
;             }
;             if (!NOH && !PLAIN) {
; #pragma unroll
;                 for (int rh = 0; rh < 2; ++rh) { u32x2 rv; rv.x = __shfl_xor(hw[1][rh].x, 8); rv.y = __shfl_xor(hw[1][rh].y, 8);
;                     const unsigned e0 = ERN_EOFF(g, 0, rh);
;                     const unsigned ee = odd ? (e0 - DM + 32) : e0, eo2 = odd ? e0 : (e0 + DM + 32);
;                     *(u32x2*)((char*)ho + 2u * ee) = odd ? rv : hw[0][rh];
;                     *(u32x2*)((char*)ho + 2u * eo2) = odd ? hw[0][rh] : rv; }
;             }
;             if (!PLAIN) { sq0 += __shfl_xor(sq0, 1); sq0 += __shfl_xor(sq0, 2); sq0 += __shfl_xor(sq0, 4);
;             sq1 += __shfl_xor(sq1, 1); sq1 += __shfl_xor(sq1, 2); sq1 += __shfl_xor(sq1, 4); }
;             if (!PLAIN && pc == 0) { sst[g * 16 + rr] = sq0; sst[g * 16 + 8 + rr] = sq1; }
	v_add_u32_e32 v250, 0xfffff040, v206
	v_cndmask_b32_e64 v250, v206, v250, s[40:41]
	v_cndmask_b32_e64 v248, v186, v188, s[40:41]
	v_cndmask_b32_e64 v249, v187, v189, s[40:41]
	global_store_dwordx2 v250, v[248:249], s[20:21]
	v_cndmask_b32_e64 v246, v188, v186, s[40:41]
	v_cndmask_b32_e64 v247, v189, v187, s[40:41]
	v_mul_f32_e32 v119, v119, v119
	v_mul_f32_e32 v127, v127, v127
	v_mul_f32_e32 v129, v129, v129
	v_fmac_f32_e32 v119, v118, v118
	v_mul_f32_e32 v118, v121, v121
	v_fmac_f32_e32 v129, v128, v128
	v_fmac_f32_e32 v118, v120, v120
	v_mul_f32_e32 v115, v115, v115
	v_fmac_f32_e32 v127, v126, v126
	v_add_f32_e32 v118, v119, v118
	v_fmac_f32_e32 v115, v114, v114
	v_mul_f32_e32 v114, v117, v117
	v_add_f32_e32 v117, v127, v129
	v_add_f32_e32 v117, v117, v118
	v_xor_b32_e32 v118, 1, v199
	v_cmp_lt_i32_e32 vcc, v118, v183
	v_mul_f32_e32 v123, v123, v123
	v_mul_f32_e32 v125, v125, v125
	v_cndmask_b32_e32 v118, v199, v118, vcc
	v_lshlrev_b32_e32 v190, 2, v118
	ds_bpermute_b32 v118, v190, v117
	v_fmac_f32_e32 v114, v116, v116
	v_fmac_f32_e32 v125, v124, v124
	v_fmac_f32_e32 v123, v122, v122
	v_add_f32_e32 v114, v115, v114
	s_waitcnt lgkmcnt(0)
	v_add_f32_e32 v116, v117, v118
	v_xor_b32_e32 v117, 2, v199
	v_cmp_lt_i32_e32 vcc, v117, v183
	v_add_f32_e32 v115, v123, v125
	v_add_f32_e32 v115, v115, v114
	v_cndmask_b32_e32 v117, v199, v117, vcc
	v_lshlrev_b32_e32 v191, 2, v117
	ds_bpermute_b32 v117, v191, v116
	ds_bpermute_b32 v118, v190, v115
	s_waitcnt lgkmcnt(1)
	v_add_f32_e32 v114, v116, v117
	s_waitcnt lgkmcnt(0)
	v_add_f32_e32 v117, v115, v118
	ds_bpermute_b32 v118, v191, v117
	v_xor_b32_e32 v116, 4, v199
	v_cmp_lt_i32_e32 vcc, v116, v183
	s_nop 1
	v_cndmask_b32_e32 v115, v199, v116, vcc
	v_lshlrev_b32_e32 v204, 2, v115
	s_waitcnt lgkmcnt(0)
	v_add_f32_e32 v116, v117, v118
	ds_bpermute_b32 v115, v204, v114
	ds_bpermute_b32 v117, v204, v116
	v_add_u32_e32 v118, 0x1040, v206
	v_cndmask_b32_e64 v118, v206, v118, s[38:39]
	global_store_dwordx2 v118, v[246:247], s[20:21]
	s_and_saveexec_b64 s[16:17], s[42:43]
	s_cbranch_execz .LBB0_1608
	s_waitcnt lgkmcnt(1)
	v_add_f32_e32 v114, v114, v115
	s_waitcnt lgkmcnt(0)
	v_add_f32_e32 v115, v116, v117
	ds_write2_b32 v194, v114, v115 offset1:8
.LBB0_1608:
	s_or_b64 exec, exec, s[16:17]
	v_lshl_add_u64 v[206:207], s[22:23], 0, v[154:155]
	v_add_u32_e32 v114, 0x40000, v205
	v_add_u32_e32 v154, 0x50000, v205
	v_add_u32_e32 v186, 0x40080, v205
	global_load_dwordx4 v[122:125], v154, s[22:23] nt
	global_load_dwordx4 v[118:121], v186, s[22:23] nt
	v_add_u32_e32 v188, 0x50080, v205
	global_load_dwordx4 v[126:129], v114, s[22:23] nt
	s_waitcnt lgkmcnt(0)
	global_load_dwordx4 v[114:117], v188, s[22:23] nt
	ds_write_b128 v200, v[110:113]
	ds_write_b128 v200, v[106:109] offset:64
	ds_read_b128 v[106:109], v201
	ds_read_b128 v[110:113], v201 offset:1152
	v_mov_b32_e32 v185, v155
	v_mov_b32_e32 v183, v155
	v_lshl_add_u64 v[182:183], s[22:23], 0, v[182:183]
	s_waitcnt lgkmcnt(1)
	v_pk_fma_f32 v[108:109], v[176:177], v[108:109], v[144:145]
	v_add_u32_e32 v144, 0x8000, v202
	v_pk_fma_f32 v[106:107], v[180:181], v[106:107], v[142:143]
	v_lshlrev_b32_e32 v142, 2, v144
	s_waitcnt lgkmcnt(0)
	v_pk_fma_f32 v[110:111], v[180:181], v[110:111], v[138:139]
	global_store_dwordx4 v142, v[106:109], s[22:23] nt
	v_pk_mul_f32 v[142:143], v[178:179], v[106:107]
	v_pk_fma_f32 v[112:113], v[176:177], v[112:113], v[140:141]
	v_pk_mul_f32 v[138:139], v[178:179], v[110:111]
	v_pk_mul_f32 v[208:209], v[174:175], v[108:109]
	v_cvt_pk_bf16_f32 v142, v142, v143
	v_pk_mul_f32 v[140:141], v[174:175], v[112:113]
	v_cvt_pk_bf16_f32 v143, v208, v209
	global_store_dwordx4 v[206:207], v[110:113], off nt
	v_cvt_pk_bf16_f32 v138, v138, v139
	v_cvt_pk_bf16_f32 v139, v140, v141
	ds_write_b128 v200, v[102:105]
	ds_write_b128 v200, v[98:101] offset:64
	ds_read_b128 v[98:101], v201
	ds_read_b128 v[102:105], v201 offset:1152
	v_lshl_add_u64 v[140:141], s[22:23], 0, v[184:185]
	s_waitcnt lgkmcnt(1)
	v_pk_fma_f32 v[98:99], v[168:169], v[98:99], v[134:135]
	v_pk_fma_f32 v[100:101], v[166:167], v[100:101], v[136:137]
	v_pk_mul_f32 v[136:137], v[172:173], v[98:99]
	global_store_dwordx4 v[140:141], v[98:101], off nt
	v_pk_mul_f32 v[134:135], v[170:171], v[100:101]
	v_cvt_pk_bf16_f32 v136, v136, v137
	s_waitcnt lgkmcnt(0)
	v_pk_fma_f32 v[102:103], v[168:169], v[102:103], v[130:131]
	v_cvt_pk_bf16_f32 v137, v134, v135
	ds_bpermute_b32 v130, v203, v136
	ds_bpermute_b32 v131, v203, v137
	v_pk_fma_f32 v[104:105], v[166:167], v[104:105], v[132:133]
	v_pk_mul_f32 v[132:133], v[172:173], v[102:103]
	v_pk_mul_f32 v[134:135], v[170:171], v[104:105]
	global_store_dwordx4 v[182:183], v[102:105], off nt
	v_cvt_pk_bf16_f32 v132, v132, v133
	v_cvt_pk_bf16_f32 v133, v134, v135
	v_lshlrev_b32_e32 v134, 1, v144
	s_waitcnt lgkmcnt(0)
	v_add_u32_e32 v250, 0xfffff040, v134
	v_cndmask_b32_e64 v250, v134, v250, s[40:41]
	v_cndmask_b32_e64 v248, v142, v130, s[40:41]
	v_cndmask_b32_e64 v249, v143, v131, s[40:41]
	global_store_dwordx2 v250, v[248:249], s[20:21]
	v_cndmask_b32_e64 v246, v130, v142, s[40:41]
	v_cndmask_b32_e64 v247, v131, v143, s[40:41]
	s_waitcnt lgkmcnt(1)
	v_add_u32_e32 v130, 0x1040, v134
	v_cndmask_b32_e64 v130, v134, v130, s[38:39]
	global_store_dwordx2 v130, v[246:247], s[20:21]
	ds_bpermute_b32 v130, v203, v132
	s_waitcnt lgkmcnt(1)
	ds_bpermute_b32 v131, v203, v133
	v_add_u32_e32 v133, 0xc000, v202
	v_lshlrev_b32_e32 v132, 1, v133
	s_waitcnt lgkmcnt(0)
	v_add_u32_e32 v250, 0xfffff040, v132
	v_cndmask_b32_e64 v250, v132, v250, s[40:41]
	v_cndmask_b32_e64 v248, v138, v130, s[40:41]
	v_cndmask_b32_e64 v249, v139, v131, s[40:41]
	global_store_dwordx2 v250, v[248:249], s[20:21]
	v_cndmask_b32_e64 v246, v130, v138, s[40:41]
	v_cndmask_b32_e64 v247, v131, v139, s[40:41]
	v_mul_f32_e32 v99, v99, v99
	v_fmac_f32_e32 v99, v98, v98
	v_mul_f32_e32 v98, v101, v101
	v_mul_f32_e32 v109, v109, v109
	v_fmac_f32_e32 v98, v100, v100
	v_mul_f32_e32 v107, v107, v107
	v_fmac_f32_e32 v109, v108, v108
	v_mul_f32_e32 v108, v111, v111
	v_mul_f32_e32 v111, v113, v113
	v_add_f32_e32 v98, v99, v98
	v_mul_f32_e32 v99, v103, v103
	v_mul_f32_e32 v100, v105, v105
	v_fmac_f32_e32 v111, v112, v112
	v_fmac_f32_e32 v99, v102, v102
	v_fmac_f32_e32 v100, v104, v104
	v_fmac_f32_e32 v107, v106, v106
	v_fmac_f32_e32 v108, v110, v110
	v_add_f32_e32 v99, v99, v100
	v_add_f32_e32 v100, v107, v109
	v_add_f32_e32 v101, v108, v111
	v_add_f32_e32 v98, v100, v98
	v_add_f32_e32 v99, v101, v99
	ds_bpermute_b32 v100, v190, v98
	ds_bpermute_b32 v101, v190, v99
	s_waitcnt lgkmcnt(1)
	v_add_f32_e32 v98, v98, v100
	s_waitcnt lgkmcnt(0)
	v_add_f32_e32 v101, v99, v101
	ds_bpermute_b32 v100, v191, v98
	ds_bpermute_b32 v102, v191, v101
	s_waitcnt lgkmcnt(1)
	v_add_f32_e32 v98, v98, v100
	s_waitcnt lgkmcnt(0)
	v_add_f32_e32 v100, v101, v102
	ds_bpermute_b32 v99, v204, v98
	ds_bpermute_b32 v101, v204, v100
	v_add_u32_e32 v102, 0x1040, v132
	v_cndmask_b32_e64 v102, v132, v102, s[38:39]
	global_store_dwordx2 v102, v[246:247], s[20:21]
	s_and_saveexec_b64 s[16:17], s[42:43]
	s_cbranch_execz .LBB0_1618
; #define LAS __attribute__((address_space(3)))
; #define ERN_EOFF(q, m) (eb + (unsigned)((((q) & 1) * HALF + (m) * 16) * DM + ERN_COL((q) >> 1)))
;     __device__ __forceinline__ void operator()(const f32x4 (&acc)[2][2][4][2], const Unit& u, int wr, int wc, int fr, int fq) const {
;     ...
;         ERN_LOADX(0);
; #pragma unroll
;         for (int g = 0; g < 8; ++g) { const int ai = g >> 2, m = g & 3;
;             if (g + 1 < 8) ERN_LOADX(g + 1);
;             float sq0 = 0.f, sq1 = 0.f; u32x2 hw[2][2];
; #pragma unroll
;             for (int bj = 0; bj < 2; ++bj) {
;                 *(LAS f32x4*)(st + wr_off) = acc[ai][bj][m][0]; *(LAS f32x4*)(st + wr_off + 64) = acc[ai][bj][m][1];
;                 const f32x4 a0 = *(const LAS f32x4*)(st + rd_off), a1 = *(const LAS f32x4*)(st + rd_off + 8 * 144);
;                 { const f32x4 xv = xb[g & 1][bj][0] + gv[bj] * a0; __builtin_nontemporal_store(xv, (f32x4*)((char*)xo + 4u * ERN_EOFF(g, bj, 0)));
;                   sq0 += (xv.x * xv.x + xv.y * xv.y) + (xv.z * xv.z + xv.w * xv.w);
;                   const f32x4 hv = xv * gsn[bj]; hw[bj][0].x = cvt_pk_bf16(hv.x, hv.y); hw[bj][0].y = cvt_pk_bf16(hv.z, hv.w); }
;                 { const f32x4 xv = xb[g & 1][bj][1] + gv[bj] * a1; __builtin_nontemporal_store(xv, (f32x4*)((char*)xo + 4u * ERN_EOFF(g, bj, 1)));
;                   sq1 += (xv.x * xv.x + xv.y * xv.y) + (xv.z * xv.z + xv.w * xv.w);
;                   const f32x4 hv = xv * gsn[bj]; hw[bj][1].x = cvt_pk_bf16(hv.x, hv.y); hw[bj][1].y = cvt_pk_bf16(hv.z, hv.w); }
;             }
;             if (!NOH && !PLAIN) {
; #pragma unroll
;                 for (int rh = 0; rh < 2; ++rh) { u32x2 rv; rv.x = __shfl_xor(hw[1][rh].x, 8); rv.y = __shfl_xor(hw[1][rh].y, 8);
;                     const unsigned e0 = ERN_EOFF(g, 0, rh);
;                     const unsigned ee = odd ? (e0 - DM + 32) : e0, eo2 = odd ? e0 : (e0 + DM + 32);
;                     *(u32x2*)((char*)ho + 2u * ee) = odd ? rv : hw[0][rh];
;                     *(u32x2*)((char*)ho + 2u * eo2) = odd ? hw[0][rh] : rv; }
;             }
;             if (!PLAIN) { sq0 += __shfl_xor(sq0, 1); sq0 += __shfl_xor(sq0, 2); sq0 += __shfl_xor(sq0, 4);
;             sq1 += __shfl_xor(sq1, 1); sq1 += __shfl_xor(sq1, 2); sq1 += __shfl_xor(sq1, 4); }
;             if (!PLAIN && pc == 0) { sst[g * 16 + rr] = sq0; sst[g * 16 + 8 + rr] = sq1; }
;         }
	s_waitcnt lgkmcnt(1)
	v_add_f32_e32 v98, v98, v99
	s_waitcnt lgkmcnt(0)
	v_add_f32_e32 v99, v100, v101
	ds_write2_b32 v194, v98, v99 offset0:16 offset1:24
.LBB0_1618:
	s_or_b64 exec, exec, s[16:17]
	v_lshl_add_u64 v[134:135], s[22:23], 0, v[154:155]
	v_add_u32_e32 v98, 0x60000, v205
	v_add_u32_e32 v154, 0x70000, v205
	v_add_u32_e32 v130, 0x60080, v205
	global_load_dwordx4 v[106:109], v154, s[22:23] nt
	global_load_dwordx4 v[102:105], v130, s[22:23] nt
	v_add_u32_e32 v132, 0x70080, v205
	global_load_dwordx4 v[110:113], v98, s[22:23] nt
	s_waitcnt lgkmcnt(0)
	global_load_dwordx4 v[98:101], v132, s[22:23] nt
	ds_write_b128 v200, v[94:97]
	ds_write_b128 v200, v[90:93] offset:64
	ds_read_b128 v[90:93], v201
	ds_read_b128 v[94:97], v201 offset:1152
	v_mov_b32_e32 v187, v155
	v_mov_b32_e32 v189, v155
	s_waitcnt vmcnt(11) lgkmcnt(1)
	v_pk_fma_f32 v[92:93], v[176:177], v[92:93], v[128:129]
	v_add_u32_e32 v128, 0x10000, v202
	v_pk_fma_f32 v[90:91], v[180:181], v[90:91], v[126:127]
	v_lshlrev_b32_e32 v126, 2, v128
	s_waitcnt lgkmcnt(0)
	v_pk_fma_f32 v[94:95], v[180:181], v[94:95], v[122:123]
	global_store_dwordx4 v126, v[90:93], s[22:23] nt
	v_pk_mul_f32 v[126:127], v[178:179], v[90:91]
	v_pk_fma_f32 v[96:97], v[176:177], v[96:97], v[124:125]
	v_pk_mul_f32 v[122:123], v[178:179], v[94:95]
	v_pk_mul_f32 v[136:137], v[174:175], v[92:93]
	v_cvt_pk_bf16_f32 v126, v126, v127
	v_pk_mul_f32 v[124:125], v[174:175], v[96:97]
	v_cvt_pk_bf16_f32 v127, v136, v137
	global_store_dwordx4 v[134:135], v[94:97], off nt
	v_cvt_pk_bf16_f32 v122, v122, v123
	v_cvt_pk_bf16_f32 v123, v124, v125
	ds_write_b128 v200, v[86:89]
	ds_write_b128 v200, v[82:85] offset:64
	ds_read_b128 v[82:85], v201
	ds_read_b128 v[86:89], v201 offset:1152
	v_lshl_add_u64 v[124:125], s[22:23], 0, v[186:187]
	v_lshl_add_u64 v[134:135], s[22:23], 0, v[188:189]
	s_waitcnt lgkmcnt(1)
	v_pk_fma_f32 v[82:83], v[168:169], v[82:83], v[118:119]
	v_pk_fma_f32 v[84:85], v[166:167], v[84:85], v[120:121]
	v_pk_mul_f32 v[120:121], v[172:173], v[82:83]
	global_store_dwordx4 v[124:125], v[82:85], off nt
	v_pk_mul_f32 v[118:119], v[170:171], v[84:85]
	v_cvt_pk_bf16_f32 v120, v120, v121
	s_waitcnt vmcnt(13) lgkmcnt(0)
	v_pk_fma_f32 v[86:87], v[168:169], v[86:87], v[114:115]
	v_cvt_pk_bf16_f32 v121, v118, v119
	ds_bpermute_b32 v114, v203, v120
	ds_bpermute_b32 v115, v203, v121
	v_pk_fma_f32 v[88:89], v[166:167], v[88:89], v[116:117]
	v_pk_mul_f32 v[116:117], v[172:173], v[86:87]
	v_pk_mul_f32 v[118:119], v[170:171], v[88:89]
	global_store_dwordx4 v[134:135], v[86:89], off nt
	v_cvt_pk_bf16_f32 v116, v116, v117
	v_cvt_pk_bf16_f32 v117, v118, v119
	v_lshlrev_b32_e32 v118, 1, v128
	s_waitcnt lgkmcnt(0)
	v_add_u32_e32 v250, 0xfffff040, v118
	v_cndmask_b32_e64 v250, v118, v250, s[40:41]
	v_cndmask_b32_e64 v248, v126, v114, s[40:41]
	v_cndmask_b32_e64 v249, v127, v115, s[40:41]
	global_store_dwordx2 v250, v[248:249], s[20:21]
	v_cndmask_b32_e64 v246, v114, v126, s[40:41]
	v_cndmask_b32_e64 v247, v115, v127, s[40:41]
	s_waitcnt lgkmcnt(1)
	v_add_u32_e32 v114, 0x1040, v118
	v_cndmask_b32_e64 v114, v118, v114, s[38:39]
	global_store_dwordx2 v114, v[246:247], s[20:21]
	ds_bpermute_b32 v114, v203, v116
	s_waitcnt lgkmcnt(1)
	ds_bpermute_b32 v115, v203, v117
	v_add_u32_e32 v117, 0x14000, v202
	v_lshlrev_b32_e32 v116, 1, v117
	s_waitcnt lgkmcnt(0)
	v_add_u32_e32 v250, 0xfffff040, v116
	v_cndmask_b32_e64 v250, v116, v250, s[40:41]
	v_cndmask_b32_e64 v248, v122, v114, s[40:41]
	v_cndmask_b32_e64 v249, v123, v115, s[40:41]
	global_store_dwordx2 v250, v[248:249], s[20:21]
	v_cndmask_b32_e64 v246, v114, v122, s[40:41]
	v_cndmask_b32_e64 v247, v115, v123, s[40:41]
	v_mul_f32_e32 v83, v83, v83
	v_fmac_f32_e32 v83, v82, v82
	v_mul_f32_e32 v82, v85, v85
	v_mul_f32_e32 v93, v93, v93
	v_fmac_f32_e32 v82, v84, v84
	v_mul_f32_e32 v91, v91, v91
	v_fmac_f32_e32 v93, v92, v92
	v_mul_f32_e32 v92, v95, v95
	v_mul_f32_e32 v95, v97, v97
	v_add_f32_e32 v82, v83, v82
	v_mul_f32_e32 v83, v87, v87
	v_mul_f32_e32 v84, v89, v89
	v_fmac_f32_e32 v95, v96, v96
	v_fmac_f32_e32 v83, v86, v86
	v_fmac_f32_e32 v84, v88, v88
	v_fmac_f32_e32 v91, v90, v90
	v_fmac_f32_e32 v92, v94, v94
	v_add_f32_e32 v83, v83, v84
	v_add_f32_e32 v84, v91, v93
	v_add_f32_e32 v85, v92, v95
	v_add_f32_e32 v82, v84, v82
	v_add_f32_e32 v83, v85, v83
	ds_bpermute_b32 v84, v190, v82
	ds_bpermute_b32 v85, v190, v83
	s_waitcnt lgkmcnt(1)
	v_add_f32_e32 v82, v82, v84
	s_waitcnt lgkmcnt(0)
	v_add_f32_e32 v85, v83, v85
	ds_bpermute_b32 v84, v191, v82
	ds_bpermute_b32 v86, v191, v85
	s_waitcnt lgkmcnt(1)
	v_add_f32_e32 v82, v82, v84
	s_waitcnt lgkmcnt(0)
	v_add_f32_e32 v84, v85, v86
	ds_bpermute_b32 v83, v204, v82
	ds_bpermute_b32 v85, v204, v84
	v_add_u32_e32 v86, 0x1040, v116
	v_cndmask_b32_e64 v86, v116, v86, s[38:39]
	global_store_dwordx2 v86, v[246:247], s[20:21]
	s_and_saveexec_b64 s[16:17], s[42:43]
	s_cbranch_execz .LBB0_1628
	s_waitcnt lgkmcnt(1)
	v_add_f32_e32 v82, v82, v83
	s_waitcnt lgkmcnt(0)
	v_add_f32_e32 v83, v84, v85
	ds_write2_b32 v194, v82, v83 offset0:32 offset1:40
; #define LAS __attribute__((address_space(3)))
; #define ERN_EOFF(q, m) (eb + (unsigned)((((q) & 1) * HALF + (m) * 16) * DM + ERN_COL((q) >> 1)))
;     __device__ __forceinline__ void operator()(const f32x4 (&acc)[2][2][4][2], const Unit& u, int wr, int wc, int fr, int fq) const {
;     ...
;         ERN_LOADX(0);
; #pragma unroll
;         for (int g = 0; g < 8; ++g) { const int ai = g >> 2, m = g & 3;
;             if (g + 1 < 8) ERN_LOADX(g + 1);
;             float sq0 = 0.f, sq1 = 0.f; u32x2 hw[2][2];
; #pragma unroll
;             for (int bj = 0; bj < 2; ++bj) {
;                 *(LAS f32x4*)(st + wr_off) = acc[ai][bj][m][0]; *(LAS f32x4*)(st + wr_off + 64) = acc[ai][bj][m][1];
;                 const f32x4 a0 = *(const LAS f32x4*)(st + rd_off), a1 = *(const LAS f32x4*)(st + rd_off + 8 * 144);
;                 { const f32x4 xv = xb[g & 1][bj][0] + gv[bj] * a0; __builtin_nontemporal_store(xv, (f32x4*)((char*)xo + 4u * ERN_EOFF(g, bj, 0)));
;                   sq0 += (xv.x * xv.x + xv.y * xv.y) + (xv.z * xv.z + xv.w * xv.w);
;                   const f32x4 hv = xv * gsn[bj]; hw[bj][0].x = cvt_pk_bf16(hv.x, hv.y); hw[bj][0].y = cvt_pk_bf16(hv.z, hv.w); }
;                 { const f32x4 xv = xb[g & 1][bj][1] + gv[bj] * a1; __builtin_nontemporal_store(xv, (f32x4*)((char*)xo + 4u * ERN_EOFF(g, bj, 1)));
;                   sq1 += (xv.x * xv.x + xv.y * xv.y) + (xv.z * xv.z + xv.w * xv.w);
;                   const f32x4 hv = xv * gsn[bj]; hw[bj][1].x = cvt_pk_bf16(hv.x, hv.y); hw[bj][1].y = cvt_pk_bf16(hv.z, hv.w); }
;             }
;             if (!NOH && !PLAIN) {
; #pragma unroll
;                 for (int rh = 0; rh < 2; ++rh) { u32x2 rv; rv.x = __shfl_xor(hw[1][rh].x, 8); rv.y = __shfl_xor(hw[1][rh].y, 8);
;                     const unsigned e0 = ERN_EOFF(g, 0, rh);
;                     const unsigned ee = odd ? (e0 - DM + 32) : e0, eo2 = odd ? e0 : (e0 + DM + 32);
;                     *(u32x2*)((char*)ho + 2u * ee) = odd ? rv : hw[0][rh];
;                     *(u32x2*)((char*)ho + 2u * eo2) = odd ? hw[0][rh] : rv; }
;             }
;             if (!PLAIN) { sq0 += __shfl_xor(sq0, 1); sq0 += __shfl_xor(sq0, 2); sq0 += __shfl_xor(sq0, 4);
;             sq1 += __shfl_xor(sq1, 1); sq1 += __shfl_xor(sq1, 2); sq1 += __shfl_xor(sq1, 4); }
;             if (!PLAIN && pc == 0) { sst[g * 16 + rr] = sq0; sst[g * 16 + 8 + rr] = sq1; }
;         }
.LBB0_1628:
	s_or_b64 exec, exec, s[16:17]
	v_lshl_add_u64 v[116:117], s[22:23], 0, v[154:155]
	v_add_u32_e32 v82, 0x100000, v205
	s_waitcnt lgkmcnt(1)
	v_add_u32_e32 v83, 0x110000, v205
	v_add_u32_e32 v154, 0x100080, v205
	global_load_dwordx4 v[94:97], v82, s[22:23] nt
	global_load_dwordx4 v[90:93], v83, s[22:23] nt
	v_add_u32_e32 v114, 0x110080, v205
	global_load_dwordx4 v[86:89], v154, s[22:23] nt
	s_waitcnt lgkmcnt(0)
	global_load_dwordx4 v[82:85], v114, s[22:23] nt
	ds_write_b128 v200, v[78:81]
	ds_write_b128 v200, v[74:77] offset:64
	ds_read_b128 v[74:77], v201
	ds_read_b128 v[78:81], v201 offset:1152
	v_mov_b32_e32 v131, v155
	v_mov_b32_e32 v133, v155
	s_waitcnt vmcnt(11) lgkmcnt(1)
	v_pk_fma_f32 v[76:77], v[176:177], v[76:77], v[112:113]
	v_add_u32_e32 v112, 0x18000, v202
	v_pk_fma_f32 v[74:75], v[180:181], v[74:75], v[110:111]
	v_lshlrev_b32_e32 v110, 2, v112
	s_waitcnt lgkmcnt(0)
	v_pk_fma_f32 v[78:79], v[180:181], v[78:79], v[106:107]
	global_store_dwordx4 v110, v[74:77], s[22:23] nt
	v_pk_mul_f32 v[110:111], v[178:179], v[74:75]
	v_pk_fma_f32 v[80:81], v[176:177], v[80:81], v[108:109]
	v_pk_mul_f32 v[106:107], v[178:179], v[78:79]
	v_pk_mul_f32 v[118:119], v[174:175], v[76:77]
	v_cvt_pk_bf16_f32 v110, v110, v111
	v_pk_mul_f32 v[108:109], v[174:175], v[80:81]
	v_cvt_pk_bf16_f32 v111, v118, v119
	global_store_dwordx4 v[116:117], v[78:81], off nt
	v_cvt_pk_bf16_f32 v106, v106, v107
	v_cvt_pk_bf16_f32 v107, v108, v109
	ds_write_b128 v200, v[70:73]
	ds_write_b128 v200, v[66:69] offset:64
	ds_read_b128 v[66:69], v201
	ds_read_b128 v[70:73], v201 offset:1152
	v_lshl_add_u64 v[108:109], s[22:23], 0, v[130:131]
	v_lshl_add_u64 v[116:117], s[22:23], 0, v[132:133]
	s_waitcnt lgkmcnt(1)
	v_pk_fma_f32 v[66:67], v[168:169], v[66:67], v[102:103]
	v_pk_fma_f32 v[68:69], v[166:167], v[68:69], v[104:105]
	v_pk_mul_f32 v[104:105], v[172:173], v[66:67]
	global_store_dwordx4 v[108:109], v[66:69], off nt
	v_pk_mul_f32 v[102:103], v[170:171], v[68:69]
	v_cvt_pk_bf16_f32 v104, v104, v105
	s_waitcnt vmcnt(13) lgkmcnt(0)
	v_pk_fma_f32 v[70:71], v[168:169], v[70:71], v[98:99]
	v_cvt_pk_bf16_f32 v105, v102, v103
	ds_bpermute_b32 v98, v203, v104
	ds_bpermute_b32 v99, v203, v105
	v_pk_fma_f32 v[72:73], v[166:167], v[72:73], v[100:101]
	v_pk_mul_f32 v[100:101], v[172:173], v[70:71]
	v_pk_mul_f32 v[102:103], v[170:171], v[72:73]
	global_store_dwordx4 v[116:117], v[70:73], off nt
	v_cvt_pk_bf16_f32 v100, v100, v101
	v_cvt_pk_bf16_f32 v101, v102, v103
	v_lshlrev_b32_e32 v102, 1, v112
	s_waitcnt lgkmcnt(0)
	v_add_u32_e32 v250, 0xfffff040, v102
	v_cndmask_b32_e64 v250, v102, v250, s[40:41]
	v_cndmask_b32_e64 v248, v110, v98, s[40:41]
	v_cndmask_b32_e64 v249, v111, v99, s[40:41]
	global_store_dwordx2 v250, v[248:249], s[20:21]
	v_cndmask_b32_e64 v246, v98, v110, s[40:41]
	v_cndmask_b32_e64 v247, v99, v111, s[40:41]
	s_waitcnt lgkmcnt(1)
	v_add_u32_e32 v98, 0x1040, v102
	v_cndmask_b32_e64 v98, v102, v98, s[38:39]
	global_store_dwordx2 v98, v[246:247], s[20:21]
	ds_bpermute_b32 v98, v203, v100
	s_waitcnt lgkmcnt(1)
	ds_bpermute_b32 v99, v203, v101
	v_add_u32_e32 v101, 0x1c000, v202
	v_lshlrev_b32_e32 v100, 1, v101
	s_waitcnt lgkmcnt(0)
	v_add_u32_e32 v250, 0xfffff040, v100
	v_cndmask_b32_e64 v250, v100, v250, s[40:41]
	v_cndmask_b32_e64 v248, v106, v98, s[40:41]
	v_cndmask_b32_e64 v249, v107, v99, s[40:41]
	global_store_dwordx2 v250, v[248:249], s[20:21]
	v_cndmask_b32_e64 v246, v98, v106, s[40:41]
	v_cndmask_b32_e64 v247, v99, v107, s[40:41]
	v_mul_f32_e32 v67, v67, v67
	v_fmac_f32_e32 v67, v66, v66
	v_mul_f32_e32 v66, v69, v69
	v_mul_f32_e32 v77, v77, v77
	v_fmac_f32_e32 v66, v68, v68
	v_mul_f32_e32 v75, v75, v75
	v_fmac_f32_e32 v77, v76, v76
	v_mul_f32_e32 v76, v79, v79
	v_mul_f32_e32 v79, v81, v81
	v_add_f32_e32 v66, v67, v66
	v_mul_f32_e32 v67, v71, v71
	v_mul_f32_e32 v68, v73, v73
	v_fmac_f32_e32 v79, v80, v80
	v_fmac_f32_e32 v67, v70, v70
	v_fmac_f32_e32 v68, v72, v72
	v_fmac_f32_e32 v75, v74, v74
	v_fmac_f32_e32 v76, v78, v78
	v_add_f32_e32 v67, v67, v68
	v_add_f32_e32 v68, v75, v77
	v_add_f32_e32 v69, v76, v79
	v_add_f32_e32 v66, v68, v66
	v_add_f32_e32 v67, v69, v67
	ds_bpermute_b32 v68, v190, v66
	ds_bpermute_b32 v69, v190, v67
	s_waitcnt lgkmcnt(1)
	v_add_f32_e32 v66, v66, v68
	s_waitcnt lgkmcnt(0)
	v_add_f32_e32 v69, v67, v69
	ds_bpermute_b32 v68, v191, v66
	ds_bpermute_b32 v70, v191, v69
	s_waitcnt lgkmcnt(1)
	v_add_f32_e32 v66, v66, v68
	s_waitcnt lgkmcnt(0)
	v_add_f32_e32 v68, v69, v70
	ds_bpermute_b32 v67, v204, v66
	ds_bpermute_b32 v69, v204, v68
	v_add_u32_e32 v70, 0x1040, v100
	v_cndmask_b32_e64 v70, v100, v70, s[38:39]
	global_store_dwordx2 v70, v[246:247], s[20:21]
	s_and_saveexec_b64 s[16:17], s[42:43]
	s_cbranch_execz .LBB0_1638
	s_waitcnt lgkmcnt(1)
	v_add_f32_e32 v66, v66, v67
	s_waitcnt lgkmcnt(0)
	v_add_f32_e32 v67, v68, v69
	ds_write2_b32 v194, v66, v67 offset0:48 offset1:56
; #define LAS __attribute__((address_space(3)))
; #define ERN_EOFF(q, m) (eb + (unsigned)((((q) & 1) * HALF + (m) * 16) * DM + ERN_COL((q) >> 1)))
;     __device__ __forceinline__ void operator()(const f32x4 (&acc)[2][2][4][2], const Unit& u, int wr, int wc, int fr, int fq) const {
;     ...
;         ERN_LOADX(0);
; #pragma unroll
;         for (int g = 0; g < 8; ++g) { const int ai = g >> 2, m = g & 3;
;             if (g + 1 < 8) ERN_LOADX(g + 1);
;             float sq0 = 0.f, sq1 = 0.f; u32x2 hw[2][2];
; #pragma unroll
;             for (int bj = 0; bj < 2; ++bj) {
;                 *(LAS f32x4*)(st + wr_off) = acc[ai][bj][m][0]; *(LAS f32x4*)(st + wr_off + 64) = acc[ai][bj][m][1];
;                 const f32x4 a0 = *(const LAS f32x4*)(st + rd_off), a1 = *(const LAS f32x4*)(st + rd_off + 8 * 144);
;                 { const f32x4 xv = xb[g & 1][bj][0] + gv[bj] * a0; __builtin_nontemporal_store(xv, (f32x4*)((char*)xo + 4u * ERN_EOFF(g, bj, 0)));
;                   sq0 += (xv.x * xv.x + xv.y * xv.y) + (xv.z * xv.z + xv.w * xv.w);
;                   const f32x4 hv = xv * gsn[bj]; hw[bj][0].x = cvt_pk_bf16(hv.x, hv.y); hw[bj][0].y = cvt_pk_bf16(hv.z, hv.w); }
;                 { const f32x4 xv = xb[g & 1][bj][1] + gv[bj] * a1; __builtin_nontemporal_store(xv, (f32x4*)((char*)xo + 4u * ERN_EOFF(g, bj, 1)));
;                   sq1 += (xv.x * xv.x + xv.y * xv.y) + (xv.z * xv.z + xv.w * xv.w);
;                   const f32x4 hv = xv * gsn[bj]; hw[bj][1].x = cvt_pk_bf16(hv.x, hv.y); hw[bj][1].y = cvt_pk_bf16(hv.z, hv.w); }
;             }
;             if (!NOH && !PLAIN) {
; #pragma unroll
;                 for (int rh = 0; rh < 2; ++rh) { u32x2 rv; rv.x = __shfl_xor(hw[1][rh].x, 8); rv.y = __shfl_xor(hw[1][rh].y, 8);
;                     const unsigned e0 = ERN_EOFF(g, 0, rh);
;                     const unsigned ee = odd ? (e0 - DM + 32) : e0, eo2 = odd ? e0 : (e0 + DM + 32);
;                     *(u32x2*)((char*)ho + 2u * ee) = odd ? rv : hw[0][rh];
;                     *(u32x2*)((char*)ho + 2u * eo2) = odd ? hw[0][rh] : rv; }
;             }
;             if (!PLAIN) { sq0 += __shfl_xor(sq0, 1); sq0 += __shfl_xor(sq0, 2); sq0 += __shfl_xor(sq0, 4);
;             sq1 += __shfl_xor(sq1, 1); sq1 += __shfl_xor(sq1, 2); sq1 += __shfl_xor(sq1, 4); }
;             if (!PLAIN && pc == 0) { sst[g * 16 + rr] = sq0; sst[g * 16 + 8 + rr] = sq1; }
;         }
.LBB0_1638:
	s_or_b64 exec, exec, s[16:17]
	v_lshl_add_u64 v[104:105], s[22:23], 0, v[154:155]
	v_add_u32_e32 v154, 0x120000, v205
	v_add_u32_e32 v100, 0x120080, v205
	v_add_u32_e32 v102, 0x130000, v205
	global_load_dwordx4 v[78:81], v154, s[22:23] nt
	global_load_dwordx4 v[74:77], v102, s[22:23] nt
	v_add_u32_e32 v98, 0x130080, v205
	global_load_dwordx4 v[70:73], v100, s[22:23] nt
	s_waitcnt lgkmcnt(0)
	global_load_dwordx4 v[66:69], v98, s[22:23] nt
	ds_write_b128 v200, v[62:65]
	ds_write_b128 v200, v[58:61] offset:64
	ds_read_b128 v[58:61], v201
	ds_read_b128 v[62:65], v201 offset:1152
	v_mov_b32_e32 v115, v155
	s_waitcnt vmcnt(13) lgkmcnt(1)
	v_pk_fma_f32 v[60:61], v[176:177], v[60:61], v[96:97]
	v_add_u32_e32 v96, 0x40000, v202
	v_pk_fma_f32 v[58:59], v[180:181], v[58:59], v[94:95]
	v_lshlrev_b32_e32 v94, 2, v96
	s_waitcnt vmcnt(12) lgkmcnt(0)
	v_pk_fma_f32 v[64:65], v[176:177], v[64:65], v[92:93]
	v_add_u32_e32 v92, 0x44000, v202
	global_store_dwordx4 v94, v[58:61], s[22:23] nt
	v_pk_mul_f32 v[94:95], v[178:179], v[58:59]
	v_pk_fma_f32 v[62:63], v[180:181], v[62:63], v[90:91]
	v_lshlrev_b32_e32 v90, 2, v92
	v_pk_mul_f32 v[106:107], v[174:175], v[60:61]
	v_cvt_pk_bf16_f32 v94, v94, v95
	s_nop 0
	v_cvt_pk_bf16_f32 v95, v106, v107
	global_store_dwordx4 v90, v[62:65], s[22:23] nt
	v_pk_mul_f32 v[90:91], v[178:179], v[62:63]
	v_pk_mul_f32 v[106:107], v[174:175], v[64:65]
	v_cvt_pk_bf16_f32 v90, v90, v91
	s_nop 0
	v_cvt_pk_bf16_f32 v91, v106, v107
	ds_write_b128 v200, v[54:57]
	ds_write_b128 v200, v[50:53] offset:64
	ds_read_b128 v[50:53], v201
	ds_read_b128 v[54:57], v201 offset:1152
	v_lshl_add_u64 v[106:107], s[22:23], 0, v[114:115]
	s_waitcnt vmcnt(13) lgkmcnt(1)
	v_pk_fma_f32 v[50:51], v[168:169], v[50:51], v[86:87]
	v_pk_fma_f32 v[52:53], v[166:167], v[52:53], v[88:89]
	v_pk_mul_f32 v[88:89], v[172:173], v[50:51]
	global_store_dwordx4 v[104:105], v[50:53], off nt
	v_pk_mul_f32 v[86:87], v[170:171], v[52:53]
	v_cvt_pk_bf16_f32 v88, v88, v89
	s_waitcnt vmcnt(13) lgkmcnt(0)
	v_pk_fma_f32 v[54:55], v[168:169], v[54:55], v[82:83]
	v_cvt_pk_bf16_f32 v89, v86, v87
	ds_bpermute_b32 v82, v203, v88
	ds_bpermute_b32 v83, v203, v89
	v_pk_fma_f32 v[56:57], v[166:167], v[56:57], v[84:85]
	v_pk_mul_f32 v[84:85], v[172:173], v[54:55]
	v_pk_mul_f32 v[86:87], v[170:171], v[56:57]
	global_store_dwordx4 v[106:107], v[54:57], off nt
	v_cvt_pk_bf16_f32 v84, v84, v85
	v_cvt_pk_bf16_f32 v85, v86, v87
	v_lshlrev_b32_e32 v86, 1, v96
	s_waitcnt lgkmcnt(0)
	v_add_u32_e32 v250, 0xfffff040, v86
	v_cndmask_b32_e64 v250, v86, v250, s[40:41]
	v_cndmask_b32_e64 v248, v94, v82, s[40:41]
	v_cndmask_b32_e64 v249, v95, v83, s[40:41]
	global_store_dwordx2 v250, v[248:249], s[20:21]
	v_cndmask_b32_e64 v246, v82, v94, s[40:41]
	v_cndmask_b32_e64 v247, v83, v95, s[40:41]
	s_waitcnt lgkmcnt(1)
	v_add_u32_e32 v82, 0x1040, v86
	v_cndmask_b32_e64 v82, v86, v82, s[38:39]
	global_store_dwordx2 v82, v[246:247], s[20:21]
	ds_bpermute_b32 v82, v203, v84
	s_waitcnt lgkmcnt(1)
	ds_bpermute_b32 v83, v203, v85
	v_lshlrev_b32_e32 v84, 1, v92
	s_waitcnt lgkmcnt(0)
	v_add_u32_e32 v250, 0xfffff040, v84
	v_cndmask_b32_e64 v250, v84, v250, s[40:41]
	v_cndmask_b32_e64 v248, v90, v82, s[40:41]
	v_cndmask_b32_e64 v249, v91, v83, s[40:41]
	global_store_dwordx2 v250, v[248:249], s[20:21]
	v_cndmask_b32_e64 v246, v82, v90, s[40:41]
	v_cndmask_b32_e64 v247, v83, v91, s[40:41]
	v_mul_f32_e32 v51, v51, v51
	v_fmac_f32_e32 v51, v50, v50
	v_mul_f32_e32 v50, v53, v53
	v_mul_f32_e32 v61, v61, v61
	v_fmac_f32_e32 v50, v52, v52
	v_mul_f32_e32 v59, v59, v59
	v_fmac_f32_e32 v61, v60, v60
	v_mul_f32_e32 v60, v63, v63
	v_mul_f32_e32 v63, v65, v65
	v_add_f32_e32 v50, v51, v50
	v_mul_f32_e32 v51, v55, v55
	v_mul_f32_e32 v52, v57, v57
	v_fmac_f32_e32 v63, v64, v64
	v_fmac_f32_e32 v51, v54, v54
	v_fmac_f32_e32 v52, v56, v56
	v_fmac_f32_e32 v59, v58, v58
	v_fmac_f32_e32 v60, v62, v62
	v_add_f32_e32 v51, v51, v52
	v_add_f32_e32 v52, v59, v61
	v_add_f32_e32 v53, v60, v63
	v_add_f32_e32 v50, v52, v50
	v_add_f32_e32 v51, v53, v51
	ds_bpermute_b32 v52, v190, v50
	ds_bpermute_b32 v53, v190, v51
	s_waitcnt lgkmcnt(1)
	v_add_f32_e32 v50, v50, v52
	s_waitcnt lgkmcnt(0)
	v_add_f32_e32 v53, v51, v53
	ds_bpermute_b32 v52, v191, v50
	ds_bpermute_b32 v54, v191, v53
	s_waitcnt lgkmcnt(1)
	v_add_f32_e32 v50, v50, v52
	s_waitcnt lgkmcnt(0)
	v_add_f32_e32 v52, v53, v54
	ds_bpermute_b32 v51, v204, v50
	ds_bpermute_b32 v53, v204, v52
	v_add_u32_e32 v54, 0x1040, v84
	v_cndmask_b32_e64 v54, v84, v54, s[38:39]
	global_store_dwordx2 v54, v[246:247], s[20:21]
	s_and_saveexec_b64 s[16:17], s[42:43]
	s_cbranch_execz .LBB0_1648
	s_waitcnt lgkmcnt(1)
	v_add_f32_e32 v50, v50, v51
	s_waitcnt lgkmcnt(0)
	v_add_f32_e32 v51, v52, v53
	ds_write2_b32 v194, v50, v51 offset0:64 offset1:72
; #define LAS __attribute__((address_space(3)))
; #define ERN_EOFF(q, m) (eb + (unsigned)((((q) & 1) * HALF + (m) * 16) * DM + ERN_COL((q) >> 1)))
;     __device__ __forceinline__ void operator()(const f32x4 (&acc)[2][2][4][2], const Unit& u, int wr, int wc, int fr, int fq) const {
;     ...
;         ERN_LOADX(0);
; #pragma unroll
;         for (int g = 0; g < 8; ++g) { const int ai = g >> 2, m = g & 3;
;             if (g + 1 < 8) ERN_LOADX(g + 1);
;             float sq0 = 0.f, sq1 = 0.f; u32x2 hw[2][2];
; #pragma unroll
;             for (int bj = 0; bj < 2; ++bj) {
;                 *(LAS f32x4*)(st + wr_off) = acc[ai][bj][m][0]; *(LAS f32x4*)(st + wr_off + 64) = acc[ai][bj][m][1];
;                 const f32x4 a0 = *(const LAS f32x4*)(st + rd_off), a1 = *(const LAS f32x4*)(st + rd_off + 8 * 144);
;                 { const f32x4 xv = xb[g & 1][bj][0] + gv[bj] * a0; __builtin_nontemporal_store(xv, (f32x4*)((char*)xo + 4u * ERN_EOFF(g, bj, 0)));
;                   sq0 += (xv.x * xv.x + xv.y * xv.y) + (xv.z * xv.z + xv.w * xv.w);
;                   const f32x4 hv = xv * gsn[bj]; hw[bj][0].x = cvt_pk_bf16(hv.x, hv.y); hw[bj][0].y = cvt_pk_bf16(hv.z, hv.w); }
;                 { const f32x4 xv = xb[g & 1][bj][1] + gv[bj] * a1; __builtin_nontemporal_store(xv, (f32x4*)((char*)xo + 4u * ERN_EOFF(g, bj, 1)));
;                   sq1 += (xv.x * xv.x + xv.y * xv.y) + (xv.z * xv.z + xv.w * xv.w);
;                   const f32x4 hv = xv * gsn[bj]; hw[bj][1].x = cvt_pk_bf16(hv.x, hv.y); hw[bj][1].y = cvt_pk_bf16(hv.z, hv.w); }
;             }
;             if (!NOH && !PLAIN) {
; #pragma unroll
;                 for (int rh = 0; rh < 2; ++rh) { u32x2 rv; rv.x = __shfl_xor(hw[1][rh].x, 8); rv.y = __shfl_xor(hw[1][rh].y, 8);
;                     const unsigned e0 = ERN_EOFF(g, 0, rh);
;                     const unsigned ee = odd ? (e0 - DM + 32) : e0, eo2 = odd ? e0 : (e0 + DM + 32);
;                     *(u32x2*)((char*)ho + 2u * ee) = odd ? rv : hw[0][rh];
;                     *(u32x2*)((char*)ho + 2u * eo2) = odd ? hw[0][rh] : rv; }
;             }
;             if (!PLAIN) { sq0 += __shfl_xor(sq0, 1); sq0 += __shfl_xor(sq0, 2); sq0 += __shfl_xor(sq0, 4);
;             sq1 += __shfl_xor(sq1, 1); sq1 += __shfl_xor(sq1, 2); sq1 += __shfl_xor(sq1, 4); }
;             if (!PLAIN && pc == 0) { sst[g * 16 + rr] = sq0; sst[g * 16 + 8 + rr] = sq1; }
;         }
.LBB0_1648:
	s_or_b64 exec, exec, s[16:17]
	v_lshl_add_u64 v[88:89], s[22:23], 0, v[154:155]
	v_add_u32_e32 v154, 0x140000, v205
	v_add_u32_e32 v84, 0x140080, v205
	v_add_u32_e32 v86, 0x150000, v205
	global_load_dwordx4 v[62:65], v154, s[22:23] nt
	global_load_dwordx4 v[58:61], v86, s[22:23] nt
	v_add_u32_e32 v82, 0x150080, v205
	global_load_dwordx4 v[54:57], v84, s[22:23] nt
	s_waitcnt lgkmcnt(0)
	global_load_dwordx4 v[50:53], v82, s[22:23] nt
	ds_write_b128 v200, v[46:49]
	ds_write_b128 v200, v[42:45] offset:64
	ds_read_b128 v[42:45], v201
	ds_read_b128 v[46:49], v201 offset:1152
	v_mov_b32_e32 v103, v155
	v_lshl_add_u64 v[90:91], s[22:23], 0, v[102:103]
	v_mov_b32_e32 v101, v155
	s_waitcnt vmcnt(13) lgkmcnt(1)
	v_pk_fma_f32 v[42:43], v[180:181], v[42:43], v[78:79]
	s_waitcnt vmcnt(12) lgkmcnt(0)
	v_pk_fma_f32 v[46:47], v[180:181], v[46:47], v[74:75]
	v_pk_fma_f32 v[44:45], v[176:177], v[44:45], v[80:81]
	v_pk_mul_f32 v[78:79], v[178:179], v[42:43]
	v_pk_fma_f32 v[48:49], v[176:177], v[48:49], v[76:77]
	v_pk_mul_f32 v[74:75], v[178:179], v[46:47]
	global_store_dwordx4 v[88:89], v[42:45], off nt
	v_pk_mul_f32 v[80:81], v[174:175], v[44:45]
	v_cvt_pk_bf16_f32 v78, v78, v79
	v_pk_mul_f32 v[76:77], v[174:175], v[48:49]
	v_cvt_pk_bf16_f32 v79, v80, v81
	global_store_dwordx4 v[90:91], v[46:49], off nt
	v_cvt_pk_bf16_f32 v74, v74, v75
	v_cvt_pk_bf16_f32 v75, v76, v77
	ds_write_b128 v200, v[38:41]
	ds_write_b128 v200, v[34:37] offset:64
	ds_read_b128 v[34:37], v201
	ds_read_b128 v[38:41], v201 offset:1152
	v_lshl_add_u64 v[76:77], s[22:23], 0, v[100:101]
	v_mov_b32_e32 v99, v155
	v_lshl_add_u64 v[80:81], s[22:23], 0, v[98:99]
	s_waitcnt vmcnt(13) lgkmcnt(1)
	v_pk_fma_f32 v[34:35], v[168:169], v[34:35], v[70:71]
	v_pk_fma_f32 v[36:37], v[166:167], v[36:37], v[72:73]
	v_pk_mul_f32 v[72:73], v[172:173], v[34:35]
	global_store_dwordx4 v[76:77], v[34:37], off nt
	v_pk_mul_f32 v[70:71], v[170:171], v[36:37]
	v_cvt_pk_bf16_f32 v72, v72, v73
	s_waitcnt vmcnt(13) lgkmcnt(0)
	v_pk_fma_f32 v[38:39], v[168:169], v[38:39], v[66:67]
	v_cvt_pk_bf16_f32 v73, v70, v71
	ds_bpermute_b32 v66, v203, v72
	ds_bpermute_b32 v67, v203, v73
	v_pk_fma_f32 v[40:41], v[166:167], v[40:41], v[68:69]
	v_pk_mul_f32 v[68:69], v[172:173], v[38:39]
	v_pk_mul_f32 v[70:71], v[170:171], v[40:41]
	global_store_dwordx4 v[80:81], v[38:41], off nt
	v_cvt_pk_bf16_f32 v68, v68, v69
	v_cvt_pk_bf16_f32 v69, v70, v71
	v_add_u32_e32 v71, 0x48000, v202
	v_lshlrev_b32_e32 v70, 1, v71
	s_waitcnt lgkmcnt(0)
	v_add_u32_e32 v250, 0xfffff040, v70
	v_cndmask_b32_e64 v250, v70, v250, s[40:41]
	v_cndmask_b32_e64 v248, v78, v66, s[40:41]
	v_cndmask_b32_e64 v249, v79, v67, s[40:41]
	global_store_dwordx2 v250, v[248:249], s[20:21]
	v_cndmask_b32_e64 v246, v66, v78, s[40:41]
	v_cndmask_b32_e64 v247, v67, v79, s[40:41]
	s_waitcnt lgkmcnt(1)
	v_add_u32_e32 v66, 0x1040, v70
	v_cndmask_b32_e64 v66, v70, v66, s[38:39]
	global_store_dwordx2 v66, v[246:247], s[20:21]
	ds_bpermute_b32 v66, v203, v68
	s_waitcnt lgkmcnt(1)
	ds_bpermute_b32 v67, v203, v69
	v_add_u32_e32 v69, 0x4c000, v202
	v_lshlrev_b32_e32 v68, 1, v69
	s_waitcnt lgkmcnt(0)
	v_add_u32_e32 v250, 0xfffff040, v68
	v_cndmask_b32_e64 v250, v68, v250, s[40:41]
	v_cndmask_b32_e64 v248, v74, v66, s[40:41]
	v_cndmask_b32_e64 v249, v75, v67, s[40:41]
	global_store_dwordx2 v250, v[248:249], s[20:21]
	v_cndmask_b32_e64 v246, v66, v74, s[40:41]
	v_cndmask_b32_e64 v247, v67, v75, s[40:41]
	v_mul_f32_e32 v35, v35, v35
	v_fmac_f32_e32 v35, v34, v34
	v_mul_f32_e32 v34, v37, v37
	v_mul_f32_e32 v45, v45, v45
	v_fmac_f32_e32 v34, v36, v36
	v_mul_f32_e32 v43, v43, v43
	v_fmac_f32_e32 v45, v44, v44
	v_mul_f32_e32 v44, v47, v47
	v_mul_f32_e32 v47, v49, v49
	v_add_f32_e32 v34, v35, v34
	v_mul_f32_e32 v35, v39, v39
	v_mul_f32_e32 v36, v41, v41
	v_fmac_f32_e32 v47, v48, v48
	v_fmac_f32_e32 v35, v38, v38
	v_fmac_f32_e32 v36, v40, v40
	v_fmac_f32_e32 v43, v42, v42
	v_fmac_f32_e32 v44, v46, v46
	v_add_f32_e32 v35, v35, v36
	v_add_f32_e32 v36, v43, v45
	v_add_f32_e32 v37, v44, v47
	v_add_f32_e32 v34, v36, v34
	v_add_f32_e32 v35, v37, v35
	ds_bpermute_b32 v36, v190, v34
	ds_bpermute_b32 v37, v190, v35
	s_waitcnt lgkmcnt(1)
	v_add_f32_e32 v34, v34, v36
	s_waitcnt lgkmcnt(0)
	v_add_f32_e32 v37, v35, v37
	ds_bpermute_b32 v36, v191, v34
	ds_bpermute_b32 v38, v191, v37
	s_waitcnt lgkmcnt(1)
	v_add_f32_e32 v34, v34, v36
	s_waitcnt lgkmcnt(0)
	v_add_f32_e32 v36, v37, v38
	ds_bpermute_b32 v35, v204, v34
	ds_bpermute_b32 v37, v204, v36
	v_add_u32_e32 v38, 0x1040, v68
	v_cndmask_b32_e64 v38, v68, v38, s[38:39]
	global_store_dwordx2 v38, v[246:247], s[20:21]
	s_and_saveexec_b64 s[16:17], s[42:43]
	s_cbranch_execz .LBB0_1658
	s_waitcnt lgkmcnt(1)
	v_add_f32_e32 v34, v34, v35
	s_waitcnt lgkmcnt(0)
	v_add_f32_e32 v35, v36, v37
	ds_write2_b32 v194, v34, v35 offset0:80 offset1:88
; #define LAS __attribute__((address_space(3)))
; #define ERN_EOFF(q, m) (eb + (unsigned)((((q) & 1) * HALF + (m) * 16) * DM + ERN_COL((q) >> 1)))
;     __device__ __forceinline__ void operator()(const f32x4 (&acc)[2][2][4][2], const Unit& u, int wr, int wc, int fr, int fq) const {
;     ...
;         ERN_LOADX(0);
; #pragma unroll
;         for (int g = 0; g < 8; ++g) { const int ai = g >> 2, m = g & 3;
;             if (g + 1 < 8) ERN_LOADX(g + 1);
;             float sq0 = 0.f, sq1 = 0.f; u32x2 hw[2][2];
; #pragma unroll
;             for (int bj = 0; bj < 2; ++bj) {
;                 *(LAS f32x4*)(st + wr_off) = acc[ai][bj][m][0]; *(LAS f32x4*)(st + wr_off + 64) = acc[ai][bj][m][1];
;                 const f32x4 a0 = *(const LAS f32x4*)(st + rd_off), a1 = *(const LAS f32x4*)(st + rd_off + 8 * 144);
;                 { const f32x4 xv = xb[g & 1][bj][0] + gv[bj] * a0; __builtin_nontemporal_store(xv, (f32x4*)((char*)xo + 4u * ERN_EOFF(g, bj, 0)));
;                   sq0 += (xv.x * xv.x + xv.y * xv.y) + (xv.z * xv.z + xv.w * xv.w);
;                   const f32x4 hv = xv * gsn[bj]; hw[bj][0].x = cvt_pk_bf16(hv.x, hv.y); hw[bj][0].y = cvt_pk_bf16(hv.z, hv.w); }
;                 { const f32x4 xv = xb[g & 1][bj][1] + gv[bj] * a1; __builtin_nontemporal_store(xv, (f32x4*)((char*)xo + 4u * ERN_EOFF(g, bj, 1)));
;                   sq1 += (xv.x * xv.x + xv.y * xv.y) + (xv.z * xv.z + xv.w * xv.w);
;                   const f32x4 hv = xv * gsn[bj]; hw[bj][1].x = cvt_pk_bf16(hv.x, hv.y); hw[bj][1].y = cvt_pk_bf16(hv.z, hv.w); }
;             }
;             if (!NOH && !PLAIN) {
; #pragma unroll
;                 for (int rh = 0; rh < 2; ++rh) { u32x2 rv; rv.x = __shfl_xor(hw[1][rh].x, 8); rv.y = __shfl_xor(hw[1][rh].y, 8);
;                     const unsigned e0 = ERN_EOFF(g, 0, rh);
;                     const unsigned ee = odd ? (e0 - DM + 32) : e0, eo2 = odd ? e0 : (e0 + DM + 32);
;                     *(u32x2*)((char*)ho + 2u * ee) = odd ? rv : hw[0][rh];
;                     *(u32x2*)((char*)ho + 2u * eo2) = odd ? hw[0][rh] : rv; }
;             }
;             if (!PLAIN) { sq0 += __shfl_xor(sq0, 1); sq0 += __shfl_xor(sq0, 2); sq0 += __shfl_xor(sq0, 4);
;             sq1 += __shfl_xor(sq1, 1); sq1 += __shfl_xor(sq1, 2); sq1 += __shfl_xor(sq1, 4); }
;             if (!PLAIN && pc == 0) { sst[g * 16 + rr] = sq0; sst[g * 16 + 8 + rr] = sq1; }
;         }
.LBB0_1658:
	s_or_b64 exec, exec, s[16:17]
	v_lshl_add_u64 v[72:73], s[22:23], 0, v[154:155]
	v_add_u32_e32 v154, 0x160000, v205
	v_add_u32_e32 v68, 0x160080, v205
	v_add_u32_e32 v70, 0x170000, v205
	global_load_dwordx4 v[46:49], v154, s[22:23] nt
	global_load_dwordx4 v[42:45], v70, s[22:23] nt
	v_add_u32_e32 v66, 0x170080, v205
	global_load_dwordx4 v[38:41], v68, s[22:23] nt
	s_waitcnt lgkmcnt(0)
	global_load_dwordx4 v[34:37], v66, s[22:23] nt
	ds_write_b128 v200, v[30:33]
	ds_write_b128 v200, v[26:29] offset:64
	ds_read_b128 v[26:29], v201
	ds_read_b128 v[30:33], v201 offset:1152
	v_mov_b32_e32 v87, v155
	v_lshl_add_u64 v[74:75], s[22:23], 0, v[86:87]
	v_mov_b32_e32 v85, v155
	s_waitcnt vmcnt(13) lgkmcnt(1)
	v_pk_fma_f32 v[26:27], v[180:181], v[26:27], v[62:63]
	s_waitcnt vmcnt(12) lgkmcnt(0)
	v_pk_fma_f32 v[30:31], v[180:181], v[30:31], v[58:59]
	v_pk_fma_f32 v[28:29], v[176:177], v[28:29], v[64:65]
	v_pk_mul_f32 v[62:63], v[178:179], v[26:27]
	v_pk_fma_f32 v[32:33], v[176:177], v[32:33], v[60:61]
	v_pk_mul_f32 v[58:59], v[178:179], v[30:31]
	global_store_dwordx4 v[72:73], v[26:29], off nt
	v_pk_mul_f32 v[64:65], v[174:175], v[28:29]
	v_cvt_pk_bf16_f32 v62, v62, v63
	v_pk_mul_f32 v[60:61], v[174:175], v[32:33]
	v_cvt_pk_bf16_f32 v63, v64, v65
	global_store_dwordx4 v[74:75], v[30:33], off nt
	v_cvt_pk_bf16_f32 v58, v58, v59
	v_cvt_pk_bf16_f32 v59, v60, v61
	ds_write_b128 v200, v[22:25]
	ds_write_b128 v200, v[18:21] offset:64
	ds_read_b128 v[18:21], v201
	ds_read_b128 v[22:25], v201 offset:1152
	v_lshl_add_u64 v[60:61], s[22:23], 0, v[84:85]
	v_mov_b32_e32 v83, v155
	v_lshl_add_u64 v[64:65], s[22:23], 0, v[82:83]
	s_waitcnt vmcnt(13) lgkmcnt(1)
	v_pk_fma_f32 v[18:19], v[168:169], v[18:19], v[54:55]
	v_pk_fma_f32 v[20:21], v[166:167], v[20:21], v[56:57]
	v_pk_mul_f32 v[56:57], v[172:173], v[18:19]
	global_store_dwordx4 v[60:61], v[18:21], off nt
	v_pk_mul_f32 v[54:55], v[170:171], v[20:21]
	v_cvt_pk_bf16_f32 v56, v56, v57
	s_waitcnt vmcnt(13) lgkmcnt(0)
	v_pk_fma_f32 v[22:23], v[168:169], v[22:23], v[50:51]
	v_cvt_pk_bf16_f32 v57, v54, v55
	ds_bpermute_b32 v50, v203, v56
	ds_bpermute_b32 v51, v203, v57
	v_pk_fma_f32 v[24:25], v[166:167], v[24:25], v[52:53]
	v_pk_mul_f32 v[52:53], v[172:173], v[22:23]
	v_pk_mul_f32 v[54:55], v[170:171], v[24:25]
	global_store_dwordx4 v[64:65], v[22:25], off nt
	v_cvt_pk_bf16_f32 v52, v52, v53
	v_cvt_pk_bf16_f32 v53, v54, v55
	v_add_u32_e32 v55, 0x50000, v202
	v_lshlrev_b32_e32 v54, 1, v55
	s_waitcnt lgkmcnt(0)
	v_add_u32_e32 v250, 0xfffff040, v54
	v_cndmask_b32_e64 v250, v54, v250, s[40:41]
	v_cndmask_b32_e64 v248, v62, v50, s[40:41]
	v_cndmask_b32_e64 v249, v63, v51, s[40:41]
	global_store_dwordx2 v250, v[248:249], s[20:21]
	v_cndmask_b32_e64 v246, v50, v62, s[40:41]
	v_cndmask_b32_e64 v247, v51, v63, s[40:41]
	s_waitcnt lgkmcnt(1)
	v_add_u32_e32 v50, 0x1040, v54
	v_cndmask_b32_e64 v50, v54, v50, s[38:39]
	global_store_dwordx2 v50, v[246:247], s[20:21]
	ds_bpermute_b32 v50, v203, v52
	s_waitcnt lgkmcnt(1)
	ds_bpermute_b32 v51, v203, v53
	v_add_u32_e32 v53, 0x54000, v202
	v_lshlrev_b32_e32 v52, 1, v53
	s_waitcnt lgkmcnt(0)
	v_add_u32_e32 v250, 0xfffff040, v52
	v_cndmask_b32_e64 v250, v52, v250, s[40:41]
	v_cndmask_b32_e64 v248, v58, v50, s[40:41]
	v_cndmask_b32_e64 v249, v59, v51, s[40:41]
	global_store_dwordx2 v250, v[248:249], s[20:21]
	v_cndmask_b32_e64 v246, v50, v58, s[40:41]
	v_cndmask_b32_e64 v247, v51, v59, s[40:41]
	v_mul_f32_e32 v19, v19, v19
	v_fmac_f32_e32 v19, v18, v18
	v_mul_f32_e32 v18, v21, v21
	v_mul_f32_e32 v29, v29, v29
	v_fmac_f32_e32 v18, v20, v20
	v_mul_f32_e32 v27, v27, v27
	v_fmac_f32_e32 v29, v28, v28
	v_mul_f32_e32 v28, v31, v31
	v_mul_f32_e32 v31, v33, v33
	v_add_f32_e32 v18, v19, v18
	v_mul_f32_e32 v19, v23, v23
	v_mul_f32_e32 v20, v25, v25
	v_fmac_f32_e32 v31, v32, v32
	v_fmac_f32_e32 v19, v22, v22
	v_fmac_f32_e32 v20, v24, v24
	v_fmac_f32_e32 v27, v26, v26
	v_fmac_f32_e32 v28, v30, v30
	v_add_f32_e32 v19, v19, v20
	v_add_f32_e32 v20, v27, v29
	v_add_f32_e32 v21, v28, v31
	v_add_f32_e32 v18, v20, v18
	v_add_f32_e32 v19, v21, v19
	ds_bpermute_b32 v20, v190, v18
	ds_bpermute_b32 v21, v190, v19
	s_waitcnt lgkmcnt(1)
	v_add_f32_e32 v18, v18, v20
	s_waitcnt lgkmcnt(0)
	v_add_f32_e32 v21, v19, v21
	ds_bpermute_b32 v20, v191, v18
	ds_bpermute_b32 v22, v191, v21
	s_waitcnt lgkmcnt(1)
	v_add_f32_e32 v18, v18, v20
	s_waitcnt lgkmcnt(0)
	v_add_f32_e32 v20, v21, v22
	ds_bpermute_b32 v19, v204, v18
	ds_bpermute_b32 v21, v204, v20
	v_add_u32_e32 v22, 0x1040, v52
	v_cndmask_b32_e64 v22, v52, v22, s[38:39]
	global_store_dwordx2 v22, v[246:247], s[20:21]
	s_and_saveexec_b64 s[16:17], s[42:43]
	s_cbranch_execz .LBB0_1668
	s_waitcnt lgkmcnt(1)
	v_add_f32_e32 v18, v18, v19
	s_waitcnt lgkmcnt(0)
	v_add_f32_e32 v19, v20, v21
	ds_write2_b32 v194, v18, v19 offset0:96 offset1:104

; #define LAS __attribute__((address_space(3)))
;     __device__ __forceinline__ void operator()(const f32x4 (&acc)[2][2][4][2], const Unit& u, int wr, int wc, int fr, int fq) const {
;         const int s = u.pm >> 5, lane = fq * 16 + fr, rr = lane >> 3, pc = lane & 7;
;         const float* __restrict__ xi = xin + (size_t)u.pm * BM * DM; float* __restrict__ xo = xout + (size_t)u.pm * BM * DM; bf16_t* __restrict__ ho = Hn + (size_t)u.pm * BM * DM;
;         LAS unsigned char* st = lds_epi + (wr * 4 + wc) * 2304;
;         LAS float* sst = (LAS float*)(lds_epi + 18432 + (wr * 4 + wc) * 512);
;         const int colr = u.pn * BM + wc * 64 + 4 * pc;
;         const unsigned eb = (unsigned)((wr * 64 + rr) * DM + colr);
;         f32x4 gv[2], gsn[2];
; #pragma unroll
;         for (int bj = 0; bj < 2; ++bj) { gv[bj] = *(const f32x4*)(gate + (size_t)s * MODW + colr + bj * 32) * (0.5f * GS2);
;             if (!PLAIN) gsn[bj] = *(const f32x4*)(gnext + colr + bj * 32) * (*(const f32x4*)(scnext + (size_t)s * MODW + colr + bj * 32) + 1.0f); else gsn[bj] = gv[bj]; }
;         const unsigned wr_off = (unsigned)(fr * 144 + 16 * fq), rd_off = (unsigned)(rr * 144 + pc * 16);
;         const bool odd = (rr & 1) != 0;
;         f32x4 xb[2][2][2];
;     ...
;         ERN_LOADX(0);
; #pragma unroll
;         for (int g = 0; g < 8; ++g) { const int ai = g >> 2, m = g & 3;
;             if (g + 1 < 8) ERN_LOADX(g + 1);
;             float sq0 = 0.f, sq1 = 0.f; u32x2 hw[2][2];
; #pragma unroll
;             for (int bj = 0; bj < 2; ++bj) {
;                 *(LAS f32x4*)(st + wr_off) = acc[ai][bj][m][0]; *(LAS f32x4*)(st + wr_off + 64) = acc[ai][bj][m][1];
;                 const f32x4 a0 = *(const LAS f32x4*)(st + rd_off), a1 = *(const LAS f32x4*)(st + rd_off + 8 * 144);
;                 { const f32x4 xv = xb[g & 1][bj][0] + gv[bj] * a0; __builtin_nontemporal_store(xv, (f32x4*)((char*)xo + 4u * ERN_EOFF(g, bj, 0)));
;                   sq0 += (xv.x * xv.x + xv.y * xv.y) + (xv.z * xv.z + xv.w * xv.w);
;                   const f32x4 hv = xv * gsn[bj]; hw[bj][0].x = cvt_pk_bf16(hv.x, hv.y); hw[bj][0].y = cvt_pk_bf16(hv.z, hv.w); }
;                 { const f32x4 xv = xb[g & 1][bj][1] + gv[bj] * a1; __builtin_nontemporal_store(xv, (f32x4*)((char*)xo + 4u * ERN_EOFF(g, bj, 1)));
;                   sq1 += (xv.x * xv.x + xv.y * xv.y) + (xv.z * xv.z + xv.w * xv.w);
.LBB0_1929:
	s_ashr_i32 s18, s4, 5
	s_ashr_i32 s5, s4, 31
	v_lshl_or_b32 v130, s0, 8, v192
	s_mul_i32 s20, s18, 0x12000
	s_mul_hi_i32 s0, s18, 0x12000
	s_add_u32 s18, s33, s20
	v_ashrrev_i32_e32 v131, 31, v130
	s_addc_u32 s19, s34, s0
	v_lshlrev_b64 v[132:133], 2, v[130:131]
	v_lshl_add_u64 v[134:135], s[18:19], 0, v[132:133]
	s_add_u32 s18, s35, s20
	s_addc_u32 s19, s36, s0
	v_lshl_add_u64 v[136:137], s[10:11], 0, v[132:133]
	v_lshl_add_u64 v[132:133], s[18:19], 0, v[132:133]
	s_lshl_b64 s[18:19], s[4:5], 21
	s_add_u32 s20, s90, s18
	v_add_u32_e32 v202, v130, v193
	s_addc_u32 s21, s91, s19
	v_lshlrev_b32_e32 v205, 2, v202
	global_load_dwordx4 v[170:173], v[136:137], off
	global_load_dwordx4 v[166:169], v[134:135], off
	global_load_dwordx4 v[186:189], v[134:135], off offset:128
	global_load_dwordx4 v[206:209], v[132:133], off
	global_load_dwordx4 v[210:213], v[132:133], off offset:128
	global_load_dwordx4 v[214:217], v205, s[20:21] nt
	v_add_u32_e32 v130, 0x10000, v205
	global_load_dwordx4 v[218:221], v130, s[20:21] nt
	global_load_dwordx4 v[222:225], v[136:137], off offset:128
	global_load_dwordx4 v[226:229], v205, s[20:21] offset:128 nt
	v_add_u32_e32 v204, 0x10080, v205
	global_load_dwordx4 v[230:233], v204, s[20:21] nt
	v_add_u32_e32 v130, 0x20000, v205
	v_add_u32_e32 v154, 0x30000, v205
	v_add_u32_e32 v184, 0x20080, v205
	v_add_u32_e32 v182, 0x30080, v205
	global_load_dwordx4 v[142:145], v130, s[20:21] nt
	global_load_dwordx4 v[138:141], v154, s[20:21] nt
	global_load_dwordx4 v[134:137], v184, s[20:21] nt
	s_nop 0
	global_load_dwordx4 v[130:133], v182, s[20:21] nt
	ds_write_b128 v200, v[126:129]
	ds_write_b128 v200, v[122:125] offset:64
	v_and_b32_e32 v127, 64, v199
	ds_read_b128 v[122:125], v201
	ds_read_b128 v[234:237], v201 offset:1152
	v_xor_b32_e32 v126, 8, v199
	v_add_u32_e32 v183, 64, v127
	v_cmp_lt_i32_e32 vcc, v126, v183
	v_add_u32_e32 v185, 0x4000, v202
	v_lshlrev_b32_e32 v238, 2, v185
	v_cndmask_b32_e32 v126, v199, v126, vcc
	v_lshlrev_b32_e32 v203, 2, v126
	s_lshl_b64 s[18:19], s[4:5], 20
	s_add_u32 s18, s93, s18
	s_addc_u32 s19, s92, s19
	s_waitcnt vmcnt(0)
	v_pk_mul_f32 v[180:181], v[166:167], 0.5 op_sel_hi:[1,0]
	v_pk_mul_f32 v[176:177], v[168:169], 0.5 op_sel_hi:[1,0]
	v_pk_add_f32 v[126:127], v[208:209], 1.0 op_sel_hi:[1,0]
	v_pk_add_f32 v[128:129], v[206:207], 1.0 op_sel_hi:[1,0]
	v_pk_mul_f32 v[174:175], v[172:173], v[126:127]
	v_pk_mul_f32 v[178:179], v[170:171], v[128:129]
	s_waitcnt lgkmcnt(1)
	v_pk_fma_f32 v[126:127], v[180:181], v[122:123], v[214:215]
	s_waitcnt lgkmcnt(0)
	v_pk_fma_f32 v[122:123], v[180:181], v[234:235], v[218:219]
	v_pk_mul_f32 v[168:169], v[186:187], 0.5 op_sel_hi:[1,0]
	v_pk_fma_f32 v[128:129], v[176:177], v[124:125], v[216:217]
	v_pk_fma_f32 v[124:125], v[176:177], v[236:237], v[220:221]
	v_pk_mul_f32 v[186:187], v[178:179], v[122:123]
	v_pk_mul_f32 v[166:167], v[188:189], 0.5 op_sel_hi:[1,0]
	global_store_dwordx4 v205, v[126:129], s[20:21] nt
	v_pk_mul_f32 v[170:171], v[174:175], v[128:129]
	v_pk_mul_f32 v[172:173], v[178:179], v[126:127]
	v_pk_mul_f32 v[206:207], v[174:175], v[124:125]
	v_cvt_pk_bf16_f32 v188, v172, v173
	v_cvt_pk_bf16_f32 v189, v170, v171
	global_store_dwordx4 v238, v[122:125], s[20:21] nt
	v_cvt_pk_bf16_f32 v186, v186, v187
	v_cvt_pk_bf16_f32 v187, v206, v207
	ds_write_b128 v200, v[118:121]
	ds_write_b128 v200, v[114:117] offset:64
	ds_read_b128 v[114:117], v201
	ds_read_b128 v[206:209], v201 offset:1152
	v_pk_add_f32 v[190:191], v[212:213], 1.0 op_sel_hi:[1,0]
	v_pk_add_f32 v[118:119], v[210:211], 1.0 op_sel_hi:[1,0]
	v_pk_mul_f32 v[170:171], v[224:225], v[190:191]
	v_pk_mul_f32 v[172:173], v[222:223], v[118:119]
	s_waitcnt lgkmcnt(1)
	v_pk_fma_f32 v[120:121], v[166:167], v[116:117], v[228:229]
	v_pk_fma_f32 v[118:119], v[168:169], v[114:115], v[226:227]
	s_waitcnt lgkmcnt(0)
	v_pk_fma_f32 v[114:115], v[168:169], v[206:207], v[230:231]
	v_pk_mul_f32 v[190:191], v[170:171], v[120:121]
	v_pk_mul_f32 v[206:207], v[172:173], v[118:119]
	global_store_dwordx4 v205, v[118:121], s[20:21] offset:128 nt
	v_cvt_pk_bf16_f32 v206, v206, v207
	v_cvt_pk_bf16_f32 v191, v190, v191
	ds_bpermute_b32 v190, v203, v206
	ds_bpermute_b32 v191, v203, v191
	v_pk_fma_f32 v[116:117], v[166:167], v[208:209], v[232:233]
	v_pk_mul_f32 v[206:207], v[172:173], v[114:115]
	global_store_dwordx4 v204, v[114:117], s[20:21] nt
	v_cvt_pk_bf16_f32 v204, v206, v207
	v_lshlrev_b32_e32 v207, 1, v202
	v_pk_mul_f32 v[208:209], v[170:171], v[116:117]
	s_nop 0
	v_cvt_pk_bf16_f32 v206, v208, v209
	s_waitcnt lgkmcnt(0)
	v_add_u32_e32 v250, 0xfffff040, v207
	v_cndmask_b32_e64 v250, v207, v250, s[40:41]
	v_cndmask_b32_e64 v248, v188, v190, s[40:41]
	v_cndmask_b32_e64 v249, v189, v191, s[40:41]
	global_store_dwordx2 v250, v[248:249], s[18:19]
	v_cndmask_b32_e64 v246, v190, v188, s[40:41]
	v_cndmask_b32_e64 v247, v191, v189, s[40:41]
	s_waitcnt lgkmcnt(1)
	v_add_u32_e32 v190, 0x1040, v207
	v_cndmask_b32_e64 v190, v207, v190, s[38:39]
	global_store_dwordx2 v190, v[246:247], s[18:19]
	ds_bpermute_b32 v188, v203, v204
	ds_bpermute_b32 v189, v203, v206
	v_lshlrev_b32_e32 v206, 1, v185
	s_waitcnt lgkmcnt(0)
; #define LAS __attribute__((address_space(3)))
; #define ERN_EOFF(q, m) (eb + (unsigned)((((q) & 1) * HALF + (m) * 16) * DM + ERN_COL((q) >> 1)))
;     __device__ __forceinline__ void operator()(const f32x4 (&acc)[2][2][4][2], const Unit& u, int wr, int wc, int fr, int fq) const {
;     ...
;         ERN_LOADX(0);
; #pragma unroll
;         for (int g = 0; g < 8; ++g) { const int ai = g >> 2, m = g & 3;
;             if (g + 1 < 8) ERN_LOADX(g + 1);
;             float sq0 = 0.f, sq1 = 0.f; u32x2 hw[2][2];
; #pragma unroll
;             for (int bj = 0; bj < 2; ++bj) {
;                 *(LAS f32x4*)(st + wr_off) = acc[ai][bj][m][0]; *(LAS f32x4*)(st + wr_off + 64) = acc[ai][bj][m][1];
;                 const f32x4 a0 = *(const LAS f32x4*)(st + rd_off), a1 = *(const LAS f32x4*)(st + rd_off + 8 * 144);
;                 { const f32x4 xv = xb[g & 1][bj][0] + gv[bj] * a0; __builtin_nontemporal_store(xv, (f32x4*)((char*)xo + 4u * ERN_EOFF(g, bj, 0)));
;                   sq0 += (xv.x * xv.x + xv.y * xv.y) + (xv.z * xv.z + xv.w * xv.w);
;                   const f32x4 hv = xv * gsn[bj]; hw[bj][0].x = cvt_pk_bf16(hv.x, hv.y); hw[bj][0].y = cvt_pk_bf16(hv.z, hv.w); }
;                 { const f32x4 xv = xb[g & 1][bj][1] + gv[bj] * a1; __builtin_nontemporal_store(xv, (f32x4*)((char*)xo + 4u * ERN_EOFF(g, bj, 1)));
;                   sq1 += (xv.x * xv.x + xv.y * xv.y) + (xv.z * xv.z + xv.w * xv.w);
;                   const f32x4 hv = xv * gsn[bj]; hw[bj][1].x = cvt_pk_bf16(hv.x, hv.y); hw[bj][1].y = cvt_pk_bf16(hv.z, hv.w); }
;             }
;             if (!NOH && !PLAIN) {
; #pragma unroll
;                 for (int rh = 0; rh < 2; ++rh) { u32x2 rv; rv.x = __shfl_xor(hw[1][rh].x, 8); rv.y = __shfl_xor(hw[1][rh].y, 8);
;                     const unsigned e0 = ERN_EOFF(g, 0, rh);
;                     const unsigned ee = odd ? (e0 - DM + 32) : e0, eo2 = odd ? e0 : (e0 + DM + 32);
;                     *(u32x2*)((char*)ho + 2u * ee) = odd ? rv : hw[0][rh];
;                     *(u32x2*)((char*)ho + 2u * eo2) = odd ? hw[0][rh] : rv; }
;             }
;             if (!PLAIN) { sq0 += __shfl_xor(sq0, 1); sq0 += __shfl_xor(sq0, 2); sq0 += __shfl_xor(sq0, 4);
;             sq1 += __shfl_xor(sq1, 1); sq1 += __shfl_xor(sq1, 2); sq1 += __shfl_xor(sq1, 4); }
;             if (!PLAIN && pc == 0) { sst[g * 16 + rr] = sq0; sst[g * 16 + 8 + rr] = sq1; }
;         }
	v_add_u32_e32 v250, 0xfffff040, v206
	v_cndmask_b32_e64 v250, v206, v250, s[40:41]
	v_cndmask_b32_e64 v248, v186, v188, s[40:41]
	v_cndmask_b32_e64 v249, v187, v189, s[40:41]
	global_store_dwordx2 v250, v[248:249], s[18:19]
	v_cndmask_b32_e64 v246, v188, v186, s[40:41]
	v_cndmask_b32_e64 v247, v189, v187, s[40:41]
	v_mul_f32_e32 v119, v119, v119
	v_mul_f32_e32 v127, v127, v127
	v_mul_f32_e32 v129, v129, v129
	v_fmac_f32_e32 v119, v118, v118
	v_mul_f32_e32 v118, v121, v121
	v_fmac_f32_e32 v129, v128, v128
	v_fmac_f32_e32 v118, v120, v120
	v_mul_f32_e32 v115, v115, v115
	v_fmac_f32_e32 v127, v126, v126
	v_add_f32_e32 v118, v119, v118
	v_fmac_f32_e32 v115, v114, v114
	v_mul_f32_e32 v114, v117, v117
	v_add_f32_e32 v117, v127, v129
	v_add_f32_e32 v117, v117, v118
	v_xor_b32_e32 v118, 1, v199
	v_cmp_lt_i32_e32 vcc, v118, v183
	v_mul_f32_e32 v123, v123, v123
	v_mul_f32_e32 v125, v125, v125
	v_cndmask_b32_e32 v118, v199, v118, vcc
	v_lshlrev_b32_e32 v190, 2, v118
	ds_bpermute_b32 v118, v190, v117
	v_fmac_f32_e32 v114, v116, v116
	v_fmac_f32_e32 v125, v124, v124
	v_fmac_f32_e32 v123, v122, v122
	v_add_f32_e32 v114, v115, v114
	s_waitcnt lgkmcnt(0)
	v_add_f32_e32 v116, v117, v118
	v_xor_b32_e32 v117, 2, v199
	v_cmp_lt_i32_e32 vcc, v117, v183
	v_add_f32_e32 v115, v123, v125
	v_add_f32_e32 v115, v115, v114
	v_cndmask_b32_e32 v117, v199, v117, vcc
	v_lshlrev_b32_e32 v191, 2, v117
	ds_bpermute_b32 v117, v191, v116
	ds_bpermute_b32 v118, v190, v115
	s_waitcnt lgkmcnt(1)
	v_add_f32_e32 v114, v116, v117
	s_waitcnt lgkmcnt(0)
	v_add_f32_e32 v117, v115, v118
	ds_bpermute_b32 v118, v191, v117
	v_xor_b32_e32 v116, 4, v199
	v_cmp_lt_i32_e32 vcc, v116, v183
	s_nop 1
	v_cndmask_b32_e32 v115, v199, v116, vcc
	v_lshlrev_b32_e32 v204, 2, v115
	s_waitcnt lgkmcnt(0)
	v_add_f32_e32 v116, v117, v118
	ds_bpermute_b32 v115, v204, v114
	ds_bpermute_b32 v117, v204, v116
	v_add_u32_e32 v118, 0x1040, v206
	v_cndmask_b32_e64 v118, v206, v118, s[38:39]
	global_store_dwordx2 v118, v[246:247], s[18:19]
	s_and_saveexec_b64 s[22:23], s[42:43]
	s_cbranch_execz .LBB0_1939
	s_waitcnt lgkmcnt(1)
	v_add_f32_e32 v114, v114, v115
	s_waitcnt lgkmcnt(0)
	v_add_f32_e32 v115, v116, v117
	ds_write2_b32 v194, v114, v115 offset1:8
.LBB0_1939:
	s_or_b64 exec, exec, s[22:23]
	v_lshl_add_u64 v[206:207], s[20:21], 0, v[154:155]
	v_add_u32_e32 v114, 0x40000, v205
	v_add_u32_e32 v154, 0x50000, v205
	v_add_u32_e32 v186, 0x40080, v205
	global_load_dwordx4 v[122:125], v154, s[20:21] nt
	global_load_dwordx4 v[118:121], v186, s[20:21] nt
	v_add_u32_e32 v188, 0x50080, v205
	global_load_dwordx4 v[126:129], v114, s[20:21] nt
	s_waitcnt lgkmcnt(0)
	global_load_dwordx4 v[114:117], v188, s[20:21] nt
	ds_write_b128 v200, v[110:113]
	ds_write_b128 v200, v[106:109] offset:64
	ds_read_b128 v[106:109], v201
	ds_read_b128 v[110:113], v201 offset:1152
	v_mov_b32_e32 v185, v155
	v_mov_b32_e32 v183, v155
	v_lshl_add_u64 v[182:183], s[20:21], 0, v[182:183]
	s_waitcnt lgkmcnt(1)
	v_pk_fma_f32 v[108:109], v[176:177], v[108:109], v[144:145]
	v_add_u32_e32 v144, 0x8000, v202
	v_pk_fma_f32 v[106:107], v[180:181], v[106:107], v[142:143]
	v_lshlrev_b32_e32 v142, 2, v144
	s_waitcnt lgkmcnt(0)
	v_pk_fma_f32 v[110:111], v[180:181], v[110:111], v[138:139]
	global_store_dwordx4 v142, v[106:109], s[20:21] nt
	v_pk_mul_f32 v[142:143], v[178:179], v[106:107]
	v_pk_fma_f32 v[112:113], v[176:177], v[112:113], v[140:141]
	v_pk_mul_f32 v[138:139], v[178:179], v[110:111]
	v_pk_mul_f32 v[208:209], v[174:175], v[108:109]
	v_cvt_pk_bf16_f32 v142, v142, v143
	v_pk_mul_f32 v[140:141], v[174:175], v[112:113]
	v_cvt_pk_bf16_f32 v143, v208, v209
	global_store_dwordx4 v[206:207], v[110:113], off nt
	v_cvt_pk_bf16_f32 v138, v138, v139
	v_cvt_pk_bf16_f32 v139, v140, v141
	ds_write_b128 v200, v[102:105]
	ds_write_b128 v200, v[98:101] offset:64
	ds_read_b128 v[98:101], v201
	ds_read_b128 v[102:105], v201 offset:1152
	v_lshl_add_u64 v[140:141], s[20:21], 0, v[184:185]
	s_waitcnt lgkmcnt(1)
	v_pk_fma_f32 v[98:99], v[168:169], v[98:99], v[134:135]
	v_pk_fma_f32 v[100:101], v[166:167], v[100:101], v[136:137]
	v_pk_mul_f32 v[136:137], v[172:173], v[98:99]
	global_store_dwordx4 v[140:141], v[98:101], off nt
	v_pk_mul_f32 v[134:135], v[170:171], v[100:101]
	v_cvt_pk_bf16_f32 v136, v136, v137
	s_waitcnt lgkmcnt(0)
	v_pk_fma_f32 v[102:103], v[168:169], v[102:103], v[130:131]
	v_cvt_pk_bf16_f32 v137, v134, v135
	ds_bpermute_b32 v130, v203, v136
	ds_bpermute_b32 v131, v203, v137
	v_pk_fma_f32 v[104:105], v[166:167], v[104:105], v[132:133]
	v_pk_mul_f32 v[132:133], v[172:173], v[102:103]
	v_pk_mul_f32 v[134:135], v[170:171], v[104:105]
	global_store_dwordx4 v[182:183], v[102:105], off nt
	v_cvt_pk_bf16_f32 v132, v132, v133
	v_cvt_pk_bf16_f32 v133, v134, v135
	v_lshlrev_b32_e32 v134, 1, v144
	s_waitcnt lgkmcnt(0)
	v_add_u32_e32 v250, 0xfffff040, v134
	v_cndmask_b32_e64 v250, v134, v250, s[40:41]
	v_cndmask_b32_e64 v248, v142, v130, s[40:41]
	v_cndmask_b32_e64 v249, v143, v131, s[40:41]
	global_store_dwordx2 v250, v[248:249], s[18:19]
	v_cndmask_b32_e64 v246, v130, v142, s[40:41]
	v_cndmask_b32_e64 v247, v131, v143, s[40:41]
	s_waitcnt lgkmcnt(1)
	v_add_u32_e32 v130, 0x1040, v134
	v_cndmask_b32_e64 v130, v134, v130, s[38:39]
	global_store_dwordx2 v130, v[246:247], s[18:19]
	ds_bpermute_b32 v130, v203, v132
	s_waitcnt lgkmcnt(1)
	ds_bpermute_b32 v131, v203, v133
	v_add_u32_e32 v133, 0xc000, v202
	v_lshlrev_b32_e32 v132, 1, v133
	s_waitcnt lgkmcnt(0)
	v_add_u32_e32 v250, 0xfffff040, v132
	v_cndmask_b32_e64 v250, v132, v250, s[40:41]
	v_cndmask_b32_e64 v248, v138, v130, s[40:41]
	v_cndmask_b32_e64 v249, v139, v131, s[40:41]
	global_store_dwordx2 v250, v[248:249], s[18:19]
	v_cndmask_b32_e64 v246, v130, v138, s[40:41]
	v_cndmask_b32_e64 v247, v131, v139, s[40:41]
	v_mul_f32_e32 v99, v99, v99
	v_fmac_f32_e32 v99, v98, v98
	v_mul_f32_e32 v98, v101, v101
	v_mul_f32_e32 v109, v109, v109
	v_fmac_f32_e32 v98, v100, v100
	v_mul_f32_e32 v107, v107, v107
	v_fmac_f32_e32 v109, v108, v108
	v_mul_f32_e32 v108, v111, v111
	v_mul_f32_e32 v111, v113, v113
	v_add_f32_e32 v98, v99, v98
	v_mul_f32_e32 v99, v103, v103
	v_mul_f32_e32 v100, v105, v105
	v_fmac_f32_e32 v111, v112, v112
	v_fmac_f32_e32 v99, v102, v102
	v_fmac_f32_e32 v100, v104, v104
	v_fmac_f32_e32 v107, v106, v106
	v_fmac_f32_e32 v108, v110, v110
	v_add_f32_e32 v99, v99, v100
	v_add_f32_e32 v100, v107, v109
	v_add_f32_e32 v101, v108, v111
	v_add_f32_e32 v98, v100, v98
	v_add_f32_e32 v99, v101, v99
	ds_bpermute_b32 v100, v190, v98
	ds_bpermute_b32 v101, v190, v99
	s_waitcnt lgkmcnt(1)
	v_add_f32_e32 v98, v98, v100
	s_waitcnt lgkmcnt(0)
	v_add_f32_e32 v101, v99, v101
	ds_bpermute_b32 v100, v191, v98
	ds_bpermute_b32 v102, v191, v101
	s_waitcnt lgkmcnt(1)
	v_add_f32_e32 v98, v98, v100
	s_waitcnt lgkmcnt(0)
	v_add_f32_e32 v100, v101, v102
	ds_bpermute_b32 v99, v204, v98
	ds_bpermute_b32 v101, v204, v100
	v_add_u32_e32 v102, 0x1040, v132
	v_cndmask_b32_e64 v102, v132, v102, s[38:39]
	global_store_dwordx2 v102, v[246:247], s[18:19]
	s_and_saveexec_b64 s[22:23], s[42:43]
	s_cbranch_execz .LBB0_1949
; #define LAS __attribute__((address_space(3)))
; #define ERN_EOFF(q, m) (eb + (unsigned)((((q) & 1) * HALF + (m) * 16) * DM + ERN_COL((q) >> 1)))
;     __device__ __forceinline__ void operator()(const f32x4 (&acc)[2][2][4][2], const Unit& u, int wr, int wc, int fr, int fq) const {
;     ...
;         ERN_LOADX(0);
; #pragma unroll
;         for (int g = 0; g < 8; ++g) { const int ai = g >> 2, m = g & 3;
;             if (g + 1 < 8) ERN_LOADX(g + 1);
;             float sq0 = 0.f, sq1 = 0.f; u32x2 hw[2][2];
; #pragma unroll
;             for (int bj = 0; bj < 2; ++bj) {
;                 *(LAS f32x4*)(st + wr_off) = acc[ai][bj][m][0]; *(LAS f32x4*)(st + wr_off + 64) = acc[ai][bj][m][1];
;                 const f32x4 a0 = *(const LAS f32x4*)(st + rd_off), a1 = *(const LAS f32x4*)(st + rd_off + 8 * 144);
;                 { const f32x4 xv = xb[g & 1][bj][0] + gv[bj] * a0; __builtin_nontemporal_store(xv, (f32x4*)((char*)xo + 4u * ERN_EOFF(g, bj, 0)));
;                   sq0 += (xv.x * xv.x + xv.y * xv.y) + (xv.z * xv.z + xv.w * xv.w);
;                   const f32x4 hv = xv * gsn[bj]; hw[bj][0].x = cvt_pk_bf16(hv.x, hv.y); hw[bj][0].y = cvt_pk_bf16(hv.z, hv.w); }
;                 { const f32x4 xv = xb[g & 1][bj][1] + gv[bj] * a1; __builtin_nontemporal_store(xv, (f32x4*)((char*)xo + 4u * ERN_EOFF(g, bj, 1)));
;                   sq1 += (xv.x * xv.x + xv.y * xv.y) + (xv.z * xv.z + xv.w * xv.w);
;                   const f32x4 hv = xv * gsn[bj]; hw[bj][1].x = cvt_pk_bf16(hv.x, hv.y); hw[bj][1].y = cvt_pk_bf16(hv.z, hv.w); }
;             }
;             if (!NOH && !PLAIN) {
; #pragma unroll
;                 for (int rh = 0; rh < 2; ++rh) { u32x2 rv; rv.x = __shfl_xor(hw[1][rh].x, 8); rv.y = __shfl_xor(hw[1][rh].y, 8);
;                     const unsigned e0 = ERN_EOFF(g, 0, rh);
;                     const unsigned ee = odd ? (e0 - DM + 32) : e0, eo2 = odd ? e0 : (e0 + DM + 32);
;                     *(u32x2*)((char*)ho + 2u * ee) = odd ? rv : hw[0][rh];
;                     *(u32x2*)((char*)ho + 2u * eo2) = odd ? hw[0][rh] : rv; }
;             }
;             if (!PLAIN) { sq0 += __shfl_xor(sq0, 1); sq0 += __shfl_xor(sq0, 2); sq0 += __shfl_xor(sq0, 4);
;             sq1 += __shfl_xor(sq1, 1); sq1 += __shfl_xor(sq1, 2); sq1 += __shfl_xor(sq1, 4); }
;             if (!PLAIN && pc == 0) { sst[g * 16 + rr] = sq0; sst[g * 16 + 8 + rr] = sq1; }
;         }
	s_waitcnt lgkmcnt(1)
	v_add_f32_e32 v98, v98, v99
	s_waitcnt lgkmcnt(0)
	v_add_f32_e32 v99, v100, v101
	ds_write2_b32 v194, v98, v99 offset0:16 offset1:24
.LBB0_1949:
	s_or_b64 exec, exec, s[22:23]
	v_lshl_add_u64 v[134:135], s[20:21], 0, v[154:155]
	v_add_u32_e32 v98, 0x60000, v205
	v_add_u32_e32 v154, 0x70000, v205
	v_add_u32_e32 v130, 0x60080, v205
	global_load_dwordx4 v[106:109], v154, s[20:21] nt
	global_load_dwordx4 v[102:105], v130, s[20:21] nt
	v_add_u32_e32 v132, 0x70080, v205
	global_load_dwordx4 v[110:113], v98, s[20:21] nt
	s_waitcnt lgkmcnt(0)
	global_load_dwordx4 v[98:101], v132, s[20:21] nt
	ds_write_b128 v200, v[94:97]
	ds_write_b128 v200, v[90:93] offset:64
	ds_read_b128 v[90:93], v201
	ds_read_b128 v[94:97], v201 offset:1152
	v_mov_b32_e32 v187, v155
	v_mov_b32_e32 v189, v155
	s_waitcnt vmcnt(11) lgkmcnt(1)
	v_pk_fma_f32 v[92:93], v[176:177], v[92:93], v[128:129]
	v_add_u32_e32 v128, 0x10000, v202
	v_pk_fma_f32 v[90:91], v[180:181], v[90:91], v[126:127]
	v_lshlrev_b32_e32 v126, 2, v128
	s_waitcnt lgkmcnt(0)
	v_pk_fma_f32 v[94:95], v[180:181], v[94:95], v[122:123]
	global_store_dwordx4 v126, v[90:93], s[20:21] nt
	v_pk_mul_f32 v[126:127], v[178:179], v[90:91]
	v_pk_fma_f32 v[96:97], v[176:177], v[96:97], v[124:125]
	v_pk_mul_f32 v[122:123], v[178:179], v[94:95]
	v_pk_mul_f32 v[136:137], v[174:175], v[92:93]
	v_cvt_pk_bf16_f32 v126, v126, v127
	v_pk_mul_f32 v[124:125], v[174:175], v[96:97]
	v_cvt_pk_bf16_f32 v127, v136, v137
	global_store_dwordx4 v[134:135], v[94:97], off nt
	v_cvt_pk_bf16_f32 v122, v122, v123
	v_cvt_pk_bf16_f32 v123, v124, v125
	ds_write_b128 v200, v[86:89]
	ds_write_b128 v200, v[82:85] offset:64
	ds_read_b128 v[82:85], v201
	ds_read_b128 v[86:89], v201 offset:1152
	v_lshl_add_u64 v[124:125], s[20:21], 0, v[186:187]
	v_lshl_add_u64 v[134:135], s[20:21], 0, v[188:189]
	s_waitcnt lgkmcnt(1)
	v_pk_fma_f32 v[82:83], v[168:169], v[82:83], v[118:119]
	v_pk_fma_f32 v[84:85], v[166:167], v[84:85], v[120:121]
	v_pk_mul_f32 v[120:121], v[172:173], v[82:83]
	global_store_dwordx4 v[124:125], v[82:85], off nt
	v_pk_mul_f32 v[118:119], v[170:171], v[84:85]
	v_cvt_pk_bf16_f32 v120, v120, v121
	s_waitcnt vmcnt(13) lgkmcnt(0)
	v_pk_fma_f32 v[86:87], v[168:169], v[86:87], v[114:115]
	v_cvt_pk_bf16_f32 v121, v118, v119
	ds_bpermute_b32 v114, v203, v120
	ds_bpermute_b32 v115, v203, v121
	v_pk_fma_f32 v[88:89], v[166:167], v[88:89], v[116:117]
	v_pk_mul_f32 v[116:117], v[172:173], v[86:87]
	v_pk_mul_f32 v[118:119], v[170:171], v[88:89]
	global_store_dwordx4 v[134:135], v[86:89], off nt
	v_cvt_pk_bf16_f32 v116, v116, v117
	v_cvt_pk_bf16_f32 v117, v118, v119
	v_lshlrev_b32_e32 v118, 1, v128
	s_waitcnt lgkmcnt(0)
	v_add_u32_e32 v250, 0xfffff040, v118
	v_cndmask_b32_e64 v250, v118, v250, s[40:41]
	v_cndmask_b32_e64 v248, v126, v114, s[40:41]
	v_cndmask_b32_e64 v249, v127, v115, s[40:41]
	global_store_dwordx2 v250, v[248:249], s[18:19]
	v_cndmask_b32_e64 v246, v114, v126, s[40:41]
	v_cndmask_b32_e64 v247, v115, v127, s[40:41]
	s_waitcnt lgkmcnt(1)
	v_add_u32_e32 v114, 0x1040, v118
	v_cndmask_b32_e64 v114, v118, v114, s[38:39]
	global_store_dwordx2 v114, v[246:247], s[18:19]
	ds_bpermute_b32 v114, v203, v116
	s_waitcnt lgkmcnt(1)
	ds_bpermute_b32 v115, v203, v117
	v_add_u32_e32 v117, 0x14000, v202
	v_lshlrev_b32_e32 v116, 1, v117
	s_waitcnt lgkmcnt(0)
	v_add_u32_e32 v250, 0xfffff040, v116
	v_cndmask_b32_e64 v250, v116, v250, s[40:41]
	v_cndmask_b32_e64 v248, v122, v114, s[40:41]
	v_cndmask_b32_e64 v249, v123, v115, s[40:41]
	global_store_dwordx2 v250, v[248:249], s[18:19]
	v_cndmask_b32_e64 v246, v114, v122, s[40:41]
	v_cndmask_b32_e64 v247, v115, v123, s[40:41]
	v_mul_f32_e32 v83, v83, v83
	v_fmac_f32_e32 v83, v82, v82
	v_mul_f32_e32 v82, v85, v85
	v_mul_f32_e32 v93, v93, v93
	v_fmac_f32_e32 v82, v84, v84
	v_mul_f32_e32 v91, v91, v91
	v_fmac_f32_e32 v93, v92, v92
	v_mul_f32_e32 v92, v95, v95
	v_mul_f32_e32 v95, v97, v97
	v_add_f32_e32 v82, v83, v82
	v_mul_f32_e32 v83, v87, v87
	v_mul_f32_e32 v84, v89, v89
	v_fmac_f32_e32 v95, v96, v96
	v_fmac_f32_e32 v83, v86, v86
	v_fmac_f32_e32 v84, v88, v88
	v_fmac_f32_e32 v91, v90, v90
	v_fmac_f32_e32 v92, v94, v94
	v_add_f32_e32 v83, v83, v84
	v_add_f32_e32 v84, v91, v93
	v_add_f32_e32 v85, v92, v95
	v_add_f32_e32 v82, v84, v82
	v_add_f32_e32 v83, v85, v83
	ds_bpermute_b32 v84, v190, v82
	ds_bpermute_b32 v85, v190, v83
	s_waitcnt lgkmcnt(1)
	v_add_f32_e32 v82, v82, v84
	s_waitcnt lgkmcnt(0)
	v_add_f32_e32 v85, v83, v85
	ds_bpermute_b32 v84, v191, v82
	ds_bpermute_b32 v86, v191, v85
	s_waitcnt lgkmcnt(1)
	v_add_f32_e32 v82, v82, v84
	s_waitcnt lgkmcnt(0)
	v_add_f32_e32 v84, v85, v86
	ds_bpermute_b32 v83, v204, v82
	ds_bpermute_b32 v85, v204, v84
	v_add_u32_e32 v86, 0x1040, v116
	v_cndmask_b32_e64 v86, v116, v86, s[38:39]
	global_store_dwordx2 v86, v[246:247], s[18:19]
	s_and_saveexec_b64 s[22:23], s[42:43]
	s_cbranch_execz .LBB0_1959
	s_waitcnt lgkmcnt(1)
	v_add_f32_e32 v82, v82, v83
	s_waitcnt lgkmcnt(0)
	v_add_f32_e32 v83, v84, v85
	ds_write2_b32 v194, v82, v83 offset0:32 offset1:40
; #define LAS __attribute__((address_space(3)))
; #define ERN_EOFF(q, m) (eb + (unsigned)((((q) & 1) * HALF + (m) * 16) * DM + ERN_COL((q) >> 1)))
;     __device__ __forceinline__ void operator()(const f32x4 (&acc)[2][2][4][2], const Unit& u, int wr, int wc, int fr, int fq) const {
;     ...
;         ERN_LOADX(0);
; #pragma unroll
;         for (int g = 0; g < 8; ++g) { const int ai = g >> 2, m = g & 3;
;             if (g + 1 < 8) ERN_LOADX(g + 1);
;             float sq0 = 0.f, sq1 = 0.f; u32x2 hw[2][2];
; #pragma unroll
;             for (int bj = 0; bj < 2; ++bj) {
;                 *(LAS f32x4*)(st + wr_off) = acc[ai][bj][m][0]; *(LAS f32x4*)(st + wr_off + 64) = acc[ai][bj][m][1];
;                 const f32x4 a0 = *(const LAS f32x4*)(st + rd_off), a1 = *(const LAS f32x4*)(st + rd_off + 8 * 144);
;                 { const f32x4 xv = xb[g & 1][bj][0] + gv[bj] * a0; __builtin_nontemporal_store(xv, (f32x4*)((char*)xo + 4u * ERN_EOFF(g, bj, 0)));
;                   sq0 += (xv.x * xv.x + xv.y * xv.y) + (xv.z * xv.z + xv.w * xv.w);
;                   const f32x4 hv = xv * gsn[bj]; hw[bj][0].x = cvt_pk_bf16(hv.x, hv.y); hw[bj][0].y = cvt_pk_bf16(hv.z, hv.w); }
;                 { const f32x4 xv = xb[g & 1][bj][1] + gv[bj] * a1; __builtin_nontemporal_store(xv, (f32x4*)((char*)xo + 4u * ERN_EOFF(g, bj, 1)));
;                   sq1 += (xv.x * xv.x + xv.y * xv.y) + (xv.z * xv.z + xv.w * xv.w);
;                   const f32x4 hv = xv * gsn[bj]; hw[bj][1].x = cvt_pk_bf16(hv.x, hv.y); hw[bj][1].y = cvt_pk_bf16(hv.z, hv.w); }
;             }
;             if (!NOH && !PLAIN) {
; #pragma unroll
;                 for (int rh = 0; rh < 2; ++rh) { u32x2 rv; rv.x = __shfl_xor(hw[1][rh].x, 8); rv.y = __shfl_xor(hw[1][rh].y, 8);
;                     const unsigned e0 = ERN_EOFF(g, 0, rh);
;                     const unsigned ee = odd ? (e0 - DM + 32) : e0, eo2 = odd ? e0 : (e0 + DM + 32);
;                     *(u32x2*)((char*)ho + 2u * ee) = odd ? rv : hw[0][rh];
;                     *(u32x2*)((char*)ho + 2u * eo2) = odd ? hw[0][rh] : rv; }
;             }
;             if (!PLAIN) { sq0 += __shfl_xor(sq0, 1); sq0 += __shfl_xor(sq0, 2); sq0 += __shfl_xor(sq0, 4);
;             sq1 += __shfl_xor(sq1, 1); sq1 += __shfl_xor(sq1, 2); sq1 += __shfl_xor(sq1, 4); }
;             if (!PLAIN && pc == 0) { sst[g * 16 + rr] = sq0; sst[g * 16 + 8 + rr] = sq1; }
;         }
.LBB0_1959:
	s_or_b64 exec, exec, s[22:23]
	v_lshl_add_u64 v[116:117], s[20:21], 0, v[154:155]
	v_add_u32_e32 v82, 0x100000, v205
	s_waitcnt lgkmcnt(1)
	v_add_u32_e32 v83, 0x110000, v205
	v_add_u32_e32 v154, 0x100080, v205
	global_load_dwordx4 v[94:97], v82, s[20:21] nt
	global_load_dwordx4 v[90:93], v83, s[20:21] nt
	v_add_u32_e32 v114, 0x110080, v205
	global_load_dwordx4 v[86:89], v154, s[20:21] nt
	s_waitcnt lgkmcnt(0)
	global_load_dwordx4 v[82:85], v114, s[20:21] nt
	ds_write_b128 v200, v[78:81]
	ds_write_b128 v200, v[74:77] offset:64
	ds_read_b128 v[74:77], v201
	ds_read_b128 v[78:81], v201 offset:1152
	v_mov_b32_e32 v131, v155
	v_mov_b32_e32 v133, v155
	s_waitcnt vmcnt(11) lgkmcnt(1)
	v_pk_fma_f32 v[76:77], v[176:177], v[76:77], v[112:113]
	v_add_u32_e32 v112, 0x18000, v202
	v_pk_fma_f32 v[74:75], v[180:181], v[74:75], v[110:111]
	v_lshlrev_b32_e32 v110, 2, v112
	s_waitcnt lgkmcnt(0)
	v_pk_fma_f32 v[78:79], v[180:181], v[78:79], v[106:107]
	global_store_dwordx4 v110, v[74:77], s[20:21] nt
	v_pk_mul_f32 v[110:111], v[178:179], v[74:75]
	v_pk_fma_f32 v[80:81], v[176:177], v[80:81], v[108:109]
	v_pk_mul_f32 v[106:107], v[178:179], v[78:79]
	v_pk_mul_f32 v[118:119], v[174:175], v[76:77]
	v_cvt_pk_bf16_f32 v110, v110, v111
	v_pk_mul_f32 v[108:109], v[174:175], v[80:81]
	v_cvt_pk_bf16_f32 v111, v118, v119
	global_store_dwordx4 v[116:117], v[78:81], off nt
	v_cvt_pk_bf16_f32 v106, v106, v107
	v_cvt_pk_bf16_f32 v107, v108, v109
	ds_write_b128 v200, v[70:73]
	ds_write_b128 v200, v[66:69] offset:64
	ds_read_b128 v[66:69], v201
	ds_read_b128 v[70:73], v201 offset:1152
	v_lshl_add_u64 v[108:109], s[20:21], 0, v[130:131]
	v_lshl_add_u64 v[116:117], s[20:21], 0, v[132:133]
	s_waitcnt lgkmcnt(1)
	v_pk_fma_f32 v[66:67], v[168:169], v[66:67], v[102:103]
	v_pk_fma_f32 v[68:69], v[166:167], v[68:69], v[104:105]
	v_pk_mul_f32 v[104:105], v[172:173], v[66:67]
	global_store_dwordx4 v[108:109], v[66:69], off nt
	v_pk_mul_f32 v[102:103], v[170:171], v[68:69]
	v_cvt_pk_bf16_f32 v104, v104, v105
	s_waitcnt vmcnt(13) lgkmcnt(0)
	v_pk_fma_f32 v[70:71], v[168:169], v[70:71], v[98:99]
	v_cvt_pk_bf16_f32 v105, v102, v103
	ds_bpermute_b32 v98, v203, v104
	ds_bpermute_b32 v99, v203, v105
	v_pk_fma_f32 v[72:73], v[166:167], v[72:73], v[100:101]
	v_pk_mul_f32 v[100:101], v[172:173], v[70:71]
	v_pk_mul_f32 v[102:103], v[170:171], v[72:73]
	global_store_dwordx4 v[116:117], v[70:73], off nt
	v_cvt_pk_bf16_f32 v100, v100, v101
	v_cvt_pk_bf16_f32 v101, v102, v103
	v_lshlrev_b32_e32 v102, 1, v112
	s_waitcnt lgkmcnt(0)
	v_add_u32_e32 v250, 0xfffff040, v102
	v_cndmask_b32_e64 v250, v102, v250, s[40:41]
	v_cndmask_b32_e64 v248, v110, v98, s[40:41]
	v_cndmask_b32_e64 v249, v111, v99, s[40:41]
	global_store_dwordx2 v250, v[248:249], s[18:19]
	v_cndmask_b32_e64 v246, v98, v110, s[40:41]
	v_cndmask_b32_e64 v247, v99, v111, s[40:41]
	s_waitcnt lgkmcnt(1)
	v_add_u32_e32 v98, 0x1040, v102
	v_cndmask_b32_e64 v98, v102, v98, s[38:39]
	global_store_dwordx2 v98, v[246:247], s[18:19]
	ds_bpermute_b32 v98, v203, v100
	s_waitcnt lgkmcnt(1)
	ds_bpermute_b32 v99, v203, v101
	v_add_u32_e32 v101, 0x1c000, v202
	v_lshlrev_b32_e32 v100, 1, v101
	s_waitcnt lgkmcnt(0)
	v_add_u32_e32 v250, 0xfffff040, v100
	v_cndmask_b32_e64 v250, v100, v250, s[40:41]
	v_cndmask_b32_e64 v248, v106, v98, s[40:41]
	v_cndmask_b32_e64 v249, v107, v99, s[40:41]
	global_store_dwordx2 v250, v[248:249], s[18:19]
	v_cndmask_b32_e64 v246, v98, v106, s[40:41]
	v_cndmask_b32_e64 v247, v99, v107, s[40:41]
	v_mul_f32_e32 v67, v67, v67
	v_fmac_f32_e32 v67, v66, v66
	v_mul_f32_e32 v66, v69, v69
	v_mul_f32_e32 v77, v77, v77
	v_fmac_f32_e32 v66, v68, v68
	v_mul_f32_e32 v75, v75, v75
	v_fmac_f32_e32 v77, v76, v76
	v_mul_f32_e32 v76, v79, v79
	v_mul_f32_e32 v79, v81, v81
	v_add_f32_e32 v66, v67, v66
	v_mul_f32_e32 v67, v71, v71
	v_mul_f32_e32 v68, v73, v73
	v_fmac_f32_e32 v79, v80, v80
	v_fmac_f32_e32 v67, v70, v70
	v_fmac_f32_e32 v68, v72, v72
	v_fmac_f32_e32 v75, v74, v74
	v_fmac_f32_e32 v76, v78, v78
	v_add_f32_e32 v67, v67, v68
	v_add_f32_e32 v68, v75, v77
	v_add_f32_e32 v69, v76, v79
	v_add_f32_e32 v66, v68, v66
	v_add_f32_e32 v67, v69, v67
	ds_bpermute_b32 v68, v190, v66
	ds_bpermute_b32 v69, v190, v67
	s_waitcnt lgkmcnt(1)
	v_add_f32_e32 v66, v66, v68
	s_waitcnt lgkmcnt(0)
	v_add_f32_e32 v69, v67, v69
	ds_bpermute_b32 v68, v191, v66
	ds_bpermute_b32 v70, v191, v69
	s_waitcnt lgkmcnt(1)
	v_add_f32_e32 v66, v66, v68
	s_waitcnt lgkmcnt(0)
	v_add_f32_e32 v68, v69, v70
	ds_bpermute_b32 v67, v204, v66
	ds_bpermute_b32 v69, v204, v68
	v_add_u32_e32 v70, 0x1040, v100
	v_cndmask_b32_e64 v70, v100, v70, s[38:39]
	global_store_dwordx2 v70, v[246:247], s[18:19]
	s_and_saveexec_b64 s[22:23], s[42:43]
	s_cbranch_execz .LBB0_1969
	s_waitcnt lgkmcnt(1)
	v_add_f32_e32 v66, v66, v67
	s_waitcnt lgkmcnt(0)
	v_add_f32_e32 v67, v68, v69
	ds_write2_b32 v194, v66, v67 offset0:48 offset1:56
; #define LAS __attribute__((address_space(3)))
; #define ERN_EOFF(q, m) (eb + (unsigned)((((q) & 1) * HALF + (m) * 16) * DM + ERN_COL((q) >> 1)))
;     __device__ __forceinline__ void operator()(const f32x4 (&acc)[2][2][4][2], const Unit& u, int wr, int wc, int fr, int fq) const {
;     ...
;         ERN_LOADX(0);
; #pragma unroll
;         for (int g = 0; g < 8; ++g) { const int ai = g >> 2, m = g & 3;
;             if (g + 1 < 8) ERN_LOADX(g + 1);
;             float sq0 = 0.f, sq1 = 0.f; u32x2 hw[2][2];
; #pragma unroll
;             for (int bj = 0; bj < 2; ++bj) {
;                 *(LAS f32x4*)(st + wr_off) = acc[ai][bj][m][0]; *(LAS f32x4*)(st + wr_off + 64) = acc[ai][bj][m][1];
;                 const f32x4 a0 = *(const LAS f32x4*)(st + rd_off), a1 = *(const LAS f32x4*)(st + rd_off + 8 * 144);
;                 { const f32x4 xv = xb[g & 1][bj][0] + gv[bj] * a0; __builtin_nontemporal_store(xv, (f32x4*)((char*)xo + 4u * ERN_EOFF(g, bj, 0)));
;                   sq0 += (xv.x * xv.x + xv.y * xv.y) + (xv.z * xv.z + xv.w * xv.w);
;                   const f32x4 hv = xv * gsn[bj]; hw[bj][0].x = cvt_pk_bf16(hv.x, hv.y); hw[bj][0].y = cvt_pk_bf16(hv.z, hv.w); }
;                 { const f32x4 xv = xb[g & 1][bj][1] + gv[bj] * a1; __builtin_nontemporal_store(xv, (f32x4*)((char*)xo + 4u * ERN_EOFF(g, bj, 1)));
;                   sq1 += (xv.x * xv.x + xv.y * xv.y) + (xv.z * xv.z + xv.w * xv.w);
;                   const f32x4 hv = xv * gsn[bj]; hw[bj][1].x = cvt_pk_bf16(hv.x, hv.y); hw[bj][1].y = cvt_pk_bf16(hv.z, hv.w); }
;             }
;             if (!NOH && !PLAIN) {
; #pragma unroll
;                 for (int rh = 0; rh < 2; ++rh) { u32x2 rv; rv.x = __shfl_xor(hw[1][rh].x, 8); rv.y = __shfl_xor(hw[1][rh].y, 8);
;                     const unsigned e0 = ERN_EOFF(g, 0, rh);
;                     const unsigned ee = odd ? (e0 - DM + 32) : e0, eo2 = odd ? e0 : (e0 + DM + 32);
;                     *(u32x2*)((char*)ho + 2u * ee) = odd ? rv : hw[0][rh];
;                     *(u32x2*)((char*)ho + 2u * eo2) = odd ? hw[0][rh] : rv; }
;             }
;             if (!PLAIN) { sq0 += __shfl_xor(sq0, 1); sq0 += __shfl_xor(sq0, 2); sq0 += __shfl_xor(sq0, 4);
;             sq1 += __shfl_xor(sq1, 1); sq1 += __shfl_xor(sq1, 2); sq1 += __shfl_xor(sq1, 4); }
;             if (!PLAIN && pc == 0) { sst[g * 16 + rr] = sq0; sst[g * 16 + 8 + rr] = sq1; }
;         }
.LBB0_1969:
	s_or_b64 exec, exec, s[22:23]
	v_lshl_add_u64 v[104:105], s[20:21], 0, v[154:155]
	v_add_u32_e32 v154, 0x120000, v205
	v_add_u32_e32 v100, 0x120080, v205
	v_add_u32_e32 v102, 0x130000, v205
	global_load_dwordx4 v[78:81], v154, s[20:21] nt
	global_load_dwordx4 v[74:77], v102, s[20:21] nt
	v_add_u32_e32 v98, 0x130080, v205
	global_load_dwordx4 v[70:73], v100, s[20:21] nt
	s_waitcnt lgkmcnt(0)
	global_load_dwordx4 v[66:69], v98, s[20:21] nt
	ds_write_b128 v200, v[62:65]
	ds_write_b128 v200, v[58:61] offset:64
	ds_read_b128 v[58:61], v201
	ds_read_b128 v[62:65], v201 offset:1152
	v_mov_b32_e32 v115, v155
	s_waitcnt vmcnt(13) lgkmcnt(1)
	v_pk_fma_f32 v[60:61], v[176:177], v[60:61], v[96:97]
	v_add_u32_e32 v96, 0x40000, v202
	v_pk_fma_f32 v[58:59], v[180:181], v[58:59], v[94:95]
	v_lshlrev_b32_e32 v94, 2, v96
	s_waitcnt vmcnt(12) lgkmcnt(0)
	v_pk_fma_f32 v[64:65], v[176:177], v[64:65], v[92:93]
	v_add_u32_e32 v92, 0x44000, v202
	global_store_dwordx4 v94, v[58:61], s[20:21] nt
	v_pk_mul_f32 v[94:95], v[178:179], v[58:59]
	v_pk_fma_f32 v[62:63], v[180:181], v[62:63], v[90:91]
	v_lshlrev_b32_e32 v90, 2, v92
	v_pk_mul_f32 v[106:107], v[174:175], v[60:61]
	v_cvt_pk_bf16_f32 v94, v94, v95
	s_nop 0
	v_cvt_pk_bf16_f32 v95, v106, v107
	global_store_dwordx4 v90, v[62:65], s[20:21] nt
	v_pk_mul_f32 v[90:91], v[178:179], v[62:63]
	v_pk_mul_f32 v[106:107], v[174:175], v[64:65]
	v_cvt_pk_bf16_f32 v90, v90, v91
	s_nop 0
	v_cvt_pk_bf16_f32 v91, v106, v107
	ds_write_b128 v200, v[54:57]
	ds_write_b128 v200, v[50:53] offset:64
	ds_read_b128 v[50:53], v201
	ds_read_b128 v[54:57], v201 offset:1152
	v_lshl_add_u64 v[106:107], s[20:21], 0, v[114:115]
	s_waitcnt vmcnt(13) lgkmcnt(1)
	v_pk_fma_f32 v[50:51], v[168:169], v[50:51], v[86:87]
	v_pk_fma_f32 v[52:53], v[166:167], v[52:53], v[88:89]
	v_pk_mul_f32 v[88:89], v[172:173], v[50:51]
	global_store_dwordx4 v[104:105], v[50:53], off nt
	v_pk_mul_f32 v[86:87], v[170:171], v[52:53]
	v_cvt_pk_bf16_f32 v88, v88, v89
	s_waitcnt vmcnt(13) lgkmcnt(0)
	v_pk_fma_f32 v[54:55], v[168:169], v[54:55], v[82:83]
	v_cvt_pk_bf16_f32 v89, v86, v87
	ds_bpermute_b32 v82, v203, v88
	ds_bpermute_b32 v83, v203, v89
	v_pk_fma_f32 v[56:57], v[166:167], v[56:57], v[84:85]
	v_pk_mul_f32 v[84:85], v[172:173], v[54:55]
	v_pk_mul_f32 v[86:87], v[170:171], v[56:57]
	global_store_dwordx4 v[106:107], v[54:57], off nt
	v_cvt_pk_bf16_f32 v84, v84, v85
	v_cvt_pk_bf16_f32 v85, v86, v87
	v_lshlrev_b32_e32 v86, 1, v96
	s_waitcnt lgkmcnt(0)
	v_add_u32_e32 v250, 0xfffff040, v86
	v_cndmask_b32_e64 v250, v86, v250, s[40:41]
	v_cndmask_b32_e64 v248, v94, v82, s[40:41]
	v_cndmask_b32_e64 v249, v95, v83, s[40:41]
	global_store_dwordx2 v250, v[248:249], s[18:19]
	v_cndmask_b32_e64 v246, v82, v94, s[40:41]
	v_cndmask_b32_e64 v247, v83, v95, s[40:41]
	s_waitcnt lgkmcnt(1)
	v_add_u32_e32 v82, 0x1040, v86
	v_cndmask_b32_e64 v82, v86, v82, s[38:39]
	global_store_dwordx2 v82, v[246:247], s[18:19]
	ds_bpermute_b32 v82, v203, v84
	s_waitcnt lgkmcnt(1)
	ds_bpermute_b32 v83, v203, v85
	v_lshlrev_b32_e32 v84, 1, v92
	s_waitcnt lgkmcnt(0)
	v_add_u32_e32 v250, 0xfffff040, v84
	v_cndmask_b32_e64 v250, v84, v250, s[40:41]
	v_cndmask_b32_e64 v248, v90, v82, s[40:41]
	v_cndmask_b32_e64 v249, v91, v83, s[40:41]
	global_store_dwordx2 v250, v[248:249], s[18:19]
	v_cndmask_b32_e64 v246, v82, v90, s[40:41]
	v_cndmask_b32_e64 v247, v83, v91, s[40:41]
	v_mul_f32_e32 v51, v51, v51
	v_fmac_f32_e32 v51, v50, v50
	v_mul_f32_e32 v50, v53, v53
	v_mul_f32_e32 v61, v61, v61
	v_fmac_f32_e32 v50, v52, v52
	v_mul_f32_e32 v59, v59, v59
	v_fmac_f32_e32 v61, v60, v60
	v_mul_f32_e32 v60, v63, v63
	v_mul_f32_e32 v63, v65, v65
	v_add_f32_e32 v50, v51, v50
	v_mul_f32_e32 v51, v55, v55
	v_mul_f32_e32 v52, v57, v57
	v_fmac_f32_e32 v63, v64, v64
	v_fmac_f32_e32 v51, v54, v54
	v_fmac_f32_e32 v52, v56, v56
	v_fmac_f32_e32 v59, v58, v58
	v_fmac_f32_e32 v60, v62, v62
	v_add_f32_e32 v51, v51, v52
	v_add_f32_e32 v52, v59, v61
	v_add_f32_e32 v53, v60, v63
	v_add_f32_e32 v50, v52, v50
	v_add_f32_e32 v51, v53, v51
	ds_bpermute_b32 v52, v190, v50
	ds_bpermute_b32 v53, v190, v51
	s_waitcnt lgkmcnt(1)
	v_add_f32_e32 v50, v50, v52
	s_waitcnt lgkmcnt(0)
	v_add_f32_e32 v53, v51, v53
	ds_bpermute_b32 v52, v191, v50
	ds_bpermute_b32 v54, v191, v53
	s_waitcnt lgkmcnt(1)
	v_add_f32_e32 v50, v50, v52
	s_waitcnt lgkmcnt(0)
	v_add_f32_e32 v52, v53, v54
	ds_bpermute_b32 v51, v204, v50
	ds_bpermute_b32 v53, v204, v52
	v_add_u32_e32 v54, 0x1040, v84
	v_cndmask_b32_e64 v54, v84, v54, s[38:39]
	global_store_dwordx2 v54, v[246:247], s[18:19]
	s_and_saveexec_b64 s[22:23], s[42:43]
	s_cbranch_execz .LBB0_1979
	s_waitcnt lgkmcnt(1)
	v_add_f32_e32 v50, v50, v51
	s_waitcnt lgkmcnt(0)
	v_add_f32_e32 v51, v52, v53
	ds_write2_b32 v194, v50, v51 offset0:64 offset1:72
; #define LAS __attribute__((address_space(3)))
; #define ERN_EOFF(q, m) (eb + (unsigned)((((q) & 1) * HALF + (m) * 16) * DM + ERN_COL((q) >> 1)))
;     __device__ __forceinline__ void operator()(const f32x4 (&acc)[2][2][4][2], const Unit& u, int wr, int wc, int fr, int fq) const {
;     ...
;         ERN_LOADX(0);
; #pragma unroll
;         for (int g = 0; g < 8; ++g) { const int ai = g >> 2, m = g & 3;
;             if (g + 1 < 8) ERN_LOADX(g + 1);
;             float sq0 = 0.f, sq1 = 0.f; u32x2 hw[2][2];
; #pragma unroll
;             for (int bj = 0; bj < 2; ++bj) {
;                 *(LAS f32x4*)(st + wr_off) = acc[ai][bj][m][0]; *(LAS f32x4*)(st + wr_off + 64) = acc[ai][bj][m][1];
;                 const f32x4 a0 = *(const LAS f32x4*)(st + rd_off), a1 = *(const LAS f32x4*)(st + rd_off + 8 * 144);
;                 { const f32x4 xv = xb[g & 1][bj][0] + gv[bj] * a0; __builtin_nontemporal_store(xv, (f32x4*)((char*)xo + 4u * ERN_EOFF(g, bj, 0)));
;                   sq0 += (xv.x * xv.x + xv.y * xv.y) + (xv.z * xv.z + xv.w * xv.w);
;                   const f32x4 hv = xv * gsn[bj]; hw[bj][0].x = cvt_pk_bf16(hv.x, hv.y); hw[bj][0].y = cvt_pk_bf16(hv.z, hv.w); }
;                 { const f32x4 xv = xb[g & 1][bj][1] + gv[bj] * a1; __builtin_nontemporal_store(xv, (f32x4*)((char*)xo + 4u * ERN_EOFF(g, bj, 1)));
;                   sq1 += (xv.x * xv.x + xv.y * xv.y) + (xv.z * xv.z + xv.w * xv.w);
;                   const f32x4 hv = xv * gsn[bj]; hw[bj][1].x = cvt_pk_bf16(hv.x, hv.y); hw[bj][1].y = cvt_pk_bf16(hv.z, hv.w); }
;             }
;             if (!NOH && !PLAIN) {
; #pragma unroll
;                 for (int rh = 0; rh < 2; ++rh) { u32x2 rv; rv.x = __shfl_xor(hw[1][rh].x, 8); rv.y = __shfl_xor(hw[1][rh].y, 8);
;                     const unsigned e0 = ERN_EOFF(g, 0, rh);
;                     const unsigned ee = odd ? (e0 - DM + 32) : e0, eo2 = odd ? e0 : (e0 + DM + 32);
;                     *(u32x2*)((char*)ho + 2u * ee) = odd ? rv : hw[0][rh];
;                     *(u32x2*)((char*)ho + 2u * eo2) = odd ? hw[0][rh] : rv; }
;             }
;             if (!PLAIN) { sq0 += __shfl_xor(sq0, 1); sq0 += __shfl_xor(sq0, 2); sq0 += __shfl_xor(sq0, 4);
;             sq1 += __shfl_xor(sq1, 1); sq1 += __shfl_xor(sq1, 2); sq1 += __shfl_xor(sq1, 4); }
;             if (!PLAIN && pc == 0) { sst[g * 16 + rr] = sq0; sst[g * 16 + 8 + rr] = sq1; }
;         }
.LBB0_1979:
	s_or_b64 exec, exec, s[22:23]
	v_lshl_add_u64 v[88:89], s[20:21], 0, v[154:155]
	v_add_u32_e32 v154, 0x140000, v205
	v_add_u32_e32 v84, 0x140080, v205
	v_add_u32_e32 v86, 0x150000, v205
	global_load_dwordx4 v[62:65], v154, s[20:21] nt
	global_load_dwordx4 v[58:61], v86, s[20:21] nt
	v_add_u32_e32 v82, 0x150080, v205
	global_load_dwordx4 v[54:57], v84, s[20:21] nt
	s_waitcnt lgkmcnt(0)
	global_load_dwordx4 v[50:53], v82, s[20:21] nt
	ds_write_b128 v200, v[46:49]
	ds_write_b128 v200, v[42:45] offset:64
	ds_read_b128 v[42:45], v201
	ds_read_b128 v[46:49], v201 offset:1152
	v_mov_b32_e32 v103, v155
	v_lshl_add_u64 v[90:91], s[20:21], 0, v[102:103]
	v_mov_b32_e32 v101, v155
	s_waitcnt vmcnt(13) lgkmcnt(1)
	v_pk_fma_f32 v[42:43], v[180:181], v[42:43], v[78:79]
	s_waitcnt vmcnt(12) lgkmcnt(0)
	v_pk_fma_f32 v[46:47], v[180:181], v[46:47], v[74:75]
	v_pk_fma_f32 v[44:45], v[176:177], v[44:45], v[80:81]
	v_pk_mul_f32 v[78:79], v[178:179], v[42:43]
	v_pk_fma_f32 v[48:49], v[176:177], v[48:49], v[76:77]
	v_pk_mul_f32 v[74:75], v[178:179], v[46:47]
	global_store_dwordx4 v[88:89], v[42:45], off nt
	v_pk_mul_f32 v[80:81], v[174:175], v[44:45]
	v_cvt_pk_bf16_f32 v78, v78, v79
	v_pk_mul_f32 v[76:77], v[174:175], v[48:49]
	v_cvt_pk_bf16_f32 v79, v80, v81
	global_store_dwordx4 v[90:91], v[46:49], off nt
	v_cvt_pk_bf16_f32 v74, v74, v75
	v_cvt_pk_bf16_f32 v75, v76, v77
	ds_write_b128 v200, v[38:41]
	ds_write_b128 v200, v[34:37] offset:64
	ds_read_b128 v[34:37], v201
	ds_read_b128 v[38:41], v201 offset:1152
	v_lshl_add_u64 v[76:77], s[20:21], 0, v[100:101]
	v_mov_b32_e32 v99, v155
	v_lshl_add_u64 v[80:81], s[20:21], 0, v[98:99]
	s_waitcnt vmcnt(13) lgkmcnt(1)
	v_pk_fma_f32 v[34:35], v[168:169], v[34:35], v[70:71]
	v_pk_fma_f32 v[36:37], v[166:167], v[36:37], v[72:73]
	v_pk_mul_f32 v[72:73], v[172:173], v[34:35]
	global_store_dwordx4 v[76:77], v[34:37], off nt
	v_pk_mul_f32 v[70:71], v[170:171], v[36:37]
	v_cvt_pk_bf16_f32 v72, v72, v73
	s_waitcnt vmcnt(13) lgkmcnt(0)
	v_pk_fma_f32 v[38:39], v[168:169], v[38:39], v[66:67]
	v_cvt_pk_bf16_f32 v73, v70, v71
	ds_bpermute_b32 v66, v203, v72
	ds_bpermute_b32 v67, v203, v73
	v_pk_fma_f32 v[40:41], v[166:167], v[40:41], v[68:69]
	v_pk_mul_f32 v[68:69], v[172:173], v[38:39]
	v_pk_mul_f32 v[70:71], v[170:171], v[40:41]
	global_store_dwordx4 v[80:81], v[38:41], off nt
	v_cvt_pk_bf16_f32 v68, v68, v69
	v_cvt_pk_bf16_f32 v69, v70, v71
	v_add_u32_e32 v71, 0x48000, v202
	v_lshlrev_b32_e32 v70, 1, v71
	s_waitcnt lgkmcnt(0)
	v_add_u32_e32 v250, 0xfffff040, v70
	v_cndmask_b32_e64 v250, v70, v250, s[40:41]
	v_cndmask_b32_e64 v248, v78, v66, s[40:41]
	v_cndmask_b32_e64 v249, v79, v67, s[40:41]
	global_store_dwordx2 v250, v[248:249], s[18:19]
	v_cndmask_b32_e64 v246, v66, v78, s[40:41]
	v_cndmask_b32_e64 v247, v67, v79, s[40:41]
	s_waitcnt lgkmcnt(1)
	v_add_u32_e32 v66, 0x1040, v70
	v_cndmask_b32_e64 v66, v70, v66, s[38:39]
	global_store_dwordx2 v66, v[246:247], s[18:19]
	ds_bpermute_b32 v66, v203, v68
	s_waitcnt lgkmcnt(1)
	ds_bpermute_b32 v67, v203, v69
	v_add_u32_e32 v69, 0x4c000, v202
	v_lshlrev_b32_e32 v68, 1, v69
	s_waitcnt lgkmcnt(0)
	v_add_u32_e32 v250, 0xfffff040, v68
	v_cndmask_b32_e64 v250, v68, v250, s[40:41]
	v_cndmask_b32_e64 v248, v74, v66, s[40:41]
	v_cndmask_b32_e64 v249, v75, v67, s[40:41]
	global_store_dwordx2 v250, v[248:249], s[18:19]
	v_cndmask_b32_e64 v246, v66, v74, s[40:41]
	v_cndmask_b32_e64 v247, v67, v75, s[40:41]
	v_mul_f32_e32 v35, v35, v35
	v_fmac_f32_e32 v35, v34, v34
	v_mul_f32_e32 v34, v37, v37
	v_mul_f32_e32 v45, v45, v45
	v_fmac_f32_e32 v34, v36, v36
	v_mul_f32_e32 v43, v43, v43
	v_fmac_f32_e32 v45, v44, v44
	v_mul_f32_e32 v44, v47, v47
	v_mul_f32_e32 v47, v49, v49
	v_add_f32_e32 v34, v35, v34
	v_mul_f32_e32 v35, v39, v39
	v_mul_f32_e32 v36, v41, v41
	v_fmac_f32_e32 v47, v48, v48
	v_fmac_f32_e32 v35, v38, v38
	v_fmac_f32_e32 v36, v40, v40
	v_fmac_f32_e32 v43, v42, v42
	v_fmac_f32_e32 v44, v46, v46
	v_add_f32_e32 v35, v35, v36
	v_add_f32_e32 v36, v43, v45
	v_add_f32_e32 v37, v44, v47
	v_add_f32_e32 v34, v36, v34
	v_add_f32_e32 v35, v37, v35
	ds_bpermute_b32 v36, v190, v34
	ds_bpermute_b32 v37, v190, v35
	s_waitcnt lgkmcnt(1)
	v_add_f32_e32 v34, v34, v36
	s_waitcnt lgkmcnt(0)
	v_add_f32_e32 v37, v35, v37
	ds_bpermute_b32 v36, v191, v34
	ds_bpermute_b32 v38, v191, v37
	s_waitcnt lgkmcnt(1)
	v_add_f32_e32 v34, v34, v36
	s_waitcnt lgkmcnt(0)
	v_add_f32_e32 v36, v37, v38
	ds_bpermute_b32 v35, v204, v34
	ds_bpermute_b32 v37, v204, v36
	v_add_u32_e32 v38, 0x1040, v68
	v_cndmask_b32_e64 v38, v68, v38, s[38:39]
	global_store_dwordx2 v38, v[246:247], s[18:19]
	s_and_saveexec_b64 s[22:23], s[42:43]
	s_cbranch_execz .LBB0_1989
	s_waitcnt lgkmcnt(1)
	v_add_f32_e32 v34, v34, v35
	s_waitcnt lgkmcnt(0)
	v_add_f32_e32 v35, v36, v37
	ds_write2_b32 v194, v34, v35 offset0:80 offset1:88
; #define LAS __attribute__((address_space(3)))
; #define ERN_EOFF(q, m) (eb + (unsigned)((((q) & 1) * HALF + (m) * 16) * DM + ERN_COL((q) >> 1)))
;     __device__ __forceinline__ void operator()(const f32x4 (&acc)[2][2][4][2], const Unit& u, int wr, int wc, int fr, int fq) const {
;     ...
;         ERN_LOADX(0);
; #pragma unroll
;         for (int g = 0; g < 8; ++g) { const int ai = g >> 2, m = g & 3;
;             if (g + 1 < 8) ERN_LOADX(g + 1);
;             float sq0 = 0.f, sq1 = 0.f; u32x2 hw[2][2];
; #pragma unroll
;             for (int bj = 0; bj < 2; ++bj) {
;                 *(LAS f32x4*)(st + wr_off) = acc[ai][bj][m][0]; *(LAS f32x4*)(st + wr_off + 64) = acc[ai][bj][m][1];
;                 const f32x4 a0 = *(const LAS f32x4*)(st + rd_off), a1 = *(const LAS f32x4*)(st + rd_off + 8 * 144);
;                 { const f32x4 xv = xb[g & 1][bj][0] + gv[bj] * a0; __builtin_nontemporal_store(xv, (f32x4*)((char*)xo + 4u * ERN_EOFF(g, bj, 0)));
;                   sq0 += (xv.x * xv.x + xv.y * xv.y) + (xv.z * xv.z + xv.w * xv.w);
;                   const f32x4 hv = xv * gsn[bj]; hw[bj][0].x = cvt_pk_bf16(hv.x, hv.y); hw[bj][0].y = cvt_pk_bf16(hv.z, hv.w); }
;                 { const f32x4 xv = xb[g & 1][bj][1] + gv[bj] * a1; __builtin_nontemporal_store(xv, (f32x4*)((char*)xo + 4u * ERN_EOFF(g, bj, 1)));
;                   sq1 += (xv.x * xv.x + xv.y * xv.y) + (xv.z * xv.z + xv.w * xv.w);
;                   const f32x4 hv = xv * gsn[bj]; hw[bj][1].x = cvt_pk_bf16(hv.x, hv.y); hw[bj][1].y = cvt_pk_bf16(hv.z, hv.w); }
;             }
;             if (!NOH && !PLAIN) {
; #pragma unroll
;                 for (int rh = 0; rh < 2; ++rh) { u32x2 rv; rv.x = __shfl_xor(hw[1][rh].x, 8); rv.y = __shfl_xor(hw[1][rh].y, 8);
;                     const unsigned e0 = ERN_EOFF(g, 0, rh);
;                     const unsigned ee = odd ? (e0 - DM + 32) : e0, eo2 = odd ? e0 : (e0 + DM + 32);
;                     *(u32x2*)((char*)ho + 2u * ee) = odd ? rv : hw[0][rh];
;                     *(u32x2*)((char*)ho + 2u * eo2) = odd ? hw[0][rh] : rv; }
;             }
;             if (!PLAIN) { sq0 += __shfl_xor(sq0, 1); sq0 += __shfl_xor(sq0, 2); sq0 += __shfl_xor(sq0, 4);
;             sq1 += __shfl_xor(sq1, 1); sq1 += __shfl_xor(sq1, 2); sq1 += __shfl_xor(sq1, 4); }
;             if (!PLAIN && pc == 0) { sst[g * 16 + rr] = sq0; sst[g * 16 + 8 + rr] = sq1; }
;         }
.LBB0_1989:
	s_or_b64 exec, exec, s[22:23]
	v_lshl_add_u64 v[72:73], s[20:21], 0, v[154:155]
	v_add_u32_e32 v154, 0x160000, v205
	v_add_u32_e32 v68, 0x160080, v205
	v_add_u32_e32 v70, 0x170000, v205
	global_load_dwordx4 v[46:49], v154, s[20:21] nt
	global_load_dwordx4 v[42:45], v70, s[20:21] nt
	v_add_u32_e32 v66, 0x170080, v205
	global_load_dwordx4 v[38:41], v68, s[20:21] nt
	s_waitcnt lgkmcnt(0)
	global_load_dwordx4 v[34:37], v66, s[20:21] nt
	ds_write_b128 v200, v[30:33]
	ds_write_b128 v200, v[26:29] offset:64
	ds_read_b128 v[26:29], v201
	ds_read_b128 v[30:33], v201 offset:1152
	v_mov_b32_e32 v87, v155
	v_lshl_add_u64 v[74:75], s[20:21], 0, v[86:87]
	v_mov_b32_e32 v85, v155
	s_waitcnt vmcnt(13) lgkmcnt(1)
	v_pk_fma_f32 v[26:27], v[180:181], v[26:27], v[62:63]
	s_waitcnt vmcnt(12) lgkmcnt(0)
	v_pk_fma_f32 v[30:31], v[180:181], v[30:31], v[58:59]
	v_pk_fma_f32 v[28:29], v[176:177], v[28:29], v[64:65]
	v_pk_mul_f32 v[62:63], v[178:179], v[26:27]
	v_pk_fma_f32 v[32:33], v[176:177], v[32:33], v[60:61]
	v_pk_mul_f32 v[58:59], v[178:179], v[30:31]
	global_store_dwordx4 v[72:73], v[26:29], off nt
	v_pk_mul_f32 v[64:65], v[174:175], v[28:29]
	v_cvt_pk_bf16_f32 v62, v62, v63
	v_pk_mul_f32 v[60:61], v[174:175], v[32:33]
	v_cvt_pk_bf16_f32 v63, v64, v65
	global_store_dwordx4 v[74:75], v[30:33], off nt
	v_cvt_pk_bf16_f32 v58, v58, v59
	v_cvt_pk_bf16_f32 v59, v60, v61
	ds_write_b128 v200, v[22:25]
	ds_write_b128 v200, v[18:21] offset:64
	ds_read_b128 v[18:21], v201
	ds_read_b128 v[22:25], v201 offset:1152
	v_lshl_add_u64 v[60:61], s[20:21], 0, v[84:85]
	v_mov_b32_e32 v83, v155
	v_lshl_add_u64 v[64:65], s[20:21], 0, v[82:83]
	s_waitcnt vmcnt(13) lgkmcnt(1)
	v_pk_fma_f32 v[18:19], v[168:169], v[18:19], v[54:55]
	v_pk_fma_f32 v[20:21], v[166:167], v[20:21], v[56:57]
	v_pk_mul_f32 v[56:57], v[172:173], v[18:19]
	global_store_dwordx4 v[60:61], v[18:21], off nt
	v_pk_mul_f32 v[54:55], v[170:171], v[20:21]
	v_cvt_pk_bf16_f32 v56, v56, v57
	s_waitcnt vmcnt(13) lgkmcnt(0)
	v_pk_fma_f32 v[22:23], v[168:169], v[22:23], v[50:51]
	v_cvt_pk_bf16_f32 v57, v54, v55
	ds_bpermute_b32 v50, v203, v56
	ds_bpermute_b32 v51, v203, v57
	v_pk_fma_f32 v[24:25], v[166:167], v[24:25], v[52:53]
	v_pk_mul_f32 v[52:53], v[172:173], v[22:23]
	v_pk_mul_f32 v[54:55], v[170:171], v[24:25]
	global_store_dwordx4 v[64:65], v[22:25], off nt
	v_cvt_pk_bf16_f32 v52, v52, v53
	v_cvt_pk_bf16_f32 v53, v54, v55
	v_add_u32_e32 v55, 0x50000, v202
	v_lshlrev_b32_e32 v54, 1, v55
	s_waitcnt lgkmcnt(0)
	v_add_u32_e32 v250, 0xfffff040, v54
	v_cndmask_b32_e64 v250, v54, v250, s[40:41]
	v_cndmask_b32_e64 v248, v62, v50, s[40:41]
	v_cndmask_b32_e64 v249, v63, v51, s[40:41]
	global_store_dwordx2 v250, v[248:249], s[18:19]
	v_cndmask_b32_e64 v246, v50, v62, s[40:41]
	v_cndmask_b32_e64 v247, v51, v63, s[40:41]
	s_waitcnt lgkmcnt(1)
	v_add_u32_e32 v50, 0x1040, v54
	v_cndmask_b32_e64 v50, v54, v50, s[38:39]
	global_store_dwordx2 v50, v[246:247], s[18:19]
	ds_bpermute_b32 v50, v203, v52
	s_waitcnt lgkmcnt(1)
	ds_bpermute_b32 v51, v203, v53
	v_add_u32_e32 v53, 0x54000, v202
	v_lshlrev_b32_e32 v52, 1, v53
	s_waitcnt lgkmcnt(0)
	v_add_u32_e32 v250, 0xfffff040, v52
	v_cndmask_b32_e64 v250, v52, v250, s[40:41]
	v_cndmask_b32_e64 v248, v58, v50, s[40:41]
	v_cndmask_b32_e64 v249, v59, v51, s[40:41]
	global_store_dwordx2 v250, v[248:249], s[18:19]
	v_cndmask_b32_e64 v246, v50, v58, s[40:41]
	v_cndmask_b32_e64 v247, v51, v59, s[40:41]
	v_mul_f32_e32 v19, v19, v19
	v_fmac_f32_e32 v19, v18, v18
	v_mul_f32_e32 v18, v21, v21
	v_mul_f32_e32 v29, v29, v29
	v_fmac_f32_e32 v18, v20, v20
	v_mul_f32_e32 v27, v27, v27
	v_fmac_f32_e32 v29, v28, v28
	v_mul_f32_e32 v28, v31, v31
	v_mul_f32_e32 v31, v33, v33
	v_add_f32_e32 v18, v19, v18
	v_mul_f32_e32 v19, v23, v23
	v_mul_f32_e32 v20, v25, v25
	v_fmac_f32_e32 v31, v32, v32
	v_fmac_f32_e32 v19, v22, v22
	v_fmac_f32_e32 v20, v24, v24
	v_fmac_f32_e32 v27, v26, v26
	v_fmac_f32_e32 v28, v30, v30
	v_add_f32_e32 v19, v19, v20
	v_add_f32_e32 v20, v27, v29
	v_add_f32_e32 v21, v28, v31
	v_add_f32_e32 v18, v20, v18
	v_add_f32_e32 v19, v21, v19
	ds_bpermute_b32 v20, v190, v18
	ds_bpermute_b32 v21, v190, v19
	s_waitcnt lgkmcnt(1)
	v_add_f32_e32 v18, v18, v20
	s_waitcnt lgkmcnt(0)
	v_add_f32_e32 v21, v19, v21
	ds_bpermute_b32 v20, v191, v18
	ds_bpermute_b32 v22, v191, v21
	s_waitcnt lgkmcnt(1)
	v_add_f32_e32 v18, v18, v20
	s_waitcnt lgkmcnt(0)
	v_add_f32_e32 v20, v21, v22
	ds_bpermute_b32 v19, v204, v18
	ds_bpermute_b32 v21, v204, v20
	v_add_u32_e32 v22, 0x1040, v52
	v_cndmask_b32_e64 v22, v52, v22, s[38:39]
	global_store_dwordx2 v22, v[246:247], s[18:19]
	s_and_saveexec_b64 s[22:23], s[42:43]
	s_cbranch_execz .LBB0_1999
	s_waitcnt lgkmcnt(1)
	v_add_f32_e32 v18, v18, v19
	s_waitcnt lgkmcnt(0)
	v_add_f32_e32 v19, v20, v21
	ds_write2_b32 v194, v18, v19 offset0:96 offset1:104

; #define LAS __attribute__((address_space(3)))
;     __device__ __forceinline__ void operator()(const f32x4 (&acc)[2][2][4][2], const Unit& u, int wr, int wc, int fr, int fq) const {
;         const int s = u.pm >> 5, lane = fq * 16 + fr, rr = lane >> 3, pc = lane & 7;
;         const float* __restrict__ xi = xin + (size_t)u.pm * BM * DM; float* __restrict__ xo = xout + (size_t)u.pm * BM * DM; bf16_t* __restrict__ ho = Hn + (size_t)u.pm * BM * DM;
;         LAS unsigned char* st = lds_epi + (wr * 4 + wc) * 2304;
;         LAS float* sst = (LAS float*)(lds_epi + 18432 + (wr * 4 + wc) * 512);
;         const int colr = u.pn * BM + wc * 64 + 4 * pc;
;         const unsigned eb = (unsigned)((wr * 64 + rr) * DM + colr);
;         f32x4 gv[2], gsn[2];
; #pragma unroll
;         for (int bj = 0; bj < 2; ++bj) { gv[bj] = *(const f32x4*)(gate + (size_t)s * MODW + colr + bj * 32) * (0.5f * GS2);
;             if (!PLAIN) gsn[bj] = *(const f32x4*)(gnext + colr + bj * 32) * (*(const f32x4*)(scnext + (size_t)s * MODW + colr + bj * 32) + 1.0f); else gsn[bj] = gv[bj]; }
;         const unsigned wr_off = (unsigned)(fr * 144 + 16 * fq), rd_off = (unsigned)(rr * 144 + pc * 16);
;         const bool odd = (rr & 1) != 0;
;         f32x4 xb[2][2][2];
;     ...
;         ERN_LOADX(0);
; #pragma unroll
;         for (int g = 0; g < 8; ++g) { const int ai = g >> 2, m = g & 3;
;             if (g + 1 < 8) ERN_LOADX(g + 1);
;             float sq0 = 0.f, sq1 = 0.f; u32x2 hw[2][2];
; #pragma unroll
;             for (int bj = 0; bj < 2; ++bj) {
;                 *(LAS f32x4*)(st + wr_off) = acc[ai][bj][m][0]; *(LAS f32x4*)(st + wr_off + 64) = acc[ai][bj][m][1];
;                 const f32x4 a0 = *(const LAS f32x4*)(st + rd_off), a1 = *(const LAS f32x4*)(st + rd_off + 8 * 144);
;                 { const f32x4 xv = xb[g & 1][bj][0] + gv[bj] * a0; __builtin_nontemporal_store(xv, (f32x4*)((char*)xo + 4u * ERN_EOFF(g, bj, 0)));
;                   sq0 += (xv.x * xv.x + xv.y * xv.y) + (xv.z * xv.z + xv.w * xv.w);
;                   const f32x4 hv = xv * gsn[bj]; hw[bj][0].x = cvt_pk_bf16(hv.x, hv.y); hw[bj][0].y = cvt_pk_bf16(hv.z, hv.w); }
;                 { const f32x4 xv = xb[g & 1][bj][1] + gv[bj] * a1; __builtin_nontemporal_store(xv, (f32x4*)((char*)xo + 4u * ERN_EOFF(g, bj, 1)));
;                   sq1 += (xv.x * xv.x + xv.y * xv.y) + (xv.z * xv.z + xv.w * xv.w);
.LBB0_2769:
	s_ashr_i32 s13, s2, 5
	s_ashr_i32 s3, s2, 31
	v_lshl_or_b32 v50, s20, 8, v192
	s_mul_hi_i32 s15, s13, 0x12000
	s_mul_i32 s13, s13, 0x12000
	s_add_u32 s20, s44, s13
	v_ashrrev_i32_e32 v51, 31, v50
	s_addc_u32 s21, s45, s15
	v_lshlrev_b64 v[52:53], 2, v[50:51]
	v_lshl_add_u64 v[138:139], s[20:21], 0, v[52:53]
	s_add_u32 s20, s46, s13
	s_addc_u32 s21, s47, s15
	v_lshl_add_u64 v[140:141], s[6:7], 0, v[52:53]
	v_lshl_add_u64 v[52:53], s[20:21], 0, v[52:53]
	s_lshl_b64 s[20:21], s[2:3], 21
	s_add_u32 s22, s90, s20
	v_add_u32_e32 v202, v50, v193
	s_addc_u32 s23, s91, s21
	v_lshlrev_b32_e32 v205, 2, v202
	global_load_dwordx4 v[54:57], v[138:139], off
	global_load_dwordx4 v[174:177], v[140:141], off
	global_load_dwordx4 v[178:181], v[52:53], off
	global_load_dwordx4 v[206:209], v[52:53], off offset:128
	global_load_dwordx4 v[186:189], v205, s[22:23] nt
	v_add_u32_e32 v50, 0x10000, v205
	global_load_dwordx4 v[210:213], v50, s[22:23] nt
	global_load_dwordx4 v[214:217], v[140:141], off offset:128
	s_nop 0
	global_load_dwordx4 v[50:53], v[138:139], off offset:128
	global_load_dwordx4 v[218:221], v205, s[22:23] offset:128 nt
	v_add_u32_e32 v204, 0x10080, v205
	global_load_dwordx4 v[222:225], v204, s[22:23] nt
	v_add_u32_e32 v138, 0x20000, v205
	v_add_u32_e32 v162, 0x30000, v205
	v_add_u32_e32 v184, 0x20080, v205
	v_add_u32_e32 v182, 0x30080, v205
	global_load_dwordx4 v[150:153], v138, s[22:23] nt
	global_load_dwordx4 v[146:149], v162, s[22:23] nt
	global_load_dwordx4 v[142:145], v184, s[22:23] nt
	s_nop 0
	global_load_dwordx4 v[138:141], v182, s[22:23] nt
	ds_write_b128 v200, v[134:137]
	ds_write_b128 v200, v[130:133] offset:64
	v_and_b32_e32 v135, 64, v199
	ds_read_b128 v[130:133], v201
	ds_read_b128 v[226:229], v201 offset:1152
	v_xor_b32_e32 v134, 8, v199
	v_add_u32_e32 v183, 64, v135
	v_cmp_lt_i32_e32 vcc, v134, v183
	v_add_u32_e32 v185, 0x4000, v202
	v_lshlrev_b32_e32 v230, 2, v185
	v_cndmask_b32_e32 v134, v199, v134, vcc
	v_lshlrev_b32_e32 v203, 2, v134
	s_lshl_b64 s[20:21], s[2:3], 20
	s_add_u32 s20, s93, s20
	s_addc_u32 s21, s92, s21
	s_waitcnt vmcnt(0)
	v_pk_add_f32 v[134:135], v[180:181], 1.0 op_sel_hi:[1,0]
	v_pk_add_f32 v[136:137], v[178:179], 1.0 op_sel_hi:[1,0]
	v_pk_mul_f32 v[178:179], v[176:177], v[134:135]
	v_pk_mul_f32 v[180:181], v[174:175], v[136:137]
	s_waitcnt lgkmcnt(1)
	v_pk_fma_f32 v[134:135], v[54:55], v[130:131], v[186:187]
	s_waitcnt lgkmcnt(0)
	v_pk_fma_f32 v[130:131], v[54:55], v[226:227], v[210:211]
	v_pk_fma_f32 v[136:137], v[56:57], v[132:133], v[188:189]
	v_pk_fma_f32 v[132:133], v[56:57], v[228:229], v[212:213]
	v_pk_mul_f32 v[186:187], v[180:181], v[130:131]
	v_pk_add_f32 v[190:191], v[208:209], 1.0 op_sel_hi:[1,0]
	global_store_dwordx4 v205, v[134:137], s[22:23] nt
	v_pk_mul_f32 v[174:175], v[178:179], v[136:137]
	v_pk_mul_f32 v[176:177], v[180:181], v[134:135]
	v_pk_mul_f32 v[208:209], v[178:179], v[132:133]
	v_cvt_pk_bf16_f32 v188, v176, v177
	v_cvt_pk_bf16_f32 v189, v174, v175
	global_store_dwordx4 v230, v[130:133], s[22:23] nt
	v_cvt_pk_bf16_f32 v186, v186, v187
	v_cvt_pk_bf16_f32 v187, v208, v209
	ds_write_b128 v200, v[126:129]
	ds_write_b128 v200, v[122:125] offset:64
	ds_read_b128 v[122:125], v201
	v_pk_add_f32 v[126:127], v[206:207], 1.0 op_sel_hi:[1,0]
	ds_read_b128 v[206:209], v201 offset:1152
	v_pk_mul_f32 v[174:175], v[216:217], v[190:191]
	v_pk_mul_f32 v[176:177], v[214:215], v[126:127]
	s_waitcnt lgkmcnt(1)
	v_pk_fma_f32 v[128:129], v[52:53], v[124:125], v[220:221]
	v_pk_fma_f32 v[126:127], v[50:51], v[122:123], v[218:219]
	s_waitcnt lgkmcnt(0)
	v_pk_fma_f32 v[122:123], v[50:51], v[206:207], v[222:223]
	v_pk_mul_f32 v[190:191], v[174:175], v[128:129]
	v_pk_mul_f32 v[206:207], v[176:177], v[126:127]
	global_store_dwordx4 v205, v[126:129], s[22:23] offset:128 nt
	v_cvt_pk_bf16_f32 v206, v206, v207
	v_cvt_pk_bf16_f32 v191, v190, v191
	ds_bpermute_b32 v190, v203, v206
	ds_bpermute_b32 v191, v203, v191
	v_pk_fma_f32 v[124:125], v[52:53], v[208:209], v[224:225]
	v_pk_mul_f32 v[206:207], v[176:177], v[122:123]
	global_store_dwordx4 v204, v[122:125], s[22:23] nt
	v_cvt_pk_bf16_f32 v204, v206, v207
	v_lshlrev_b32_e32 v207, 1, v202
	v_pk_mul_f32 v[208:209], v[174:175], v[124:125]
	s_nop 0
	v_cvt_pk_bf16_f32 v206, v208, v209
	s_waitcnt lgkmcnt(0)
	v_add_u32_e32 v250, 0xfffff040, v207
	v_cndmask_b32_e64 v250, v207, v250, s[38:39]
	v_cndmask_b32_e64 v248, v188, v190, s[38:39]
	v_cndmask_b32_e64 v249, v189, v191, s[38:39]
	global_store_dwordx2 v250, v[248:249], s[20:21]
	v_cndmask_b32_e64 v246, v190, v188, s[38:39]
	v_cndmask_b32_e64 v247, v191, v189, s[38:39]
	s_waitcnt lgkmcnt(1)
	v_add_u32_e32 v190, 0x1040, v207
	v_cndmask_b32_e64 v190, v207, v190, s[36:37]
	global_store_dwordx2 v190, v[246:247], s[20:21]
	ds_bpermute_b32 v188, v203, v204
	ds_bpermute_b32 v189, v203, v206
	v_lshlrev_b32_e32 v206, 1, v185
	s_and_saveexec_b64 s[24:25], s[38:39]
	s_xor_b64 s[24:25], exec, s[24:25]
	s_mov_b64 s[58:59], s[70:71]
	s_cbranch_execz .LBB0_2775
	v_lshlrev_b32_e32 v206, 1, v185
	v_add_u32_e32 v185, 0xfffff040, v206
	s_waitcnt lgkmcnt(0)
	global_store_dwordx2 v185, v[188:189], s[20:21]

; #define LAS __attribute__((address_space(3)))
; #define ERN_EOFF(q, m) (eb + (unsigned)((((q) & 1) * HALF + (m) * 16) * DM + ERN_COL((q) >> 1)))
;     __device__ __forceinline__ void operator()(const f32x4 (&acc)[2][2][4][2], const Unit& u, int wr, int wc, int fr, int fq) const {
;     ...
;         ERN_LOADX(0);
; #pragma unroll
;         for (int g = 0; g < 8; ++g) { const int ai = g >> 2, m = g & 3;
;             if (g + 1 < 8) ERN_LOADX(g + 1);
;             float sq0 = 0.f, sq1 = 0.f; u32x2 hw[2][2];
; #pragma unroll
;             for (int bj = 0; bj < 2; ++bj) {
;                 *(LAS f32x4*)(st + wr_off) = acc[ai][bj][m][0]; *(LAS f32x4*)(st + wr_off + 64) = acc[ai][bj][m][1];
;                 const f32x4 a0 = *(const LAS f32x4*)(st + rd_off), a1 = *(const LAS f32x4*)(st + rd_off + 8 * 144);
;                 { const f32x4 xv = xb[g & 1][bj][0] + gv[bj] * a0; __builtin_nontemporal_store(xv, (f32x4*)((char*)xo + 4u * ERN_EOFF(g, bj, 0)));
;                   sq0 += (xv.x * xv.x + xv.y * xv.y) + (xv.z * xv.z + xv.w * xv.w);
;                   const f32x4 hv = xv * gsn[bj]; hw[bj][0].x = cvt_pk_bf16(hv.x, hv.y); hw[bj][0].y = cvt_pk_bf16(hv.z, hv.w); }
;                 { const f32x4 xv = xb[g & 1][bj][1] + gv[bj] * a1; __builtin_nontemporal_store(xv, (f32x4*)((char*)xo + 4u * ERN_EOFF(g, bj, 1)));
;                   sq1 += (xv.x * xv.x + xv.y * xv.y) + (xv.z * xv.z + xv.w * xv.w);
;                   const f32x4 hv = xv * gsn[bj]; hw[bj][1].x = cvt_pk_bf16(hv.x, hv.y); hw[bj][1].y = cvt_pk_bf16(hv.z, hv.w); }
;             }
;             if (!NOH && !PLAIN) {
; #pragma unroll
;                 for (int rh = 0; rh < 2; ++rh) { u32x2 rv; rv.x = __shfl_xor(hw[1][rh].x, 8); rv.y = __shfl_xor(hw[1][rh].y, 8);
;                     const unsigned e0 = ERN_EOFF(g, 0, rh);
;                     const unsigned ee = odd ? (e0 - DM + 32) : e0, eo2 = odd ? e0 : (e0 + DM + 32);
;                     *(u32x2*)((char*)ho + 2u * ee) = odd ? rv : hw[0][rh];
;                     *(u32x2*)((char*)ho + 2u * eo2) = odd ? hw[0][rh] : rv; }
;             }
;             if (!PLAIN) { sq0 += __shfl_xor(sq0, 1); sq0 += __shfl_xor(sq0, 2); sq0 += __shfl_xor(sq0, 4);
;             sq1 += __shfl_xor(sq1, 1); sq1 += __shfl_xor(sq1, 2); sq1 += __shfl_xor(sq1, 4); }
;             if (!PLAIN && pc == 0) { sst[g * 16 + rr] = sq0; sst[g * 16 + 8 + rr] = sq1; }
;         }
.LBB0_2779:
	s_or_b64 exec, exec, s[24:25]
	v_lshl_add_u64 v[206:207], s[22:23], 0, v[162:163]
	v_add_u32_e32 v122, 0x40000, v205
	v_add_u32_e32 v162, 0x50000, v205
	v_add_u32_e32 v186, 0x40080, v205
	global_load_dwordx4 v[130:133], v162, s[22:23] nt
	global_load_dwordx4 v[126:129], v186, s[22:23] nt
	v_add_u32_e32 v188, 0x50080, v205
	global_load_dwordx4 v[134:137], v122, s[22:23] nt
	s_waitcnt lgkmcnt(0)
	global_load_dwordx4 v[122:125], v188, s[22:23] nt
	ds_write_b128 v200, v[118:121]
	ds_write_b128 v200, v[114:117] offset:64
	ds_read_b128 v[114:117], v201
	ds_read_b128 v[118:121], v201 offset:1152
	v_mov_b32_e32 v185, v163
	v_mov_b32_e32 v183, v163
	v_lshl_add_u64 v[182:183], s[22:23], 0, v[182:183]
	s_waitcnt lgkmcnt(1)
	v_pk_fma_f32 v[116:117], v[56:57], v[116:117], v[152:153]
	v_add_u32_e32 v152, 0x8000, v202
	v_pk_fma_f32 v[114:115], v[54:55], v[114:115], v[150:151]
	v_lshlrev_b32_e32 v150, 2, v152
	s_waitcnt lgkmcnt(0)
	v_pk_fma_f32 v[118:119], v[54:55], v[118:119], v[146:147]
	global_store_dwordx4 v150, v[114:117], s[22:23] nt
	v_pk_mul_f32 v[150:151], v[180:181], v[114:115]
	v_pk_fma_f32 v[120:121], v[56:57], v[120:121], v[148:149]
	v_pk_mul_f32 v[146:147], v[180:181], v[118:119]
	v_pk_mul_f32 v[208:209], v[178:179], v[116:117]
	v_cvt_pk_bf16_f32 v150, v150, v151
	v_pk_mul_f32 v[148:149], v[178:179], v[120:121]
	v_cvt_pk_bf16_f32 v151, v208, v209
	global_store_dwordx4 v[206:207], v[118:121], off nt
	v_cvt_pk_bf16_f32 v146, v146, v147
	v_cvt_pk_bf16_f32 v147, v148, v149
	ds_write_b128 v200, v[110:113]
	ds_write_b128 v200, v[106:109] offset:64
	ds_read_b128 v[106:109], v201
	ds_read_b128 v[110:113], v201 offset:1152
	v_lshl_add_u64 v[148:149], s[22:23], 0, v[184:185]
	s_waitcnt lgkmcnt(1)
	v_pk_fma_f32 v[106:107], v[50:51], v[106:107], v[142:143]
	v_pk_fma_f32 v[108:109], v[52:53], v[108:109], v[144:145]
	v_pk_mul_f32 v[144:145], v[176:177], v[106:107]
	global_store_dwordx4 v[148:149], v[106:109], off nt
	v_pk_mul_f32 v[142:143], v[174:175], v[108:109]
	v_cvt_pk_bf16_f32 v144, v144, v145
	s_waitcnt lgkmcnt(0)
	v_pk_fma_f32 v[110:111], v[50:51], v[110:111], v[138:139]
	v_cvt_pk_bf16_f32 v145, v142, v143
	ds_bpermute_b32 v138, v203, v144
	ds_bpermute_b32 v139, v203, v145
	v_pk_fma_f32 v[112:113], v[52:53], v[112:113], v[140:141]
	v_pk_mul_f32 v[140:141], v[176:177], v[110:111]
	v_pk_mul_f32 v[142:143], v[174:175], v[112:113]
	global_store_dwordx4 v[182:183], v[110:113], off nt
	v_cvt_pk_bf16_f32 v140, v140, v141
	v_cvt_pk_bf16_f32 v141, v142, v143
	v_lshlrev_b32_e32 v142, 1, v152
	s_waitcnt lgkmcnt(0)
	v_add_u32_e32 v250, 0xfffff040, v142
	v_cndmask_b32_e64 v250, v142, v250, s[38:39]
	v_cndmask_b32_e64 v248, v150, v138, s[38:39]
	v_cndmask_b32_e64 v249, v151, v139, s[38:39]
	global_store_dwordx2 v250, v[248:249], s[20:21]
	v_cndmask_b32_e64 v246, v138, v150, s[38:39]
	v_cndmask_b32_e64 v247, v139, v151, s[38:39]
	s_waitcnt lgkmcnt(1)
	v_add_u32_e32 v138, 0x1040, v142
	v_cndmask_b32_e64 v138, v142, v138, s[36:37]
	global_store_dwordx2 v138, v[246:247], s[20:21]
	ds_bpermute_b32 v138, v203, v140
	s_waitcnt lgkmcnt(1)
	ds_bpermute_b32 v139, v203, v141
	v_add_u32_e32 v141, 0xc000, v202
	v_lshlrev_b32_e32 v140, 1, v141
	s_waitcnt lgkmcnt(0)
	v_add_u32_e32 v250, 0xfffff040, v140
	v_cndmask_b32_e64 v250, v140, v250, s[38:39]
	v_cndmask_b32_e64 v248, v146, v138, s[38:39]
	v_cndmask_b32_e64 v249, v147, v139, s[38:39]
	global_store_dwordx2 v250, v[248:249], s[20:21]
	v_cndmask_b32_e64 v246, v138, v146, s[38:39]
	v_cndmask_b32_e64 v247, v139, v147, s[38:39]
	v_mul_f32_e32 v107, v107, v107
	v_fmac_f32_e32 v107, v106, v106
	v_mul_f32_e32 v106, v109, v109
	v_mul_f32_e32 v117, v117, v117
	v_fmac_f32_e32 v106, v108, v108
	v_mul_f32_e32 v115, v115, v115
	v_fmac_f32_e32 v117, v116, v116
	v_mul_f32_e32 v116, v119, v119
	v_mul_f32_e32 v119, v121, v121
	v_add_f32_e32 v106, v107, v106
	v_mul_f32_e32 v107, v111, v111
	v_mul_f32_e32 v108, v113, v113
	v_fmac_f32_e32 v119, v120, v120
	v_fmac_f32_e32 v107, v110, v110
	v_fmac_f32_e32 v108, v112, v112
	v_fmac_f32_e32 v115, v114, v114
	v_fmac_f32_e32 v116, v118, v118
	v_add_f32_e32 v107, v107, v108
	v_add_f32_e32 v108, v115, v117
	v_add_f32_e32 v109, v116, v119
	v_add_f32_e32 v106, v108, v106
	v_add_f32_e32 v107, v109, v107
	ds_bpermute_b32 v108, v190, v106
	ds_bpermute_b32 v109, v190, v107
	s_waitcnt lgkmcnt(1)
	v_add_f32_e32 v106, v106, v108
	s_waitcnt lgkmcnt(0)
	v_add_f32_e32 v109, v107, v109
	ds_bpermute_b32 v108, v191, v106
	ds_bpermute_b32 v110, v191, v109
	s_waitcnt lgkmcnt(1)
	v_add_f32_e32 v106, v106, v108
	s_waitcnt lgkmcnt(0)
	v_add_f32_e32 v108, v109, v110
	ds_bpermute_b32 v107, v204, v106
	ds_bpermute_b32 v109, v204, v108
	v_add_u32_e32 v110, 0x1040, v140
	v_cndmask_b32_e64 v110, v140, v110, s[36:37]
	global_store_dwordx2 v110, v[246:247], s[20:21]
	s_and_saveexec_b64 s[24:25], s[40:41]
	s_cbranch_execz .LBB0_2789
	s_waitcnt lgkmcnt(1)
	v_add_f32_e32 v106, v106, v107
	s_waitcnt lgkmcnt(0)
	v_add_f32_e32 v107, v108, v109
	ds_write2_b32 v194, v106, v107 offset0:16 offset1:24
; #define LAS __attribute__((address_space(3)))
; #define ERN_EOFF(q, m) (eb + (unsigned)((((q) & 1) * HALF + (m) * 16) * DM + ERN_COL((q) >> 1)))
;     __device__ __forceinline__ void operator()(const f32x4 (&acc)[2][2][4][2], const Unit& u, int wr, int wc, int fr, int fq) const {
;     ...
;         ERN_LOADX(0);
; #pragma unroll
;         for (int g = 0; g < 8; ++g) { const int ai = g >> 2, m = g & 3;
;             if (g + 1 < 8) ERN_LOADX(g + 1);
;             float sq0 = 0.f, sq1 = 0.f; u32x2 hw[2][2];
; #pragma unroll
;             for (int bj = 0; bj < 2; ++bj) {
;                 *(LAS f32x4*)(st + wr_off) = acc[ai][bj][m][0]; *(LAS f32x4*)(st + wr_off + 64) = acc[ai][bj][m][1];
;                 const f32x4 a0 = *(const LAS f32x4*)(st + rd_off), a1 = *(const LAS f32x4*)(st + rd_off + 8 * 144);
;                 { const f32x4 xv = xb[g & 1][bj][0] + gv[bj] * a0; __builtin_nontemporal_store(xv, (f32x4*)((char*)xo + 4u * ERN_EOFF(g, bj, 0)));
;                   sq0 += (xv.x * xv.x + xv.y * xv.y) + (xv.z * xv.z + xv.w * xv.w);
;                   const f32x4 hv = xv * gsn[bj]; hw[bj][0].x = cvt_pk_bf16(hv.x, hv.y); hw[bj][0].y = cvt_pk_bf16(hv.z, hv.w); }
;                 { const f32x4 xv = xb[g & 1][bj][1] + gv[bj] * a1; __builtin_nontemporal_store(xv, (f32x4*)((char*)xo + 4u * ERN_EOFF(g, bj, 1)));
;                   sq1 += (xv.x * xv.x + xv.y * xv.y) + (xv.z * xv.z + xv.w * xv.w);
;                   const f32x4 hv = xv * gsn[bj]; hw[bj][1].x = cvt_pk_bf16(hv.x, hv.y); hw[bj][1].y = cvt_pk_bf16(hv.z, hv.w); }
;             }
;             if (!NOH && !PLAIN) {
; #pragma unroll
;                 for (int rh = 0; rh < 2; ++rh) { u32x2 rv; rv.x = __shfl_xor(hw[1][rh].x, 8); rv.y = __shfl_xor(hw[1][rh].y, 8);
;                     const unsigned e0 = ERN_EOFF(g, 0, rh);
;                     const unsigned ee = odd ? (e0 - DM + 32) : e0, eo2 = odd ? e0 : (e0 + DM + 32);
;                     *(u32x2*)((char*)ho + 2u * ee) = odd ? rv : hw[0][rh];
;                     *(u32x2*)((char*)ho + 2u * eo2) = odd ? hw[0][rh] : rv; }
;             }
;             if (!PLAIN) { sq0 += __shfl_xor(sq0, 1); sq0 += __shfl_xor(sq0, 2); sq0 += __shfl_xor(sq0, 4);
;             sq1 += __shfl_xor(sq1, 1); sq1 += __shfl_xor(sq1, 2); sq1 += __shfl_xor(sq1, 4); }
;             if (!PLAIN && pc == 0) { sst[g * 16 + rr] = sq0; sst[g * 16 + 8 + rr] = sq1; }
;         }
.LBB0_2789:
	s_or_b64 exec, exec, s[24:25]
	v_lshl_add_u64 v[142:143], s[22:23], 0, v[162:163]
	v_add_u32_e32 v106, 0x60000, v205
	v_add_u32_e32 v162, 0x70000, v205
	v_add_u32_e32 v138, 0x60080, v205
	global_load_dwordx4 v[114:117], v162, s[22:23] nt
	global_load_dwordx4 v[110:113], v138, s[22:23] nt
	v_add_u32_e32 v140, 0x70080, v205
	global_load_dwordx4 v[118:121], v106, s[22:23] nt
	s_waitcnt lgkmcnt(0)
	global_load_dwordx4 v[106:109], v140, s[22:23] nt
	ds_write_b128 v200, v[102:105]
	ds_write_b128 v200, v[98:101] offset:64
	ds_read_b128 v[98:101], v201
	ds_read_b128 v[102:105], v201 offset:1152
	v_mov_b32_e32 v187, v163
	v_mov_b32_e32 v189, v163
	s_waitcnt vmcnt(11) lgkmcnt(1)
	v_pk_fma_f32 v[100:101], v[56:57], v[100:101], v[136:137]
	v_add_u32_e32 v136, 0x10000, v202
	v_pk_fma_f32 v[98:99], v[54:55], v[98:99], v[134:135]
	v_lshlrev_b32_e32 v134, 2, v136
	s_waitcnt lgkmcnt(0)
	v_pk_fma_f32 v[102:103], v[54:55], v[102:103], v[130:131]
	global_store_dwordx4 v134, v[98:101], s[22:23] nt
	v_pk_mul_f32 v[134:135], v[180:181], v[98:99]
	v_pk_fma_f32 v[104:105], v[56:57], v[104:105], v[132:133]
	v_pk_mul_f32 v[130:131], v[180:181], v[102:103]
	v_pk_mul_f32 v[144:145], v[178:179], v[100:101]
	v_cvt_pk_bf16_f32 v134, v134, v135
	v_pk_mul_f32 v[132:133], v[178:179], v[104:105]
	v_cvt_pk_bf16_f32 v135, v144, v145
	global_store_dwordx4 v[142:143], v[102:105], off nt
	v_cvt_pk_bf16_f32 v130, v130, v131
	v_cvt_pk_bf16_f32 v131, v132, v133
	ds_write_b128 v200, v[94:97]
	ds_write_b128 v200, v[90:93] offset:64
	ds_read_b128 v[90:93], v201
	ds_read_b128 v[94:97], v201 offset:1152
	v_lshl_add_u64 v[132:133], s[22:23], 0, v[186:187]
	v_lshl_add_u64 v[142:143], s[22:23], 0, v[188:189]
	s_waitcnt lgkmcnt(1)
	v_pk_fma_f32 v[90:91], v[50:51], v[90:91], v[126:127]
	v_pk_fma_f32 v[92:93], v[52:53], v[92:93], v[128:129]
	v_pk_mul_f32 v[128:129], v[176:177], v[90:91]
	global_store_dwordx4 v[132:133], v[90:93], off nt
	v_pk_mul_f32 v[126:127], v[174:175], v[92:93]
	v_cvt_pk_bf16_f32 v128, v128, v129
	s_waitcnt vmcnt(13) lgkmcnt(0)
	v_pk_fma_f32 v[94:95], v[50:51], v[94:95], v[122:123]
	v_cvt_pk_bf16_f32 v129, v126, v127
	ds_bpermute_b32 v122, v203, v128
	ds_bpermute_b32 v123, v203, v129
	v_pk_fma_f32 v[96:97], v[52:53], v[96:97], v[124:125]
	v_pk_mul_f32 v[124:125], v[176:177], v[94:95]
	v_pk_mul_f32 v[126:127], v[174:175], v[96:97]
	global_store_dwordx4 v[142:143], v[94:97], off nt
	v_cvt_pk_bf16_f32 v124, v124, v125
	v_cvt_pk_bf16_f32 v125, v126, v127
	v_lshlrev_b32_e32 v126, 1, v136
	s_waitcnt lgkmcnt(0)
	v_add_u32_e32 v250, 0xfffff040, v126
	v_cndmask_b32_e64 v250, v126, v250, s[38:39]
	v_cndmask_b32_e64 v248, v134, v122, s[38:39]
	v_cndmask_b32_e64 v249, v135, v123, s[38:39]
	global_store_dwordx2 v250, v[248:249], s[20:21]
	v_cndmask_b32_e64 v246, v122, v134, s[38:39]
	v_cndmask_b32_e64 v247, v123, v135, s[38:39]
	s_waitcnt lgkmcnt(1)
	v_add_u32_e32 v122, 0x1040, v126
	v_cndmask_b32_e64 v122, v126, v122, s[36:37]
	global_store_dwordx2 v122, v[246:247], s[20:21]
	ds_bpermute_b32 v122, v203, v124
	s_waitcnt lgkmcnt(1)
	ds_bpermute_b32 v123, v203, v125
	v_add_u32_e32 v125, 0x14000, v202
	v_lshlrev_b32_e32 v124, 1, v125
	s_waitcnt lgkmcnt(0)
	v_add_u32_e32 v250, 0xfffff040, v124
	v_cndmask_b32_e64 v250, v124, v250, s[38:39]
	v_cndmask_b32_e64 v248, v130, v122, s[38:39]
	v_cndmask_b32_e64 v249, v131, v123, s[38:39]
	global_store_dwordx2 v250, v[248:249], s[20:21]
	v_cndmask_b32_e64 v246, v122, v130, s[38:39]
	v_cndmask_b32_e64 v247, v123, v131, s[38:39]
	v_mul_f32_e32 v91, v91, v91
	v_fmac_f32_e32 v91, v90, v90
	v_mul_f32_e32 v90, v93, v93
	v_mul_f32_e32 v101, v101, v101
	v_fmac_f32_e32 v90, v92, v92
	v_mul_f32_e32 v99, v99, v99
	v_fmac_f32_e32 v101, v100, v100
	v_mul_f32_e32 v100, v103, v103
	v_mul_f32_e32 v103, v105, v105
	v_add_f32_e32 v90, v91, v90
	v_mul_f32_e32 v91, v95, v95
	v_mul_f32_e32 v92, v97, v97
	v_fmac_f32_e32 v103, v104, v104
	v_fmac_f32_e32 v91, v94, v94
	v_fmac_f32_e32 v92, v96, v96
	v_fmac_f32_e32 v99, v98, v98
	v_fmac_f32_e32 v100, v102, v102
	v_add_f32_e32 v91, v91, v92
	v_add_f32_e32 v92, v99, v101
	v_add_f32_e32 v93, v100, v103
	v_add_f32_e32 v90, v92, v90
	v_add_f32_e32 v91, v93, v91
	ds_bpermute_b32 v92, v190, v90
	ds_bpermute_b32 v93, v190, v91
	s_waitcnt lgkmcnt(1)
	v_add_f32_e32 v90, v90, v92
	s_waitcnt lgkmcnt(0)
	v_add_f32_e32 v93, v91, v93
	ds_bpermute_b32 v92, v191, v90
	ds_bpermute_b32 v94, v191, v93
	s_waitcnt lgkmcnt(1)
	v_add_f32_e32 v90, v90, v92
	s_waitcnt lgkmcnt(0)
	v_add_f32_e32 v92, v93, v94
	ds_bpermute_b32 v91, v204, v90
	ds_bpermute_b32 v93, v204, v92
	v_add_u32_e32 v94, 0x1040, v124
	v_cndmask_b32_e64 v94, v124, v94, s[36:37]
	global_store_dwordx2 v94, v[246:247], s[20:21]
	s_and_saveexec_b64 s[24:25], s[40:41]
	s_cbranch_execz .LBB0_2799
	s_waitcnt lgkmcnt(1)
	v_add_f32_e32 v90, v90, v91
	s_waitcnt lgkmcnt(0)
	v_add_f32_e32 v91, v92, v93
	ds_write2_b32 v194, v90, v91 offset0:32 offset1:40
; #define LAS __attribute__((address_space(3)))
; #define ERN_EOFF(q, m) (eb + (unsigned)((((q) & 1) * HALF + (m) * 16) * DM + ERN_COL((q) >> 1)))
;     __device__ __forceinline__ void operator()(const f32x4 (&acc)[2][2][4][2], const Unit& u, int wr, int wc, int fr, int fq) const {
;     ...
;         ERN_LOADX(0);
; #pragma unroll
;         for (int g = 0; g < 8; ++g) { const int ai = g >> 2, m = g & 3;
;             if (g + 1 < 8) ERN_LOADX(g + 1);
;             float sq0 = 0.f, sq1 = 0.f; u32x2 hw[2][2];
; #pragma unroll
;             for (int bj = 0; bj < 2; ++bj) {
;                 *(LAS f32x4*)(st + wr_off) = acc[ai][bj][m][0]; *(LAS f32x4*)(st + wr_off + 64) = acc[ai][bj][m][1];
;                 const f32x4 a0 = *(const LAS f32x4*)(st + rd_off), a1 = *(const LAS f32x4*)(st + rd_off + 8 * 144);
;                 { const f32x4 xv = xb[g & 1][bj][0] + gv[bj] * a0; __builtin_nontemporal_store(xv, (f32x4*)((char*)xo + 4u * ERN_EOFF(g, bj, 0)));
;                   sq0 += (xv.x * xv.x + xv.y * xv.y) + (xv.z * xv.z + xv.w * xv.w);
;                   const f32x4 hv = xv * gsn[bj]; hw[bj][0].x = cvt_pk_bf16(hv.x, hv.y); hw[bj][0].y = cvt_pk_bf16(hv.z, hv.w); }
;                 { const f32x4 xv = xb[g & 1][bj][1] + gv[bj] * a1; __builtin_nontemporal_store(xv, (f32x4*)((char*)xo + 4u * ERN_EOFF(g, bj, 1)));
;                   sq1 += (xv.x * xv.x + xv.y * xv.y) + (xv.z * xv.z + xv.w * xv.w);
;                   const f32x4 hv = xv * gsn[bj]; hw[bj][1].x = cvt_pk_bf16(hv.x, hv.y); hw[bj][1].y = cvt_pk_bf16(hv.z, hv.w); }
;             }
;             if (!NOH && !PLAIN) {
; #pragma unroll
;                 for (int rh = 0; rh < 2; ++rh) { u32x2 rv; rv.x = __shfl_xor(hw[1][rh].x, 8); rv.y = __shfl_xor(hw[1][rh].y, 8);
;                     const unsigned e0 = ERN_EOFF(g, 0, rh);
;                     const unsigned ee = odd ? (e0 - DM + 32) : e0, eo2 = odd ? e0 : (e0 + DM + 32);
;                     *(u32x2*)((char*)ho + 2u * ee) = odd ? rv : hw[0][rh];
;                     *(u32x2*)((char*)ho + 2u * eo2) = odd ? hw[0][rh] : rv; }
;             }
;             if (!PLAIN) { sq0 += __shfl_xor(sq0, 1); sq0 += __shfl_xor(sq0, 2); sq0 += __shfl_xor(sq0, 4);
;             sq1 += __shfl_xor(sq1, 1); sq1 += __shfl_xor(sq1, 2); sq1 += __shfl_xor(sq1, 4); }
;             if (!PLAIN && pc == 0) { sst[g * 16 + rr] = sq0; sst[g * 16 + 8 + rr] = sq1; }
;         }
.LBB0_2799:
	s_or_b64 exec, exec, s[24:25]
	v_lshl_add_u64 v[124:125], s[22:23], 0, v[162:163]
	v_add_u32_e32 v90, 0x100000, v205
	s_waitcnt lgkmcnt(1)
	v_add_u32_e32 v91, 0x110000, v205
	v_add_u32_e32 v162, 0x100080, v205
	global_load_dwordx4 v[102:105], v90, s[22:23] nt
	global_load_dwordx4 v[98:101], v91, s[22:23] nt
	v_add_u32_e32 v122, 0x110080, v205
	global_load_dwordx4 v[94:97], v162, s[22:23] nt
	s_waitcnt lgkmcnt(0)
	global_load_dwordx4 v[90:93], v122, s[22:23] nt
	ds_write_b128 v200, v[86:89]
	ds_write_b128 v200, v[82:85] offset:64
	ds_read_b128 v[82:85], v201
	ds_read_b128 v[86:89], v201 offset:1152
	v_mov_b32_e32 v139, v163
	v_mov_b32_e32 v141, v163
	s_waitcnt vmcnt(11) lgkmcnt(1)
	v_pk_fma_f32 v[84:85], v[56:57], v[84:85], v[120:121]
	v_add_u32_e32 v120, 0x18000, v202
	v_pk_fma_f32 v[82:83], v[54:55], v[82:83], v[118:119]
	v_lshlrev_b32_e32 v118, 2, v120
	s_waitcnt lgkmcnt(0)
	v_pk_fma_f32 v[86:87], v[54:55], v[86:87], v[114:115]
	global_store_dwordx4 v118, v[82:85], s[22:23] nt
	v_pk_mul_f32 v[118:119], v[180:181], v[82:83]
	v_pk_fma_f32 v[88:89], v[56:57], v[88:89], v[116:117]
	v_pk_mul_f32 v[114:115], v[180:181], v[86:87]
	v_pk_mul_f32 v[126:127], v[178:179], v[84:85]
	v_cvt_pk_bf16_f32 v118, v118, v119
	v_pk_mul_f32 v[116:117], v[178:179], v[88:89]
	v_cvt_pk_bf16_f32 v119, v126, v127
	global_store_dwordx4 v[124:125], v[86:89], off nt
	v_cvt_pk_bf16_f32 v114, v114, v115
	v_cvt_pk_bf16_f32 v115, v116, v117
	ds_write_b128 v200, v[78:81]
	ds_write_b128 v200, v[74:77] offset:64
	ds_read_b128 v[74:77], v201
	ds_read_b128 v[78:81], v201 offset:1152
	v_lshl_add_u64 v[116:117], s[22:23], 0, v[138:139]
	v_lshl_add_u64 v[124:125], s[22:23], 0, v[140:141]
	s_waitcnt lgkmcnt(1)
	v_pk_fma_f32 v[74:75], v[50:51], v[74:75], v[110:111]
	v_pk_fma_f32 v[76:77], v[52:53], v[76:77], v[112:113]
	v_pk_mul_f32 v[112:113], v[176:177], v[74:75]
	global_store_dwordx4 v[116:117], v[74:77], off nt
	v_pk_mul_f32 v[110:111], v[174:175], v[76:77]
	v_cvt_pk_bf16_f32 v112, v112, v113
	s_waitcnt vmcnt(13) lgkmcnt(0)
	v_pk_fma_f32 v[78:79], v[50:51], v[78:79], v[106:107]
	v_cvt_pk_bf16_f32 v113, v110, v111
	ds_bpermute_b32 v106, v203, v112
	ds_bpermute_b32 v107, v203, v113
	v_pk_fma_f32 v[80:81], v[52:53], v[80:81], v[108:109]
	v_pk_mul_f32 v[108:109], v[176:177], v[78:79]
	v_pk_mul_f32 v[110:111], v[174:175], v[80:81]
	global_store_dwordx4 v[124:125], v[78:81], off nt
	v_cvt_pk_bf16_f32 v108, v108, v109
	v_cvt_pk_bf16_f32 v109, v110, v111
	v_lshlrev_b32_e32 v110, 1, v120
	s_waitcnt lgkmcnt(0)
	v_add_u32_e32 v250, 0xfffff040, v110
	v_cndmask_b32_e64 v250, v110, v250, s[38:39]
	v_cndmask_b32_e64 v248, v118, v106, s[38:39]
	v_cndmask_b32_e64 v249, v119, v107, s[38:39]
	global_store_dwordx2 v250, v[248:249], s[20:21]
	v_cndmask_b32_e64 v246, v106, v118, s[38:39]
	v_cndmask_b32_e64 v247, v107, v119, s[38:39]
	s_waitcnt lgkmcnt(1)
	v_add_u32_e32 v106, 0x1040, v110
	v_cndmask_b32_e64 v106, v110, v106, s[36:37]
	global_store_dwordx2 v106, v[246:247], s[20:21]
	ds_bpermute_b32 v106, v203, v108
	s_waitcnt lgkmcnt(1)
	ds_bpermute_b32 v107, v203, v109
	v_add_u32_e32 v109, 0x1c000, v202
	v_lshlrev_b32_e32 v108, 1, v109
	s_waitcnt lgkmcnt(0)
	v_add_u32_e32 v250, 0xfffff040, v108
	v_cndmask_b32_e64 v250, v108, v250, s[38:39]
	v_cndmask_b32_e64 v248, v114, v106, s[38:39]
	v_cndmask_b32_e64 v249, v115, v107, s[38:39]
	global_store_dwordx2 v250, v[248:249], s[20:21]
	v_cndmask_b32_e64 v246, v106, v114, s[38:39]
	v_cndmask_b32_e64 v247, v107, v115, s[38:39]
	v_mul_f32_e32 v75, v75, v75
	v_fmac_f32_e32 v75, v74, v74
	v_mul_f32_e32 v74, v77, v77
	v_mul_f32_e32 v85, v85, v85
	v_fmac_f32_e32 v74, v76, v76
	v_mul_f32_e32 v83, v83, v83
	v_fmac_f32_e32 v85, v84, v84
	v_mul_f32_e32 v84, v87, v87
	v_mul_f32_e32 v87, v89, v89
	v_add_f32_e32 v74, v75, v74
	v_mul_f32_e32 v75, v79, v79
	v_mul_f32_e32 v76, v81, v81
	v_fmac_f32_e32 v87, v88, v88
	v_fmac_f32_e32 v75, v78, v78
	v_fmac_f32_e32 v76, v80, v80
	v_fmac_f32_e32 v83, v82, v82
	v_fmac_f32_e32 v84, v86, v86
	v_add_f32_e32 v75, v75, v76
	v_add_f32_e32 v76, v83, v85
	v_add_f32_e32 v77, v84, v87
	v_add_f32_e32 v74, v76, v74
	v_add_f32_e32 v75, v77, v75
	ds_bpermute_b32 v76, v190, v74
	ds_bpermute_b32 v77, v190, v75
	s_waitcnt lgkmcnt(1)
	v_add_f32_e32 v74, v74, v76
	s_waitcnt lgkmcnt(0)
	v_add_f32_e32 v77, v75, v77
	ds_bpermute_b32 v76, v191, v74
	ds_bpermute_b32 v78, v191, v77
	s_waitcnt lgkmcnt(1)
	v_add_f32_e32 v74, v74, v76
	s_waitcnt lgkmcnt(0)
	v_add_f32_e32 v76, v77, v78
	ds_bpermute_b32 v75, v204, v74
	ds_bpermute_b32 v77, v204, v76
	v_add_u32_e32 v78, 0x1040, v108
	v_cndmask_b32_e64 v78, v108, v78, s[36:37]
	global_store_dwordx2 v78, v[246:247], s[20:21]
	s_and_saveexec_b64 s[24:25], s[40:41]
	s_cbranch_execz .LBB0_2809
	s_waitcnt lgkmcnt(1)
	v_add_f32_e32 v74, v74, v75
	s_waitcnt lgkmcnt(0)
	v_add_f32_e32 v75, v76, v77
	ds_write2_b32 v194, v74, v75 offset0:48 offset1:56
; #define LAS __attribute__((address_space(3)))
; #define ERN_EOFF(q, m) (eb + (unsigned)((((q) & 1) * HALF + (m) * 16) * DM + ERN_COL((q) >> 1)))
;     __device__ __forceinline__ void operator()(const f32x4 (&acc)[2][2][4][2], const Unit& u, int wr, int wc, int fr, int fq) const {
;     ...
;         ERN_LOADX(0);
; #pragma unroll
;         for (int g = 0; g < 8; ++g) { const int ai = g >> 2, m = g & 3;
;             if (g + 1 < 8) ERN_LOADX(g + 1);
;             float sq0 = 0.f, sq1 = 0.f; u32x2 hw[2][2];
; #pragma unroll
;             for (int bj = 0; bj < 2; ++bj) {
;                 *(LAS f32x4*)(st + wr_off) = acc[ai][bj][m][0]; *(LAS f32x4*)(st + wr_off + 64) = acc[ai][bj][m][1];
;                 const f32x4 a0 = *(const LAS f32x4*)(st + rd_off), a1 = *(const LAS f32x4*)(st + rd_off + 8 * 144);
;                 { const f32x4 xv = xb[g & 1][bj][0] + gv[bj] * a0; __builtin_nontemporal_store(xv, (f32x4*)((char*)xo + 4u * ERN_EOFF(g, bj, 0)));
;                   sq0 += (xv.x * xv.x + xv.y * xv.y) + (xv.z * xv.z + xv.w * xv.w);
;                   const f32x4 hv = xv * gsn[bj]; hw[bj][0].x = cvt_pk_bf16(hv.x, hv.y); hw[bj][0].y = cvt_pk_bf16(hv.z, hv.w); }
;                 { const f32x4 xv = xb[g & 1][bj][1] + gv[bj] * a1; __builtin_nontemporal_store(xv, (f32x4*)((char*)xo + 4u * ERN_EOFF(g, bj, 1)));
;                   sq1 += (xv.x * xv.x + xv.y * xv.y) + (xv.z * xv.z + xv.w * xv.w);
;                   const f32x4 hv = xv * gsn[bj]; hw[bj][1].x = cvt_pk_bf16(hv.x, hv.y); hw[bj][1].y = cvt_pk_bf16(hv.z, hv.w); }
;             }
;             if (!NOH && !PLAIN) {
; #pragma unroll
;                 for (int rh = 0; rh < 2; ++rh) { u32x2 rv; rv.x = __shfl_xor(hw[1][rh].x, 8); rv.y = __shfl_xor(hw[1][rh].y, 8);
;                     const unsigned e0 = ERN_EOFF(g, 0, rh);
;                     const unsigned ee = odd ? (e0 - DM + 32) : e0, eo2 = odd ? e0 : (e0 + DM + 32);
;                     *(u32x2*)((char*)ho + 2u * ee) = odd ? rv : hw[0][rh];
;                     *(u32x2*)((char*)ho + 2u * eo2) = odd ? hw[0][rh] : rv; }
;             }
;             if (!PLAIN) { sq0 += __shfl_xor(sq0, 1); sq0 += __shfl_xor(sq0, 2); sq0 += __shfl_xor(sq0, 4);
;             sq1 += __shfl_xor(sq1, 1); sq1 += __shfl_xor(sq1, 2); sq1 += __shfl_xor(sq1, 4); }
;             if (!PLAIN && pc == 0) { sst[g * 16 + rr] = sq0; sst[g * 16 + 8 + rr] = sq1; }
;         }
.LBB0_2809:
	s_or_b64 exec, exec, s[24:25]
	v_lshl_add_u64 v[112:113], s[22:23], 0, v[162:163]
	v_add_u32_e32 v162, 0x120000, v205
	v_add_u32_e32 v108, 0x120080, v205
	v_add_u32_e32 v110, 0x130000, v205
	global_load_dwordx4 v[86:89], v162, s[22:23] nt
	global_load_dwordx4 v[82:85], v110, s[22:23] nt
	v_add_u32_e32 v106, 0x130080, v205
	global_load_dwordx4 v[78:81], v108, s[22:23] nt
	s_waitcnt lgkmcnt(0)
	global_load_dwordx4 v[74:77], v106, s[22:23] nt
	ds_write_b128 v200, v[70:73]
	ds_write_b128 v200, v[66:69] offset:64
	ds_read_b128 v[66:69], v201
	ds_read_b128 v[70:73], v201 offset:1152
	v_mov_b32_e32 v123, v163
	s_waitcnt vmcnt(13) lgkmcnt(1)
	v_pk_fma_f32 v[68:69], v[56:57], v[68:69], v[104:105]
	v_add_u32_e32 v104, 0x40000, v202
	v_pk_fma_f32 v[66:67], v[54:55], v[66:67], v[102:103]
	v_lshlrev_b32_e32 v102, 2, v104
	s_waitcnt vmcnt(12) lgkmcnt(0)
	v_pk_fma_f32 v[72:73], v[56:57], v[72:73], v[100:101]
	v_add_u32_e32 v100, 0x44000, v202
	global_store_dwordx4 v102, v[66:69], s[22:23] nt
	v_pk_mul_f32 v[102:103], v[180:181], v[66:67]
	v_pk_fma_f32 v[70:71], v[54:55], v[70:71], v[98:99]
	v_lshlrev_b32_e32 v98, 2, v100
	v_pk_mul_f32 v[114:115], v[178:179], v[68:69]
	v_cvt_pk_bf16_f32 v102, v102, v103
	s_nop 0
	v_cvt_pk_bf16_f32 v103, v114, v115
	global_store_dwordx4 v98, v[70:73], s[22:23] nt
	v_pk_mul_f32 v[98:99], v[180:181], v[70:71]
	v_pk_mul_f32 v[114:115], v[178:179], v[72:73]
	v_cvt_pk_bf16_f32 v98, v98, v99
	s_nop 0
	v_cvt_pk_bf16_f32 v99, v114, v115
	ds_write_b128 v200, v[62:65]
	ds_write_b128 v200, v[58:61] offset:64
	ds_read_b128 v[58:61], v201
	ds_read_b128 v[62:65], v201 offset:1152
	v_lshl_add_u64 v[114:115], s[22:23], 0, v[122:123]
	s_waitcnt vmcnt(13) lgkmcnt(1)
	v_pk_fma_f32 v[58:59], v[50:51], v[58:59], v[94:95]
	v_pk_fma_f32 v[60:61], v[52:53], v[60:61], v[96:97]
	v_pk_mul_f32 v[96:97], v[176:177], v[58:59]
	global_store_dwordx4 v[112:113], v[58:61], off nt
	v_pk_mul_f32 v[94:95], v[174:175], v[60:61]
	v_cvt_pk_bf16_f32 v96, v96, v97
	s_waitcnt vmcnt(13) lgkmcnt(0)
	v_pk_fma_f32 v[62:63], v[50:51], v[62:63], v[90:91]
	v_cvt_pk_bf16_f32 v97, v94, v95
	ds_bpermute_b32 v90, v203, v96
	ds_bpermute_b32 v91, v203, v97
	v_pk_fma_f32 v[64:65], v[52:53], v[64:65], v[92:93]
	v_pk_mul_f32 v[92:93], v[176:177], v[62:63]
	v_pk_mul_f32 v[94:95], v[174:175], v[64:65]
	global_store_dwordx4 v[114:115], v[62:65], off nt
	v_cvt_pk_bf16_f32 v92, v92, v93
	v_cvt_pk_bf16_f32 v93, v94, v95
	v_lshlrev_b32_e32 v94, 1, v104
	s_waitcnt lgkmcnt(0)
	v_add_u32_e32 v250, 0xfffff040, v94
	v_cndmask_b32_e64 v250, v94, v250, s[38:39]
	v_cndmask_b32_e64 v248, v102, v90, s[38:39]
	v_cndmask_b32_e64 v249, v103, v91, s[38:39]
	global_store_dwordx2 v250, v[248:249], s[20:21]
	v_cndmask_b32_e64 v246, v90, v102, s[38:39]
	v_cndmask_b32_e64 v247, v91, v103, s[38:39]
	s_waitcnt lgkmcnt(1)
	v_add_u32_e32 v90, 0x1040, v94
	v_cndmask_b32_e64 v90, v94, v90, s[36:37]
	global_store_dwordx2 v90, v[246:247], s[20:21]
	ds_bpermute_b32 v90, v203, v92
	s_waitcnt lgkmcnt(1)
	ds_bpermute_b32 v91, v203, v93
	v_lshlrev_b32_e32 v92, 1, v100
	s_waitcnt lgkmcnt(0)
	v_add_u32_e32 v250, 0xfffff040, v92
	v_cndmask_b32_e64 v250, v92, v250, s[38:39]
	v_cndmask_b32_e64 v248, v98, v90, s[38:39]
	v_cndmask_b32_e64 v249, v99, v91, s[38:39]
	global_store_dwordx2 v250, v[248:249], s[20:21]
	v_cndmask_b32_e64 v246, v90, v98, s[38:39]
	v_cndmask_b32_e64 v247, v91, v99, s[38:39]
	v_mul_f32_e32 v59, v59, v59
	v_fmac_f32_e32 v59, v58, v58
	v_mul_f32_e32 v58, v61, v61
	v_mul_f32_e32 v69, v69, v69
	v_fmac_f32_e32 v58, v60, v60
	v_mul_f32_e32 v67, v67, v67
	v_fmac_f32_e32 v69, v68, v68
	v_mul_f32_e32 v68, v71, v71
	v_mul_f32_e32 v71, v73, v73
	v_add_f32_e32 v58, v59, v58
	v_mul_f32_e32 v59, v63, v63
	v_mul_f32_e32 v60, v65, v65
	v_fmac_f32_e32 v71, v72, v72
	v_fmac_f32_e32 v59, v62, v62
	v_fmac_f32_e32 v60, v64, v64
	v_fmac_f32_e32 v67, v66, v66
	v_fmac_f32_e32 v68, v70, v70
	v_add_f32_e32 v59, v59, v60
	v_add_f32_e32 v60, v67, v69
	v_add_f32_e32 v61, v68, v71
	v_add_f32_e32 v58, v60, v58
	v_add_f32_e32 v59, v61, v59
	ds_bpermute_b32 v60, v190, v58
	ds_bpermute_b32 v61, v190, v59
	s_waitcnt lgkmcnt(1)
	v_add_f32_e32 v58, v58, v60
	s_waitcnt lgkmcnt(0)
	v_add_f32_e32 v61, v59, v61
	ds_bpermute_b32 v60, v191, v58
	ds_bpermute_b32 v62, v191, v61
	s_waitcnt lgkmcnt(1)
	v_add_f32_e32 v58, v58, v60
	s_waitcnt lgkmcnt(0)
	v_add_f32_e32 v60, v61, v62
	ds_bpermute_b32 v59, v204, v58
	ds_bpermute_b32 v61, v204, v60
	v_add_u32_e32 v62, 0x1040, v92
	v_cndmask_b32_e64 v62, v92, v62, s[36:37]
	global_store_dwordx2 v62, v[246:247], s[20:21]
	s_and_saveexec_b64 s[24:25], s[40:41]
	s_cbranch_execz .LBB0_2819
	s_waitcnt lgkmcnt(1)
	v_add_f32_e32 v58, v58, v59
	s_waitcnt lgkmcnt(0)
	v_add_f32_e32 v59, v60, v61
	ds_write2_b32 v194, v58, v59 offset0:64 offset1:72
; #define LAS __attribute__((address_space(3)))
; #define ERN_EOFF(q, m) (eb + (unsigned)((((q) & 1) * HALF + (m) * 16) * DM + ERN_COL((q) >> 1)))
;     __device__ __forceinline__ void operator()(const f32x4 (&acc)[2][2][4][2], const Unit& u, int wr, int wc, int fr, int fq) const {
;     ...
;         ERN_LOADX(0);
; #pragma unroll
;         for (int g = 0; g < 8; ++g) { const int ai = g >> 2, m = g & 3;
;             if (g + 1 < 8) ERN_LOADX(g + 1);
;             float sq0 = 0.f, sq1 = 0.f; u32x2 hw[2][2];
; #pragma unroll
;             for (int bj = 0; bj < 2; ++bj) {
;                 *(LAS f32x4*)(st + wr_off) = acc[ai][bj][m][0]; *(LAS f32x4*)(st + wr_off + 64) = acc[ai][bj][m][1];
;                 const f32x4 a0 = *(const LAS f32x4*)(st + rd_off), a1 = *(const LAS f32x4*)(st + rd_off + 8 * 144);
;                 { const f32x4 xv = xb[g & 1][bj][0] + gv[bj] * a0; __builtin_nontemporal_store(xv, (f32x4*)((char*)xo + 4u * ERN_EOFF(g, bj, 0)));
;                   sq0 += (xv.x * xv.x + xv.y * xv.y) + (xv.z * xv.z + xv.w * xv.w);
;                   const f32x4 hv = xv * gsn[bj]; hw[bj][0].x = cvt_pk_bf16(hv.x, hv.y); hw[bj][0].y = cvt_pk_bf16(hv.z, hv.w); }
;                 { const f32x4 xv = xb[g & 1][bj][1] + gv[bj] * a1; __builtin_nontemporal_store(xv, (f32x4*)((char*)xo + 4u * ERN_EOFF(g, bj, 1)));
;                   sq1 += (xv.x * xv.x + xv.y * xv.y) + (xv.z * xv.z + xv.w * xv.w);
;                   const f32x4 hv = xv * gsn[bj]; hw[bj][1].x = cvt_pk_bf16(hv.x, hv.y); hw[bj][1].y = cvt_pk_bf16(hv.z, hv.w); }
;             }
;             if (!NOH && !PLAIN) {
; #pragma unroll
;                 for (int rh = 0; rh < 2; ++rh) { u32x2 rv; rv.x = __shfl_xor(hw[1][rh].x, 8); rv.y = __shfl_xor(hw[1][rh].y, 8);
;                     const unsigned e0 = ERN_EOFF(g, 0, rh);
;                     const unsigned ee = odd ? (e0 - DM + 32) : e0, eo2 = odd ? e0 : (e0 + DM + 32);
;                     *(u32x2*)((char*)ho + 2u * ee) = odd ? rv : hw[0][rh];
;                     *(u32x2*)((char*)ho + 2u * eo2) = odd ? hw[0][rh] : rv; }
;             }
;             if (!PLAIN) { sq0 += __shfl_xor(sq0, 1); sq0 += __shfl_xor(sq0, 2); sq0 += __shfl_xor(sq0, 4);
;             sq1 += __shfl_xor(sq1, 1); sq1 += __shfl_xor(sq1, 2); sq1 += __shfl_xor(sq1, 4); }
;             if (!PLAIN && pc == 0) { sst[g * 16 + rr] = sq0; sst[g * 16 + 8 + rr] = sq1; }
;         }
.LBB0_2819:
	s_or_b64 exec, exec, s[24:25]
	v_lshl_add_u64 v[96:97], s[22:23], 0, v[162:163]
	v_add_u32_e32 v162, 0x140000, v205
	v_add_u32_e32 v92, 0x140080, v205
	v_add_u32_e32 v94, 0x150000, v205
	global_load_dwordx4 v[70:73], v162, s[22:23] nt
	global_load_dwordx4 v[66:69], v94, s[22:23] nt
	v_add_u32_e32 v90, 0x150080, v205
	global_load_dwordx4 v[62:65], v92, s[22:23] nt
	s_waitcnt lgkmcnt(0)
	global_load_dwordx4 v[58:61], v90, s[22:23] nt
	ds_write_b128 v200, v[46:49]
	ds_write_b128 v200, v[42:45] offset:64
	ds_read_b128 v[42:45], v201
	ds_read_b128 v[46:49], v201 offset:1152
	v_mov_b32_e32 v111, v163
	v_lshl_add_u64 v[98:99], s[22:23], 0, v[110:111]
	v_mov_b32_e32 v109, v163
	s_waitcnt vmcnt(13) lgkmcnt(1)
	v_pk_fma_f32 v[42:43], v[54:55], v[42:43], v[86:87]
	s_waitcnt vmcnt(12) lgkmcnt(0)
	v_pk_fma_f32 v[46:47], v[54:55], v[46:47], v[82:83]
	v_pk_fma_f32 v[44:45], v[56:57], v[44:45], v[88:89]
	v_pk_mul_f32 v[86:87], v[180:181], v[42:43]
	v_pk_fma_f32 v[48:49], v[56:57], v[48:49], v[84:85]
	v_pk_mul_f32 v[82:83], v[180:181], v[46:47]
	global_store_dwordx4 v[96:97], v[42:45], off nt
	v_pk_mul_f32 v[88:89], v[178:179], v[44:45]
	v_cvt_pk_bf16_f32 v86, v86, v87
	v_pk_mul_f32 v[84:85], v[178:179], v[48:49]
	v_cvt_pk_bf16_f32 v87, v88, v89
	global_store_dwordx4 v[98:99], v[46:49], off nt
	v_cvt_pk_bf16_f32 v82, v82, v83
	v_cvt_pk_bf16_f32 v83, v84, v85
	ds_write_b128 v200, v[38:41]
	ds_write_b128 v200, v[34:37] offset:64
	ds_read_b128 v[34:37], v201
	ds_read_b128 v[38:41], v201 offset:1152
	v_lshl_add_u64 v[84:85], s[22:23], 0, v[108:109]
	v_mov_b32_e32 v107, v163
	v_lshl_add_u64 v[88:89], s[22:23], 0, v[106:107]
	s_waitcnt vmcnt(13) lgkmcnt(1)
	v_pk_fma_f32 v[34:35], v[50:51], v[34:35], v[78:79]
	v_pk_fma_f32 v[36:37], v[52:53], v[36:37], v[80:81]
	v_pk_mul_f32 v[80:81], v[176:177], v[34:35]
	global_store_dwordx4 v[84:85], v[34:37], off nt
	v_pk_mul_f32 v[78:79], v[174:175], v[36:37]
	v_cvt_pk_bf16_f32 v80, v80, v81
	s_waitcnt vmcnt(13) lgkmcnt(0)
	v_pk_fma_f32 v[38:39], v[50:51], v[38:39], v[74:75]
	v_cvt_pk_bf16_f32 v81, v78, v79
	ds_bpermute_b32 v74, v203, v80
	ds_bpermute_b32 v75, v203, v81
	v_pk_fma_f32 v[40:41], v[52:53], v[40:41], v[76:77]
	v_pk_mul_f32 v[76:77], v[176:177], v[38:39]
	v_pk_mul_f32 v[78:79], v[174:175], v[40:41]
	global_store_dwordx4 v[88:89], v[38:41], off nt
	v_cvt_pk_bf16_f32 v76, v76, v77
	v_cvt_pk_bf16_f32 v77, v78, v79
	v_add_u32_e32 v79, 0x48000, v202
	v_lshlrev_b32_e32 v78, 1, v79
	s_waitcnt lgkmcnt(0)
	v_add_u32_e32 v250, 0xfffff040, v78
	v_cndmask_b32_e64 v250, v78, v250, s[38:39]
	v_cndmask_b32_e64 v248, v86, v74, s[38:39]
	v_cndmask_b32_e64 v249, v87, v75, s[38:39]
	global_store_dwordx2 v250, v[248:249], s[20:21]
	v_cndmask_b32_e64 v246, v74, v86, s[38:39]
	v_cndmask_b32_e64 v247, v75, v87, s[38:39]
	s_waitcnt lgkmcnt(1)
	v_add_u32_e32 v74, 0x1040, v78
	v_cndmask_b32_e64 v74, v78, v74, s[36:37]
	global_store_dwordx2 v74, v[246:247], s[20:21]
	ds_bpermute_b32 v74, v203, v76
	s_waitcnt lgkmcnt(1)
	ds_bpermute_b32 v75, v203, v77
	v_add_u32_e32 v77, 0x4c000, v202
	v_lshlrev_b32_e32 v76, 1, v77
	s_waitcnt lgkmcnt(0)
	v_add_u32_e32 v250, 0xfffff040, v76
	v_cndmask_b32_e64 v250, v76, v250, s[38:39]
	v_cndmask_b32_e64 v248, v82, v74, s[38:39]
	v_cndmask_b32_e64 v249, v83, v75, s[38:39]
	global_store_dwordx2 v250, v[248:249], s[20:21]
	v_cndmask_b32_e64 v246, v74, v82, s[38:39]
	v_cndmask_b32_e64 v247, v75, v83, s[38:39]
	v_mul_f32_e32 v35, v35, v35
	v_fmac_f32_e32 v35, v34, v34
	v_mul_f32_e32 v34, v37, v37
	v_mul_f32_e32 v45, v45, v45
	v_fmac_f32_e32 v34, v36, v36
	v_mul_f32_e32 v43, v43, v43
	v_fmac_f32_e32 v45, v44, v44
	v_mul_f32_e32 v44, v47, v47
	v_mul_f32_e32 v47, v49, v49
	v_add_f32_e32 v34, v35, v34
	v_mul_f32_e32 v35, v39, v39
	v_mul_f32_e32 v36, v41, v41
	v_fmac_f32_e32 v47, v48, v48
	v_fmac_f32_e32 v35, v38, v38
	v_fmac_f32_e32 v36, v40, v40
	v_fmac_f32_e32 v43, v42, v42
	v_fmac_f32_e32 v44, v46, v46
	v_add_f32_e32 v35, v35, v36
	v_add_f32_e32 v36, v43, v45
	v_add_f32_e32 v37, v44, v47
	v_add_f32_e32 v34, v36, v34
	v_add_f32_e32 v35, v37, v35
	ds_bpermute_b32 v36, v190, v34
	ds_bpermute_b32 v37, v190, v35
	s_waitcnt lgkmcnt(1)
	v_add_f32_e32 v34, v34, v36
	s_waitcnt lgkmcnt(0)
	v_add_f32_e32 v37, v35, v37
	ds_bpermute_b32 v36, v191, v34
	ds_bpermute_b32 v38, v191, v37
	s_waitcnt lgkmcnt(1)
	v_add_f32_e32 v34, v34, v36
	s_waitcnt lgkmcnt(0)
	v_add_f32_e32 v36, v37, v38
	ds_bpermute_b32 v35, v204, v34
	ds_bpermute_b32 v37, v204, v36
	v_add_u32_e32 v38, 0x1040, v76
	v_cndmask_b32_e64 v38, v76, v38, s[36:37]
	global_store_dwordx2 v38, v[246:247], s[20:21]
	s_and_saveexec_b64 s[24:25], s[40:41]
	s_cbranch_execz .LBB0_2829
	s_waitcnt lgkmcnt(1)
	v_add_f32_e32 v34, v34, v35
	s_waitcnt lgkmcnt(0)
	v_add_f32_e32 v35, v36, v37
	ds_write2_b32 v194, v34, v35 offset0:80 offset1:88
; #define LAS __attribute__((address_space(3)))
; #define ERN_EOFF(q, m) (eb + (unsigned)((((q) & 1) * HALF + (m) * 16) * DM + ERN_COL((q) >> 1)))
;     __device__ __forceinline__ void operator()(const f32x4 (&acc)[2][2][4][2], const Unit& u, int wr, int wc, int fr, int fq) const {
;     ...
;         ERN_LOADX(0);
; #pragma unroll
;         for (int g = 0; g < 8; ++g) { const int ai = g >> 2, m = g & 3;
;             if (g + 1 < 8) ERN_LOADX(g + 1);
;             float sq0 = 0.f, sq1 = 0.f; u32x2 hw[2][2];
; #pragma unroll
;             for (int bj = 0; bj < 2; ++bj) {
;                 *(LAS f32x4*)(st + wr_off) = acc[ai][bj][m][0]; *(LAS f32x4*)(st + wr_off + 64) = acc[ai][bj][m][1];
;                 const f32x4 a0 = *(const LAS f32x4*)(st + rd_off), a1 = *(const LAS f32x4*)(st + rd_off + 8 * 144);
;                 { const f32x4 xv = xb[g & 1][bj][0] + gv[bj] * a0; __builtin_nontemporal_store(xv, (f32x4*)((char*)xo + 4u * ERN_EOFF(g, bj, 0)));
;                   sq0 += (xv.x * xv.x + xv.y * xv.y) + (xv.z * xv.z + xv.w * xv.w);
;                   const f32x4 hv = xv * gsn[bj]; hw[bj][0].x = cvt_pk_bf16(hv.x, hv.y); hw[bj][0].y = cvt_pk_bf16(hv.z, hv.w); }
;                 { const f32x4 xv = xb[g & 1][bj][1] + gv[bj] * a1; __builtin_nontemporal_store(xv, (f32x4*)((char*)xo + 4u * ERN_EOFF(g, bj, 1)));
;                   sq1 += (xv.x * xv.x + xv.y * xv.y) + (xv.z * xv.z + xv.w * xv.w);
;                   const f32x4 hv = xv * gsn[bj]; hw[bj][1].x = cvt_pk_bf16(hv.x, hv.y); hw[bj][1].y = cvt_pk_bf16(hv.z, hv.w); }
;             }
;             if (!NOH && !PLAIN) {
; #pragma unroll
;                 for (int rh = 0; rh < 2; ++rh) { u32x2 rv; rv.x = __shfl_xor(hw[1][rh].x, 8); rv.y = __shfl_xor(hw[1][rh].y, 8);
;                     const unsigned e0 = ERN_EOFF(g, 0, rh);
;                     const unsigned ee = odd ? (e0 - DM + 32) : e0, eo2 = odd ? e0 : (e0 + DM + 32);
;                     *(u32x2*)((char*)ho + 2u * ee) = odd ? rv : hw[0][rh];
;                     *(u32x2*)((char*)ho + 2u * eo2) = odd ? hw[0][rh] : rv; }
;             }
;             if (!PLAIN) { sq0 += __shfl_xor(sq0, 1); sq0 += __shfl_xor(sq0, 2); sq0 += __shfl_xor(sq0, 4);
;             sq1 += __shfl_xor(sq1, 1); sq1 += __shfl_xor(sq1, 2); sq1 += __shfl_xor(sq1, 4); }
;             if (!PLAIN && pc == 0) { sst[g * 16 + rr] = sq0; sst[g * 16 + 8 + rr] = sq1; }
;         }
.LBB0_2829:
	s_or_b64 exec, exec, s[24:25]
	v_lshl_add_u64 v[80:81], s[22:23], 0, v[162:163]
	v_add_u32_e32 v162, 0x160000, v205
	v_add_u32_e32 v76, 0x160080, v205
	v_add_u32_e32 v78, 0x170000, v205
	global_load_dwordx4 v[46:49], v162, s[22:23] nt
	global_load_dwordx4 v[42:45], v78, s[22:23] nt
	v_add_u32_e32 v74, 0x170080, v205
	global_load_dwordx4 v[38:41], v76, s[22:23] nt
	s_waitcnt lgkmcnt(0)
	global_load_dwordx4 v[34:37], v74, s[22:23] nt
	ds_write_b128 v200, v[30:33]
	ds_write_b128 v200, v[26:29] offset:64
	ds_read_b128 v[26:29], v201
	ds_read_b128 v[30:33], v201 offset:1152
	v_mov_b32_e32 v95, v163
	v_lshl_add_u64 v[82:83], s[22:23], 0, v[94:95]
	v_mov_b32_e32 v93, v163
	s_waitcnt vmcnt(13) lgkmcnt(1)
	v_pk_fma_f32 v[26:27], v[54:55], v[26:27], v[70:71]
	s_waitcnt vmcnt(12) lgkmcnt(0)
	v_pk_fma_f32 v[30:31], v[54:55], v[30:31], v[66:67]
	v_pk_fma_f32 v[28:29], v[56:57], v[28:29], v[72:73]
	v_pk_mul_f32 v[70:71], v[180:181], v[26:27]
	v_pk_fma_f32 v[32:33], v[56:57], v[32:33], v[68:69]
	v_pk_mul_f32 v[66:67], v[180:181], v[30:31]
	global_store_dwordx4 v[80:81], v[26:29], off nt
	v_pk_mul_f32 v[72:73], v[178:179], v[28:29]
	v_cvt_pk_bf16_f32 v70, v70, v71
	v_pk_mul_f32 v[68:69], v[178:179], v[32:33]
	v_cvt_pk_bf16_f32 v71, v72, v73
	global_store_dwordx4 v[82:83], v[30:33], off nt
	v_cvt_pk_bf16_f32 v66, v66, v67
	v_cvt_pk_bf16_f32 v67, v68, v69
	ds_write_b128 v200, v[22:25]
	ds_write_b128 v200, v[18:21] offset:64
	ds_read_b128 v[18:21], v201
	ds_read_b128 v[22:25], v201 offset:1152
	v_lshl_add_u64 v[68:69], s[22:23], 0, v[92:93]
	v_mov_b32_e32 v91, v163
	v_lshl_add_u64 v[72:73], s[22:23], 0, v[90:91]
	s_waitcnt vmcnt(13) lgkmcnt(1)
	v_pk_fma_f32 v[18:19], v[50:51], v[18:19], v[62:63]
	v_pk_fma_f32 v[20:21], v[52:53], v[20:21], v[64:65]
	v_pk_mul_f32 v[64:65], v[176:177], v[18:19]
	global_store_dwordx4 v[68:69], v[18:21], off nt
	v_pk_mul_f32 v[62:63], v[174:175], v[20:21]
	v_cvt_pk_bf16_f32 v64, v64, v65
	s_waitcnt vmcnt(13) lgkmcnt(0)
	v_pk_fma_f32 v[22:23], v[50:51], v[22:23], v[58:59]
	v_cvt_pk_bf16_f32 v65, v62, v63
	ds_bpermute_b32 v58, v203, v64
	ds_bpermute_b32 v59, v203, v65
	v_pk_fma_f32 v[24:25], v[52:53], v[24:25], v[60:61]
	v_pk_mul_f32 v[60:61], v[176:177], v[22:23]
	v_pk_mul_f32 v[62:63], v[174:175], v[24:25]
	global_store_dwordx4 v[72:73], v[22:25], off nt
	v_cvt_pk_bf16_f32 v60, v60, v61
	v_cvt_pk_bf16_f32 v61, v62, v63
	v_add_u32_e32 v63, 0x50000, v202
	v_lshlrev_b32_e32 v62, 1, v63
	s_waitcnt lgkmcnt(0)
	v_add_u32_e32 v250, 0xfffff040, v62
	v_cndmask_b32_e64 v250, v62, v250, s[38:39]
	v_cndmask_b32_e64 v248, v70, v58, s[38:39]
	v_cndmask_b32_e64 v249, v71, v59, s[38:39]
	global_store_dwordx2 v250, v[248:249], s[20:21]
	v_cndmask_b32_e64 v246, v58, v70, s[38:39]
	v_cndmask_b32_e64 v247, v59, v71, s[38:39]
	s_waitcnt lgkmcnt(1)
	v_add_u32_e32 v58, 0x1040, v62
	v_cndmask_b32_e64 v58, v62, v58, s[36:37]
	global_store_dwordx2 v58, v[246:247], s[20:21]
	ds_bpermute_b32 v58, v203, v60
	s_waitcnt lgkmcnt(1)
	ds_bpermute_b32 v59, v203, v61
	v_add_u32_e32 v61, 0x54000, v202
	v_lshlrev_b32_e32 v60, 1, v61
	s_waitcnt lgkmcnt(0)
	v_add_u32_e32 v250, 0xfffff040, v60
	v_cndmask_b32_e64 v250, v60, v250, s[38:39]
	v_cndmask_b32_e64 v248, v66, v58, s[38:39]
	v_cndmask_b32_e64 v249, v67, v59, s[38:39]
	global_store_dwordx2 v250, v[248:249], s[20:21]
	v_cndmask_b32_e64 v246, v58, v66, s[38:39]
	v_cndmask_b32_e64 v247, v59, v67, s[38:39]
	v_mul_f32_e32 v19, v19, v19
	v_fmac_f32_e32 v19, v18, v18
	v_mul_f32_e32 v18, v21, v21
	v_mul_f32_e32 v29, v29, v29
	v_fmac_f32_e32 v18, v20, v20
	v_mul_f32_e32 v27, v27, v27
	v_fmac_f32_e32 v29, v28, v28
	v_mul_f32_e32 v28, v31, v31
	v_mul_f32_e32 v31, v33, v33
	v_add_f32_e32 v18, v19, v18
	v_mul_f32_e32 v19, v23, v23
	v_mul_f32_e32 v20, v25, v25
	v_fmac_f32_e32 v31, v32, v32
	v_fmac_f32_e32 v19, v22, v22
	v_fmac_f32_e32 v20, v24, v24
	v_fmac_f32_e32 v27, v26, v26
	v_fmac_f32_e32 v28, v30, v30
	v_add_f32_e32 v19, v19, v20
	v_add_f32_e32 v20, v27, v29
	v_add_f32_e32 v21, v28, v31
	v_add_f32_e32 v18, v20, v18
	v_add_f32_e32 v19, v21, v19
	ds_bpermute_b32 v20, v190, v18
	ds_bpermute_b32 v21, v190, v19
	s_waitcnt lgkmcnt(1)
	v_add_f32_e32 v18, v18, v20
	s_waitcnt lgkmcnt(0)
	v_add_f32_e32 v21, v19, v21
	ds_bpermute_b32 v20, v191, v18
	ds_bpermute_b32 v22, v191, v21
	s_waitcnt lgkmcnt(1)
	v_add_f32_e32 v18, v18, v20
	s_waitcnt lgkmcnt(0)
	v_add_f32_e32 v20, v21, v22
	ds_bpermute_b32 v19, v204, v18
	ds_bpermute_b32 v21, v204, v20
	v_add_u32_e32 v22, 0x1040, v60
	v_cndmask_b32_e64 v22, v60, v22, s[36:37]
	global_store_dwordx2 v22, v[246:247], s[20:21]
	s_and_saveexec_b64 s[24:25], s[40:41]
	s_cbranch_execz .LBB0_2839
	s_waitcnt lgkmcnt(1)
	v_add_f32_e32 v18, v18, v19
	s_waitcnt lgkmcnt(0)
	v_add_f32_e32 v19, v20, v21
	ds_write2_b32 v194, v18, v19 offset0:96 offset1:104

; #define LAS __attribute__((address_space(3)))
;     __device__ __forceinline__ void operator()(const f32x4 (&acc)[2][2][4][2], const Unit& u, int wr, int wc, int fr, int fq) const {
;         const int s = u.pm >> 5, lane = fq * 16 + fr, rr = lane >> 3, pc = lane & 7;
;         const float* __restrict__ xi = xin + (size_t)u.pm * BM * DM; float* __restrict__ xo = xout + (size_t)u.pm * BM * DM; bf16_t* __restrict__ ho = Hn + (size_t)u.pm * BM * DM;
;         LAS unsigned char* st = lds_epi + (wr * 4 + wc) * 2304;
;         LAS float* sst = (LAS float*)(lds_epi + 18432 + (wr * 4 + wc) * 512);
;         const int colr = u.pn * BM + wc * 64 + 4 * pc;
;         const unsigned eb = (unsigned)((wr * 64 + rr) * DM + colr);
;         f32x4 gv[2], gsn[2];
; #pragma unroll
;         for (int bj = 0; bj < 2; ++bj) { gv[bj] = *(const f32x4*)(gate + (size_t)s * MODW + colr + bj * 32) * (0.5f * GS2);
;             if (!PLAIN) gsn[bj] = *(const f32x4*)(gnext + colr + bj * 32) * (*(const f32x4*)(scnext + (size_t)s * MODW + colr + bj * 32) + 1.0f); else gsn[bj] = gv[bj]; }
;         const unsigned wr_off = (unsigned)(fr * 144 + 16 * fq), rd_off = (unsigned)(rr * 144 + pc * 16);
;         const bool odd = (rr & 1) != 0;
;         f32x4 xb[2][2][2];
;     ...
;         ERN_LOADX(0);
; #pragma unroll
;         for (int g = 0; g < 8; ++g) { const int ai = g >> 2, m = g & 3;
;             if (g + 1 < 8) ERN_LOADX(g + 1);
;             float sq0 = 0.f, sq1 = 0.f; u32x2 hw[2][2];
; #pragma unroll
;             for (int bj = 0; bj < 2; ++bj) {
;                 *(LAS f32x4*)(st + wr_off) = acc[ai][bj][m][0]; *(LAS f32x4*)(st + wr_off + 64) = acc[ai][bj][m][1];
;                 const f32x4 a0 = *(const LAS f32x4*)(st + rd_off), a1 = *(const LAS f32x4*)(st + rd_off + 8 * 144);
;                 { const f32x4 xv = xb[g & 1][bj][0] + gv[bj] * a0; __builtin_nontemporal_store(xv, (f32x4*)((char*)xo + 4u * ERN_EOFF(g, bj, 0)));
;                   sq0 += (xv.x * xv.x + xv.y * xv.y) + (xv.z * xv.z + xv.w * xv.w);
;                   const f32x4 hv = xv * gsn[bj]; hw[bj][0].x = cvt_pk_bf16(hv.x, hv.y); hw[bj][0].y = cvt_pk_bf16(hv.z, hv.w); }
;                 { const f32x4 xv = xb[g & 1][bj][1] + gv[bj] * a1; __builtin_nontemporal_store(xv, (f32x4*)((char*)xo + 4u * ERN_EOFF(g, bj, 1)));
;                   sq1 += (xv.x * xv.x + xv.y * xv.y) + (xv.z * xv.z + xv.w * xv.w);
.LBB0_3005:
	s_ashr_i32 s14, s12, 5
	s_ashr_i32 s13, s12, 31
	s_mul_hi_i32 s15, s14, 0x12000
	s_mul_i32 s14, s14, 0x12000
	v_lshl_or_b32 v152, s38, 8, v145
	s_add_u32 s14, s29, s14
	s_addc_u32 s15, s30, s15
	v_ashrrev_i32_e32 v153, 31, v152
	s_lshl_b64 s[12:13], s[12:13], 21
	v_lshl_add_u64 v[166:167], v[152:153], 2, s[14:15]
	s_add_u32 s12, s90, s12
	global_load_dwordx4 v[154:157], v[166:167], off
	s_addc_u32 s13, s91, s13
	v_lshl_add_u32 v152, v152, 2, v146
	global_load_dwordx4 v[158:161], v152, s[12:13] nt
	v_add_u32_e32 v153, 0x10000, v152
	global_load_dwordx4 v[162:165], v153, s[12:13] nt
	s_nop 0
	global_load_dwordx4 v[166:169], v[166:167], off offset:128
	s_nop 0
	global_load_dwordx4 v[170:173], v152, s[12:13] offset:128 nt
	v_add_u32_e32 v198, 0x10080, v152
	global_load_dwordx4 v[174:177], v198, s[12:13] nt
	v_add_u32_e32 v199, 0x20000, v152
	global_load_dwordx4 v[178:181], v199, s[12:13] nt
	v_add_u32_e32 v200, 0x30000, v152
	global_load_dwordx4 v[182:185], v200, s[12:13] nt
	v_add_u32_e32 v201, 0x20080, v152
	global_load_dwordx4 v[186:189], v201, s[12:13] nt
	v_add_u32_e32 v202, 0x30080, v152
	global_load_dwordx4 v[190:193], v202, s[12:13] nt
	ds_write_b128 v150, v[124:127]
	ds_write_b128 v150, v[120:123] offset:64
	ds_read_b128 v[124:127], v151
	ds_read_b128 v[194:197], v151 offset:1152
	v_add_u32_e32 v203, 0x40000, v152
	v_add_u32_e32 v204, 0x50000, v152
	s_mov_b64 s[14:15], -1
	s_and_b64 vcc, exec, s[0:1]
	s_waitcnt vmcnt(0)
	v_pk_mul_f32 v[120:121], v[156:157], 0.5 op_sel_hi:[1,0]
	v_pk_mul_f32 v[122:123], v[154:155], 0.5 op_sel_hi:[1,0]
	s_waitcnt lgkmcnt(1)
	v_pk_fma_f32 v[126:127], v[120:121], v[126:127], v[160:161]
	v_pk_fma_f32 v[124:125], v[122:123], v[124:125], v[158:159]
	s_waitcnt lgkmcnt(0)
	v_pk_fma_f32 v[156:157], v[120:121], v[196:197], v[164:165]
	v_pk_fma_f32 v[154:155], v[122:123], v[194:195], v[162:163]
	global_store_dwordx4 v152, v[124:127], s[12:13] nt
	v_pk_mul_f32 v[158:159], v[120:121], v[156:157]
	v_pk_mul_f32 v[160:161], v[122:123], v[154:155]
	v_pk_mul_f32 v[124:125], v[122:123], v[124:125]
	v_pk_mul_f32 v[126:127], v[120:121], v[126:127]
	v_cvt_pk_bf16_f32 v124, v124, v125
	s_nop 0
	v_cvt_pk_bf16_f32 v124, v126, v127
	global_store_dwordx4 v153, v[154:157], s[12:13] nt
	v_cvt_pk_bf16_f32 v124, v160, v161
	v_add_u32_e32 v153, 0x40080, v152
	v_cvt_pk_bf16_f32 v124, v158, v159
	ds_write_b128 v150, v[116:119]
	ds_write_b128 v150, v[108:111] offset:64
	ds_read_b128 v[116:119], v151
	ds_read_b128 v[124:127], v151 offset:1152
	v_pk_mul_f32 v[108:109], v[168:169], 0.5 op_sel_hi:[1,0]
	v_pk_mul_f32 v[110:111], v[166:167], 0.5 op_sel_hi:[1,0]
	v_add_u32_e32 v166, 0x50080, v152
	s_waitcnt lgkmcnt(1)
	v_pk_fma_f32 v[118:119], v[108:109], v[118:119], v[172:173]
	v_pk_fma_f32 v[116:117], v[110:111], v[116:117], v[170:171]
	s_waitcnt lgkmcnt(0)
	v_pk_fma_f32 v[126:127], v[108:109], v[126:127], v[176:177]
	v_pk_fma_f32 v[124:125], v[110:111], v[124:125], v[174:175]
	global_store_dwordx4 v152, v[116:119], s[12:13] offset:128 nt
	v_pk_mul_f32 v[154:155], v[108:109], v[126:127]
	v_pk_mul_f32 v[156:157], v[110:111], v[124:125]
	v_pk_mul_f32 v[116:117], v[110:111], v[116:117]
	v_pk_mul_f32 v[118:119], v[108:109], v[118:119]
	v_cvt_pk_bf16_f32 v116, v116, v117
	s_nop 0
	v_cvt_pk_bf16_f32 v116, v118, v119
	global_store_dwordx4 v198, v[124:127], s[12:13] nt
	v_cvt_pk_bf16_f32 v116, v156, v157
	s_nop 0
	v_cvt_pk_bf16_f32 v116, v154, v155
	global_load_dwordx4 v[116:119], v203, s[12:13] nt
	global_load_dwordx4 v[124:127], v204, s[12:13] nt
	ds_write_b128 v150, v[112:115]
	ds_write_b128 v150, v[104:107] offset:64
	ds_read_b128 v[104:107], v151
	ds_read_b128 v[112:115], v151 offset:1152
	global_load_dwordx4 v[154:157], v153, s[12:13] nt
	global_load_dwordx4 v[158:161], v166, s[12:13] nt
	s_waitcnt lgkmcnt(1)
	v_pk_fma_f32 v[106:107], v[120:121], v[106:107], v[180:181]
	v_pk_fma_f32 v[104:105], v[122:123], v[104:105], v[178:179]
	s_waitcnt lgkmcnt(0)
	v_pk_fma_f32 v[114:115], v[120:121], v[114:115], v[184:185]
	v_pk_fma_f32 v[112:113], v[122:123], v[112:113], v[182:183]
	global_store_dwordx4 v199, v[104:107], s[12:13] nt
	v_pk_mul_f32 v[162:163], v[120:121], v[114:115]
	v_pk_mul_f32 v[164:165], v[122:123], v[112:113]
	v_pk_mul_f32 v[104:105], v[122:123], v[104:105]
	v_pk_mul_f32 v[106:107], v[120:121], v[106:107]
	v_cvt_pk_bf16_f32 v104, v104, v105
	s_nop 0
	v_cvt_pk_bf16_f32 v104, v106, v107
	global_store_dwordx4 v200, v[112:115], s[12:13] nt
	v_cvt_pk_bf16_f32 v104, v164, v165
	v_add_u32_e32 v164, 0x60080, v152
	v_cvt_pk_bf16_f32 v104, v162, v163
	ds_write_b128 v150, v[100:103]
	ds_write_b128 v150, v[96:99] offset:64
	ds_read_b128 v[96:99], v151
	ds_read_b128 v[100:103], v151 offset:1152
	v_add_u32_e32 v162, 0x60000, v152
	v_add_u32_e32 v163, 0x70000, v152
	v_add_u32_e32 v165, 0x70080, v152
	s_waitcnt lgkmcnt(1)
	v_pk_fma_f32 v[98:99], v[108:109], v[98:99], v[188:189]
	v_pk_fma_f32 v[96:97], v[110:111], v[96:97], v[186:187]
	s_waitcnt lgkmcnt(0)
	v_pk_fma_f32 v[102:103], v[108:109], v[102:103], v[192:193]
	v_pk_fma_f32 v[100:101], v[110:111], v[100:101], v[190:191]
	global_store_dwordx4 v201, v[96:99], s[12:13] nt
	v_pk_mul_f32 v[104:105], v[108:109], v[102:103]
	v_pk_mul_f32 v[106:107], v[110:111], v[100:101]
	v_pk_mul_f32 v[96:97], v[110:111], v[96:97]
	v_pk_mul_f32 v[98:99], v[108:109], v[98:99]
	v_cvt_pk_bf16_f32 v96, v96, v97
	s_nop 0
	v_cvt_pk_bf16_f32 v96, v98, v99
	global_store_dwordx4 v202, v[100:103], s[12:13] nt
	v_cvt_pk_bf16_f32 v96, v106, v107
	s_nop 0
	v_cvt_pk_bf16_f32 v96, v104, v105
	global_load_dwordx4 v[96:99], v162, s[12:13] nt
	global_load_dwordx4 v[100:103], v163, s[12:13] nt
	global_load_dwordx4 v[104:107], v164, s[12:13] nt
	global_load_dwordx4 v[112:115], v165, s[12:13] nt
	ds_write_b128 v150, v[92:95]
	ds_write_b128 v150, v[88:91] offset:64
	ds_read_b128 v[88:91], v151
	ds_read_b128 v[92:95], v151 offset:1152
	s_waitcnt vmcnt(11) lgkmcnt(1)
; #define LAS __attribute__((address_space(3)))
; __device__ __forceinline__ unsigned cvt_pk_bf16(float lo, float hi) { unsigned r; asm volatile("v_cvt_pk_bf16_f32 %0, %1, %2" : "=v"(r) : "v"(lo), "v"(hi)); return r; }
; #define ERN_EOFF(q, m) (eb + (unsigned)((((q) & 1) * HALF + (m) * 16) * DM + ERN_COL((q) >> 1)))
; #define ERN_LOADX(q) do { _Pragma("unroll") for (int m = 0; m < 4; ++m) xb[(q) & 1][m] = *(const f32x4*)((const char*)xi + 4u * ERN_EOFF(q, m)); } while (0)
; #define ERN_LOADX(g) do { _Pragma("unroll") for (int bj_ = 0; bj_ < 2; ++bj_) _Pragma("unroll") for (int rh_ = 0; rh_ < 2; ++rh_) xb[(g) & 1][bj_][rh_] = *(const f32x4*)((const char*)xi + 4u * ERN_EOFF(g, bj_, rh_)); } while (0)
;     __device__ __forceinline__ void operator()(const f32x4 (&acc)[2][2][4][2], const Unit& u, int wr, int wc, int fr, int fq) const {
;     ...
;         for (int g = 0; g < 8; ++g) { const int ai = g >> 2, m = g & 3;
;             if (g + 1 < 8) ERN_LOADX(g + 1);
;             float sq0 = 0.f, sq1 = 0.f; u32x2 hw[2][2];
; #pragma unroll
;             for (int bj = 0; bj < 2; ++bj) {
;                 *(LAS f32x4*)(st + wr_off) = acc[ai][bj][m][0]; *(LAS f32x4*)(st + wr_off + 64) = acc[ai][bj][m][1];
;                 const f32x4 a0 = *(const LAS f32x4*)(st + rd_off), a1 = *(const LAS f32x4*)(st + rd_off + 8 * 144);
;                 { const f32x4 xv = xb[g & 1][bj][0] + gv[bj] * a0; __builtin_nontemporal_store(xv, (f32x4*)((char*)xo + 4u * ERN_EOFF(g, bj, 0)));
;                   sq0 += (xv.x * xv.x + xv.y * xv.y) + (xv.z * xv.z + xv.w * xv.w);
;                   const f32x4 hv = xv * gsn[bj]; hw[bj][0].x = cvt_pk_bf16(hv.x, hv.y); hw[bj][0].y = cvt_pk_bf16(hv.z, hv.w); }
;                 { const f32x4 xv = xb[g & 1][bj][1] + gv[bj] * a1; __builtin_nontemporal_store(xv, (f32x4*)((char*)xo + 4u * ERN_EOFF(g, bj, 1)));
;                   sq1 += (xv.x * xv.x + xv.y * xv.y) + (xv.z * xv.z + xv.w * xv.w);
;                   const f32x4 hv = xv * gsn[bj]; hw[bj][1].x = cvt_pk_bf16(hv.x, hv.y); hw[bj][1].y = cvt_pk_bf16(hv.z, hv.w); }
;             }
	v_pk_fma_f32 v[90:91], v[120:121], v[90:91], v[118:119]
	v_pk_fma_f32 v[88:89], v[122:123], v[88:89], v[116:117]
	s_waitcnt vmcnt(10) lgkmcnt(0)
	v_pk_fma_f32 v[94:95], v[120:121], v[94:95], v[126:127]
	v_pk_fma_f32 v[92:93], v[122:123], v[92:93], v[124:125]
	global_store_dwordx4 v203, v[88:91], s[12:13] nt
	v_pk_mul_f32 v[116:117], v[120:121], v[94:95]
	v_pk_mul_f32 v[118:119], v[122:123], v[92:93]
	v_pk_mul_f32 v[88:89], v[122:123], v[88:89]
	v_pk_mul_f32 v[90:91], v[120:121], v[90:91]
	v_cvt_pk_bf16_f32 v88, v88, v89
	s_nop 0
	v_cvt_pk_bf16_f32 v88, v90, v91
	global_store_dwordx4 v204, v[92:95], s[12:13] nt
	v_cvt_pk_bf16_f32 v88, v118, v119
	v_add_u32_e32 v118, 0x100080, v152
	v_cvt_pk_bf16_f32 v88, v116, v117
	ds_write_b128 v150, v[84:87]
	ds_write_b128 v150, v[80:83] offset:64
	ds_read_b128 v[80:83], v151
	ds_read_b128 v[84:87], v151 offset:1152
	v_add_u32_e32 v116, 0x100000, v152
	v_add_u32_e32 v117, 0x110000, v152
	v_add_u32_e32 v119, 0x110080, v152
	s_waitcnt vmcnt(11) lgkmcnt(1)
	v_pk_fma_f32 v[82:83], v[108:109], v[82:83], v[156:157]
	v_pk_fma_f32 v[80:81], v[110:111], v[80:81], v[154:155]
	s_waitcnt vmcnt(10) lgkmcnt(0)
	v_pk_fma_f32 v[86:87], v[108:109], v[86:87], v[160:161]
	v_pk_fma_f32 v[84:85], v[110:111], v[84:85], v[158:159]
	global_store_dwordx4 v153, v[80:83], s[12:13] nt
	v_pk_mul_f32 v[88:89], v[108:109], v[86:87]
	v_pk_mul_f32 v[90:91], v[110:111], v[84:85]
	v_pk_mul_f32 v[80:81], v[110:111], v[80:81]
	v_pk_mul_f32 v[82:83], v[108:109], v[82:83]
	v_cvt_pk_bf16_f32 v80, v80, v81
	s_nop 0
	v_cvt_pk_bf16_f32 v80, v82, v83
	global_store_dwordx4 v166, v[84:87], s[12:13] nt
	v_cvt_pk_bf16_f32 v80, v90, v91
	s_nop 0
	v_cvt_pk_bf16_f32 v80, v88, v89
	global_load_dwordx4 v[80:83], v116, s[12:13] nt
	global_load_dwordx4 v[84:87], v117, s[12:13] nt
	ds_write_b128 v150, v[76:79]
	ds_write_b128 v150, v[72:75] offset:64
	ds_read_b128 v[72:75], v151
	ds_read_b128 v[76:79], v151 offset:1152
	global_load_dwordx4 v[88:91], v118, s[12:13] nt
	global_load_dwordx4 v[92:95], v119, s[12:13] nt
	s_waitcnt vmcnt(11) lgkmcnt(1)
	v_pk_fma_f32 v[74:75], v[120:121], v[74:75], v[98:99]
	v_pk_fma_f32 v[72:73], v[122:123], v[72:73], v[96:97]
	s_waitcnt vmcnt(10) lgkmcnt(0)
	v_pk_fma_f32 v[78:79], v[120:121], v[78:79], v[102:103]
	v_pk_fma_f32 v[76:77], v[122:123], v[76:77], v[100:101]
	global_store_dwordx4 v162, v[72:75], s[12:13] nt
	v_pk_mul_f32 v[96:97], v[120:121], v[78:79]
	v_pk_mul_f32 v[98:99], v[122:123], v[76:77]
	v_pk_mul_f32 v[72:73], v[122:123], v[72:73]
	v_pk_mul_f32 v[74:75], v[120:121], v[74:75]
	v_cvt_pk_bf16_f32 v72, v72, v73
	s_nop 0
	v_cvt_pk_bf16_f32 v72, v74, v75
	global_store_dwordx4 v163, v[76:79], s[12:13] nt
	v_cvt_pk_bf16_f32 v72, v98, v99
	v_add_u32_e32 v98, 0x120080, v152
	v_cvt_pk_bf16_f32 v72, v96, v97
	ds_write_b128 v150, v[68:71]
	ds_write_b128 v150, v[64:67] offset:64
	ds_read_b128 v[64:67], v151
	ds_read_b128 v[68:71], v151 offset:1152
	v_add_u32_e32 v96, 0x120000, v152
	v_add_u32_e32 v97, 0x130000, v152
	v_add_u32_e32 v99, 0x130080, v152
	s_waitcnt vmcnt(11) lgkmcnt(1)
	v_pk_fma_f32 v[66:67], v[108:109], v[66:67], v[106:107]
	v_pk_fma_f32 v[64:65], v[110:111], v[64:65], v[104:105]
	s_waitcnt vmcnt(10) lgkmcnt(0)
	v_pk_fma_f32 v[70:71], v[108:109], v[70:71], v[114:115]
	v_pk_fma_f32 v[68:69], v[110:111], v[68:69], v[112:113]
	global_store_dwordx4 v164, v[64:67], s[12:13] nt
	v_pk_mul_f32 v[72:73], v[108:109], v[70:71]
	v_pk_mul_f32 v[74:75], v[110:111], v[68:69]
	v_pk_mul_f32 v[64:65], v[110:111], v[64:65]
	v_pk_mul_f32 v[66:67], v[108:109], v[66:67]
	v_cvt_pk_bf16_f32 v64, v64, v65
	s_nop 0
	v_cvt_pk_bf16_f32 v64, v66, v67
	global_store_dwordx4 v165, v[68:71], s[12:13] nt
	v_cvt_pk_bf16_f32 v64, v74, v75
	s_nop 0
	v_cvt_pk_bf16_f32 v64, v72, v73
	global_load_dwordx4 v[64:67], v96, s[12:13] nt
	global_load_dwordx4 v[68:71], v97, s[12:13] nt
	global_load_dwordx4 v[72:75], v98, s[12:13] nt
	global_load_dwordx4 v[76:79], v99, s[12:13] nt
	ds_write_b128 v150, v[60:63]
	ds_write_b128 v150, v[56:59] offset:64
	ds_read_b128 v[56:59], v151
	ds_read_b128 v[60:63], v151 offset:1152
	s_waitcnt vmcnt(11) lgkmcnt(1)
	v_pk_fma_f32 v[58:59], v[120:121], v[58:59], v[82:83]
	v_pk_fma_f32 v[56:57], v[122:123], v[56:57], v[80:81]
	s_waitcnt vmcnt(10) lgkmcnt(0)
	v_pk_fma_f32 v[62:63], v[120:121], v[62:63], v[86:87]
	v_pk_fma_f32 v[60:61], v[122:123], v[60:61], v[84:85]
	global_store_dwordx4 v116, v[56:59], s[12:13] nt
	v_pk_mul_f32 v[80:81], v[120:121], v[62:63]
	v_pk_mul_f32 v[82:83], v[122:123], v[60:61]
	v_pk_mul_f32 v[56:57], v[122:123], v[56:57]
	v_pk_mul_f32 v[58:59], v[120:121], v[58:59]
	v_cvt_pk_bf16_f32 v56, v56, v57
	s_nop 0
	v_cvt_pk_bf16_f32 v56, v58, v59
	global_store_dwordx4 v117, v[60:63], s[12:13] nt
	v_cvt_pk_bf16_f32 v56, v82, v83
	v_add_u32_e32 v82, 0x140080, v152
	v_cvt_pk_bf16_f32 v56, v80, v81
	ds_write_b128 v150, v[52:55]
	ds_write_b128 v150, v[48:51] offset:64
	ds_read_b128 v[48:51], v151
	ds_read_b128 v[52:55], v151 offset:1152
	v_add_u32_e32 v80, 0x140000, v152
	v_add_u32_e32 v81, 0x150000, v152
	v_add_u32_e32 v83, 0x150080, v152
	s_waitcnt vmcnt(11) lgkmcnt(1)
	v_pk_fma_f32 v[50:51], v[108:109], v[50:51], v[90:91]
	v_pk_fma_f32 v[48:49], v[110:111], v[48:49], v[88:89]
	s_waitcnt vmcnt(10) lgkmcnt(0)
; #define LAS __attribute__((address_space(3)))
; __device__ __forceinline__ unsigned cvt_pk_bf16(float lo, float hi) { unsigned r; asm volatile("v_cvt_pk_bf16_f32 %0, %1, %2" : "=v"(r) : "v"(lo), "v"(hi)); return r; }
; #define ERN_EOFF(q, m) (eb + (unsigned)((((q) & 1) * HALF + (m) * 16) * DM + ERN_COL((q) >> 1)))
; #define ERN_LOADX(q) do { _Pragma("unroll") for (int m = 0; m < 4; ++m) xb[(q) & 1][m] = *(const f32x4*)((const char*)xi + 4u * ERN_EOFF(q, m)); } while (0)
; #define ERN_LOADX(g) do { _Pragma("unroll") for (int bj_ = 0; bj_ < 2; ++bj_) _Pragma("unroll") for (int rh_ = 0; rh_ < 2; ++rh_) xb[(g) & 1][bj_][rh_] = *(const f32x4*)((const char*)xi + 4u * ERN_EOFF(g, bj_, rh_)); } while (0)
;     __device__ __forceinline__ void operator()(const f32x4 (&acc)[2][2][4][2], const Unit& u, int wr, int wc, int fr, int fq) const {
;     ...
;         for (int g = 0; g < 8; ++g) { const int ai = g >> 2, m = g & 3;
;             if (g + 1 < 8) ERN_LOADX(g + 1);
;             float sq0 = 0.f, sq1 = 0.f; u32x2 hw[2][2];
; #pragma unroll
;             for (int bj = 0; bj < 2; ++bj) {
;                 *(LAS f32x4*)(st + wr_off) = acc[ai][bj][m][0]; *(LAS f32x4*)(st + wr_off + 64) = acc[ai][bj][m][1];
;                 const f32x4 a0 = *(const LAS f32x4*)(st + rd_off), a1 = *(const LAS f32x4*)(st + rd_off + 8 * 144);
;                 { const f32x4 xv = xb[g & 1][bj][0] + gv[bj] * a0; __builtin_nontemporal_store(xv, (f32x4*)((char*)xo + 4u * ERN_EOFF(g, bj, 0)));
;                   sq0 += (xv.x * xv.x + xv.y * xv.y) + (xv.z * xv.z + xv.w * xv.w);
;                   const f32x4 hv = xv * gsn[bj]; hw[bj][0].x = cvt_pk_bf16(hv.x, hv.y); hw[bj][0].y = cvt_pk_bf16(hv.z, hv.w); }
;                 { const f32x4 xv = xb[g & 1][bj][1] + gv[bj] * a1; __builtin_nontemporal_store(xv, (f32x4*)((char*)xo + 4u * ERN_EOFF(g, bj, 1)));
;                   sq1 += (xv.x * xv.x + xv.y * xv.y) + (xv.z * xv.z + xv.w * xv.w);
;                   const f32x4 hv = xv * gsn[bj]; hw[bj][1].x = cvt_pk_bf16(hv.x, hv.y); hw[bj][1].y = cvt_pk_bf16(hv.z, hv.w); }
;             }
	v_pk_fma_f32 v[54:55], v[108:109], v[54:55], v[94:95]
	v_pk_fma_f32 v[52:53], v[110:111], v[52:53], v[92:93]
	global_store_dwordx4 v118, v[48:51], s[12:13] nt
	v_pk_mul_f32 v[56:57], v[108:109], v[54:55]
	v_pk_mul_f32 v[58:59], v[110:111], v[52:53]
	v_pk_mul_f32 v[48:49], v[110:111], v[48:49]
	v_pk_mul_f32 v[50:51], v[108:109], v[50:51]
	v_cvt_pk_bf16_f32 v48, v48, v49
	s_nop 0
	v_cvt_pk_bf16_f32 v48, v50, v51
	global_store_dwordx4 v119, v[52:55], s[12:13] nt
	v_cvt_pk_bf16_f32 v48, v58, v59
	s_nop 0
	v_cvt_pk_bf16_f32 v48, v56, v57
	global_load_dwordx4 v[48:51], v80, s[12:13] nt
	global_load_dwordx4 v[52:55], v81, s[12:13] nt
	ds_write_b128 v150, v[44:47]
	ds_write_b128 v150, v[40:43] offset:64
	ds_read_b128 v[40:43], v151
	ds_read_b128 v[44:47], v151 offset:1152
	global_load_dwordx4 v[56:59], v82, s[12:13] nt
	global_load_dwordx4 v[60:63], v83, s[12:13] nt
	s_waitcnt vmcnt(11) lgkmcnt(1)
	v_pk_fma_f32 v[42:43], v[120:121], v[42:43], v[66:67]
	v_pk_fma_f32 v[40:41], v[122:123], v[40:41], v[64:65]
	s_waitcnt vmcnt(10) lgkmcnt(0)
	v_pk_fma_f32 v[46:47], v[120:121], v[46:47], v[70:71]
	v_pk_fma_f32 v[44:45], v[122:123], v[44:45], v[68:69]
	global_store_dwordx4 v96, v[40:43], s[12:13] nt
	v_pk_mul_f32 v[64:65], v[120:121], v[46:47]
	v_pk_mul_f32 v[66:67], v[122:123], v[44:45]
	v_pk_mul_f32 v[40:41], v[122:123], v[40:41]
	v_pk_mul_f32 v[42:43], v[120:121], v[42:43]
	v_cvt_pk_bf16_f32 v40, v40, v41
	s_nop 0
	v_cvt_pk_bf16_f32 v40, v42, v43
	global_store_dwordx4 v97, v[44:47], s[12:13] nt
	v_cvt_pk_bf16_f32 v40, v66, v67
	v_add_u32_e32 v66, 0x160080, v152
	v_cvt_pk_bf16_f32 v40, v64, v65
	ds_write_b128 v150, v[36:39]
	ds_write_b128 v150, v[32:35] offset:64
	ds_read_b128 v[32:35], v151
	ds_read_b128 v[36:39], v151 offset:1152
	v_add_u32_e32 v64, 0x160000, v152
	v_add_u32_e32 v65, 0x170000, v152
	v_add_u32_e32 v67, 0x170080, v152
	s_waitcnt vmcnt(11) lgkmcnt(1)
	v_pk_fma_f32 v[34:35], v[108:109], v[34:35], v[74:75]
	v_pk_fma_f32 v[32:33], v[110:111], v[32:33], v[72:73]
	s_waitcnt vmcnt(10) lgkmcnt(0)
	v_pk_fma_f32 v[38:39], v[108:109], v[38:39], v[78:79]
	v_pk_fma_f32 v[36:37], v[110:111], v[36:37], v[76:77]
	global_store_dwordx4 v98, v[32:35], s[12:13] nt
	v_pk_mul_f32 v[40:41], v[108:109], v[38:39]
	v_pk_mul_f32 v[42:43], v[110:111], v[36:37]
	v_pk_mul_f32 v[32:33], v[110:111], v[32:33]
	v_pk_mul_f32 v[34:35], v[108:109], v[34:35]
	v_cvt_pk_bf16_f32 v32, v32, v33
	s_nop 0
	v_cvt_pk_bf16_f32 v32, v34, v35
	global_store_dwordx4 v99, v[36:39], s[12:13] nt
	v_cvt_pk_bf16_f32 v32, v42, v43
	s_nop 0
	v_cvt_pk_bf16_f32 v32, v40, v41
	global_load_dwordx4 v[32:35], v64, s[12:13] nt
	global_load_dwordx4 v[36:39], v65, s[12:13] nt
	global_load_dwordx4 v[40:43], v66, s[12:13] nt
	global_load_dwordx4 v[44:47], v67, s[12:13] nt
	ds_write_b128 v150, v[28:31]
	ds_write_b128 v150, v[24:27] offset:64
	ds_read_b128 v[24:27], v151
	ds_read_b128 v[28:31], v151 offset:1152
	s_waitcnt vmcnt(11) lgkmcnt(1)
	v_pk_fma_f32 v[26:27], v[120:121], v[26:27], v[50:51]
	v_pk_fma_f32 v[24:25], v[122:123], v[24:25], v[48:49]
	s_waitcnt vmcnt(10) lgkmcnt(0)
	v_pk_fma_f32 v[30:31], v[120:121], v[30:31], v[54:55]
	v_pk_fma_f32 v[28:29], v[122:123], v[28:29], v[52:53]
	global_store_dwordx4 v80, v[24:27], s[12:13] nt
	v_pk_mul_f32 v[48:49], v[120:121], v[30:31]
	v_pk_mul_f32 v[50:51], v[122:123], v[28:29]
	v_pk_mul_f32 v[24:25], v[122:123], v[24:25]
	v_pk_mul_f32 v[26:27], v[120:121], v[26:27]
	v_cvt_pk_bf16_f32 v24, v24, v25
	s_nop 0
	v_cvt_pk_bf16_f32 v24, v26, v27
	global_store_dwordx4 v81, v[28:31], s[12:13] nt
	v_cvt_pk_bf16_f32 v24, v50, v51
	s_nop 0
	v_cvt_pk_bf16_f32 v24, v48, v49
	ds_write_b128 v150, v[20:23]
	ds_write_b128 v150, v[16:19] offset:64
	ds_read_b128 v[16:19], v151
	ds_read_b128 v[20:23], v151 offset:1152
	s_waitcnt vmcnt(11) lgkmcnt(1)
	v_pk_fma_f32 v[18:19], v[108:109], v[18:19], v[58:59]
	v_pk_fma_f32 v[16:17], v[110:111], v[16:17], v[56:57]
	s_waitcnt vmcnt(10) lgkmcnt(0)
	v_pk_fma_f32 v[22:23], v[108:109], v[22:23], v[62:63]
	v_pk_fma_f32 v[20:21], v[110:111], v[20:21], v[60:61]
	global_store_dwordx4 v82, v[16:19], s[12:13] nt
	v_pk_mul_f32 v[24:25], v[108:109], v[22:23]
	v_pk_mul_f32 v[26:27], v[110:111], v[20:21]
	v_pk_mul_f32 v[16:17], v[110:111], v[16:17]
	v_pk_mul_f32 v[18:19], v[108:109], v[18:19]
	v_cvt_pk_bf16_f32 v16, v16, v17
	s_nop 0
	v_cvt_pk_bf16_f32 v16, v18, v19
	global_store_dwordx4 v83, v[20:23], s[12:13] nt
	v_cvt_pk_bf16_f32 v16, v26, v27
	s_nop 0
	v_cvt_pk_bf16_f32 v16, v24, v25
	ds_write_b128 v150, v[12:15]
	ds_write_b128 v150, v[8:11] offset:64
	ds_read_b128 v[8:11], v151
	ds_read_b128 v[12:15], v151 offset:1152
	s_waitcnt vmcnt(7) lgkmcnt(1)
	v_pk_fma_f32 v[10:11], v[120:121], v[10:11], v[34:35]
	v_pk_fma_f32 v[8:9], v[122:123], v[8:9], v[32:33]
	s_waitcnt vmcnt(6) lgkmcnt(0)
	v_pk_fma_f32 v[14:15], v[120:121], v[14:15], v[38:39]
	v_pk_fma_f32 v[12:13], v[122:123], v[12:13], v[36:37]
	global_store_dwordx4 v64, v[8:11], s[12:13] nt
	v_pk_mul_f32 v[16:17], v[120:121], v[14:15]
	v_pk_mul_f32 v[18:19], v[122:123], v[12:13]
	v_pk_mul_f32 v[8:9], v[122:123], v[8:9]
	v_pk_mul_f32 v[10:11], v[120:121], v[10:11]
	v_cvt_pk_bf16_f32 v8, v8, v9
	s_nop 0
	v_cvt_pk_bf16_f32 v8, v10, v11
	global_store_dwordx4 v65, v[12:15], s[12:13] nt
	v_cvt_pk_bf16_f32 v8, v18, v19
	s_nop 0
	v_cvt_pk_bf16_f32 v8, v16, v17
	ds_write_b128 v150, v[4:7]
	ds_write_b128 v150, v[0:3] offset:64
	ds_read_b128 v[0:3], v151
	ds_read_b128 v[4:7], v151 offset:1152
	s_waitcnt vmcnt(7) lgkmcnt(1)
	v_pk_fma_f32 v[2:3], v[108:109], v[2:3], v[42:43]
	v_pk_fma_f32 v[0:1], v[110:111], v[0:1], v[40:41]
	s_waitcnt vmcnt(6) lgkmcnt(0)
	v_pk_fma_f32 v[6:7], v[108:109], v[6:7], v[46:47]
	v_pk_fma_f32 v[4:5], v[110:111], v[4:5], v[44:45]
	global_store_dwordx4 v66, v[0:3], s[12:13] nt
	v_pk_mul_f32 v[8:9], v[108:109], v[6:7]
	v_pk_mul_f32 v[10:11], v[110:111], v[4:5]
	v_pk_mul_f32 v[0:1], v[110:111], v[0:1]
	v_pk_mul_f32 v[2:3], v[108:109], v[2:3]
	v_cvt_pk_bf16_f32 v0, v0, v1
	s_nop 0
	v_cvt_pk_bf16_f32 v0, v2, v3
	global_store_dwordx4 v67, v[4:7], s[12:13] nt
	v_cvt_pk_bf16_f32 v0, v10, v11
	s_nop 0
	v_cvt_pk_bf16_f32 v0, v8, v9
	s_cbranch_vccz .LBB0_2990
	s_andn2_b64 vcc, exec, s[4:5]
	s_cbranch_vccnz .LBB0_2989
	s_barrier
	s_branch .LBB0_2989
